# gather: expert ids (dot phase) and per-expert coefficients (value phase) both served from wave-private LDS rows, on top of the LDS assembly of dot results
# baseline (speedup 1.0000x reference)
; DEV int opaque_tid() { int t = (int)threadIdx.x; asm volatile("" : "+v"(t)); return t; }
; __device__ void peer_gather_phase(const Params& P, int l, bool do_store) {
;   const int lane = opaque_tid() & 63, w = opaque_tid() >> 6;
;   const unsigned char* U = P.U8 + (size_t)l * 16384 * 768 + (lane & 31) * 24;
;   const unsigned char* V = P.V8 + (size_t)l * 16384 * 512 + lane * 8;
;   const float* SU = P.SU + l * 16384;
;   const float* SV = P.SV + l * 16384;
;   int nev0, nev1; float ngv0, ngv1; uint4 nxa, nxc;
;   {
;     const int t = blockIdx.x * 4 + w;
;     nev0 = P.EXP[(size_t)t * 128 + lane]; nev1 = P.EXP[(size_t)t * 128 + 64 + lane];
;     ngv0 = P.GATE[(size_t)t * 128 + lane]; ngv1 = P.GATE[(size_t)t * 128 + 64 + lane];
;     const bf16_t* xb = P.XB + (size_t)t * 1024 + lane * 16;
;     nxa = *(const uint4*)xb; nxc = *(const uint4*)(xb + 8);
;   }
; __device__ void run_phase(const Params& P, int ph, char* smem, bool do_store) {
;     ...
;   const int l = (ph - 1) >> 3, sub = (ph - 1) & 7;
;   const int G = gridDim.x, bid = blockIdx.x;
;   switch (sub) {
.LBB0_14:
	v_readlane_b32 s4, v248, 27
	s_add_i32 s4, s4, 1
	v_readlane_b32 s2, v249, 37
	s_cmp_eq_u32 s4, s2
	v_writelane_b32 v248, s4, 27
	s_cselect_b64 s[4:5], -1, 0
	v_writelane_b32 v248, s4, 32
	s_mov_b64 s[0:1], -1
	s_nop 0
	v_writelane_b32 v248, s5, 33
	v_readlane_b32 s4, v249, 38
	v_readlane_b32 s5, v249, 39
	s_and_b64 vcc, exec, s[4:5]
	s_cbranch_vccz .LBB0_310
	v_readlane_b32 s0, v251, 58
	v_readlane_b32 s1, v251, 59
	s_load_dword s0, s[0:1], 0x0
	s_waitcnt lgkmcnt(0)
	v_writelane_b32 v248, s0, 34
	s_nop 1
	v_writelane_b32 v248, s1, 35
	v_readlane_b32 s0, v249, 40
	s_cmp_lt_i32 s0, 4
	s_mov_b64 s[0:1], -1
	s_cbranch_scc1 .LBB0_65
	v_readlane_b32 s0, v249, 40
	s_cmp_lt_i32 s0, 6
	s_mov_b64 s[0:1], -1
	s_cbranch_scc1 .LBB0_39
	v_readlane_b32 s0, v249, 40
	s_cmp_gt_i32 s0, 6
	s_cbranch_scc0 .LBB0_38
	v_readlane_b32 s0, v251, 60
	v_readlane_b32 s1, v251, 61
	v_mov_b32_e32 v0, v202
	v_mov_b32_e32 v1, v202
	s_andn2_b64 vcc, exec, s[0:1]
	s_cbranch_vccnz .LBB0_38
	v_ashrrev_i32_e32 v73, 6, v1
	v_and_b32_e32 v1, 31, v0
	v_readlane_b32 s0, v249, 41
	v_mul_u32_u24_e32 v176, 24, v1
	v_readlane_b32 s1, v249, 42
	v_and_b32_e32 v72, 63, v0
	v_readlane_b32 s4, v251, 2
	v_lshl_add_u64 v[74:75], s[0:1], 0, v[176:177]
	v_readlane_b32 s0, v249, 43
	v_lshlrev_b32_e32 v176, 3, v72
	v_readlane_b32 s1, v249, 44
	v_readlane_b32 s5, v251, 3
	v_readlane_b32 s6, v251, 4
	v_lshl_add_u64 v[76:77], s[0:1], 0, v[176:177]
	v_readlane_b32 s0, v251, 62
	v_lshlrev_b32_e32 v176, 5, v72
	v_readlane_b32 s7, v251, 5
	v_add_u32_e32 v2, s0, v73
	v_ashrrev_i32_e32 v3, 31, v2
	v_lshlrev_b64 v[4:5], 11, v[2:3]
	v_lshl_add_u64 v[4:5], s[28:29], 0, v[4:5]
	v_lshlrev_b64 v[2:3], 9, v[2:3]
	v_lshl_add_u64 v[4:5], v[4:5], 0, v[176:177]
	v_lshl_or_b32 v2, v72, 2, v2
	global_load_dwordx4 v[64:67], v[4:5], off offset:16
	global_load_dwordx4 v[68:71], v[4:5], off
	v_lshl_add_u64 v[4:5], s[4:5], 0, v[2:3]
	v_lshl_add_u64 v[2:3], s[6:7], 0, v[2:3]
	global_load_dword v93, v[4:5], off offset:256
	global_load_dword v91, v[4:5], off
	global_load_dword v188, v[2:3], off offset:256
	global_load_dword v179, v[2:3], off
	v_readlane_b32 s0, v249, 49
	v_readlane_b32 s4, v248, 32
	v_readlane_b32 s1, v249, 50
	v_readlane_b32 s5, v248, 33
	s_and_b64 s[38:39], s[0:1], s[4:5]
	v_readlane_b32 s0, v248, 1
	v_readlane_b32 s1, v248, 2
	s_and_b64 s[0:1], s[0:1], s[4:5]
	s_xor_b64 s[0:1], s[0:1], -1
	v_writelane_b32 v248, s0, 45
	v_lshl_add_u64 v[78:79], s[28:29], 0, v[176:177]
	v_lshlrev_b32_e32 v176, 6, v72
	v_writelane_b32 v248, s1, 46
	v_readlane_b32 s0, v249, 54
	v_readlane_b32 s1, v249, 55
	v_lshlrev_b32_e32 v0, 5, v0
	v_readlane_b32 s44, v252, 12
	v_lshl_add_u64 v[82:83], s[0:1], 0, v[176:177]
	v_readlane_b32 s0, v249, 56
	v_readlane_b32 s1, v249, 57
	v_lshlrev_b32_e32 v2, 4, v72
	v_and_b32_e32 v0, 0x3e0, v0
	v_readlane_b32 s58, v252, 26
	v_readlane_b32 s59, v252, 27
	v_lshl_add_u64 v[84:85], s[0:1], 0, v[176:177]
	v_readlane_b32 s0, v249, 5
	v_cmp_lt_u32_e64 s[40:41], 31, v72
	v_lshl_add_u64 v[80:81], s[58:59], 0, v[176:177]
	v_lshlrev_b32_e32 v86, 1, v0
	v_lshlrev_b32_e32 v176, 1, v2
	v_mov_b32_e32 v87, v177
	s_mov_b32 s2, s0
	s_movk_i32 s33, 0x300
	v_readlane_b32 s45, v252, 13
	v_readlane_b32 s46, v252, 14
	v_readlane_b32 s47, v252, 15
	v_readlane_b32 s48, v252, 16
	v_readlane_b32 s49, v252, 17
	v_readlane_b32 s50, v252, 18
	v_readlane_b32 s51, v252, 19
	v_readlane_b32 s52, v252, 20
	v_readlane_b32 s53, v252, 21
	v_readlane_b32 s54, v252, 22
	v_readlane_b32 s55, v252, 23
	v_readlane_b32 s56, v252, 24
	v_readlane_b32 s57, v252, 25
	v_readlane_b32 s1, v249, 6
	v_lshrrev_b32_e32 v74, 5, v72
	v_lshlrev_b32_e32 v74, 2, v74
	v_lshl_add_u32 v74, v73, 10, v74
	v_lshlrev_b32_e32 v75, 2, v72
	v_lshl_add_u32 v75, v73, 10, v75
	v_lshlrev_b32_e32 v193, 10, v73
	s_branch .LBB0_21

; __device__ void peer_gather_phase(const Params& P, int l, bool do_store) {
;     ...
;     auto load_batch = [&](uint2 (&u6)[12], uint2 (&v8)[8], int bt) {
;       const int evs = (bt < 8) ? ev0 : ev1;
;       const int kb = (bt & 7) * 8;
; #pragma unroll
;       for (int pr = 0; pr < 4; ++pr) {
;         const int ea = __builtin_amdgcn_readlane(evs, kb + 2 * pr), eb = __builtin_amdgcn_readlane(evs, kb + 2 * pr + 1);
;         const uint2* up = (const uint2*)(U + (size_t)(uphi ? eb : ea) * 768);
;         u6[3 * pr] = up[0]; u6[3 * pr + 1] = up[1]; u6[3 * pr + 2] = up[2];
;         v8[2 * pr] = *(const uint2*)(V + (size_t)ea * 512);
;         v8[2 * pr + 1] = *(const uint2*)(V + (size_t)eb * 512);
;       }
;     };
;     auto compute_batch = [&](const uint2 (&u6)[12], const uint2 (&v8)[8], int bt) {
;       const int kb = (bt & 7) * 8;
;       float dvec = 0.f;
; #pragma unroll
;       for (int pr = 0; pr < 4; ++pr) {
;         v6u_t qv; qv[0] = u6[3 * pr].x; qv[1] = u6[3 * pr].y; qv[2] = u6[3 * pr + 1].x; qv[3] = u6[3 * pr + 1].y; qv[4] = u6[3 * pr + 2].x; qv[5] = u6[3 * pr + 2].y;
;         const v32f_t wv = __builtin_amdgcn_cvt_scalef32_pk32_f32_fp6(qv, 1.0f);
;         f32x2 a2 = f32x2{0.f, 0.f};
; #pragma unroll
;         for (int i = 0; i < 16; ++i) a2 += f32x2{wv[2 * i], wv[2 * i + 1]} * xu[i];
;         float hs = a2.x + a2.y;
;         hs += dpp_row_shr(hs, 1); hs += dpp_row_shr(hs, 2); hs += dpp_row_shr(hs, 4); hs += dpp_row_shr(hs, 8);
;         hs += __builtin_bit_cast(float, __builtin_amdgcn_update_dpp(0, __builtin_bit_cast(int, hs), 0x142, 0xa, 0xf, false));
;         const float da = __builtin_bit_cast(float, __builtin_amdgcn_readlane(__builtin_bit_cast(int, hs), 31));
;         const float db = __builtin_bit_cast(float, __builtin_amdgcn_readlane(__builtin_bit_cast(int, hs), 63));
;         dvec = (lane == kb + 2 * pr) ? da : dvec;
;         dvec = (lane == kb + 2 * pr + 1) ? db : dvec;
;       }
.LBB0_22:
	ds_write_b32 v75, v92 offset:256
	ds_read_b32 v76, v74 offset:320
	s_waitcnt lgkmcnt(0)
	v_mad_u32_u24 v167, v76, s33, v195
	ds_read_b32 v77, v74 offset:328
	s_waitcnt vmcnt(32)
	v_cvt_scalef32_pk32_f32_fp6 v[0:31], v[50:55], 1.0
	global_load_dwordx2 v[54:55], v167, s[62:63] offset:16
	global_load_dwordx4 v[50:53], v167, s[62:63]
	v_pk_mul_f32 v[246:247], v[0:1], v[96:97]
	v_pk_mul_f32 v[254:255], v[2:3], v[98:99]
	v_pk_mul_f32 v[160:161], v[4:5], v[100:101]
	v_pk_fma_f32 v[246:247], v[6:7], v[102:103], v[246:247]
	v_pk_fma_f32 v[254:255], v[8:9], v[104:105], v[254:255]
	v_pk_fma_f32 v[160:161], v[10:11], v[106:107], v[160:161]
	v_pk_fma_f32 v[246:247], v[12:13], v[108:109], v[246:247]
	v_pk_fma_f32 v[254:255], v[14:15], v[110:111], v[254:255]
	v_pk_fma_f32 v[160:161], v[16:17], v[112:113], v[160:161]
	v_pk_fma_f32 v[246:247], v[18:19], v[114:115], v[246:247]
	v_pk_fma_f32 v[254:255], v[20:21], v[116:117], v[254:255]
	v_pk_fma_f32 v[160:161], v[22:23], v[118:119], v[160:161]
	v_pk_fma_f32 v[246:247], v[24:25], v[120:121], v[246:247]
	v_pk_fma_f32 v[254:255], v[26:27], v[122:123], v[254:255]
	v_pk_fma_f32 v[160:161], v[28:29], v[124:125], v[160:161]
	v_pk_fma_f32 v[246:247], v[30:31], v[126:127], v[246:247]
	v_pk_add_f32 v[254:255], v[254:255], v[160:161]
	s_nop 0
	v_pk_add_f32 v[246:247], v[246:247], v[254:255]
	s_nop 0
	v_add_f32_e32 v162, v246, v247
	s_waitcnt lgkmcnt(0)
	v_mad_u32_u24 v167, v77, s33, v195
	ds_read_b32 v76, v74 offset:336
	s_waitcnt vmcnt(32)
	v_cvt_scalef32_pk32_f32_fp6 v[0:31], v[44:49], 1.0
	global_load_dwordx2 v[48:49], v167, s[62:63] offset:16
	global_load_dwordx4 v[44:47], v167, s[62:63]
	v_pk_mul_f32 v[246:247], v[0:1], v[96:97]
	v_pk_mul_f32 v[254:255], v[2:3], v[98:99]
	v_pk_mul_f32 v[160:161], v[4:5], v[100:101]
	v_pk_fma_f32 v[246:247], v[6:7], v[102:103], v[246:247]
	v_pk_fma_f32 v[254:255], v[8:9], v[104:105], v[254:255]
	v_pk_fma_f32 v[160:161], v[10:11], v[106:107], v[160:161]
	v_pk_fma_f32 v[246:247], v[12:13], v[108:109], v[246:247]
	v_pk_fma_f32 v[254:255], v[14:15], v[110:111], v[254:255]
	v_pk_fma_f32 v[160:161], v[16:17], v[112:113], v[160:161]
	v_pk_fma_f32 v[246:247], v[18:19], v[114:115], v[246:247]
	v_pk_fma_f32 v[254:255], v[20:21], v[116:117], v[254:255]
	v_pk_fma_f32 v[160:161], v[22:23], v[118:119], v[160:161]
	v_pk_fma_f32 v[246:247], v[24:25], v[120:121], v[246:247]
	v_pk_fma_f32 v[254:255], v[26:27], v[122:123], v[254:255]
	v_pk_fma_f32 v[160:161], v[28:29], v[124:125], v[160:161]
	v_pk_fma_f32 v[246:247], v[30:31], v[126:127], v[246:247]
	v_pk_add_f32 v[254:255], v[254:255], v[160:161]
	s_nop 0
	v_pk_add_f32 v[246:247], v[246:247], v[254:255]
	s_nop 0
	v_add_f32_e32 v163, v246, v247
	s_waitcnt lgkmcnt(0)
	v_mad_u32_u24 v167, v76, s33, v195
	ds_read_b32 v77, v74 offset:344
	s_waitcnt vmcnt(32)
	v_cvt_scalef32_pk32_f32_fp6 v[0:31], v[38:43], 1.0
	global_load_dwordx2 v[42:43], v167, s[62:63] offset:16
	global_load_dwordx4 v[38:41], v167, s[62:63]
	v_pk_mul_f32 v[246:247], v[0:1], v[96:97]
	v_pk_mul_f32 v[254:255], v[2:3], v[98:99]
	v_pk_mul_f32 v[160:161], v[4:5], v[100:101]
	v_pk_fma_f32 v[246:247], v[6:7], v[102:103], v[246:247]
	v_pk_fma_f32 v[254:255], v[8:9], v[104:105], v[254:255]
	v_pk_fma_f32 v[160:161], v[10:11], v[106:107], v[160:161]
	v_pk_fma_f32 v[246:247], v[12:13], v[108:109], v[246:247]
	v_pk_fma_f32 v[254:255], v[14:15], v[110:111], v[254:255]
	v_pk_fma_f32 v[160:161], v[16:17], v[112:113], v[160:161]
	v_pk_fma_f32 v[246:247], v[18:19], v[114:115], v[246:247]
	v_pk_fma_f32 v[254:255], v[20:21], v[116:117], v[254:255]
	v_pk_fma_f32 v[160:161], v[22:23], v[118:119], v[160:161]
	v_pk_fma_f32 v[246:247], v[24:25], v[120:121], v[246:247]
	v_pk_fma_f32 v[254:255], v[26:27], v[122:123], v[254:255]
	v_pk_fma_f32 v[160:161], v[28:29], v[124:125], v[160:161]
	v_pk_fma_f32 v[246:247], v[30:31], v[126:127], v[246:247]
	v_pk_add_f32 v[254:255], v[254:255], v[160:161]
	s_nop 0
	v_pk_add_f32 v[246:247], v[246:247], v[254:255]
	s_nop 0
	v_add_f32_e32 v164, v246, v247
	s_waitcnt lgkmcnt(0)
	v_mad_u32_u24 v167, v77, s33, v195
	ds_read_b32 v76, v74 offset:352
	s_waitcnt vmcnt(32)
	v_cvt_scalef32_pk32_f32_fp6 v[0:31], v[32:37], 1.0
	global_load_dwordx2 v[36:37], v167, s[62:63] offset:16
	global_load_dwordx4 v[32:35], v167, s[62:63]
	v_pk_mul_f32 v[246:247], v[0:1], v[96:97]
	v_pk_mul_f32 v[254:255], v[2:3], v[98:99]
	v_pk_mul_f32 v[160:161], v[4:5], v[100:101]
	v_pk_fma_f32 v[246:247], v[6:7], v[102:103], v[246:247]
	v_pk_fma_f32 v[254:255], v[8:9], v[104:105], v[254:255]
	v_pk_fma_f32 v[160:161], v[10:11], v[106:107], v[160:161]
	v_pk_fma_f32 v[246:247], v[12:13], v[108:109], v[246:247]
	v_pk_fma_f32 v[254:255], v[14:15], v[110:111], v[254:255]
	v_pk_fma_f32 v[160:161], v[16:17], v[112:113], v[160:161]
	v_pk_fma_f32 v[246:247], v[18:19], v[114:115], v[246:247]
	v_pk_fma_f32 v[254:255], v[20:21], v[116:117], v[254:255]
	v_pk_fma_f32 v[160:161], v[22:23], v[118:119], v[160:161]
	v_pk_fma_f32 v[246:247], v[24:25], v[120:121], v[246:247]
	v_pk_fma_f32 v[254:255], v[26:27], v[122:123], v[254:255]
	v_pk_fma_f32 v[160:161], v[28:29], v[124:125], v[160:161]
	v_pk_fma_f32 v[246:247], v[30:31], v[126:127], v[246:247]
	v_pk_add_f32 v[254:255], v[254:255], v[160:161]
	s_nop 0
	v_pk_add_f32 v[246:247], v[246:247], v[254:255]
	s_nop 0
	v_add_f32_e32 v165, v246, v247
	v_add_f32_dpp v162, v162, v162 row_shr:1 row_mask:0xf bank_mask:0xf bound_ctrl:1
	v_add_f32_dpp v163, v163, v163 row_shr:1 row_mask:0xf bank_mask:0xf bound_ctrl:1
	v_add_f32_dpp v164, v164, v164 row_shr:1 row_mask:0xf bank_mask:0xf bound_ctrl:1
	v_add_f32_dpp v165, v165, v165 row_shr:1 row_mask:0xf bank_mask:0xf bound_ctrl:1
; __device__ void peer_gather_phase(const Params& P, int l, bool do_store) {
;     ...
;       for (int pr = 0; pr < 4; ++pr) {
;         v6u_t qv; qv[0] = u6[3 * pr].x; qv[1] = u6[3 * pr].y; qv[2] = u6[3 * pr + 1].x; qv[3] = u6[3 * pr + 1].y; qv[4] = u6[3 * pr + 2].x; qv[5] = u6[3 * pr + 2].y;
;         const v32f_t wv = __builtin_amdgcn_cvt_scalef32_pk32_f32_fp6(qv, 1.0f);
;         f32x2 a2 = f32x2{0.f, 0.f};
; #pragma unroll
;         for (int i = 0; i < 16; ++i) a2 += f32x2{wv[2 * i], wv[2 * i + 1]} * xu[i];
;         float hs = a2.x + a2.y;
;         hs += dpp_row_shr(hs, 1); hs += dpp_row_shr(hs, 2); hs += dpp_row_shr(hs, 4); hs += dpp_row_shr(hs, 8);
;         hs += __builtin_bit_cast(float, __builtin_amdgcn_update_dpp(0, __builtin_bit_cast(int, hs), 0x142, 0xa, 0xf, false));
;         const float da = __builtin_bit_cast(float, __builtin_amdgcn_readlane(__builtin_bit_cast(int, hs), 31));
;         const float db = __builtin_bit_cast(float, __builtin_amdgcn_readlane(__builtin_bit_cast(int, hs), 63));
;         dvec = (lane == kb + 2 * pr) ? da : dvec;
;         dvec = (lane == kb + 2 * pr + 1) ? db : dvec;
	v_add_f32_dpp v162, v162, v162 row_shr:2 row_mask:0xf bank_mask:0xf bound_ctrl:1
	v_add_f32_dpp v163, v163, v163 row_shr:2 row_mask:0xf bank_mask:0xf bound_ctrl:1
	v_add_f32_dpp v164, v164, v164 row_shr:2 row_mask:0xf bank_mask:0xf bound_ctrl:1
	v_add_f32_dpp v165, v165, v165 row_shr:2 row_mask:0xf bank_mask:0xf bound_ctrl:1
	v_add_f32_dpp v162, v162, v162 row_shr:4 row_mask:0xf bank_mask:0xf bound_ctrl:1
	v_add_f32_dpp v163, v163, v163 row_shr:4 row_mask:0xf bank_mask:0xf bound_ctrl:1
	v_add_f32_dpp v164, v164, v164 row_shr:4 row_mask:0xf bank_mask:0xf bound_ctrl:1
	v_add_f32_dpp v165, v165, v165 row_shr:4 row_mask:0xf bank_mask:0xf bound_ctrl:1
	v_add_f32_dpp v162, v162, v162 row_shr:8 row_mask:0xf bank_mask:0xf bound_ctrl:1
	v_add_f32_dpp v163, v163, v163 row_shr:8 row_mask:0xf bank_mask:0xf bound_ctrl:1
	v_add_f32_dpp v164, v164, v164 row_shr:8 row_mask:0xf bank_mask:0xf bound_ctrl:1
	v_add_f32_dpp v165, v165, v165 row_shr:8 row_mask:0xf bank_mask:0xf bound_ctrl:1
	v_add_f32_dpp v162, v162, v162 row_bcast:15 row_mask:0xa bank_mask:0xf
	v_add_f32_dpp v163, v163, v163 row_bcast:15 row_mask:0xa bank_mask:0xf
	v_add_f32_dpp v164, v164, v164 row_bcast:15 row_mask:0xa bank_mask:0xf
	v_add_f32_dpp v165, v165, v165 row_bcast:15 row_mask:0xa bank_mask:0xf
	s_mov_b64 s[98:99], exec
	s_mov_b32 exec_lo, 0x80000000
	s_mov_b32 exec_hi, 0x80000000
	ds_write_b32 v74, v162
	ds_write_b32 v74, v163 offset:8
	ds_write_b32 v74, v164 offset:16
	ds_write_b32 v74, v165 offset:24
	s_mov_b64 exec, s[98:99]
	s_waitcnt lgkmcnt(0)
	v_mad_u32_u24 v167, v76, s33, v195
	ds_read_b32 v77, v74 offset:360
	s_waitcnt vmcnt(32)
	v_cvt_scalef32_pk32_f32_fp6 v[0:31], v[196:201], 1.0
	global_load_dwordx2 v[200:201], v167, s[62:63] offset:16
	global_load_dwordx4 v[196:199], v167, s[62:63]
	v_pk_mul_f32 v[246:247], v[0:1], v[96:97]
	v_pk_mul_f32 v[254:255], v[2:3], v[98:99]
	v_pk_mul_f32 v[160:161], v[4:5], v[100:101]
	v_pk_fma_f32 v[246:247], v[6:7], v[102:103], v[246:247]
	v_pk_fma_f32 v[254:255], v[8:9], v[104:105], v[254:255]
	v_pk_fma_f32 v[160:161], v[10:11], v[106:107], v[160:161]
	v_pk_fma_f32 v[246:247], v[12:13], v[108:109], v[246:247]
	v_pk_fma_f32 v[254:255], v[14:15], v[110:111], v[254:255]
	v_pk_fma_f32 v[160:161], v[16:17], v[112:113], v[160:161]
	v_pk_fma_f32 v[246:247], v[18:19], v[114:115], v[246:247]
	v_pk_fma_f32 v[254:255], v[20:21], v[116:117], v[254:255]
	v_pk_fma_f32 v[160:161], v[22:23], v[118:119], v[160:161]
	v_pk_fma_f32 v[246:247], v[24:25], v[120:121], v[246:247]
	v_pk_fma_f32 v[254:255], v[26:27], v[122:123], v[254:255]
	v_pk_fma_f32 v[160:161], v[28:29], v[124:125], v[160:161]
	v_pk_fma_f32 v[246:247], v[30:31], v[126:127], v[246:247]
	v_pk_add_f32 v[254:255], v[254:255], v[160:161]
	s_nop 0
	v_pk_add_f32 v[246:247], v[246:247], v[254:255]
	s_nop 0
	v_add_f32_e32 v162, v246, v247
	s_waitcnt lgkmcnt(0)
	v_mad_u32_u24 v167, v77, s33, v195
	ds_read_b32 v76, v74 offset:368
	s_waitcnt vmcnt(32)
	v_cvt_scalef32_pk32_f32_fp6 v[0:31], v[228:233], 1.0
	global_load_dwordx2 v[232:233], v167, s[62:63] offset:16
	global_load_dwordx4 v[228:231], v167, s[62:63]
	v_pk_mul_f32 v[246:247], v[0:1], v[96:97]
	v_pk_mul_f32 v[254:255], v[2:3], v[98:99]
	v_pk_mul_f32 v[160:161], v[4:5], v[100:101]
	v_pk_fma_f32 v[246:247], v[6:7], v[102:103], v[246:247]
	v_pk_fma_f32 v[254:255], v[8:9], v[104:105], v[254:255]
	v_pk_fma_f32 v[160:161], v[10:11], v[106:107], v[160:161]
	v_pk_fma_f32 v[246:247], v[12:13], v[108:109], v[246:247]
	v_pk_fma_f32 v[254:255], v[14:15], v[110:111], v[254:255]
	v_pk_fma_f32 v[160:161], v[16:17], v[112:113], v[160:161]
	v_pk_fma_f32 v[246:247], v[18:19], v[114:115], v[246:247]
	v_pk_fma_f32 v[254:255], v[20:21], v[116:117], v[254:255]
	v_pk_fma_f32 v[160:161], v[22:23], v[118:119], v[160:161]
	v_pk_fma_f32 v[246:247], v[24:25], v[120:121], v[246:247]
	v_pk_fma_f32 v[254:255], v[26:27], v[122:123], v[254:255]
	v_pk_fma_f32 v[160:161], v[28:29], v[124:125], v[160:161]
	v_pk_fma_f32 v[246:247], v[30:31], v[126:127], v[246:247]
	v_pk_add_f32 v[254:255], v[254:255], v[160:161]
	s_nop 0
	v_pk_add_f32 v[246:247], v[246:247], v[254:255]
	s_nop 0
	v_add_f32_e32 v163, v246, v247
	s_waitcnt lgkmcnt(0)
	v_mad_u32_u24 v167, v76, s33, v195
	ds_read_b32 v77, v74 offset:376
	s_waitcnt vmcnt(32)
	v_cvt_scalef32_pk32_f32_fp6 v[0:31], v[234:239], 1.0
	global_load_dwordx2 v[238:239], v167, s[62:63] offset:16
	global_load_dwordx4 v[234:237], v167, s[62:63]
	v_pk_mul_f32 v[246:247], v[0:1], v[96:97]
	v_pk_mul_f32 v[254:255], v[2:3], v[98:99]
	v_pk_mul_f32 v[160:161], v[4:5], v[100:101]
	v_pk_fma_f32 v[246:247], v[6:7], v[102:103], v[246:247]
	v_pk_fma_f32 v[254:255], v[8:9], v[104:105], v[254:255]
	v_pk_fma_f32 v[160:161], v[10:11], v[106:107], v[160:161]
	v_pk_fma_f32 v[246:247], v[12:13], v[108:109], v[246:247]
	v_pk_fma_f32 v[254:255], v[14:15], v[110:111], v[254:255]
	v_pk_fma_f32 v[160:161], v[16:17], v[112:113], v[160:161]
	v_pk_fma_f32 v[246:247], v[18:19], v[114:115], v[246:247]
	v_pk_fma_f32 v[254:255], v[20:21], v[116:117], v[254:255]
	v_pk_fma_f32 v[160:161], v[22:23], v[118:119], v[160:161]
	v_pk_fma_f32 v[246:247], v[24:25], v[120:121], v[246:247]
	v_pk_fma_f32 v[254:255], v[26:27], v[122:123], v[254:255]
	v_pk_fma_f32 v[160:161], v[28:29], v[124:125], v[160:161]
	v_pk_fma_f32 v[246:247], v[30:31], v[126:127], v[246:247]
	v_pk_add_f32 v[254:255], v[254:255], v[160:161]
	s_nop 0
	v_pk_add_f32 v[246:247], v[246:247], v[254:255]
	s_nop 0
	v_add_f32_e32 v164, v246, v247
	s_waitcnt lgkmcnt(0)
	v_mad_u32_u24 v167, v77, s33, v195
	ds_read_b32 v76, v74 offset:384
	s_waitcnt vmcnt(32)
; __device__ void peer_gather_phase(const Params& P, int l, bool do_store) {
;     ...
;       for (int pr = 0; pr < 4; ++pr) {
;         v6u_t qv; qv[0] = u6[3 * pr].x; qv[1] = u6[3 * pr].y; qv[2] = u6[3 * pr + 1].x; qv[3] = u6[3 * pr + 1].y; qv[4] = u6[3 * pr + 2].x; qv[5] = u6[3 * pr + 2].y;
;         const v32f_t wv = __builtin_amdgcn_cvt_scalef32_pk32_f32_fp6(qv, 1.0f);
;         f32x2 a2 = f32x2{0.f, 0.f};
; #pragma unroll
;         for (int i = 0; i < 16; ++i) a2 += f32x2{wv[2 * i], wv[2 * i + 1]} * xu[i];
;         float hs = a2.x + a2.y;
;         hs += dpp_row_shr(hs, 1); hs += dpp_row_shr(hs, 2); hs += dpp_row_shr(hs, 4); hs += dpp_row_shr(hs, 8);
;         hs += __builtin_bit_cast(float, __builtin_amdgcn_update_dpp(0, __builtin_bit_cast(int, hs), 0x142, 0xa, 0xf, false));
;         const float da = __builtin_bit_cast(float, __builtin_amdgcn_readlane(__builtin_bit_cast(int, hs), 31));
;         const float db = __builtin_bit_cast(float, __builtin_amdgcn_readlane(__builtin_bit_cast(int, hs), 63));
;         dvec = (lane == kb + 2 * pr) ? da : dvec;
;         dvec = (lane == kb + 2 * pr + 1) ? db : dvec;
	v_cvt_scalef32_pk32_f32_fp6 v[0:31], v[240:245], 1.0
	global_load_dwordx2 v[244:245], v167, s[62:63] offset:16
	global_load_dwordx4 v[240:243], v167, s[62:63]
	v_pk_mul_f32 v[246:247], v[0:1], v[96:97]
	v_pk_mul_f32 v[254:255], v[2:3], v[98:99]
	v_pk_mul_f32 v[160:161], v[4:5], v[100:101]
	v_pk_fma_f32 v[246:247], v[6:7], v[102:103], v[246:247]
	v_pk_fma_f32 v[254:255], v[8:9], v[104:105], v[254:255]
	v_pk_fma_f32 v[160:161], v[10:11], v[106:107], v[160:161]
	v_pk_fma_f32 v[246:247], v[12:13], v[108:109], v[246:247]
	v_pk_fma_f32 v[254:255], v[14:15], v[110:111], v[254:255]
	v_pk_fma_f32 v[160:161], v[16:17], v[112:113], v[160:161]
	v_pk_fma_f32 v[246:247], v[18:19], v[114:115], v[246:247]
	v_pk_fma_f32 v[254:255], v[20:21], v[116:117], v[254:255]
	v_pk_fma_f32 v[160:161], v[22:23], v[118:119], v[160:161]
	v_pk_fma_f32 v[246:247], v[24:25], v[120:121], v[246:247]
	v_pk_fma_f32 v[254:255], v[26:27], v[122:123], v[254:255]
	v_pk_fma_f32 v[160:161], v[28:29], v[124:125], v[160:161]
	v_pk_fma_f32 v[246:247], v[30:31], v[126:127], v[246:247]
	v_pk_add_f32 v[254:255], v[254:255], v[160:161]
	s_nop 0
	v_pk_add_f32 v[246:247], v[246:247], v[254:255]
	s_nop 0
	v_add_f32_e32 v165, v246, v247
	v_add_f32_dpp v162, v162, v162 row_shr:1 row_mask:0xf bank_mask:0xf bound_ctrl:1
	v_add_f32_dpp v163, v163, v163 row_shr:1 row_mask:0xf bank_mask:0xf bound_ctrl:1
	v_add_f32_dpp v164, v164, v164 row_shr:1 row_mask:0xf bank_mask:0xf bound_ctrl:1
	v_add_f32_dpp v165, v165, v165 row_shr:1 row_mask:0xf bank_mask:0xf bound_ctrl:1
	v_add_f32_dpp v162, v162, v162 row_shr:2 row_mask:0xf bank_mask:0xf bound_ctrl:1
	v_add_f32_dpp v163, v163, v163 row_shr:2 row_mask:0xf bank_mask:0xf bound_ctrl:1
	v_add_f32_dpp v164, v164, v164 row_shr:2 row_mask:0xf bank_mask:0xf bound_ctrl:1
	v_add_f32_dpp v165, v165, v165 row_shr:2 row_mask:0xf bank_mask:0xf bound_ctrl:1
	v_add_f32_dpp v162, v162, v162 row_shr:4 row_mask:0xf bank_mask:0xf bound_ctrl:1
	v_add_f32_dpp v163, v163, v163 row_shr:4 row_mask:0xf bank_mask:0xf bound_ctrl:1
	v_add_f32_dpp v164, v164, v164 row_shr:4 row_mask:0xf bank_mask:0xf bound_ctrl:1
	v_add_f32_dpp v165, v165, v165 row_shr:4 row_mask:0xf bank_mask:0xf bound_ctrl:1
	v_add_f32_dpp v162, v162, v162 row_shr:8 row_mask:0xf bank_mask:0xf bound_ctrl:1
	v_add_f32_dpp v163, v163, v163 row_shr:8 row_mask:0xf bank_mask:0xf bound_ctrl:1
	v_add_f32_dpp v164, v164, v164 row_shr:8 row_mask:0xf bank_mask:0xf bound_ctrl:1
	v_add_f32_dpp v165, v165, v165 row_shr:8 row_mask:0xf bank_mask:0xf bound_ctrl:1
	v_add_f32_dpp v162, v162, v162 row_bcast:15 row_mask:0xa bank_mask:0xf
	v_add_f32_dpp v163, v163, v163 row_bcast:15 row_mask:0xa bank_mask:0xf
	v_add_f32_dpp v164, v164, v164 row_bcast:15 row_mask:0xa bank_mask:0xf
	v_add_f32_dpp v165, v165, v165 row_bcast:15 row_mask:0xa bank_mask:0xf
	s_mov_b64 s[98:99], exec
	s_mov_b32 exec_lo, 0x80000000
	s_mov_b32 exec_hi, 0x80000000
	ds_write_b32 v74, v162 offset:32
	ds_write_b32 v74, v163 offset:40
	ds_write_b32 v74, v164 offset:48
	ds_write_b32 v74, v165 offset:56
	s_mov_b64 exec, s[98:99]
	s_waitcnt lgkmcnt(0)
	v_mad_u32_u24 v167, v76, s33, v195
	ds_read_b32 v77, v74 offset:392
	s_waitcnt vmcnt(14)
	v_cvt_scalef32_pk32_f32_fp6 v[0:31], v[50:55], 1.0
	global_load_dwordx2 v[54:55], v167, s[62:63] offset:16
	global_load_dwordx4 v[50:53], v167, s[62:63]
	v_pk_mul_f32 v[246:247], v[0:1], v[96:97]
	v_pk_mul_f32 v[254:255], v[2:3], v[98:99]
	v_pk_mul_f32 v[160:161], v[4:5], v[100:101]
	v_pk_fma_f32 v[246:247], v[6:7], v[102:103], v[246:247]
	v_pk_fma_f32 v[254:255], v[8:9], v[104:105], v[254:255]
	v_pk_fma_f32 v[160:161], v[10:11], v[106:107], v[160:161]
	v_pk_fma_f32 v[246:247], v[12:13], v[108:109], v[246:247]
	v_pk_fma_f32 v[254:255], v[14:15], v[110:111], v[254:255]
	v_pk_fma_f32 v[160:161], v[16:17], v[112:113], v[160:161]
	v_pk_fma_f32 v[246:247], v[18:19], v[114:115], v[246:247]
	v_pk_fma_f32 v[254:255], v[20:21], v[116:117], v[254:255]
	v_pk_fma_f32 v[160:161], v[22:23], v[118:119], v[160:161]
	v_pk_fma_f32 v[246:247], v[24:25], v[120:121], v[246:247]
	v_pk_fma_f32 v[254:255], v[26:27], v[122:123], v[254:255]
	v_pk_fma_f32 v[160:161], v[28:29], v[124:125], v[160:161]
	v_pk_fma_f32 v[246:247], v[30:31], v[126:127], v[246:247]
	v_pk_add_f32 v[254:255], v[254:255], v[160:161]
	s_nop 0
	v_pk_add_f32 v[246:247], v[246:247], v[254:255]
	s_nop 0
	v_add_f32_e32 v162, v246, v247
	s_waitcnt lgkmcnt(0)
	v_mad_u32_u24 v167, v77, s33, v195
	ds_read_b32 v76, v74 offset:400
	s_waitcnt vmcnt(14)
	v_cvt_scalef32_pk32_f32_fp6 v[0:31], v[44:49], 1.0
	global_load_dwordx2 v[48:49], v167, s[62:63] offset:16
	global_load_dwordx4 v[44:47], v167, s[62:63]
	v_pk_mul_f32 v[246:247], v[0:1], v[96:97]
	v_pk_mul_f32 v[254:255], v[2:3], v[98:99]
	v_pk_mul_f32 v[160:161], v[4:5], v[100:101]
	v_pk_fma_f32 v[246:247], v[6:7], v[102:103], v[246:247]
	v_pk_fma_f32 v[254:255], v[8:9], v[104:105], v[254:255]
	v_pk_fma_f32 v[160:161], v[10:11], v[106:107], v[160:161]
	v_pk_fma_f32 v[246:247], v[12:13], v[108:109], v[246:247]
	v_pk_fma_f32 v[254:255], v[14:15], v[110:111], v[254:255]
	v_pk_fma_f32 v[160:161], v[16:17], v[112:113], v[160:161]
	v_pk_fma_f32 v[246:247], v[18:19], v[114:115], v[246:247]
	v_pk_fma_f32 v[254:255], v[20:21], v[116:117], v[254:255]
	v_pk_fma_f32 v[160:161], v[22:23], v[118:119], v[160:161]
	v_pk_fma_f32 v[246:247], v[24:25], v[120:121], v[246:247]
	v_pk_fma_f32 v[254:255], v[26:27], v[122:123], v[254:255]
	v_pk_fma_f32 v[160:161], v[28:29], v[124:125], v[160:161]
	v_pk_fma_f32 v[246:247], v[30:31], v[126:127], v[246:247]
	v_pk_add_f32 v[254:255], v[254:255], v[160:161]
	s_nop 0
	v_pk_add_f32 v[246:247], v[246:247], v[254:255]
	s_nop 0
	v_add_f32_e32 v163, v246, v247
	s_waitcnt lgkmcnt(0)
; __device__ void peer_gather_phase(const Params& P, int l, bool do_store) {
;     ...
;       for (int pr = 0; pr < 4; ++pr) {
;         v6u_t qv; qv[0] = u6[3 * pr].x; qv[1] = u6[3 * pr].y; qv[2] = u6[3 * pr + 1].x; qv[3] = u6[3 * pr + 1].y; qv[4] = u6[3 * pr + 2].x; qv[5] = u6[3 * pr + 2].y;
;         const v32f_t wv = __builtin_amdgcn_cvt_scalef32_pk32_f32_fp6(qv, 1.0f);
;         f32x2 a2 = f32x2{0.f, 0.f};
; #pragma unroll
;         for (int i = 0; i < 16; ++i) a2 += f32x2{wv[2 * i], wv[2 * i + 1]} * xu[i];
;         float hs = a2.x + a2.y;
;         hs += dpp_row_shr(hs, 1); hs += dpp_row_shr(hs, 2); hs += dpp_row_shr(hs, 4); hs += dpp_row_shr(hs, 8);
;         hs += __builtin_bit_cast(float, __builtin_amdgcn_update_dpp(0, __builtin_bit_cast(int, hs), 0x142, 0xa, 0xf, false));
;         const float da = __builtin_bit_cast(float, __builtin_amdgcn_readlane(__builtin_bit_cast(int, hs), 31));
;         const float db = __builtin_bit_cast(float, __builtin_amdgcn_readlane(__builtin_bit_cast(int, hs), 63));
;         dvec = (lane == kb + 2 * pr) ? da : dvec;
;         dvec = (lane == kb + 2 * pr + 1) ? db : dvec;
	v_mad_u32_u24 v167, v76, s33, v195
	ds_read_b32 v77, v74 offset:408
	s_waitcnt vmcnt(14)
	v_cvt_scalef32_pk32_f32_fp6 v[0:31], v[38:43], 1.0
	global_load_dwordx2 v[42:43], v167, s[62:63] offset:16
	global_load_dwordx4 v[38:41], v167, s[62:63]
	v_pk_mul_f32 v[246:247], v[0:1], v[96:97]
	v_pk_mul_f32 v[254:255], v[2:3], v[98:99]
	v_pk_mul_f32 v[160:161], v[4:5], v[100:101]
	v_pk_fma_f32 v[246:247], v[6:7], v[102:103], v[246:247]
	v_pk_fma_f32 v[254:255], v[8:9], v[104:105], v[254:255]
	v_pk_fma_f32 v[160:161], v[10:11], v[106:107], v[160:161]
	v_pk_fma_f32 v[246:247], v[12:13], v[108:109], v[246:247]
	v_pk_fma_f32 v[254:255], v[14:15], v[110:111], v[254:255]
	v_pk_fma_f32 v[160:161], v[16:17], v[112:113], v[160:161]
	v_pk_fma_f32 v[246:247], v[18:19], v[114:115], v[246:247]
	v_pk_fma_f32 v[254:255], v[20:21], v[116:117], v[254:255]
	v_pk_fma_f32 v[160:161], v[22:23], v[118:119], v[160:161]
	v_pk_fma_f32 v[246:247], v[24:25], v[120:121], v[246:247]
	v_pk_fma_f32 v[254:255], v[26:27], v[122:123], v[254:255]
	v_pk_fma_f32 v[160:161], v[28:29], v[124:125], v[160:161]
	v_pk_fma_f32 v[246:247], v[30:31], v[126:127], v[246:247]
	v_pk_add_f32 v[254:255], v[254:255], v[160:161]
	s_nop 0
	v_pk_add_f32 v[246:247], v[246:247], v[254:255]
	s_nop 0
	v_add_f32_e32 v164, v246, v247
	s_waitcnt lgkmcnt(0)
	v_mad_u32_u24 v167, v77, s33, v195
	ds_read_b32 v76, v74 offset:416
	s_waitcnt vmcnt(14)
	v_cvt_scalef32_pk32_f32_fp6 v[0:31], v[32:37], 1.0
	global_load_dwordx2 v[36:37], v167, s[62:63] offset:16
	global_load_dwordx4 v[32:35], v167, s[62:63]
	v_pk_mul_f32 v[246:247], v[0:1], v[96:97]
	v_pk_mul_f32 v[254:255], v[2:3], v[98:99]
	v_pk_mul_f32 v[160:161], v[4:5], v[100:101]
	v_pk_fma_f32 v[246:247], v[6:7], v[102:103], v[246:247]
	v_pk_fma_f32 v[254:255], v[8:9], v[104:105], v[254:255]
	v_pk_fma_f32 v[160:161], v[10:11], v[106:107], v[160:161]
	v_pk_fma_f32 v[246:247], v[12:13], v[108:109], v[246:247]
	v_pk_fma_f32 v[254:255], v[14:15], v[110:111], v[254:255]
	v_pk_fma_f32 v[160:161], v[16:17], v[112:113], v[160:161]
	v_pk_fma_f32 v[246:247], v[18:19], v[114:115], v[246:247]
	v_pk_fma_f32 v[254:255], v[20:21], v[116:117], v[254:255]
	v_pk_fma_f32 v[160:161], v[22:23], v[118:119], v[160:161]
	v_pk_fma_f32 v[246:247], v[24:25], v[120:121], v[246:247]
	v_pk_fma_f32 v[254:255], v[26:27], v[122:123], v[254:255]
	v_pk_fma_f32 v[160:161], v[28:29], v[124:125], v[160:161]
	v_pk_fma_f32 v[246:247], v[30:31], v[126:127], v[246:247]
	v_pk_add_f32 v[254:255], v[254:255], v[160:161]
	s_nop 0
	v_pk_add_f32 v[246:247], v[246:247], v[254:255]
	s_nop 0
	v_add_f32_e32 v165, v246, v247
	v_add_f32_dpp v162, v162, v162 row_shr:1 row_mask:0xf bank_mask:0xf bound_ctrl:1
	v_add_f32_dpp v163, v163, v163 row_shr:1 row_mask:0xf bank_mask:0xf bound_ctrl:1
	v_add_f32_dpp v164, v164, v164 row_shr:1 row_mask:0xf bank_mask:0xf bound_ctrl:1
	v_add_f32_dpp v165, v165, v165 row_shr:1 row_mask:0xf bank_mask:0xf bound_ctrl:1
	v_add_f32_dpp v162, v162, v162 row_shr:2 row_mask:0xf bank_mask:0xf bound_ctrl:1
	v_add_f32_dpp v163, v163, v163 row_shr:2 row_mask:0xf bank_mask:0xf bound_ctrl:1
	v_add_f32_dpp v164, v164, v164 row_shr:2 row_mask:0xf bank_mask:0xf bound_ctrl:1
	v_add_f32_dpp v165, v165, v165 row_shr:2 row_mask:0xf bank_mask:0xf bound_ctrl:1
	v_add_f32_dpp v162, v162, v162 row_shr:4 row_mask:0xf bank_mask:0xf bound_ctrl:1
	v_add_f32_dpp v163, v163, v163 row_shr:4 row_mask:0xf bank_mask:0xf bound_ctrl:1
	v_add_f32_dpp v164, v164, v164 row_shr:4 row_mask:0xf bank_mask:0xf bound_ctrl:1
	v_add_f32_dpp v165, v165, v165 row_shr:4 row_mask:0xf bank_mask:0xf bound_ctrl:1
	v_add_f32_dpp v162, v162, v162 row_shr:8 row_mask:0xf bank_mask:0xf bound_ctrl:1
	v_add_f32_dpp v163, v163, v163 row_shr:8 row_mask:0xf bank_mask:0xf bound_ctrl:1
	v_add_f32_dpp v164, v164, v164 row_shr:8 row_mask:0xf bank_mask:0xf bound_ctrl:1
	v_add_f32_dpp v165, v165, v165 row_shr:8 row_mask:0xf bank_mask:0xf bound_ctrl:1
	v_add_f32_dpp v162, v162, v162 row_bcast:15 row_mask:0xa bank_mask:0xf
	v_add_f32_dpp v163, v163, v163 row_bcast:15 row_mask:0xa bank_mask:0xf
	v_add_f32_dpp v164, v164, v164 row_bcast:15 row_mask:0xa bank_mask:0xf
	v_add_f32_dpp v165, v165, v165 row_bcast:15 row_mask:0xa bank_mask:0xf
	s_mov_b64 s[98:99], exec
	s_mov_b32 exec_lo, 0x80000000
	s_mov_b32 exec_hi, 0x80000000
	ds_write_b32 v74, v162 offset:64
	ds_write_b32 v74, v163 offset:72
	ds_write_b32 v74, v164 offset:80
	ds_write_b32 v74, v165 offset:88
	s_mov_b64 exec, s[98:99]
	s_waitcnt lgkmcnt(0)
	v_mad_u32_u24 v167, v76, s33, v195
	ds_read_b32 v77, v74 offset:424
	s_waitcnt vmcnt(14)
	v_cvt_scalef32_pk32_f32_fp6 v[0:31], v[196:201], 1.0
	global_load_dwordx2 v[200:201], v167, s[62:63] offset:16
	global_load_dwordx4 v[196:199], v167, s[62:63]
	v_pk_mul_f32 v[246:247], v[0:1], v[96:97]
	v_pk_mul_f32 v[254:255], v[2:3], v[98:99]
	v_pk_mul_f32 v[160:161], v[4:5], v[100:101]
	v_pk_fma_f32 v[246:247], v[6:7], v[102:103], v[246:247]
	v_pk_fma_f32 v[254:255], v[8:9], v[104:105], v[254:255]
	v_pk_fma_f32 v[160:161], v[10:11], v[106:107], v[160:161]
	v_pk_fma_f32 v[246:247], v[12:13], v[108:109], v[246:247]
	v_pk_fma_f32 v[254:255], v[14:15], v[110:111], v[254:255]
	v_pk_fma_f32 v[160:161], v[16:17], v[112:113], v[160:161]
	v_pk_fma_f32 v[246:247], v[18:19], v[114:115], v[246:247]
	v_pk_fma_f32 v[254:255], v[20:21], v[116:117], v[254:255]
	v_pk_fma_f32 v[160:161], v[22:23], v[118:119], v[160:161]
	v_pk_fma_f32 v[246:247], v[24:25], v[120:121], v[246:247]
	v_pk_fma_f32 v[254:255], v[26:27], v[122:123], v[254:255]
	v_pk_fma_f32 v[160:161], v[28:29], v[124:125], v[160:161]
	v_pk_fma_f32 v[246:247], v[30:31], v[126:127], v[246:247]
	v_pk_add_f32 v[254:255], v[254:255], v[160:161]
	s_nop 0
	v_pk_add_f32 v[246:247], v[246:247], v[254:255]
	s_nop 0
	v_add_f32_e32 v162, v246, v247
	s_waitcnt lgkmcnt(0)
; __device__ void peer_gather_phase(const Params& P, int l, bool do_store) {
;     ...
;       for (int pr = 0; pr < 4; ++pr) {
;         v6u_t qv; qv[0] = u6[3 * pr].x; qv[1] = u6[3 * pr].y; qv[2] = u6[3 * pr + 1].x; qv[3] = u6[3 * pr + 1].y; qv[4] = u6[3 * pr + 2].x; qv[5] = u6[3 * pr + 2].y;
;         const v32f_t wv = __builtin_amdgcn_cvt_scalef32_pk32_f32_fp6(qv, 1.0f);
;         f32x2 a2 = f32x2{0.f, 0.f};
; #pragma unroll
;         for (int i = 0; i < 16; ++i) a2 += f32x2{wv[2 * i], wv[2 * i + 1]} * xu[i];
;         float hs = a2.x + a2.y;
;         hs += dpp_row_shr(hs, 1); hs += dpp_row_shr(hs, 2); hs += dpp_row_shr(hs, 4); hs += dpp_row_shr(hs, 8);
;         hs += __builtin_bit_cast(float, __builtin_amdgcn_update_dpp(0, __builtin_bit_cast(int, hs), 0x142, 0xa, 0xf, false));
;         const float da = __builtin_bit_cast(float, __builtin_amdgcn_readlane(__builtin_bit_cast(int, hs), 31));
;         const float db = __builtin_bit_cast(float, __builtin_amdgcn_readlane(__builtin_bit_cast(int, hs), 63));
;         dvec = (lane == kb + 2 * pr) ? da : dvec;
;         dvec = (lane == kb + 2 * pr + 1) ? db : dvec;
	v_mad_u32_u24 v167, v77, s33, v195
	ds_read_b32 v76, v74 offset:432
	s_waitcnt vmcnt(14)
	v_cvt_scalef32_pk32_f32_fp6 v[0:31], v[228:233], 1.0
	global_load_dwordx2 v[232:233], v167, s[62:63] offset:16
	global_load_dwordx4 v[228:231], v167, s[62:63]
	v_pk_mul_f32 v[246:247], v[0:1], v[96:97]
	v_pk_mul_f32 v[254:255], v[2:3], v[98:99]
	v_pk_mul_f32 v[160:161], v[4:5], v[100:101]
	v_pk_fma_f32 v[246:247], v[6:7], v[102:103], v[246:247]
	v_pk_fma_f32 v[254:255], v[8:9], v[104:105], v[254:255]
	v_pk_fma_f32 v[160:161], v[10:11], v[106:107], v[160:161]
	v_pk_fma_f32 v[246:247], v[12:13], v[108:109], v[246:247]
	v_pk_fma_f32 v[254:255], v[14:15], v[110:111], v[254:255]
	v_pk_fma_f32 v[160:161], v[16:17], v[112:113], v[160:161]
	v_pk_fma_f32 v[246:247], v[18:19], v[114:115], v[246:247]
	v_pk_fma_f32 v[254:255], v[20:21], v[116:117], v[254:255]
	v_pk_fma_f32 v[160:161], v[22:23], v[118:119], v[160:161]
	v_pk_fma_f32 v[246:247], v[24:25], v[120:121], v[246:247]
	v_pk_fma_f32 v[254:255], v[26:27], v[122:123], v[254:255]
	v_pk_fma_f32 v[160:161], v[28:29], v[124:125], v[160:161]
	v_pk_fma_f32 v[246:247], v[30:31], v[126:127], v[246:247]
	v_pk_add_f32 v[254:255], v[254:255], v[160:161]
	s_nop 0
	v_pk_add_f32 v[246:247], v[246:247], v[254:255]
	s_nop 0
	v_add_f32_e32 v163, v246, v247
	s_waitcnt lgkmcnt(0)
	v_mad_u32_u24 v167, v76, s33, v195
	ds_read_b32 v77, v74 offset:440
	s_waitcnt vmcnt(14)
	v_cvt_scalef32_pk32_f32_fp6 v[0:31], v[234:239], 1.0
	global_load_dwordx2 v[238:239], v167, s[62:63] offset:16
	global_load_dwordx4 v[234:237], v167, s[62:63]
	v_pk_mul_f32 v[246:247], v[0:1], v[96:97]
	v_pk_mul_f32 v[254:255], v[2:3], v[98:99]
	v_pk_mul_f32 v[160:161], v[4:5], v[100:101]
	v_pk_fma_f32 v[246:247], v[6:7], v[102:103], v[246:247]
	v_pk_fma_f32 v[254:255], v[8:9], v[104:105], v[254:255]
	v_pk_fma_f32 v[160:161], v[10:11], v[106:107], v[160:161]
	v_pk_fma_f32 v[246:247], v[12:13], v[108:109], v[246:247]
	v_pk_fma_f32 v[254:255], v[14:15], v[110:111], v[254:255]
	v_pk_fma_f32 v[160:161], v[16:17], v[112:113], v[160:161]
	v_pk_fma_f32 v[246:247], v[18:19], v[114:115], v[246:247]
	v_pk_fma_f32 v[254:255], v[20:21], v[116:117], v[254:255]
	v_pk_fma_f32 v[160:161], v[22:23], v[118:119], v[160:161]
	v_pk_fma_f32 v[246:247], v[24:25], v[120:121], v[246:247]
	v_pk_fma_f32 v[254:255], v[26:27], v[122:123], v[254:255]
	v_pk_fma_f32 v[160:161], v[28:29], v[124:125], v[160:161]
	v_pk_fma_f32 v[246:247], v[30:31], v[126:127], v[246:247]
	v_pk_add_f32 v[254:255], v[254:255], v[160:161]
	s_nop 0
	v_pk_add_f32 v[246:247], v[246:247], v[254:255]
	s_nop 0
	v_add_f32_e32 v164, v246, v247
	s_waitcnt lgkmcnt(0)
	v_mad_u32_u24 v167, v77, s33, v195
	ds_read_b32 v76, v74 offset:448
	s_waitcnt vmcnt(14)
	v_cvt_scalef32_pk32_f32_fp6 v[0:31], v[240:245], 1.0
	global_load_dwordx2 v[244:245], v167, s[62:63] offset:16
	global_load_dwordx4 v[240:243], v167, s[62:63]
	v_pk_mul_f32 v[246:247], v[0:1], v[96:97]
	v_pk_mul_f32 v[254:255], v[2:3], v[98:99]
	v_pk_mul_f32 v[160:161], v[4:5], v[100:101]
	v_pk_fma_f32 v[246:247], v[6:7], v[102:103], v[246:247]
	v_pk_fma_f32 v[254:255], v[8:9], v[104:105], v[254:255]
	v_pk_fma_f32 v[160:161], v[10:11], v[106:107], v[160:161]
	v_pk_fma_f32 v[246:247], v[12:13], v[108:109], v[246:247]
	v_pk_fma_f32 v[254:255], v[14:15], v[110:111], v[254:255]
	v_pk_fma_f32 v[160:161], v[16:17], v[112:113], v[160:161]
	v_pk_fma_f32 v[246:247], v[18:19], v[114:115], v[246:247]
	v_pk_fma_f32 v[254:255], v[20:21], v[116:117], v[254:255]
	v_pk_fma_f32 v[160:161], v[22:23], v[118:119], v[160:161]
	v_pk_fma_f32 v[246:247], v[24:25], v[120:121], v[246:247]
	v_pk_fma_f32 v[254:255], v[26:27], v[122:123], v[254:255]
	v_pk_fma_f32 v[160:161], v[28:29], v[124:125], v[160:161]
	v_pk_fma_f32 v[246:247], v[30:31], v[126:127], v[246:247]
	v_pk_add_f32 v[254:255], v[254:255], v[160:161]
	s_nop 0
	v_pk_add_f32 v[246:247], v[246:247], v[254:255]
	s_nop 0
	v_add_f32_e32 v165, v246, v247
	v_add_f32_dpp v162, v162, v162 row_shr:1 row_mask:0xf bank_mask:0xf bound_ctrl:1
	v_add_f32_dpp v163, v163, v163 row_shr:1 row_mask:0xf bank_mask:0xf bound_ctrl:1
	v_add_f32_dpp v164, v164, v164 row_shr:1 row_mask:0xf bank_mask:0xf bound_ctrl:1
	v_add_f32_dpp v165, v165, v165 row_shr:1 row_mask:0xf bank_mask:0xf bound_ctrl:1
	v_add_f32_dpp v162, v162, v162 row_shr:2 row_mask:0xf bank_mask:0xf bound_ctrl:1
	v_add_f32_dpp v163, v163, v163 row_shr:2 row_mask:0xf bank_mask:0xf bound_ctrl:1
	v_add_f32_dpp v164, v164, v164 row_shr:2 row_mask:0xf bank_mask:0xf bound_ctrl:1
	v_add_f32_dpp v165, v165, v165 row_shr:2 row_mask:0xf bank_mask:0xf bound_ctrl:1
	v_add_f32_dpp v162, v162, v162 row_shr:4 row_mask:0xf bank_mask:0xf bound_ctrl:1
	v_add_f32_dpp v163, v163, v163 row_shr:4 row_mask:0xf bank_mask:0xf bound_ctrl:1
	v_add_f32_dpp v164, v164, v164 row_shr:4 row_mask:0xf bank_mask:0xf bound_ctrl:1
	v_add_f32_dpp v165, v165, v165 row_shr:4 row_mask:0xf bank_mask:0xf bound_ctrl:1
	v_add_f32_dpp v162, v162, v162 row_shr:8 row_mask:0xf bank_mask:0xf bound_ctrl:1
	v_add_f32_dpp v163, v163, v163 row_shr:8 row_mask:0xf bank_mask:0xf bound_ctrl:1
	v_add_f32_dpp v164, v164, v164 row_shr:8 row_mask:0xf bank_mask:0xf bound_ctrl:1
	v_add_f32_dpp v165, v165, v165 row_shr:8 row_mask:0xf bank_mask:0xf bound_ctrl:1
	v_add_f32_dpp v162, v162, v162 row_bcast:15 row_mask:0xa bank_mask:0xf
	v_add_f32_dpp v163, v163, v163 row_bcast:15 row_mask:0xa bank_mask:0xf
	v_add_f32_dpp v164, v164, v164 row_bcast:15 row_mask:0xa bank_mask:0xf
	v_add_f32_dpp v165, v165, v165 row_bcast:15 row_mask:0xa bank_mask:0xf
	s_mov_b64 s[98:99], exec
	s_mov_b32 exec_lo, 0x80000000
	s_mov_b32 exec_hi, 0x80000000
	ds_write_b32 v74, v162 offset:96
	ds_write_b32 v74, v163 offset:104
	ds_write_b32 v74, v164 offset:112
	ds_write_b32 v74, v165 offset:120
	s_mov_b64 exec, s[98:99]
	s_waitcnt lgkmcnt(0)
; __device__ void peer_gather_phase(const Params& P, int l, bool do_store) {
;     ...
;       for (int pr = 0; pr < 4; ++pr) {
;         v6u_t qv; qv[0] = u6[3 * pr].x; qv[1] = u6[3 * pr].y; qv[2] = u6[3 * pr + 1].x; qv[3] = u6[3 * pr + 1].y; qv[4] = u6[3 * pr + 2].x; qv[5] = u6[3 * pr + 2].y;
;         const v32f_t wv = __builtin_amdgcn_cvt_scalef32_pk32_f32_fp6(qv, 1.0f);
;         f32x2 a2 = f32x2{0.f, 0.f};
; #pragma unroll
;         for (int i = 0; i < 16; ++i) a2 += f32x2{wv[2 * i], wv[2 * i + 1]} * xu[i];
;         float hs = a2.x + a2.y;
;         hs += dpp_row_shr(hs, 1); hs += dpp_row_shr(hs, 2); hs += dpp_row_shr(hs, 4); hs += dpp_row_shr(hs, 8);
;         hs += __builtin_bit_cast(float, __builtin_amdgcn_update_dpp(0, __builtin_bit_cast(int, hs), 0x142, 0xa, 0xf, false));
;         const float da = __builtin_bit_cast(float, __builtin_amdgcn_readlane(__builtin_bit_cast(int, hs), 31));
;         const float db = __builtin_bit_cast(float, __builtin_amdgcn_readlane(__builtin_bit_cast(int, hs), 63));
;         dvec = (lane == kb + 2 * pr) ? da : dvec;
;         dvec = (lane == kb + 2 * pr + 1) ? db : dvec;
	v_mad_u32_u24 v167, v76, s33, v195
	ds_read_b32 v77, v74 offset:456
	s_waitcnt vmcnt(14)
	v_cvt_scalef32_pk32_f32_fp6 v[0:31], v[50:55], 1.0
	global_load_dwordx2 v[54:55], v167, s[62:63] offset:16
	global_load_dwordx4 v[50:53], v167, s[62:63]
	v_pk_mul_f32 v[246:247], v[0:1], v[96:97]
	v_pk_mul_f32 v[254:255], v[2:3], v[98:99]
	v_pk_mul_f32 v[160:161], v[4:5], v[100:101]
	v_pk_fma_f32 v[246:247], v[6:7], v[102:103], v[246:247]
	v_pk_fma_f32 v[254:255], v[8:9], v[104:105], v[254:255]
	v_pk_fma_f32 v[160:161], v[10:11], v[106:107], v[160:161]
	v_pk_fma_f32 v[246:247], v[12:13], v[108:109], v[246:247]
	v_pk_fma_f32 v[254:255], v[14:15], v[110:111], v[254:255]
	v_pk_fma_f32 v[160:161], v[16:17], v[112:113], v[160:161]
	v_pk_fma_f32 v[246:247], v[18:19], v[114:115], v[246:247]
	v_pk_fma_f32 v[254:255], v[20:21], v[116:117], v[254:255]
	v_pk_fma_f32 v[160:161], v[22:23], v[118:119], v[160:161]
	v_pk_fma_f32 v[246:247], v[24:25], v[120:121], v[246:247]
	v_pk_fma_f32 v[254:255], v[26:27], v[122:123], v[254:255]
	v_pk_fma_f32 v[160:161], v[28:29], v[124:125], v[160:161]
	v_pk_fma_f32 v[246:247], v[30:31], v[126:127], v[246:247]
	v_pk_add_f32 v[254:255], v[254:255], v[160:161]
	s_nop 0
	v_pk_add_f32 v[246:247], v[246:247], v[254:255]
	s_nop 0
	v_add_f32_e32 v162, v246, v247
	s_waitcnt lgkmcnt(0)
	v_mad_u32_u24 v167, v77, s33, v195
	ds_read_b32 v76, v74 offset:464
	s_waitcnt vmcnt(14)
	v_cvt_scalef32_pk32_f32_fp6 v[0:31], v[44:49], 1.0
	global_load_dwordx2 v[48:49], v167, s[62:63] offset:16
	global_load_dwordx4 v[44:47], v167, s[62:63]
	v_pk_mul_f32 v[246:247], v[0:1], v[96:97]
	v_pk_mul_f32 v[254:255], v[2:3], v[98:99]
	v_pk_mul_f32 v[160:161], v[4:5], v[100:101]
	v_pk_fma_f32 v[246:247], v[6:7], v[102:103], v[246:247]
	v_pk_fma_f32 v[254:255], v[8:9], v[104:105], v[254:255]
	v_pk_fma_f32 v[160:161], v[10:11], v[106:107], v[160:161]
	v_pk_fma_f32 v[246:247], v[12:13], v[108:109], v[246:247]
	v_pk_fma_f32 v[254:255], v[14:15], v[110:111], v[254:255]
	v_pk_fma_f32 v[160:161], v[16:17], v[112:113], v[160:161]
	v_pk_fma_f32 v[246:247], v[18:19], v[114:115], v[246:247]
	v_pk_fma_f32 v[254:255], v[20:21], v[116:117], v[254:255]
	v_pk_fma_f32 v[160:161], v[22:23], v[118:119], v[160:161]
	v_pk_fma_f32 v[246:247], v[24:25], v[120:121], v[246:247]
	v_pk_fma_f32 v[254:255], v[26:27], v[122:123], v[254:255]
	v_pk_fma_f32 v[160:161], v[28:29], v[124:125], v[160:161]
	v_pk_fma_f32 v[246:247], v[30:31], v[126:127], v[246:247]
	v_pk_add_f32 v[254:255], v[254:255], v[160:161]
	s_nop 0
	v_pk_add_f32 v[246:247], v[246:247], v[254:255]
	s_nop 0
	v_add_f32_e32 v163, v246, v247
	s_waitcnt lgkmcnt(0)
	v_mad_u32_u24 v167, v76, s33, v195
	ds_read_b32 v77, v74 offset:472
	s_waitcnt vmcnt(14)
	v_cvt_scalef32_pk32_f32_fp6 v[0:31], v[38:43], 1.0
	global_load_dwordx2 v[42:43], v167, s[62:63] offset:16
	global_load_dwordx4 v[38:41], v167, s[62:63]
	v_pk_mul_f32 v[246:247], v[0:1], v[96:97]
	v_pk_mul_f32 v[254:255], v[2:3], v[98:99]
	v_pk_mul_f32 v[160:161], v[4:5], v[100:101]
	v_pk_fma_f32 v[246:247], v[6:7], v[102:103], v[246:247]
	v_pk_fma_f32 v[254:255], v[8:9], v[104:105], v[254:255]
	v_pk_fma_f32 v[160:161], v[10:11], v[106:107], v[160:161]
	v_pk_fma_f32 v[246:247], v[12:13], v[108:109], v[246:247]
	v_pk_fma_f32 v[254:255], v[14:15], v[110:111], v[254:255]
	v_pk_fma_f32 v[160:161], v[16:17], v[112:113], v[160:161]
	v_pk_fma_f32 v[246:247], v[18:19], v[114:115], v[246:247]
	v_pk_fma_f32 v[254:255], v[20:21], v[116:117], v[254:255]
	v_pk_fma_f32 v[160:161], v[22:23], v[118:119], v[160:161]
	v_pk_fma_f32 v[246:247], v[24:25], v[120:121], v[246:247]
	v_pk_fma_f32 v[254:255], v[26:27], v[122:123], v[254:255]
	v_pk_fma_f32 v[160:161], v[28:29], v[124:125], v[160:161]
	v_pk_fma_f32 v[246:247], v[30:31], v[126:127], v[246:247]
	v_pk_add_f32 v[254:255], v[254:255], v[160:161]
	s_nop 0
	v_pk_add_f32 v[246:247], v[246:247], v[254:255]
	s_nop 0
	v_add_f32_e32 v164, v246, v247
	s_waitcnt lgkmcnt(0)
	v_mad_u32_u24 v167, v77, s33, v195
	ds_read_b32 v76, v74 offset:480
	s_waitcnt vmcnt(14)
	v_cvt_scalef32_pk32_f32_fp6 v[0:31], v[32:37], 1.0
	global_load_dwordx2 v[36:37], v167, s[62:63] offset:16
	global_load_dwordx4 v[32:35], v167, s[62:63]
	v_pk_mul_f32 v[246:247], v[0:1], v[96:97]
	v_pk_mul_f32 v[254:255], v[2:3], v[98:99]
	v_pk_mul_f32 v[160:161], v[4:5], v[100:101]
	v_pk_fma_f32 v[246:247], v[6:7], v[102:103], v[246:247]
	v_pk_fma_f32 v[254:255], v[8:9], v[104:105], v[254:255]
	v_pk_fma_f32 v[160:161], v[10:11], v[106:107], v[160:161]
	v_pk_fma_f32 v[246:247], v[12:13], v[108:109], v[246:247]
	v_pk_fma_f32 v[254:255], v[14:15], v[110:111], v[254:255]
	v_pk_fma_f32 v[160:161], v[16:17], v[112:113], v[160:161]
	v_pk_fma_f32 v[246:247], v[18:19], v[114:115], v[246:247]
	v_pk_fma_f32 v[254:255], v[20:21], v[116:117], v[254:255]
	v_pk_fma_f32 v[160:161], v[22:23], v[118:119], v[160:161]
	v_pk_fma_f32 v[246:247], v[24:25], v[120:121], v[246:247]
	v_pk_fma_f32 v[254:255], v[26:27], v[122:123], v[254:255]
	v_pk_fma_f32 v[160:161], v[28:29], v[124:125], v[160:161]
	v_pk_fma_f32 v[246:247], v[30:31], v[126:127], v[246:247]
	v_pk_add_f32 v[254:255], v[254:255], v[160:161]
	s_nop 0
	v_pk_add_f32 v[246:247], v[246:247], v[254:255]
	s_nop 0
	v_add_f32_e32 v165, v246, v247
	v_add_f32_dpp v162, v162, v162 row_shr:1 row_mask:0xf bank_mask:0xf bound_ctrl:1
	v_add_f32_dpp v163, v163, v163 row_shr:1 row_mask:0xf bank_mask:0xf bound_ctrl:1
	v_add_f32_dpp v164, v164, v164 row_shr:1 row_mask:0xf bank_mask:0xf bound_ctrl:1
	v_add_f32_dpp v165, v165, v165 row_shr:1 row_mask:0xf bank_mask:0xf bound_ctrl:1
	v_add_f32_dpp v162, v162, v162 row_shr:2 row_mask:0xf bank_mask:0xf bound_ctrl:1
; __device__ void peer_gather_phase(const Params& P, int l, bool do_store) {
;     ...
;       for (int pr = 0; pr < 4; ++pr) {
;         v6u_t qv; qv[0] = u6[3 * pr].x; qv[1] = u6[3 * pr].y; qv[2] = u6[3 * pr + 1].x; qv[3] = u6[3 * pr + 1].y; qv[4] = u6[3 * pr + 2].x; qv[5] = u6[3 * pr + 2].y;
;         const v32f_t wv = __builtin_amdgcn_cvt_scalef32_pk32_f32_fp6(qv, 1.0f);
;         f32x2 a2 = f32x2{0.f, 0.f};
; #pragma unroll
;         for (int i = 0; i < 16; ++i) a2 += f32x2{wv[2 * i], wv[2 * i + 1]} * xu[i];
;         float hs = a2.x + a2.y;
;         hs += dpp_row_shr(hs, 1); hs += dpp_row_shr(hs, 2); hs += dpp_row_shr(hs, 4); hs += dpp_row_shr(hs, 8);
;         hs += __builtin_bit_cast(float, __builtin_amdgcn_update_dpp(0, __builtin_bit_cast(int, hs), 0x142, 0xa, 0xf, false));
;         const float da = __builtin_bit_cast(float, __builtin_amdgcn_readlane(__builtin_bit_cast(int, hs), 31));
;         const float db = __builtin_bit_cast(float, __builtin_amdgcn_readlane(__builtin_bit_cast(int, hs), 63));
;         dvec = (lane == kb + 2 * pr) ? da : dvec;
;         dvec = (lane == kb + 2 * pr + 1) ? db : dvec;
	v_add_f32_dpp v163, v163, v163 row_shr:2 row_mask:0xf bank_mask:0xf bound_ctrl:1
	v_add_f32_dpp v164, v164, v164 row_shr:2 row_mask:0xf bank_mask:0xf bound_ctrl:1
	v_add_f32_dpp v165, v165, v165 row_shr:2 row_mask:0xf bank_mask:0xf bound_ctrl:1
	v_add_f32_dpp v162, v162, v162 row_shr:4 row_mask:0xf bank_mask:0xf bound_ctrl:1
	v_add_f32_dpp v163, v163, v163 row_shr:4 row_mask:0xf bank_mask:0xf bound_ctrl:1
	v_add_f32_dpp v164, v164, v164 row_shr:4 row_mask:0xf bank_mask:0xf bound_ctrl:1
	v_add_f32_dpp v165, v165, v165 row_shr:4 row_mask:0xf bank_mask:0xf bound_ctrl:1
	v_add_f32_dpp v162, v162, v162 row_shr:8 row_mask:0xf bank_mask:0xf bound_ctrl:1
	v_add_f32_dpp v163, v163, v163 row_shr:8 row_mask:0xf bank_mask:0xf bound_ctrl:1
	v_add_f32_dpp v164, v164, v164 row_shr:8 row_mask:0xf bank_mask:0xf bound_ctrl:1
	v_add_f32_dpp v165, v165, v165 row_shr:8 row_mask:0xf bank_mask:0xf bound_ctrl:1
	v_add_f32_dpp v162, v162, v162 row_bcast:15 row_mask:0xa bank_mask:0xf
	v_add_f32_dpp v163, v163, v163 row_bcast:15 row_mask:0xa bank_mask:0xf
	v_add_f32_dpp v164, v164, v164 row_bcast:15 row_mask:0xa bank_mask:0xf
	v_add_f32_dpp v165, v165, v165 row_bcast:15 row_mask:0xa bank_mask:0xf
	s_mov_b64 s[98:99], exec
	s_mov_b32 exec_lo, 0x80000000
	s_mov_b32 exec_hi, 0x80000000
	ds_write_b32 v74, v162 offset:128
	ds_write_b32 v74, v163 offset:136
	ds_write_b32 v74, v164 offset:144
	ds_write_b32 v74, v165 offset:152
	s_mov_b64 exec, s[98:99]
	s_waitcnt lgkmcnt(0)
	v_mad_u32_u24 v167, v76, s33, v195
	ds_read_b32 v77, v74 offset:488
	s_waitcnt vmcnt(14)
	v_cvt_scalef32_pk32_f32_fp6 v[0:31], v[196:201], 1.0
	global_load_dwordx2 v[200:201], v167, s[62:63] offset:16
	global_load_dwordx4 v[196:199], v167, s[62:63]
	v_pk_mul_f32 v[246:247], v[0:1], v[96:97]
	v_pk_mul_f32 v[254:255], v[2:3], v[98:99]
	v_pk_mul_f32 v[160:161], v[4:5], v[100:101]
	v_pk_fma_f32 v[246:247], v[6:7], v[102:103], v[246:247]
	v_pk_fma_f32 v[254:255], v[8:9], v[104:105], v[254:255]
	v_pk_fma_f32 v[160:161], v[10:11], v[106:107], v[160:161]
	v_pk_fma_f32 v[246:247], v[12:13], v[108:109], v[246:247]
	v_pk_fma_f32 v[254:255], v[14:15], v[110:111], v[254:255]
	v_pk_fma_f32 v[160:161], v[16:17], v[112:113], v[160:161]
	v_pk_fma_f32 v[246:247], v[18:19], v[114:115], v[246:247]
	v_pk_fma_f32 v[254:255], v[20:21], v[116:117], v[254:255]
	v_pk_fma_f32 v[160:161], v[22:23], v[118:119], v[160:161]
	v_pk_fma_f32 v[246:247], v[24:25], v[120:121], v[246:247]
	v_pk_fma_f32 v[254:255], v[26:27], v[122:123], v[254:255]
	v_pk_fma_f32 v[160:161], v[28:29], v[124:125], v[160:161]
	v_pk_fma_f32 v[246:247], v[30:31], v[126:127], v[246:247]
	v_pk_add_f32 v[254:255], v[254:255], v[160:161]
	s_nop 0
	v_pk_add_f32 v[246:247], v[246:247], v[254:255]
	s_nop 0
	v_add_f32_e32 v162, v246, v247
	s_waitcnt lgkmcnt(0)
	v_mad_u32_u24 v167, v77, s33, v195
	ds_read_b32 v76, v74 offset:496
	s_waitcnt vmcnt(14)
	v_cvt_scalef32_pk32_f32_fp6 v[0:31], v[228:233], 1.0
	global_load_dwordx2 v[232:233], v167, s[62:63] offset:16
	global_load_dwordx4 v[228:231], v167, s[62:63]
	v_pk_mul_f32 v[246:247], v[0:1], v[96:97]
	v_pk_mul_f32 v[254:255], v[2:3], v[98:99]
	v_pk_mul_f32 v[160:161], v[4:5], v[100:101]
	v_pk_fma_f32 v[246:247], v[6:7], v[102:103], v[246:247]
	v_pk_fma_f32 v[254:255], v[8:9], v[104:105], v[254:255]
	v_pk_fma_f32 v[160:161], v[10:11], v[106:107], v[160:161]
	v_pk_fma_f32 v[246:247], v[12:13], v[108:109], v[246:247]
	v_pk_fma_f32 v[254:255], v[14:15], v[110:111], v[254:255]
	v_pk_fma_f32 v[160:161], v[16:17], v[112:113], v[160:161]
	v_pk_fma_f32 v[246:247], v[18:19], v[114:115], v[246:247]
	v_pk_fma_f32 v[254:255], v[20:21], v[116:117], v[254:255]
	v_pk_fma_f32 v[160:161], v[22:23], v[118:119], v[160:161]
	v_pk_fma_f32 v[246:247], v[24:25], v[120:121], v[246:247]
	v_pk_fma_f32 v[254:255], v[26:27], v[122:123], v[254:255]
	v_pk_fma_f32 v[160:161], v[28:29], v[124:125], v[160:161]
	v_pk_fma_f32 v[246:247], v[30:31], v[126:127], v[246:247]
	v_pk_add_f32 v[254:255], v[254:255], v[160:161]
	s_nop 0
	v_pk_add_f32 v[246:247], v[246:247], v[254:255]
	s_nop 0
	v_add_f32_e32 v163, v246, v247
	s_waitcnt lgkmcnt(0)
	v_mad_u32_u24 v167, v76, s33, v195
	ds_read_b32 v77, v74 offset:504
	s_waitcnt vmcnt(14)
	v_cvt_scalef32_pk32_f32_fp6 v[0:31], v[234:239], 1.0
	global_load_dwordx2 v[238:239], v167, s[62:63] offset:16
	global_load_dwordx4 v[234:237], v167, s[62:63]
	v_pk_mul_f32 v[246:247], v[0:1], v[96:97]
	v_pk_mul_f32 v[254:255], v[2:3], v[98:99]
	v_pk_mul_f32 v[160:161], v[4:5], v[100:101]
	v_pk_fma_f32 v[246:247], v[6:7], v[102:103], v[246:247]
	v_pk_fma_f32 v[254:255], v[8:9], v[104:105], v[254:255]
	v_pk_fma_f32 v[160:161], v[10:11], v[106:107], v[160:161]
	v_pk_fma_f32 v[246:247], v[12:13], v[108:109], v[246:247]
	v_pk_fma_f32 v[254:255], v[14:15], v[110:111], v[254:255]
	v_pk_fma_f32 v[160:161], v[16:17], v[112:113], v[160:161]
	v_pk_fma_f32 v[246:247], v[18:19], v[114:115], v[246:247]
	v_pk_fma_f32 v[254:255], v[20:21], v[116:117], v[254:255]
	v_pk_fma_f32 v[160:161], v[22:23], v[118:119], v[160:161]
	v_pk_fma_f32 v[246:247], v[24:25], v[120:121], v[246:247]
	v_pk_fma_f32 v[254:255], v[26:27], v[122:123], v[254:255]
	v_pk_fma_f32 v[160:161], v[28:29], v[124:125], v[160:161]
	v_pk_fma_f32 v[246:247], v[30:31], v[126:127], v[246:247]
	v_pk_add_f32 v[254:255], v[254:255], v[160:161]
	s_nop 0
	v_pk_add_f32 v[246:247], v[246:247], v[254:255]
	s_nop 0
	v_add_f32_e32 v164, v246, v247
	s_waitcnt lgkmcnt(0)
	v_mad_u32_u24 v167, v77, s33, v195
	s_waitcnt vmcnt(14)
; __device__ void peer_gather_phase(const Params& P, int l, bool do_store) {
;     ...
;       for (int pr = 0; pr < 4; ++pr) {
;         v6u_t qv; qv[0] = u6[3 * pr].x; qv[1] = u6[3 * pr].y; qv[2] = u6[3 * pr + 1].x; qv[3] = u6[3 * pr + 1].y; qv[4] = u6[3 * pr + 2].x; qv[5] = u6[3 * pr + 2].y;
;         const v32f_t wv = __builtin_amdgcn_cvt_scalef32_pk32_f32_fp6(qv, 1.0f);
;         f32x2 a2 = f32x2{0.f, 0.f};
; #pragma unroll
;         for (int i = 0; i < 16; ++i) a2 += f32x2{wv[2 * i], wv[2 * i + 1]} * xu[i];
;         float hs = a2.x + a2.y;
;         hs += dpp_row_shr(hs, 1); hs += dpp_row_shr(hs, 2); hs += dpp_row_shr(hs, 4); hs += dpp_row_shr(hs, 8);
;         hs += __builtin_bit_cast(float, __builtin_amdgcn_update_dpp(0, __builtin_bit_cast(int, hs), 0x142, 0xa, 0xf, false));
;         const float da = __builtin_bit_cast(float, __builtin_amdgcn_readlane(__builtin_bit_cast(int, hs), 31));
;         const float db = __builtin_bit_cast(float, __builtin_amdgcn_readlane(__builtin_bit_cast(int, hs), 63));
;         dvec = (lane == kb + 2 * pr) ? da : dvec;
;         dvec = (lane == kb + 2 * pr + 1) ? db : dvec;
	v_cvt_scalef32_pk32_f32_fp6 v[0:31], v[240:245], 1.0
	global_load_dwordx2 v[244:245], v167, s[62:63] offset:16
	global_load_dwordx4 v[240:243], v167, s[62:63]
	v_pk_mul_f32 v[246:247], v[0:1], v[96:97]
	v_pk_mul_f32 v[254:255], v[2:3], v[98:99]
	v_pk_mul_f32 v[160:161], v[4:5], v[100:101]
	v_pk_fma_f32 v[246:247], v[6:7], v[102:103], v[246:247]
	v_pk_fma_f32 v[254:255], v[8:9], v[104:105], v[254:255]
	v_pk_fma_f32 v[160:161], v[10:11], v[106:107], v[160:161]
	v_pk_fma_f32 v[246:247], v[12:13], v[108:109], v[246:247]
	v_pk_fma_f32 v[254:255], v[14:15], v[110:111], v[254:255]
	v_pk_fma_f32 v[160:161], v[16:17], v[112:113], v[160:161]
	v_pk_fma_f32 v[246:247], v[18:19], v[114:115], v[246:247]
	v_pk_fma_f32 v[254:255], v[20:21], v[116:117], v[254:255]
	v_pk_fma_f32 v[160:161], v[22:23], v[118:119], v[160:161]
	v_pk_fma_f32 v[246:247], v[24:25], v[120:121], v[246:247]
	v_pk_fma_f32 v[254:255], v[26:27], v[122:123], v[254:255]
	v_pk_fma_f32 v[160:161], v[28:29], v[124:125], v[160:161]
	v_pk_fma_f32 v[246:247], v[30:31], v[126:127], v[246:247]
	v_pk_add_f32 v[254:255], v[254:255], v[160:161]
	s_nop 0
	v_pk_add_f32 v[246:247], v[246:247], v[254:255]
	s_nop 0
	v_add_f32_e32 v165, v246, v247
	v_add_f32_dpp v162, v162, v162 row_shr:1 row_mask:0xf bank_mask:0xf bound_ctrl:1
	v_add_f32_dpp v163, v163, v163 row_shr:1 row_mask:0xf bank_mask:0xf bound_ctrl:1
	v_add_f32_dpp v164, v164, v164 row_shr:1 row_mask:0xf bank_mask:0xf bound_ctrl:1
	v_add_f32_dpp v165, v165, v165 row_shr:1 row_mask:0xf bank_mask:0xf bound_ctrl:1
	v_add_f32_dpp v162, v162, v162 row_shr:2 row_mask:0xf bank_mask:0xf bound_ctrl:1
	v_add_f32_dpp v163, v163, v163 row_shr:2 row_mask:0xf bank_mask:0xf bound_ctrl:1
	v_add_f32_dpp v164, v164, v164 row_shr:2 row_mask:0xf bank_mask:0xf bound_ctrl:1
	v_add_f32_dpp v165, v165, v165 row_shr:2 row_mask:0xf bank_mask:0xf bound_ctrl:1
	v_add_f32_dpp v162, v162, v162 row_shr:4 row_mask:0xf bank_mask:0xf bound_ctrl:1
	v_add_f32_dpp v163, v163, v163 row_shr:4 row_mask:0xf bank_mask:0xf bound_ctrl:1
	v_add_f32_dpp v164, v164, v164 row_shr:4 row_mask:0xf bank_mask:0xf bound_ctrl:1
	v_add_f32_dpp v165, v165, v165 row_shr:4 row_mask:0xf bank_mask:0xf bound_ctrl:1
	v_add_f32_dpp v162, v162, v162 row_shr:8 row_mask:0xf bank_mask:0xf bound_ctrl:1
	v_add_f32_dpp v163, v163, v163 row_shr:8 row_mask:0xf bank_mask:0xf bound_ctrl:1
	v_add_f32_dpp v164, v164, v164 row_shr:8 row_mask:0xf bank_mask:0xf bound_ctrl:1
	v_add_f32_dpp v165, v165, v165 row_shr:8 row_mask:0xf bank_mask:0xf bound_ctrl:1
	v_add_f32_dpp v162, v162, v162 row_bcast:15 row_mask:0xa bank_mask:0xf
	v_add_f32_dpp v163, v163, v163 row_bcast:15 row_mask:0xa bank_mask:0xf
	v_add_f32_dpp v164, v164, v164 row_bcast:15 row_mask:0xa bank_mask:0xf
	v_add_f32_dpp v165, v165, v165 row_bcast:15 row_mask:0xa bank_mask:0xf
	s_mov_b64 s[98:99], exec
	s_mov_b32 exec_lo, 0x80000000
	s_mov_b32 exec_hi, 0x80000000
	ds_write_b32 v74, v162 offset:160
	ds_write_b32 v74, v163 offset:168
	ds_write_b32 v74, v164 offset:176
	ds_write_b32 v74, v165 offset:184
	s_mov_b64 exec, s[98:99]
	ds_write_b32 v75, v90 offset:256
	ds_read_b32 v76, v74 offset:256
	s_waitcnt lgkmcnt(0)
	v_mad_u32_u24 v167, v76, s33, v195
	ds_read_b32 v77, v74 offset:264
	s_waitcnt vmcnt(14)
	v_cvt_scalef32_pk32_f32_fp6 v[0:31], v[50:55], 1.0
	global_load_dwordx2 v[54:55], v167, s[62:63] offset:16
	global_load_dwordx4 v[50:53], v167, s[62:63]
	v_pk_mul_f32 v[246:247], v[0:1], v[96:97]
	v_pk_mul_f32 v[254:255], v[2:3], v[98:99]
	v_pk_mul_f32 v[160:161], v[4:5], v[100:101]
	v_pk_fma_f32 v[246:247], v[6:7], v[102:103], v[246:247]
	v_pk_fma_f32 v[254:255], v[8:9], v[104:105], v[254:255]
	v_pk_fma_f32 v[160:161], v[10:11], v[106:107], v[160:161]
	v_pk_fma_f32 v[246:247], v[12:13], v[108:109], v[246:247]
	v_pk_fma_f32 v[254:255], v[14:15], v[110:111], v[254:255]
	v_pk_fma_f32 v[160:161], v[16:17], v[112:113], v[160:161]
	v_pk_fma_f32 v[246:247], v[18:19], v[114:115], v[246:247]
	v_pk_fma_f32 v[254:255], v[20:21], v[116:117], v[254:255]
	v_pk_fma_f32 v[160:161], v[22:23], v[118:119], v[160:161]
	v_pk_fma_f32 v[246:247], v[24:25], v[120:121], v[246:247]
	v_pk_fma_f32 v[254:255], v[26:27], v[122:123], v[254:255]
	v_pk_fma_f32 v[160:161], v[28:29], v[124:125], v[160:161]
	v_pk_fma_f32 v[246:247], v[30:31], v[126:127], v[246:247]
	v_pk_add_f32 v[254:255], v[254:255], v[160:161]
	s_nop 0
	v_pk_add_f32 v[246:247], v[246:247], v[254:255]
	s_nop 0
	v_add_f32_e32 v162, v246, v247
	s_waitcnt lgkmcnt(0)
	v_mad_u32_u24 v167, v77, s33, v195
	ds_read_b32 v76, v74 offset:272
	s_waitcnt vmcnt(14)
	v_cvt_scalef32_pk32_f32_fp6 v[0:31], v[44:49], 1.0
	global_load_dwordx2 v[48:49], v167, s[62:63] offset:16
	global_load_dwordx4 v[44:47], v167, s[62:63]
	v_pk_mul_f32 v[246:247], v[0:1], v[96:97]
	v_pk_mul_f32 v[254:255], v[2:3], v[98:99]
	v_pk_mul_f32 v[160:161], v[4:5], v[100:101]
	v_pk_fma_f32 v[246:247], v[6:7], v[102:103], v[246:247]
	v_pk_fma_f32 v[254:255], v[8:9], v[104:105], v[254:255]
	v_pk_fma_f32 v[160:161], v[10:11], v[106:107], v[160:161]
	v_pk_fma_f32 v[246:247], v[12:13], v[108:109], v[246:247]
	v_pk_fma_f32 v[254:255], v[14:15], v[110:111], v[254:255]
	v_pk_fma_f32 v[160:161], v[16:17], v[112:113], v[160:161]
	v_pk_fma_f32 v[246:247], v[18:19], v[114:115], v[246:247]
	v_pk_fma_f32 v[254:255], v[20:21], v[116:117], v[254:255]
	v_pk_fma_f32 v[160:161], v[22:23], v[118:119], v[160:161]
	v_pk_fma_f32 v[246:247], v[24:25], v[120:121], v[246:247]
	v_pk_fma_f32 v[254:255], v[26:27], v[122:123], v[254:255]
	v_pk_fma_f32 v[160:161], v[28:29], v[124:125], v[160:161]
	v_pk_fma_f32 v[246:247], v[30:31], v[126:127], v[246:247]
	v_pk_add_f32 v[254:255], v[254:255], v[160:161]
	s_nop 0
	v_pk_add_f32 v[246:247], v[246:247], v[254:255]
	s_nop 0
	v_add_f32_e32 v163, v246, v247
	s_waitcnt lgkmcnt(0)
; __device__ void peer_gather_phase(const Params& P, int l, bool do_store) {
;     ...
;       for (int pr = 0; pr < 4; ++pr) {
;         v6u_t qv; qv[0] = u6[3 * pr].x; qv[1] = u6[3 * pr].y; qv[2] = u6[3 * pr + 1].x; qv[3] = u6[3 * pr + 1].y; qv[4] = u6[3 * pr + 2].x; qv[5] = u6[3 * pr + 2].y;
;         const v32f_t wv = __builtin_amdgcn_cvt_scalef32_pk32_f32_fp6(qv, 1.0f);
;         f32x2 a2 = f32x2{0.f, 0.f};
; #pragma unroll
;         for (int i = 0; i < 16; ++i) a2 += f32x2{wv[2 * i], wv[2 * i + 1]} * xu[i];
;         float hs = a2.x + a2.y;
;         hs += dpp_row_shr(hs, 1); hs += dpp_row_shr(hs, 2); hs += dpp_row_shr(hs, 4); hs += dpp_row_shr(hs, 8);
;         hs += __builtin_bit_cast(float, __builtin_amdgcn_update_dpp(0, __builtin_bit_cast(int, hs), 0x142, 0xa, 0xf, false));
;         const float da = __builtin_bit_cast(float, __builtin_amdgcn_readlane(__builtin_bit_cast(int, hs), 31));
;         const float db = __builtin_bit_cast(float, __builtin_amdgcn_readlane(__builtin_bit_cast(int, hs), 63));
;         dvec = (lane == kb + 2 * pr) ? da : dvec;
;         dvec = (lane == kb + 2 * pr + 1) ? db : dvec;
	v_mad_u32_u24 v167, v76, s33, v195
	ds_read_b32 v77, v74 offset:280
	s_waitcnt vmcnt(14)
	v_cvt_scalef32_pk32_f32_fp6 v[0:31], v[38:43], 1.0
	global_load_dwordx2 v[42:43], v167, s[62:63] offset:16
	global_load_dwordx4 v[38:41], v167, s[62:63]
	v_pk_mul_f32 v[246:247], v[0:1], v[96:97]
	v_pk_mul_f32 v[254:255], v[2:3], v[98:99]
	v_pk_mul_f32 v[160:161], v[4:5], v[100:101]
	v_pk_fma_f32 v[246:247], v[6:7], v[102:103], v[246:247]
	v_pk_fma_f32 v[254:255], v[8:9], v[104:105], v[254:255]
	v_pk_fma_f32 v[160:161], v[10:11], v[106:107], v[160:161]
	v_pk_fma_f32 v[246:247], v[12:13], v[108:109], v[246:247]
	v_pk_fma_f32 v[254:255], v[14:15], v[110:111], v[254:255]
	v_pk_fma_f32 v[160:161], v[16:17], v[112:113], v[160:161]
	v_pk_fma_f32 v[246:247], v[18:19], v[114:115], v[246:247]
	v_pk_fma_f32 v[254:255], v[20:21], v[116:117], v[254:255]
	v_pk_fma_f32 v[160:161], v[22:23], v[118:119], v[160:161]
	v_pk_fma_f32 v[246:247], v[24:25], v[120:121], v[246:247]
	v_pk_fma_f32 v[254:255], v[26:27], v[122:123], v[254:255]
	v_pk_fma_f32 v[160:161], v[28:29], v[124:125], v[160:161]
	v_pk_fma_f32 v[246:247], v[30:31], v[126:127], v[246:247]
	v_pk_add_f32 v[254:255], v[254:255], v[160:161]
	s_nop 0
	v_pk_add_f32 v[246:247], v[246:247], v[254:255]
	s_nop 0
	v_add_f32_e32 v164, v246, v247
	s_waitcnt lgkmcnt(0)
	v_mad_u32_u24 v167, v77, s33, v195
	ds_read_b32 v76, v74 offset:288
	s_waitcnt vmcnt(14)
	v_cvt_scalef32_pk32_f32_fp6 v[0:31], v[32:37], 1.0
	global_load_dwordx2 v[36:37], v167, s[62:63] offset:16
	global_load_dwordx4 v[32:35], v167, s[62:63]
	v_pk_mul_f32 v[246:247], v[0:1], v[96:97]
	v_pk_mul_f32 v[254:255], v[2:3], v[98:99]
	v_pk_mul_f32 v[160:161], v[4:5], v[100:101]
	v_pk_fma_f32 v[246:247], v[6:7], v[102:103], v[246:247]
	v_pk_fma_f32 v[254:255], v[8:9], v[104:105], v[254:255]
	v_pk_fma_f32 v[160:161], v[10:11], v[106:107], v[160:161]
	v_pk_fma_f32 v[246:247], v[12:13], v[108:109], v[246:247]
	v_pk_fma_f32 v[254:255], v[14:15], v[110:111], v[254:255]
	v_pk_fma_f32 v[160:161], v[16:17], v[112:113], v[160:161]
	v_pk_fma_f32 v[246:247], v[18:19], v[114:115], v[246:247]
	v_pk_fma_f32 v[254:255], v[20:21], v[116:117], v[254:255]
	v_pk_fma_f32 v[160:161], v[22:23], v[118:119], v[160:161]
	v_pk_fma_f32 v[246:247], v[24:25], v[120:121], v[246:247]
	v_pk_fma_f32 v[254:255], v[26:27], v[122:123], v[254:255]
	v_pk_fma_f32 v[160:161], v[28:29], v[124:125], v[160:161]
	v_pk_fma_f32 v[246:247], v[30:31], v[126:127], v[246:247]
	v_pk_add_f32 v[254:255], v[254:255], v[160:161]
	s_nop 0
	v_pk_add_f32 v[246:247], v[246:247], v[254:255]
	s_nop 0
	v_add_f32_e32 v165, v246, v247
	v_add_f32_dpp v162, v162, v162 row_shr:1 row_mask:0xf bank_mask:0xf bound_ctrl:1
	v_add_f32_dpp v163, v163, v163 row_shr:1 row_mask:0xf bank_mask:0xf bound_ctrl:1
	v_add_f32_dpp v164, v164, v164 row_shr:1 row_mask:0xf bank_mask:0xf bound_ctrl:1
	v_add_f32_dpp v165, v165, v165 row_shr:1 row_mask:0xf bank_mask:0xf bound_ctrl:1
	v_add_f32_dpp v162, v162, v162 row_shr:2 row_mask:0xf bank_mask:0xf bound_ctrl:1
	v_add_f32_dpp v163, v163, v163 row_shr:2 row_mask:0xf bank_mask:0xf bound_ctrl:1
	v_add_f32_dpp v164, v164, v164 row_shr:2 row_mask:0xf bank_mask:0xf bound_ctrl:1
	v_add_f32_dpp v165, v165, v165 row_shr:2 row_mask:0xf bank_mask:0xf bound_ctrl:1
	v_add_f32_dpp v162, v162, v162 row_shr:4 row_mask:0xf bank_mask:0xf bound_ctrl:1
	v_add_f32_dpp v163, v163, v163 row_shr:4 row_mask:0xf bank_mask:0xf bound_ctrl:1
	v_add_f32_dpp v164, v164, v164 row_shr:4 row_mask:0xf bank_mask:0xf bound_ctrl:1
	v_add_f32_dpp v165, v165, v165 row_shr:4 row_mask:0xf bank_mask:0xf bound_ctrl:1
	v_add_f32_dpp v162, v162, v162 row_shr:8 row_mask:0xf bank_mask:0xf bound_ctrl:1
	v_add_f32_dpp v163, v163, v163 row_shr:8 row_mask:0xf bank_mask:0xf bound_ctrl:1
	v_add_f32_dpp v164, v164, v164 row_shr:8 row_mask:0xf bank_mask:0xf bound_ctrl:1
	v_add_f32_dpp v165, v165, v165 row_shr:8 row_mask:0xf bank_mask:0xf bound_ctrl:1
	v_add_f32_dpp v162, v162, v162 row_bcast:15 row_mask:0xa bank_mask:0xf
	v_add_f32_dpp v163, v163, v163 row_bcast:15 row_mask:0xa bank_mask:0xf
	v_add_f32_dpp v164, v164, v164 row_bcast:15 row_mask:0xa bank_mask:0xf
	v_add_f32_dpp v165, v165, v165 row_bcast:15 row_mask:0xa bank_mask:0xf
	s_mov_b64 s[98:99], exec
	s_mov_b32 exec_lo, 0x80000000
	s_mov_b32 exec_hi, 0x80000000
	ds_write_b32 v74, v162 offset:192
	ds_write_b32 v74, v163 offset:200
	ds_write_b32 v74, v164 offset:208
	ds_write_b32 v74, v165 offset:216
	s_mov_b64 exec, s[98:99]
	s_waitcnt lgkmcnt(0)
	v_mad_u32_u24 v167, v76, s33, v195
	ds_read_b32 v77, v74 offset:296
	s_waitcnt vmcnt(14)
	v_cvt_scalef32_pk32_f32_fp6 v[0:31], v[196:201], 1.0
	global_load_dwordx2 v[200:201], v167, s[62:63] offset:16
	global_load_dwordx4 v[196:199], v167, s[62:63]
	v_pk_mul_f32 v[246:247], v[0:1], v[96:97]
	v_pk_mul_f32 v[254:255], v[2:3], v[98:99]
	v_pk_mul_f32 v[160:161], v[4:5], v[100:101]
	v_pk_fma_f32 v[246:247], v[6:7], v[102:103], v[246:247]
	v_pk_fma_f32 v[254:255], v[8:9], v[104:105], v[254:255]
	v_pk_fma_f32 v[160:161], v[10:11], v[106:107], v[160:161]
	v_pk_fma_f32 v[246:247], v[12:13], v[108:109], v[246:247]
	v_pk_fma_f32 v[254:255], v[14:15], v[110:111], v[254:255]
	v_pk_fma_f32 v[160:161], v[16:17], v[112:113], v[160:161]
	v_pk_fma_f32 v[246:247], v[18:19], v[114:115], v[246:247]
	v_pk_fma_f32 v[254:255], v[20:21], v[116:117], v[254:255]
	v_pk_fma_f32 v[160:161], v[22:23], v[118:119], v[160:161]
	v_pk_fma_f32 v[246:247], v[24:25], v[120:121], v[246:247]
	v_pk_fma_f32 v[254:255], v[26:27], v[122:123], v[254:255]
	v_pk_fma_f32 v[160:161], v[28:29], v[124:125], v[160:161]
	v_pk_fma_f32 v[246:247], v[30:31], v[126:127], v[246:247]
	v_pk_add_f32 v[254:255], v[254:255], v[160:161]
	s_nop 0
	v_pk_add_f32 v[246:247], v[246:247], v[254:255]
	s_nop 0
	v_add_f32_e32 v162, v246, v247
	s_waitcnt lgkmcnt(0)
; __device__ void peer_gather_phase(const Params& P, int l, bool do_store) {
;     ...
;       for (int pr = 0; pr < 4; ++pr) {
;         v6u_t qv; qv[0] = u6[3 * pr].x; qv[1] = u6[3 * pr].y; qv[2] = u6[3 * pr + 1].x; qv[3] = u6[3 * pr + 1].y; qv[4] = u6[3 * pr + 2].x; qv[5] = u6[3 * pr + 2].y;
;         const v32f_t wv = __builtin_amdgcn_cvt_scalef32_pk32_f32_fp6(qv, 1.0f);
;         f32x2 a2 = f32x2{0.f, 0.f};
; #pragma unroll
;         for (int i = 0; i < 16; ++i) a2 += f32x2{wv[2 * i], wv[2 * i + 1]} * xu[i];
;         float hs = a2.x + a2.y;
;         hs += dpp_row_shr(hs, 1); hs += dpp_row_shr(hs, 2); hs += dpp_row_shr(hs, 4); hs += dpp_row_shr(hs, 8);
;         hs += __builtin_bit_cast(float, __builtin_amdgcn_update_dpp(0, __builtin_bit_cast(int, hs), 0x142, 0xa, 0xf, false));
;         const float da = __builtin_bit_cast(float, __builtin_amdgcn_readlane(__builtin_bit_cast(int, hs), 31));
;         const float db = __builtin_bit_cast(float, __builtin_amdgcn_readlane(__builtin_bit_cast(int, hs), 63));
;         dvec = (lane == kb + 2 * pr) ? da : dvec;
;         dvec = (lane == kb + 2 * pr + 1) ? db : dvec;
;       }
	v_mad_u32_u24 v167, v77, s33, v195
	ds_read_b32 v76, v74 offset:304
	s_waitcnt vmcnt(14)
	v_cvt_scalef32_pk32_f32_fp6 v[0:31], v[228:233], 1.0
	global_load_dwordx2 v[232:233], v167, s[62:63] offset:16
	global_load_dwordx4 v[228:231], v167, s[62:63]
	v_pk_mul_f32 v[246:247], v[0:1], v[96:97]
	v_pk_mul_f32 v[254:255], v[2:3], v[98:99]
	v_pk_mul_f32 v[160:161], v[4:5], v[100:101]
	v_pk_fma_f32 v[246:247], v[6:7], v[102:103], v[246:247]
	v_pk_fma_f32 v[254:255], v[8:9], v[104:105], v[254:255]
	v_pk_fma_f32 v[160:161], v[10:11], v[106:107], v[160:161]
	v_pk_fma_f32 v[246:247], v[12:13], v[108:109], v[246:247]
	v_pk_fma_f32 v[254:255], v[14:15], v[110:111], v[254:255]
	v_pk_fma_f32 v[160:161], v[16:17], v[112:113], v[160:161]
	v_pk_fma_f32 v[246:247], v[18:19], v[114:115], v[246:247]
	v_pk_fma_f32 v[254:255], v[20:21], v[116:117], v[254:255]
	v_pk_fma_f32 v[160:161], v[22:23], v[118:119], v[160:161]
	v_pk_fma_f32 v[246:247], v[24:25], v[120:121], v[246:247]
	v_pk_fma_f32 v[254:255], v[26:27], v[122:123], v[254:255]
	v_pk_fma_f32 v[160:161], v[28:29], v[124:125], v[160:161]
	v_pk_fma_f32 v[246:247], v[30:31], v[126:127], v[246:247]
	v_pk_add_f32 v[254:255], v[254:255], v[160:161]
	s_nop 0
	v_pk_add_f32 v[246:247], v[246:247], v[254:255]
	s_nop 0
	v_add_f32_e32 v163, v246, v247
	s_waitcnt lgkmcnt(0)
	v_mad_u32_u24 v167, v76, s33, v195
	ds_read_b32 v77, v74 offset:312
	s_waitcnt vmcnt(14)
	v_cvt_scalef32_pk32_f32_fp6 v[0:31], v[234:239], 1.0
	global_load_dwordx2 v[238:239], v167, s[62:63] offset:16
	global_load_dwordx4 v[234:237], v167, s[62:63]
	v_pk_mul_f32 v[246:247], v[0:1], v[96:97]
	v_pk_mul_f32 v[254:255], v[2:3], v[98:99]
	v_pk_mul_f32 v[160:161], v[4:5], v[100:101]
	v_pk_fma_f32 v[246:247], v[6:7], v[102:103], v[246:247]
	v_pk_fma_f32 v[254:255], v[8:9], v[104:105], v[254:255]
	v_pk_fma_f32 v[160:161], v[10:11], v[106:107], v[160:161]
	v_pk_fma_f32 v[246:247], v[12:13], v[108:109], v[246:247]
	v_pk_fma_f32 v[254:255], v[14:15], v[110:111], v[254:255]
	v_pk_fma_f32 v[160:161], v[16:17], v[112:113], v[160:161]
	v_pk_fma_f32 v[246:247], v[18:19], v[114:115], v[246:247]
	v_pk_fma_f32 v[254:255], v[20:21], v[116:117], v[254:255]
	v_pk_fma_f32 v[160:161], v[22:23], v[118:119], v[160:161]
	v_pk_fma_f32 v[246:247], v[24:25], v[120:121], v[246:247]
	v_pk_fma_f32 v[254:255], v[26:27], v[122:123], v[254:255]
	v_pk_fma_f32 v[160:161], v[28:29], v[124:125], v[160:161]
	v_pk_fma_f32 v[246:247], v[30:31], v[126:127], v[246:247]
	v_pk_add_f32 v[254:255], v[254:255], v[160:161]
	s_nop 0
	v_pk_add_f32 v[246:247], v[246:247], v[254:255]
	s_nop 0
	v_add_f32_e32 v164, v246, v247
	s_waitcnt lgkmcnt(0)
	v_mad_u32_u24 v167, v77, s33, v195
	s_waitcnt vmcnt(14)
	v_cvt_scalef32_pk32_f32_fp6 v[0:31], v[240:245], 1.0
	global_load_dwordx2 v[244:245], v167, s[62:63] offset:16
	global_load_dwordx4 v[240:243], v167, s[62:63]
	v_pk_mul_f32 v[246:247], v[0:1], v[96:97]
	v_pk_mul_f32 v[254:255], v[2:3], v[98:99]
	v_pk_mul_f32 v[160:161], v[4:5], v[100:101]
	v_pk_fma_f32 v[246:247], v[6:7], v[102:103], v[246:247]
	v_pk_fma_f32 v[254:255], v[8:9], v[104:105], v[254:255]
	v_pk_fma_f32 v[160:161], v[10:11], v[106:107], v[160:161]
	v_pk_fma_f32 v[246:247], v[12:13], v[108:109], v[246:247]
	v_pk_fma_f32 v[254:255], v[14:15], v[110:111], v[254:255]
	v_pk_fma_f32 v[160:161], v[16:17], v[112:113], v[160:161]
	v_pk_fma_f32 v[246:247], v[18:19], v[114:115], v[246:247]
	v_pk_fma_f32 v[254:255], v[20:21], v[116:117], v[254:255]
	v_pk_fma_f32 v[160:161], v[22:23], v[118:119], v[160:161]
	v_pk_fma_f32 v[246:247], v[24:25], v[120:121], v[246:247]
	v_pk_fma_f32 v[254:255], v[26:27], v[122:123], v[254:255]
	v_pk_fma_f32 v[160:161], v[28:29], v[124:125], v[160:161]
	v_pk_fma_f32 v[246:247], v[30:31], v[126:127], v[246:247]
	v_pk_add_f32 v[254:255], v[254:255], v[160:161]
	s_nop 0
	v_pk_add_f32 v[246:247], v[246:247], v[254:255]
	s_nop 0
	v_add_f32_e32 v165, v246, v247
	v_add_f32_dpp v162, v162, v162 row_shr:1 row_mask:0xf bank_mask:0xf bound_ctrl:1
	v_add_f32_dpp v163, v163, v163 row_shr:1 row_mask:0xf bank_mask:0xf bound_ctrl:1
	v_add_f32_dpp v164, v164, v164 row_shr:1 row_mask:0xf bank_mask:0xf bound_ctrl:1
	v_add_f32_dpp v165, v165, v165 row_shr:1 row_mask:0xf bank_mask:0xf bound_ctrl:1
	v_add_f32_dpp v162, v162, v162 row_shr:2 row_mask:0xf bank_mask:0xf bound_ctrl:1
	v_add_f32_dpp v163, v163, v163 row_shr:2 row_mask:0xf bank_mask:0xf bound_ctrl:1
	v_add_f32_dpp v164, v164, v164 row_shr:2 row_mask:0xf bank_mask:0xf bound_ctrl:1
	v_add_f32_dpp v165, v165, v165 row_shr:2 row_mask:0xf bank_mask:0xf bound_ctrl:1
	v_add_f32_dpp v162, v162, v162 row_shr:4 row_mask:0xf bank_mask:0xf bound_ctrl:1
	v_add_f32_dpp v163, v163, v163 row_shr:4 row_mask:0xf bank_mask:0xf bound_ctrl:1
	v_add_f32_dpp v164, v164, v164 row_shr:4 row_mask:0xf bank_mask:0xf bound_ctrl:1
	v_add_f32_dpp v165, v165, v165 row_shr:4 row_mask:0xf bank_mask:0xf bound_ctrl:1
	v_add_f32_dpp v162, v162, v162 row_shr:8 row_mask:0xf bank_mask:0xf bound_ctrl:1
	v_add_f32_dpp v163, v163, v163 row_shr:8 row_mask:0xf bank_mask:0xf bound_ctrl:1
	v_add_f32_dpp v164, v164, v164 row_shr:8 row_mask:0xf bank_mask:0xf bound_ctrl:1
	v_add_f32_dpp v165, v165, v165 row_shr:8 row_mask:0xf bank_mask:0xf bound_ctrl:1
	v_add_f32_dpp v162, v162, v162 row_bcast:15 row_mask:0xa bank_mask:0xf
	v_add_f32_dpp v163, v163, v163 row_bcast:15 row_mask:0xa bank_mask:0xf
	v_add_f32_dpp v164, v164, v164 row_bcast:15 row_mask:0xa bank_mask:0xf
	v_add_f32_dpp v165, v165, v165 row_bcast:15 row_mask:0xa bank_mask:0xf
	s_mov_b64 s[98:99], exec
	s_mov_b32 exec_lo, 0x80000000
	s_mov_b32 exec_hi, 0x80000000
	ds_write_b32 v74, v162 offset:224
	ds_write_b32 v74, v163 offset:232
	ds_write_b32 v74, v164 offset:240
	ds_write_b32 v74, v165 offset:248
	s_mov_b64 exec, s[98:99]
	ds_read_b32 v166, v75
	s_waitcnt lgkmcnt(0)
; __device__ void peer_gather_phase(const Params& P, int l, bool do_store) {
;     ...
;       const float sux = (bt < 8) ? sux0 : sux1;
;       const float gsx = (bt < 8) ? gsx0 : gsx1;
;       const float avec = gelu_t(dvec * sux) * gsx;
; #pragma unroll
;       for (int j = 0; j < 8; ++j) {
;         const float a = __builtin_bit_cast(float, __builtin_amdgcn_readlane(__builtin_bit_cast(int, avec), kb + j));
;         const f32x2 aa = f32x2{a, a};
;         y[0] += aa * __builtin_amdgcn_cvt_scalef32_pk_f32_fp4(v8[j].x, 1.0f, 0); y[1] += aa * __builtin_amdgcn_cvt_scalef32_pk_f32_fp4(v8[j].x, 1.0f, 1);
;         y[2] += aa * __builtin_amdgcn_cvt_scalef32_pk_f32_fp4(v8[j].x, 1.0f, 2); y[3] += aa * __builtin_amdgcn_cvt_scalef32_pk_f32_fp4(v8[j].x, 1.0f, 3);
;         y[4] += aa * __builtin_amdgcn_cvt_scalef32_pk_f32_fp4(v8[j].y, 1.0f, 0); y[5] += aa * __builtin_amdgcn_cvt_scalef32_pk_f32_fp4(v8[j].y, 1.0f, 1);
;         y[6] += aa * __builtin_amdgcn_cvt_scalef32_pk_f32_fp4(v8[j].y, 1.0f, 2); y[7] += aa * __builtin_amdgcn_cvt_scalef32_pk_f32_fp4(v8[j].y, 1.0f, 3);
;       }
	v_mul_f32_e32 v0, v189, v166
	v_mul_f32_e32 v1, 0x3d372713, v0
	v_mul_f32_e32 v1, v0, v1
	v_fma_f32 v1, v0, v1, v0
	v_mul_f32_e32 v1, 0x3f4c422a, v1
	v_add_f32_e32 v1, v1, v1
	v_mul_f32_e32 v1, 0x3fb8aa3b, v1
	v_exp_f32_e32 v1, v1
	v_mul_f32_e32 v0, 0.5, v0
	v_add_f32_e32 v1, 1.0, v1
	v_div_scale_f32 v2, s[0:1], v1, v1, 2.0
	v_rcp_f32_e32 v3, v2
	s_nop 0
	v_fma_f32 v4, -v2, v3, 1.0
	v_fmac_f32_e32 v3, v4, v3
	v_div_scale_f32 v4, vcc, 2.0, v1, 2.0
	v_mul_f32_e32 v5, v4, v3
	v_fma_f32 v6, -v2, v5, v4
	v_fmac_f32_e32 v5, v6, v3
	v_fma_f32 v2, -v2, v5, v4
	v_div_fmas_f32 v2, v2, v3, v5
	v_div_fixup_f32 v1, v2, v1, 2.0
	v_sub_f32_e32 v1, 1.0, v1
	v_add_f32_e32 v1, 1.0, v1
	v_mul_f32_e32 v0, v0, v1
	v_mul_f32_e32 v167, v191, v0
	ds_write_b32 v75, v167 offset:512
	ds_read_b32 v76, v193 offset:512
	ds_read_b32 v194, v193 offset:516
	s_waitcnt vmcnt(48)
	v_cvt_scalef32_pk_f32_fp4 v[0:1], v144, 1.0
	v_cvt_scalef32_pk_f32_fp4 v[2:3], v144, 1.0 op_sel:[1,0,0]
	v_cvt_scalef32_pk_f32_fp4 v[4:5], v144, 1.0 op_sel:[0,1,0]
	v_cvt_scalef32_pk_f32_fp4 v[6:7], v144, 1.0 op_sel:[1,1,0]
	v_cvt_scalef32_pk_f32_fp4 v[8:9], v145, 1.0
	v_cvt_scalef32_pk_f32_fp4 v[10:11], v145, 1.0 op_sel:[1,0,0]
	v_cvt_scalef32_pk_f32_fp4 v[12:13], v145, 1.0 op_sel:[0,1,0]
	v_cvt_scalef32_pk_f32_fp4 v[14:15], v145, 1.0 op_sel:[1,1,0]
	v_readlane_b32 s54, v92, 16
	s_lshl_b32 s56, s54, 9
	s_add_u32 s56, s64, s56
	s_addc_u32 s57, s65, 0
	global_load_dwordx2 v[144:145], v227, s[56:57]
	s_waitcnt lgkmcnt(1)
	v_pk_fma_f32 v[130:131], v[0:1], v[76:77], v[130:131] op_sel_hi:[1,0,1]
	v_pk_fma_f32 v[138:139], v[2:3], v[76:77], v[138:139] op_sel_hi:[1,0,1]
	v_pk_fma_f32 v[140:141], v[4:5], v[76:77], v[140:141] op_sel_hi:[1,0,1]
	v_pk_fma_f32 v[142:143], v[6:7], v[76:77], v[142:143] op_sel_hi:[1,0,1]
	v_pk_fma_f32 v[128:129], v[8:9], v[76:77], v[128:129] op_sel_hi:[1,0,1]
	v_pk_fma_f32 v[132:133], v[10:11], v[76:77], v[132:133] op_sel_hi:[1,0,1]
	v_pk_fma_f32 v[134:135], v[12:13], v[76:77], v[134:135] op_sel_hi:[1,0,1]
	v_pk_fma_f32 v[136:137], v[14:15], v[76:77], v[136:137] op_sel_hi:[1,0,1]
	ds_read_b32 v76, v193 offset:520
	s_waitcnt vmcnt(48)
	v_cvt_scalef32_pk_f32_fp4 v[0:1], v146, 1.0
	v_cvt_scalef32_pk_f32_fp4 v[2:3], v146, 1.0 op_sel:[1,0,0]
	v_cvt_scalef32_pk_f32_fp4 v[4:5], v146, 1.0 op_sel:[0,1,0]
	v_cvt_scalef32_pk_f32_fp4 v[6:7], v146, 1.0 op_sel:[1,1,0]
	v_cvt_scalef32_pk_f32_fp4 v[8:9], v147, 1.0
	v_cvt_scalef32_pk_f32_fp4 v[10:11], v147, 1.0 op_sel:[1,0,0]
	v_cvt_scalef32_pk_f32_fp4 v[12:13], v147, 1.0 op_sel:[0,1,0]
	v_cvt_scalef32_pk_f32_fp4 v[14:15], v147, 1.0 op_sel:[1,1,0]
	v_readlane_b32 s54, v92, 17
	s_lshl_b32 s56, s54, 9
	s_add_u32 s56, s64, s56
	s_addc_u32 s57, s65, 0
	global_load_dwordx2 v[146:147], v227, s[56:57]
	s_waitcnt lgkmcnt(1)
	v_pk_fma_f32 v[130:131], v[0:1], v[194:195], v[130:131] op_sel_hi:[1,0,1]
	v_pk_fma_f32 v[138:139], v[2:3], v[194:195], v[138:139] op_sel_hi:[1,0,1]
	v_pk_fma_f32 v[140:141], v[4:5], v[194:195], v[140:141] op_sel_hi:[1,0,1]
	v_pk_fma_f32 v[142:143], v[6:7], v[194:195], v[142:143] op_sel_hi:[1,0,1]
	v_pk_fma_f32 v[128:129], v[8:9], v[194:195], v[128:129] op_sel_hi:[1,0,1]
	v_pk_fma_f32 v[132:133], v[10:11], v[194:195], v[132:133] op_sel_hi:[1,0,1]
	v_pk_fma_f32 v[134:135], v[12:13], v[194:195], v[134:135] op_sel_hi:[1,0,1]
	v_pk_fma_f32 v[136:137], v[14:15], v[194:195], v[136:137] op_sel_hi:[1,0,1]
	ds_read_b32 v194, v193 offset:524
	s_waitcnt vmcnt(48)
	v_cvt_scalef32_pk_f32_fp4 v[0:1], v148, 1.0
	v_cvt_scalef32_pk_f32_fp4 v[2:3], v148, 1.0 op_sel:[1,0,0]
	v_cvt_scalef32_pk_f32_fp4 v[4:5], v148, 1.0 op_sel:[0,1,0]
	v_cvt_scalef32_pk_f32_fp4 v[6:7], v148, 1.0 op_sel:[1,1,0]
	v_cvt_scalef32_pk_f32_fp4 v[8:9], v149, 1.0
	v_cvt_scalef32_pk_f32_fp4 v[10:11], v149, 1.0 op_sel:[1,0,0]
	v_cvt_scalef32_pk_f32_fp4 v[12:13], v149, 1.0 op_sel:[0,1,0]
	v_cvt_scalef32_pk_f32_fp4 v[14:15], v149, 1.0 op_sel:[1,1,0]
	v_readlane_b32 s54, v92, 18
	s_lshl_b32 s56, s54, 9
	s_add_u32 s56, s64, s56
	s_addc_u32 s57, s65, 0
	global_load_dwordx2 v[148:149], v227, s[56:57]
	s_waitcnt lgkmcnt(1)
	v_pk_fma_f32 v[130:131], v[0:1], v[76:77], v[130:131] op_sel_hi:[1,0,1]
	v_pk_fma_f32 v[138:139], v[2:3], v[76:77], v[138:139] op_sel_hi:[1,0,1]
	v_pk_fma_f32 v[140:141], v[4:5], v[76:77], v[140:141] op_sel_hi:[1,0,1]
	v_pk_fma_f32 v[142:143], v[6:7], v[76:77], v[142:143] op_sel_hi:[1,0,1]
	v_pk_fma_f32 v[128:129], v[8:9], v[76:77], v[128:129] op_sel_hi:[1,0,1]
	v_pk_fma_f32 v[132:133], v[10:11], v[76:77], v[132:133] op_sel_hi:[1,0,1]
	v_pk_fma_f32 v[134:135], v[12:13], v[76:77], v[134:135] op_sel_hi:[1,0,1]
	v_pk_fma_f32 v[136:137], v[14:15], v[76:77], v[136:137] op_sel_hi:[1,0,1]
	ds_read_b32 v76, v193 offset:528
	s_waitcnt vmcnt(48)
	v_cvt_scalef32_pk_f32_fp4 v[0:1], v150, 1.0
	v_cvt_scalef32_pk_f32_fp4 v[2:3], v150, 1.0 op_sel:[1,0,0]
	v_cvt_scalef32_pk_f32_fp4 v[4:5], v150, 1.0 op_sel:[0,1,0]
	v_cvt_scalef32_pk_f32_fp4 v[6:7], v150, 1.0 op_sel:[1,1,0]
	v_cvt_scalef32_pk_f32_fp4 v[8:9], v151, 1.0
	v_cvt_scalef32_pk_f32_fp4 v[10:11], v151, 1.0 op_sel:[1,0,0]
	v_cvt_scalef32_pk_f32_fp4 v[12:13], v151, 1.0 op_sel:[0,1,0]
	v_cvt_scalef32_pk_f32_fp4 v[14:15], v151, 1.0 op_sel:[1,1,0]
	v_readlane_b32 s54, v92, 19
	s_lshl_b32 s56, s54, 9
	s_add_u32 s56, s64, s56
	s_addc_u32 s57, s65, 0
	global_load_dwordx2 v[150:151], v227, s[56:57]
	s_waitcnt lgkmcnt(1)
; __device__ void peer_gather_phase(const Params& P, int l, bool do_store) {
;     ...
;       const float avec = gelu_t(dvec * sux) * gsx;
; #pragma unroll
;       for (int j = 0; j < 8; ++j) {
;         const float a = __builtin_bit_cast(float, __builtin_amdgcn_readlane(__builtin_bit_cast(int, avec), kb + j));
;         const f32x2 aa = f32x2{a, a};
;         y[0] += aa * __builtin_amdgcn_cvt_scalef32_pk_f32_fp4(v8[j].x, 1.0f, 0); y[1] += aa * __builtin_amdgcn_cvt_scalef32_pk_f32_fp4(v8[j].x, 1.0f, 1);
;         y[2] += aa * __builtin_amdgcn_cvt_scalef32_pk_f32_fp4(v8[j].x, 1.0f, 2); y[3] += aa * __builtin_amdgcn_cvt_scalef32_pk_f32_fp4(v8[j].x, 1.0f, 3);
;         y[4] += aa * __builtin_amdgcn_cvt_scalef32_pk_f32_fp4(v8[j].y, 1.0f, 0); y[5] += aa * __builtin_amdgcn_cvt_scalef32_pk_f32_fp4(v8[j].y, 1.0f, 1);
;         y[6] += aa * __builtin_amdgcn_cvt_scalef32_pk_f32_fp4(v8[j].y, 1.0f, 2); y[7] += aa * __builtin_amdgcn_cvt_scalef32_pk_f32_fp4(v8[j].y, 1.0f, 3);
	v_pk_fma_f32 v[130:131], v[0:1], v[194:195], v[130:131] op_sel_hi:[1,0,1]
	v_pk_fma_f32 v[138:139], v[2:3], v[194:195], v[138:139] op_sel_hi:[1,0,1]
	v_pk_fma_f32 v[140:141], v[4:5], v[194:195], v[140:141] op_sel_hi:[1,0,1]
	v_pk_fma_f32 v[142:143], v[6:7], v[194:195], v[142:143] op_sel_hi:[1,0,1]
	v_pk_fma_f32 v[128:129], v[8:9], v[194:195], v[128:129] op_sel_hi:[1,0,1]
	v_pk_fma_f32 v[132:133], v[10:11], v[194:195], v[132:133] op_sel_hi:[1,0,1]
	v_pk_fma_f32 v[134:135], v[12:13], v[194:195], v[134:135] op_sel_hi:[1,0,1]
	v_pk_fma_f32 v[136:137], v[14:15], v[194:195], v[136:137] op_sel_hi:[1,0,1]
	ds_read_b32 v194, v193 offset:532
	s_waitcnt vmcnt(48)
	v_cvt_scalef32_pk_f32_fp4 v[0:1], v152, 1.0
	v_cvt_scalef32_pk_f32_fp4 v[2:3], v152, 1.0 op_sel:[1,0,0]
	v_cvt_scalef32_pk_f32_fp4 v[4:5], v152, 1.0 op_sel:[0,1,0]
	v_cvt_scalef32_pk_f32_fp4 v[6:7], v152, 1.0 op_sel:[1,1,0]
	v_cvt_scalef32_pk_f32_fp4 v[8:9], v153, 1.0
	v_cvt_scalef32_pk_f32_fp4 v[10:11], v153, 1.0 op_sel:[1,0,0]
	v_cvt_scalef32_pk_f32_fp4 v[12:13], v153, 1.0 op_sel:[0,1,0]
	v_cvt_scalef32_pk_f32_fp4 v[14:15], v153, 1.0 op_sel:[1,1,0]
	v_readlane_b32 s54, v92, 20
	s_lshl_b32 s56, s54, 9
	s_add_u32 s56, s64, s56
	s_addc_u32 s57, s65, 0
	global_load_dwordx2 v[152:153], v227, s[56:57]
	s_waitcnt lgkmcnt(1)
	v_pk_fma_f32 v[130:131], v[0:1], v[76:77], v[130:131] op_sel_hi:[1,0,1]
	v_pk_fma_f32 v[138:139], v[2:3], v[76:77], v[138:139] op_sel_hi:[1,0,1]
	v_pk_fma_f32 v[140:141], v[4:5], v[76:77], v[140:141] op_sel_hi:[1,0,1]
	v_pk_fma_f32 v[142:143], v[6:7], v[76:77], v[142:143] op_sel_hi:[1,0,1]
	v_pk_fma_f32 v[128:129], v[8:9], v[76:77], v[128:129] op_sel_hi:[1,0,1]
	v_pk_fma_f32 v[132:133], v[10:11], v[76:77], v[132:133] op_sel_hi:[1,0,1]
	v_pk_fma_f32 v[134:135], v[12:13], v[76:77], v[134:135] op_sel_hi:[1,0,1]
	v_pk_fma_f32 v[136:137], v[14:15], v[76:77], v[136:137] op_sel_hi:[1,0,1]
	ds_read_b32 v76, v193 offset:536
	s_waitcnt vmcnt(48)
	v_cvt_scalef32_pk_f32_fp4 v[0:1], v154, 1.0
	v_cvt_scalef32_pk_f32_fp4 v[2:3], v154, 1.0 op_sel:[1,0,0]
	v_cvt_scalef32_pk_f32_fp4 v[4:5], v154, 1.0 op_sel:[0,1,0]
	v_cvt_scalef32_pk_f32_fp4 v[6:7], v154, 1.0 op_sel:[1,1,0]
	v_cvt_scalef32_pk_f32_fp4 v[8:9], v155, 1.0
	v_cvt_scalef32_pk_f32_fp4 v[10:11], v155, 1.0 op_sel:[1,0,0]
	v_cvt_scalef32_pk_f32_fp4 v[12:13], v155, 1.0 op_sel:[0,1,0]
	v_cvt_scalef32_pk_f32_fp4 v[14:15], v155, 1.0 op_sel:[1,1,0]
	v_readlane_b32 s54, v92, 21
	s_lshl_b32 s56, s54, 9
	s_add_u32 s56, s64, s56
	s_addc_u32 s57, s65, 0
	global_load_dwordx2 v[154:155], v227, s[56:57]
	s_waitcnt lgkmcnt(1)
	v_pk_fma_f32 v[130:131], v[0:1], v[194:195], v[130:131] op_sel_hi:[1,0,1]
	v_pk_fma_f32 v[138:139], v[2:3], v[194:195], v[138:139] op_sel_hi:[1,0,1]
	v_pk_fma_f32 v[140:141], v[4:5], v[194:195], v[140:141] op_sel_hi:[1,0,1]
	v_pk_fma_f32 v[142:143], v[6:7], v[194:195], v[142:143] op_sel_hi:[1,0,1]
	v_pk_fma_f32 v[128:129], v[8:9], v[194:195], v[128:129] op_sel_hi:[1,0,1]
	v_pk_fma_f32 v[132:133], v[10:11], v[194:195], v[132:133] op_sel_hi:[1,0,1]
	v_pk_fma_f32 v[134:135], v[12:13], v[194:195], v[134:135] op_sel_hi:[1,0,1]
	v_pk_fma_f32 v[136:137], v[14:15], v[194:195], v[136:137] op_sel_hi:[1,0,1]
	ds_read_b32 v194, v193 offset:540
	s_waitcnt vmcnt(48)
	v_cvt_scalef32_pk_f32_fp4 v[0:1], v156, 1.0
	v_cvt_scalef32_pk_f32_fp4 v[2:3], v156, 1.0 op_sel:[1,0,0]
	v_cvt_scalef32_pk_f32_fp4 v[4:5], v156, 1.0 op_sel:[0,1,0]
	v_cvt_scalef32_pk_f32_fp4 v[6:7], v156, 1.0 op_sel:[1,1,0]
	v_cvt_scalef32_pk_f32_fp4 v[8:9], v157, 1.0
	v_cvt_scalef32_pk_f32_fp4 v[10:11], v157, 1.0 op_sel:[1,0,0]
	v_cvt_scalef32_pk_f32_fp4 v[12:13], v157, 1.0 op_sel:[0,1,0]
	v_cvt_scalef32_pk_f32_fp4 v[14:15], v157, 1.0 op_sel:[1,1,0]
	v_readlane_b32 s54, v92, 22
	s_lshl_b32 s56, s54, 9
	s_add_u32 s56, s64, s56
	s_addc_u32 s57, s65, 0
	global_load_dwordx2 v[156:157], v227, s[56:57]
	s_waitcnt lgkmcnt(1)
	v_pk_fma_f32 v[130:131], v[0:1], v[76:77], v[130:131] op_sel_hi:[1,0,1]
	v_pk_fma_f32 v[138:139], v[2:3], v[76:77], v[138:139] op_sel_hi:[1,0,1]
	v_pk_fma_f32 v[140:141], v[4:5], v[76:77], v[140:141] op_sel_hi:[1,0,1]
	v_pk_fma_f32 v[142:143], v[6:7], v[76:77], v[142:143] op_sel_hi:[1,0,1]
	v_pk_fma_f32 v[128:129], v[8:9], v[76:77], v[128:129] op_sel_hi:[1,0,1]
	v_pk_fma_f32 v[132:133], v[10:11], v[76:77], v[132:133] op_sel_hi:[1,0,1]
	v_pk_fma_f32 v[134:135], v[12:13], v[76:77], v[134:135] op_sel_hi:[1,0,1]
	v_pk_fma_f32 v[136:137], v[14:15], v[76:77], v[136:137] op_sel_hi:[1,0,1]
	ds_read_b32 v76, v193 offset:544
	s_waitcnt vmcnt(48)
	v_cvt_scalef32_pk_f32_fp4 v[0:1], v158, 1.0
	v_cvt_scalef32_pk_f32_fp4 v[2:3], v158, 1.0 op_sel:[1,0,0]
	v_cvt_scalef32_pk_f32_fp4 v[4:5], v158, 1.0 op_sel:[0,1,0]
	v_cvt_scalef32_pk_f32_fp4 v[6:7], v158, 1.0 op_sel:[1,1,0]
	v_cvt_scalef32_pk_f32_fp4 v[8:9], v159, 1.0
	v_cvt_scalef32_pk_f32_fp4 v[10:11], v159, 1.0 op_sel:[1,0,0]
	v_cvt_scalef32_pk_f32_fp4 v[12:13], v159, 1.0 op_sel:[0,1,0]
	v_cvt_scalef32_pk_f32_fp4 v[14:15], v159, 1.0 op_sel:[1,1,0]
	v_readlane_b32 s54, v92, 23
	s_lshl_b32 s56, s54, 9
	s_add_u32 s56, s64, s56
	s_addc_u32 s57, s65, 0
	global_load_dwordx2 v[158:159], v227, s[56:57]
	s_waitcnt lgkmcnt(1)
	v_pk_fma_f32 v[130:131], v[0:1], v[194:195], v[130:131] op_sel_hi:[1,0,1]
	v_pk_fma_f32 v[138:139], v[2:3], v[194:195], v[138:139] op_sel_hi:[1,0,1]
	v_pk_fma_f32 v[140:141], v[4:5], v[194:195], v[140:141] op_sel_hi:[1,0,1]
	v_pk_fma_f32 v[142:143], v[6:7], v[194:195], v[142:143] op_sel_hi:[1,0,1]
	v_pk_fma_f32 v[128:129], v[8:9], v[194:195], v[128:129] op_sel_hi:[1,0,1]
	v_pk_fma_f32 v[132:133], v[10:11], v[194:195], v[132:133] op_sel_hi:[1,0,1]
	v_pk_fma_f32 v[134:135], v[12:13], v[194:195], v[134:135] op_sel_hi:[1,0,1]
	v_pk_fma_f32 v[136:137], v[14:15], v[194:195], v[136:137] op_sel_hi:[1,0,1]
	ds_read_b32 v194, v193 offset:548
	s_waitcnt vmcnt(48)
; __device__ void peer_gather_phase(const Params& P, int l, bool do_store) {
;     ...
;       const float avec = gelu_t(dvec * sux) * gsx;
; #pragma unroll
;       for (int j = 0; j < 8; ++j) {
;         const float a = __builtin_bit_cast(float, __builtin_amdgcn_readlane(__builtin_bit_cast(int, avec), kb + j));
;         const f32x2 aa = f32x2{a, a};
;         y[0] += aa * __builtin_amdgcn_cvt_scalef32_pk_f32_fp4(v8[j].x, 1.0f, 0); y[1] += aa * __builtin_amdgcn_cvt_scalef32_pk_f32_fp4(v8[j].x, 1.0f, 1);
;         y[2] += aa * __builtin_amdgcn_cvt_scalef32_pk_f32_fp4(v8[j].x, 1.0f, 2); y[3] += aa * __builtin_amdgcn_cvt_scalef32_pk_f32_fp4(v8[j].x, 1.0f, 3);
;         y[4] += aa * __builtin_amdgcn_cvt_scalef32_pk_f32_fp4(v8[j].y, 1.0f, 0); y[5] += aa * __builtin_amdgcn_cvt_scalef32_pk_f32_fp4(v8[j].y, 1.0f, 1);
;         y[6] += aa * __builtin_amdgcn_cvt_scalef32_pk_f32_fp4(v8[j].y, 1.0f, 2); y[7] += aa * __builtin_amdgcn_cvt_scalef32_pk_f32_fp4(v8[j].y, 1.0f, 3);
	v_cvt_scalef32_pk_f32_fp4 v[0:1], v168, 1.0
	v_cvt_scalef32_pk_f32_fp4 v[2:3], v168, 1.0 op_sel:[1,0,0]
	v_cvt_scalef32_pk_f32_fp4 v[4:5], v168, 1.0 op_sel:[0,1,0]
	v_cvt_scalef32_pk_f32_fp4 v[6:7], v168, 1.0 op_sel:[1,1,0]
	v_cvt_scalef32_pk_f32_fp4 v[8:9], v169, 1.0
	v_cvt_scalef32_pk_f32_fp4 v[10:11], v169, 1.0 op_sel:[1,0,0]
	v_cvt_scalef32_pk_f32_fp4 v[12:13], v169, 1.0 op_sel:[0,1,0]
	v_cvt_scalef32_pk_f32_fp4 v[14:15], v169, 1.0 op_sel:[1,1,0]
	v_readlane_b32 s54, v92, 24
	s_lshl_b32 s56, s54, 9
	s_add_u32 s56, s64, s56
	s_addc_u32 s57, s65, 0
	global_load_dwordx2 v[168:169], v227, s[56:57]
	s_waitcnt lgkmcnt(1)
	v_pk_fma_f32 v[130:131], v[0:1], v[76:77], v[130:131] op_sel_hi:[1,0,1]
	v_pk_fma_f32 v[138:139], v[2:3], v[76:77], v[138:139] op_sel_hi:[1,0,1]
	v_pk_fma_f32 v[140:141], v[4:5], v[76:77], v[140:141] op_sel_hi:[1,0,1]
	v_pk_fma_f32 v[142:143], v[6:7], v[76:77], v[142:143] op_sel_hi:[1,0,1]
	v_pk_fma_f32 v[128:129], v[8:9], v[76:77], v[128:129] op_sel_hi:[1,0,1]
	v_pk_fma_f32 v[132:133], v[10:11], v[76:77], v[132:133] op_sel_hi:[1,0,1]
	v_pk_fma_f32 v[134:135], v[12:13], v[76:77], v[134:135] op_sel_hi:[1,0,1]
	v_pk_fma_f32 v[136:137], v[14:15], v[76:77], v[136:137] op_sel_hi:[1,0,1]
	ds_read_b32 v76, v193 offset:552
	s_waitcnt vmcnt(48)
	v_cvt_scalef32_pk_f32_fp4 v[0:1], v170, 1.0
	v_cvt_scalef32_pk_f32_fp4 v[2:3], v170, 1.0 op_sel:[1,0,0]
	v_cvt_scalef32_pk_f32_fp4 v[4:5], v170, 1.0 op_sel:[0,1,0]
	v_cvt_scalef32_pk_f32_fp4 v[6:7], v170, 1.0 op_sel:[1,1,0]
	v_cvt_scalef32_pk_f32_fp4 v[8:9], v171, 1.0
	v_cvt_scalef32_pk_f32_fp4 v[10:11], v171, 1.0 op_sel:[1,0,0]
	v_cvt_scalef32_pk_f32_fp4 v[12:13], v171, 1.0 op_sel:[0,1,0]
	v_cvt_scalef32_pk_f32_fp4 v[14:15], v171, 1.0 op_sel:[1,1,0]
	v_readlane_b32 s54, v92, 25
	s_lshl_b32 s56, s54, 9
	s_add_u32 s56, s64, s56
	s_addc_u32 s57, s65, 0
	global_load_dwordx2 v[170:171], v227, s[56:57]
	s_waitcnt lgkmcnt(1)
	v_pk_fma_f32 v[130:131], v[0:1], v[194:195], v[130:131] op_sel_hi:[1,0,1]
	v_pk_fma_f32 v[138:139], v[2:3], v[194:195], v[138:139] op_sel_hi:[1,0,1]
	v_pk_fma_f32 v[140:141], v[4:5], v[194:195], v[140:141] op_sel_hi:[1,0,1]
	v_pk_fma_f32 v[142:143], v[6:7], v[194:195], v[142:143] op_sel_hi:[1,0,1]
	v_pk_fma_f32 v[128:129], v[8:9], v[194:195], v[128:129] op_sel_hi:[1,0,1]
	v_pk_fma_f32 v[132:133], v[10:11], v[194:195], v[132:133] op_sel_hi:[1,0,1]
	v_pk_fma_f32 v[134:135], v[12:13], v[194:195], v[134:135] op_sel_hi:[1,0,1]
	v_pk_fma_f32 v[136:137], v[14:15], v[194:195], v[136:137] op_sel_hi:[1,0,1]
	ds_read_b32 v194, v193 offset:556
	s_waitcnt vmcnt(48)
	v_cvt_scalef32_pk_f32_fp4 v[0:1], v172, 1.0
	v_cvt_scalef32_pk_f32_fp4 v[2:3], v172, 1.0 op_sel:[1,0,0]
	v_cvt_scalef32_pk_f32_fp4 v[4:5], v172, 1.0 op_sel:[0,1,0]
	v_cvt_scalef32_pk_f32_fp4 v[6:7], v172, 1.0 op_sel:[1,1,0]
	v_cvt_scalef32_pk_f32_fp4 v[8:9], v173, 1.0
	v_cvt_scalef32_pk_f32_fp4 v[10:11], v173, 1.0 op_sel:[1,0,0]
	v_cvt_scalef32_pk_f32_fp4 v[12:13], v173, 1.0 op_sel:[0,1,0]
	v_cvt_scalef32_pk_f32_fp4 v[14:15], v173, 1.0 op_sel:[1,1,0]
	v_readlane_b32 s54, v92, 26
	s_lshl_b32 s56, s54, 9
	s_add_u32 s56, s64, s56
	s_addc_u32 s57, s65, 0
	global_load_dwordx2 v[172:173], v227, s[56:57]
	s_waitcnt lgkmcnt(1)
	v_pk_fma_f32 v[130:131], v[0:1], v[76:77], v[130:131] op_sel_hi:[1,0,1]
	v_pk_fma_f32 v[138:139], v[2:3], v[76:77], v[138:139] op_sel_hi:[1,0,1]
	v_pk_fma_f32 v[140:141], v[4:5], v[76:77], v[140:141] op_sel_hi:[1,0,1]
	v_pk_fma_f32 v[142:143], v[6:7], v[76:77], v[142:143] op_sel_hi:[1,0,1]
	v_pk_fma_f32 v[128:129], v[8:9], v[76:77], v[128:129] op_sel_hi:[1,0,1]
	v_pk_fma_f32 v[132:133], v[10:11], v[76:77], v[132:133] op_sel_hi:[1,0,1]
	v_pk_fma_f32 v[134:135], v[12:13], v[76:77], v[134:135] op_sel_hi:[1,0,1]
	v_pk_fma_f32 v[136:137], v[14:15], v[76:77], v[136:137] op_sel_hi:[1,0,1]
	ds_read_b32 v76, v193 offset:560
	s_waitcnt vmcnt(48)
	v_cvt_scalef32_pk_f32_fp4 v[0:1], v174, 1.0
	v_cvt_scalef32_pk_f32_fp4 v[2:3], v174, 1.0 op_sel:[1,0,0]
	v_cvt_scalef32_pk_f32_fp4 v[4:5], v174, 1.0 op_sel:[0,1,0]
	v_cvt_scalef32_pk_f32_fp4 v[6:7], v174, 1.0 op_sel:[1,1,0]
	v_cvt_scalef32_pk_f32_fp4 v[8:9], v175, 1.0
	v_cvt_scalef32_pk_f32_fp4 v[10:11], v175, 1.0 op_sel:[1,0,0]
	v_cvt_scalef32_pk_f32_fp4 v[12:13], v175, 1.0 op_sel:[0,1,0]
	v_cvt_scalef32_pk_f32_fp4 v[14:15], v175, 1.0 op_sel:[1,1,0]
	v_readlane_b32 s54, v92, 27
	s_lshl_b32 s56, s54, 9
	s_add_u32 s56, s64, s56
	s_addc_u32 s57, s65, 0
	global_load_dwordx2 v[174:175], v227, s[56:57]
	s_waitcnt lgkmcnt(1)
	v_pk_fma_f32 v[130:131], v[0:1], v[194:195], v[130:131] op_sel_hi:[1,0,1]
	v_pk_fma_f32 v[138:139], v[2:3], v[194:195], v[138:139] op_sel_hi:[1,0,1]
	v_pk_fma_f32 v[140:141], v[4:5], v[194:195], v[140:141] op_sel_hi:[1,0,1]
	v_pk_fma_f32 v[142:143], v[6:7], v[194:195], v[142:143] op_sel_hi:[1,0,1]
	v_pk_fma_f32 v[128:129], v[8:9], v[194:195], v[128:129] op_sel_hi:[1,0,1]
	v_pk_fma_f32 v[132:133], v[10:11], v[194:195], v[132:133] op_sel_hi:[1,0,1]
	v_pk_fma_f32 v[134:135], v[12:13], v[194:195], v[134:135] op_sel_hi:[1,0,1]
	v_pk_fma_f32 v[136:137], v[14:15], v[194:195], v[136:137] op_sel_hi:[1,0,1]
	ds_read_b32 v194, v193 offset:564
	s_waitcnt vmcnt(48)
	v_cvt_scalef32_pk_f32_fp4 v[0:1], v180, 1.0
	v_cvt_scalef32_pk_f32_fp4 v[2:3], v180, 1.0 op_sel:[1,0,0]
	v_cvt_scalef32_pk_f32_fp4 v[4:5], v180, 1.0 op_sel:[0,1,0]
	v_cvt_scalef32_pk_f32_fp4 v[6:7], v180, 1.0 op_sel:[1,1,0]
	v_cvt_scalef32_pk_f32_fp4 v[8:9], v181, 1.0
	v_cvt_scalef32_pk_f32_fp4 v[10:11], v181, 1.0 op_sel:[1,0,0]
	v_cvt_scalef32_pk_f32_fp4 v[12:13], v181, 1.0 op_sel:[0,1,0]
	v_cvt_scalef32_pk_f32_fp4 v[14:15], v181, 1.0 op_sel:[1,1,0]
	v_readlane_b32 s54, v92, 28
	s_lshl_b32 s56, s54, 9
	s_add_u32 s56, s64, s56
	s_addc_u32 s57, s65, 0
	global_load_dwordx2 v[180:181], v227, s[56:57]
	s_waitcnt lgkmcnt(1)
; __device__ void peer_gather_phase(const Params& P, int l, bool do_store) {
;     ...
;       const float avec = gelu_t(dvec * sux) * gsx;
; #pragma unroll
;       for (int j = 0; j < 8; ++j) {
;         const float a = __builtin_bit_cast(float, __builtin_amdgcn_readlane(__builtin_bit_cast(int, avec), kb + j));
;         const f32x2 aa = f32x2{a, a};
;         y[0] += aa * __builtin_amdgcn_cvt_scalef32_pk_f32_fp4(v8[j].x, 1.0f, 0); y[1] += aa * __builtin_amdgcn_cvt_scalef32_pk_f32_fp4(v8[j].x, 1.0f, 1);
;         y[2] += aa * __builtin_amdgcn_cvt_scalef32_pk_f32_fp4(v8[j].x, 1.0f, 2); y[3] += aa * __builtin_amdgcn_cvt_scalef32_pk_f32_fp4(v8[j].x, 1.0f, 3);
;         y[4] += aa * __builtin_amdgcn_cvt_scalef32_pk_f32_fp4(v8[j].y, 1.0f, 0); y[5] += aa * __builtin_amdgcn_cvt_scalef32_pk_f32_fp4(v8[j].y, 1.0f, 1);
;         y[6] += aa * __builtin_amdgcn_cvt_scalef32_pk_f32_fp4(v8[j].y, 1.0f, 2); y[7] += aa * __builtin_amdgcn_cvt_scalef32_pk_f32_fp4(v8[j].y, 1.0f, 3);
	v_pk_fma_f32 v[130:131], v[0:1], v[76:77], v[130:131] op_sel_hi:[1,0,1]
	v_pk_fma_f32 v[138:139], v[2:3], v[76:77], v[138:139] op_sel_hi:[1,0,1]
	v_pk_fma_f32 v[140:141], v[4:5], v[76:77], v[140:141] op_sel_hi:[1,0,1]
	v_pk_fma_f32 v[142:143], v[6:7], v[76:77], v[142:143] op_sel_hi:[1,0,1]
	v_pk_fma_f32 v[128:129], v[8:9], v[76:77], v[128:129] op_sel_hi:[1,0,1]
	v_pk_fma_f32 v[132:133], v[10:11], v[76:77], v[132:133] op_sel_hi:[1,0,1]
	v_pk_fma_f32 v[134:135], v[12:13], v[76:77], v[134:135] op_sel_hi:[1,0,1]
	v_pk_fma_f32 v[136:137], v[14:15], v[76:77], v[136:137] op_sel_hi:[1,0,1]
	ds_read_b32 v76, v193 offset:568
	s_waitcnt vmcnt(48)
	v_cvt_scalef32_pk_f32_fp4 v[0:1], v182, 1.0
	v_cvt_scalef32_pk_f32_fp4 v[2:3], v182, 1.0 op_sel:[1,0,0]
	v_cvt_scalef32_pk_f32_fp4 v[4:5], v182, 1.0 op_sel:[0,1,0]
	v_cvt_scalef32_pk_f32_fp4 v[6:7], v182, 1.0 op_sel:[1,1,0]
	v_cvt_scalef32_pk_f32_fp4 v[8:9], v183, 1.0
	v_cvt_scalef32_pk_f32_fp4 v[10:11], v183, 1.0 op_sel:[1,0,0]
	v_cvt_scalef32_pk_f32_fp4 v[12:13], v183, 1.0 op_sel:[0,1,0]
	v_cvt_scalef32_pk_f32_fp4 v[14:15], v183, 1.0 op_sel:[1,1,0]
	v_readlane_b32 s54, v92, 29
	s_lshl_b32 s56, s54, 9
	s_add_u32 s56, s64, s56
	s_addc_u32 s57, s65, 0
	global_load_dwordx2 v[182:183], v227, s[56:57]
	s_waitcnt lgkmcnt(1)
	v_pk_fma_f32 v[130:131], v[0:1], v[194:195], v[130:131] op_sel_hi:[1,0,1]
	v_pk_fma_f32 v[138:139], v[2:3], v[194:195], v[138:139] op_sel_hi:[1,0,1]
	v_pk_fma_f32 v[140:141], v[4:5], v[194:195], v[140:141] op_sel_hi:[1,0,1]
	v_pk_fma_f32 v[142:143], v[6:7], v[194:195], v[142:143] op_sel_hi:[1,0,1]
	v_pk_fma_f32 v[128:129], v[8:9], v[194:195], v[128:129] op_sel_hi:[1,0,1]
	v_pk_fma_f32 v[132:133], v[10:11], v[194:195], v[132:133] op_sel_hi:[1,0,1]
	v_pk_fma_f32 v[134:135], v[12:13], v[194:195], v[134:135] op_sel_hi:[1,0,1]
	v_pk_fma_f32 v[136:137], v[14:15], v[194:195], v[136:137] op_sel_hi:[1,0,1]
	ds_read_b32 v194, v193 offset:572
	s_waitcnt vmcnt(48)
	v_cvt_scalef32_pk_f32_fp4 v[0:1], v184, 1.0
	v_cvt_scalef32_pk_f32_fp4 v[2:3], v184, 1.0 op_sel:[1,0,0]
	v_cvt_scalef32_pk_f32_fp4 v[4:5], v184, 1.0 op_sel:[0,1,0]
	v_cvt_scalef32_pk_f32_fp4 v[6:7], v184, 1.0 op_sel:[1,1,0]
	v_cvt_scalef32_pk_f32_fp4 v[8:9], v185, 1.0
	v_cvt_scalef32_pk_f32_fp4 v[10:11], v185, 1.0 op_sel:[1,0,0]
	v_cvt_scalef32_pk_f32_fp4 v[12:13], v185, 1.0 op_sel:[0,1,0]
	v_cvt_scalef32_pk_f32_fp4 v[14:15], v185, 1.0 op_sel:[1,1,0]
	v_readlane_b32 s54, v92, 30
	s_lshl_b32 s56, s54, 9
	s_add_u32 s56, s64, s56
	s_addc_u32 s57, s65, 0
	global_load_dwordx2 v[184:185], v227, s[56:57]
	s_waitcnt lgkmcnt(1)
	v_pk_fma_f32 v[130:131], v[0:1], v[76:77], v[130:131] op_sel_hi:[1,0,1]
	v_pk_fma_f32 v[138:139], v[2:3], v[76:77], v[138:139] op_sel_hi:[1,0,1]
	v_pk_fma_f32 v[140:141], v[4:5], v[76:77], v[140:141] op_sel_hi:[1,0,1]
	v_pk_fma_f32 v[142:143], v[6:7], v[76:77], v[142:143] op_sel_hi:[1,0,1]
	v_pk_fma_f32 v[128:129], v[8:9], v[76:77], v[128:129] op_sel_hi:[1,0,1]
	v_pk_fma_f32 v[132:133], v[10:11], v[76:77], v[132:133] op_sel_hi:[1,0,1]
	v_pk_fma_f32 v[134:135], v[12:13], v[76:77], v[134:135] op_sel_hi:[1,0,1]
	v_pk_fma_f32 v[136:137], v[14:15], v[76:77], v[136:137] op_sel_hi:[1,0,1]
	ds_read_b32 v76, v193 offset:576
	s_waitcnt vmcnt(48)
	v_cvt_scalef32_pk_f32_fp4 v[0:1], v186, 1.0
	v_cvt_scalef32_pk_f32_fp4 v[2:3], v186, 1.0 op_sel:[1,0,0]
	v_cvt_scalef32_pk_f32_fp4 v[4:5], v186, 1.0 op_sel:[0,1,0]
	v_cvt_scalef32_pk_f32_fp4 v[6:7], v186, 1.0 op_sel:[1,1,0]
	v_cvt_scalef32_pk_f32_fp4 v[8:9], v187, 1.0
	v_cvt_scalef32_pk_f32_fp4 v[10:11], v187, 1.0 op_sel:[1,0,0]
	v_cvt_scalef32_pk_f32_fp4 v[12:13], v187, 1.0 op_sel:[0,1,0]
	v_cvt_scalef32_pk_f32_fp4 v[14:15], v187, 1.0 op_sel:[1,1,0]
	v_readlane_b32 s54, v92, 31
	s_lshl_b32 s56, s54, 9
	s_add_u32 s56, s64, s56
	s_addc_u32 s57, s65, 0
	global_load_dwordx2 v[186:187], v227, s[56:57]
	s_waitcnt lgkmcnt(1)
	v_pk_fma_f32 v[130:131], v[0:1], v[194:195], v[130:131] op_sel_hi:[1,0,1]
	v_pk_fma_f32 v[138:139], v[2:3], v[194:195], v[138:139] op_sel_hi:[1,0,1]
	v_pk_fma_f32 v[140:141], v[4:5], v[194:195], v[140:141] op_sel_hi:[1,0,1]
	v_pk_fma_f32 v[142:143], v[6:7], v[194:195], v[142:143] op_sel_hi:[1,0,1]
	v_pk_fma_f32 v[128:129], v[8:9], v[194:195], v[128:129] op_sel_hi:[1,0,1]
	v_pk_fma_f32 v[132:133], v[10:11], v[194:195], v[132:133] op_sel_hi:[1,0,1]
	v_pk_fma_f32 v[134:135], v[12:13], v[194:195], v[134:135] op_sel_hi:[1,0,1]
	v_pk_fma_f32 v[136:137], v[14:15], v[194:195], v[136:137] op_sel_hi:[1,0,1]
	ds_read_b32 v194, v193 offset:580
	s_waitcnt vmcnt(15)
	v_cvt_scalef32_pk_f32_fp4 v[0:1], v144, 1.0
	v_cvt_scalef32_pk_f32_fp4 v[2:3], v144, 1.0 op_sel:[1,0,0]
	v_cvt_scalef32_pk_f32_fp4 v[4:5], v144, 1.0 op_sel:[0,1,0]
	v_cvt_scalef32_pk_f32_fp4 v[6:7], v144, 1.0 op_sel:[1,1,0]
	v_cvt_scalef32_pk_f32_fp4 v[8:9], v145, 1.0
	v_cvt_scalef32_pk_f32_fp4 v[10:11], v145, 1.0 op_sel:[1,0,0]
	v_cvt_scalef32_pk_f32_fp4 v[12:13], v145, 1.0 op_sel:[0,1,0]
	v_cvt_scalef32_pk_f32_fp4 v[14:15], v145, 1.0 op_sel:[1,1,0]
	v_readlane_b32 s54, v92, 32
	s_lshl_b32 s56, s54, 9
	s_add_u32 s56, s64, s56
	s_addc_u32 s57, s65, 0
	global_load_dwordx2 v[144:145], v227, s[56:57]
	s_waitcnt lgkmcnt(1)
	v_pk_fma_f32 v[130:131], v[0:1], v[76:77], v[130:131] op_sel_hi:[1,0,1]
	v_pk_fma_f32 v[138:139], v[2:3], v[76:77], v[138:139] op_sel_hi:[1,0,1]
	v_pk_fma_f32 v[140:141], v[4:5], v[76:77], v[140:141] op_sel_hi:[1,0,1]
	v_pk_fma_f32 v[142:143], v[6:7], v[76:77], v[142:143] op_sel_hi:[1,0,1]
	v_pk_fma_f32 v[128:129], v[8:9], v[76:77], v[128:129] op_sel_hi:[1,0,1]
	v_pk_fma_f32 v[132:133], v[10:11], v[76:77], v[132:133] op_sel_hi:[1,0,1]
	v_pk_fma_f32 v[134:135], v[12:13], v[76:77], v[134:135] op_sel_hi:[1,0,1]
	v_pk_fma_f32 v[136:137], v[14:15], v[76:77], v[136:137] op_sel_hi:[1,0,1]
	ds_read_b32 v76, v193 offset:584
	s_waitcnt vmcnt(15)
; __device__ void peer_gather_phase(const Params& P, int l, bool do_store) {
;     ...
;       const float avec = gelu_t(dvec * sux) * gsx;
; #pragma unroll
;       for (int j = 0; j < 8; ++j) {
;         const float a = __builtin_bit_cast(float, __builtin_amdgcn_readlane(__builtin_bit_cast(int, avec), kb + j));
;         const f32x2 aa = f32x2{a, a};
;         y[0] += aa * __builtin_amdgcn_cvt_scalef32_pk_f32_fp4(v8[j].x, 1.0f, 0); y[1] += aa * __builtin_amdgcn_cvt_scalef32_pk_f32_fp4(v8[j].x, 1.0f, 1);
;         y[2] += aa * __builtin_amdgcn_cvt_scalef32_pk_f32_fp4(v8[j].x, 1.0f, 2); y[3] += aa * __builtin_amdgcn_cvt_scalef32_pk_f32_fp4(v8[j].x, 1.0f, 3);
;         y[4] += aa * __builtin_amdgcn_cvt_scalef32_pk_f32_fp4(v8[j].y, 1.0f, 0); y[5] += aa * __builtin_amdgcn_cvt_scalef32_pk_f32_fp4(v8[j].y, 1.0f, 1);
;         y[6] += aa * __builtin_amdgcn_cvt_scalef32_pk_f32_fp4(v8[j].y, 1.0f, 2); y[7] += aa * __builtin_amdgcn_cvt_scalef32_pk_f32_fp4(v8[j].y, 1.0f, 3);
	v_cvt_scalef32_pk_f32_fp4 v[0:1], v146, 1.0
	v_cvt_scalef32_pk_f32_fp4 v[2:3], v146, 1.0 op_sel:[1,0,0]
	v_cvt_scalef32_pk_f32_fp4 v[4:5], v146, 1.0 op_sel:[0,1,0]
	v_cvt_scalef32_pk_f32_fp4 v[6:7], v146, 1.0 op_sel:[1,1,0]
	v_cvt_scalef32_pk_f32_fp4 v[8:9], v147, 1.0
	v_cvt_scalef32_pk_f32_fp4 v[10:11], v147, 1.0 op_sel:[1,0,0]
	v_cvt_scalef32_pk_f32_fp4 v[12:13], v147, 1.0 op_sel:[0,1,0]
	v_cvt_scalef32_pk_f32_fp4 v[14:15], v147, 1.0 op_sel:[1,1,0]
	v_readlane_b32 s54, v92, 33
	s_lshl_b32 s56, s54, 9
	s_add_u32 s56, s64, s56
	s_addc_u32 s57, s65, 0
	global_load_dwordx2 v[146:147], v227, s[56:57]
	s_waitcnt lgkmcnt(1)
	v_pk_fma_f32 v[130:131], v[0:1], v[194:195], v[130:131] op_sel_hi:[1,0,1]
	v_pk_fma_f32 v[138:139], v[2:3], v[194:195], v[138:139] op_sel_hi:[1,0,1]
	v_pk_fma_f32 v[140:141], v[4:5], v[194:195], v[140:141] op_sel_hi:[1,0,1]
	v_pk_fma_f32 v[142:143], v[6:7], v[194:195], v[142:143] op_sel_hi:[1,0,1]
	v_pk_fma_f32 v[128:129], v[8:9], v[194:195], v[128:129] op_sel_hi:[1,0,1]
	v_pk_fma_f32 v[132:133], v[10:11], v[194:195], v[132:133] op_sel_hi:[1,0,1]
	v_pk_fma_f32 v[134:135], v[12:13], v[194:195], v[134:135] op_sel_hi:[1,0,1]
	v_pk_fma_f32 v[136:137], v[14:15], v[194:195], v[136:137] op_sel_hi:[1,0,1]
	ds_read_b32 v194, v193 offset:588
	s_waitcnt vmcnt(15)
	v_cvt_scalef32_pk_f32_fp4 v[0:1], v148, 1.0
	v_cvt_scalef32_pk_f32_fp4 v[2:3], v148, 1.0 op_sel:[1,0,0]
	v_cvt_scalef32_pk_f32_fp4 v[4:5], v148, 1.0 op_sel:[0,1,0]
	v_cvt_scalef32_pk_f32_fp4 v[6:7], v148, 1.0 op_sel:[1,1,0]
	v_cvt_scalef32_pk_f32_fp4 v[8:9], v149, 1.0
	v_cvt_scalef32_pk_f32_fp4 v[10:11], v149, 1.0 op_sel:[1,0,0]
	v_cvt_scalef32_pk_f32_fp4 v[12:13], v149, 1.0 op_sel:[0,1,0]
	v_cvt_scalef32_pk_f32_fp4 v[14:15], v149, 1.0 op_sel:[1,1,0]
	v_readlane_b32 s54, v92, 34
	s_lshl_b32 s56, s54, 9
	s_add_u32 s56, s64, s56
	s_addc_u32 s57, s65, 0
	global_load_dwordx2 v[148:149], v227, s[56:57]
	s_waitcnt lgkmcnt(1)
	v_pk_fma_f32 v[130:131], v[0:1], v[76:77], v[130:131] op_sel_hi:[1,0,1]
	v_pk_fma_f32 v[138:139], v[2:3], v[76:77], v[138:139] op_sel_hi:[1,0,1]
	v_pk_fma_f32 v[140:141], v[4:5], v[76:77], v[140:141] op_sel_hi:[1,0,1]
	v_pk_fma_f32 v[142:143], v[6:7], v[76:77], v[142:143] op_sel_hi:[1,0,1]
	v_pk_fma_f32 v[128:129], v[8:9], v[76:77], v[128:129] op_sel_hi:[1,0,1]
	v_pk_fma_f32 v[132:133], v[10:11], v[76:77], v[132:133] op_sel_hi:[1,0,1]
	v_pk_fma_f32 v[134:135], v[12:13], v[76:77], v[134:135] op_sel_hi:[1,0,1]
	v_pk_fma_f32 v[136:137], v[14:15], v[76:77], v[136:137] op_sel_hi:[1,0,1]
	ds_read_b32 v76, v193 offset:592
	s_waitcnt vmcnt(15)
	v_cvt_scalef32_pk_f32_fp4 v[0:1], v150, 1.0
	v_cvt_scalef32_pk_f32_fp4 v[2:3], v150, 1.0 op_sel:[1,0,0]
	v_cvt_scalef32_pk_f32_fp4 v[4:5], v150, 1.0 op_sel:[0,1,0]
	v_cvt_scalef32_pk_f32_fp4 v[6:7], v150, 1.0 op_sel:[1,1,0]
	v_cvt_scalef32_pk_f32_fp4 v[8:9], v151, 1.0
	v_cvt_scalef32_pk_f32_fp4 v[10:11], v151, 1.0 op_sel:[1,0,0]
	v_cvt_scalef32_pk_f32_fp4 v[12:13], v151, 1.0 op_sel:[0,1,0]
	v_cvt_scalef32_pk_f32_fp4 v[14:15], v151, 1.0 op_sel:[1,1,0]
	v_readlane_b32 s54, v92, 35
	s_lshl_b32 s56, s54, 9
	s_add_u32 s56, s64, s56
	s_addc_u32 s57, s65, 0
	global_load_dwordx2 v[150:151], v227, s[56:57]
	s_waitcnt lgkmcnt(1)
	v_pk_fma_f32 v[130:131], v[0:1], v[194:195], v[130:131] op_sel_hi:[1,0,1]
	v_pk_fma_f32 v[138:139], v[2:3], v[194:195], v[138:139] op_sel_hi:[1,0,1]
	v_pk_fma_f32 v[140:141], v[4:5], v[194:195], v[140:141] op_sel_hi:[1,0,1]
	v_pk_fma_f32 v[142:143], v[6:7], v[194:195], v[142:143] op_sel_hi:[1,0,1]
	v_pk_fma_f32 v[128:129], v[8:9], v[194:195], v[128:129] op_sel_hi:[1,0,1]
	v_pk_fma_f32 v[132:133], v[10:11], v[194:195], v[132:133] op_sel_hi:[1,0,1]
	v_pk_fma_f32 v[134:135], v[12:13], v[194:195], v[134:135] op_sel_hi:[1,0,1]
	v_pk_fma_f32 v[136:137], v[14:15], v[194:195], v[136:137] op_sel_hi:[1,0,1]
	ds_read_b32 v194, v193 offset:596
	s_waitcnt vmcnt(15)
	v_cvt_scalef32_pk_f32_fp4 v[0:1], v152, 1.0
	v_cvt_scalef32_pk_f32_fp4 v[2:3], v152, 1.0 op_sel:[1,0,0]
	v_cvt_scalef32_pk_f32_fp4 v[4:5], v152, 1.0 op_sel:[0,1,0]
	v_cvt_scalef32_pk_f32_fp4 v[6:7], v152, 1.0 op_sel:[1,1,0]
	v_cvt_scalef32_pk_f32_fp4 v[8:9], v153, 1.0
	v_cvt_scalef32_pk_f32_fp4 v[10:11], v153, 1.0 op_sel:[1,0,0]
	v_cvt_scalef32_pk_f32_fp4 v[12:13], v153, 1.0 op_sel:[0,1,0]
	v_cvt_scalef32_pk_f32_fp4 v[14:15], v153, 1.0 op_sel:[1,1,0]
	v_readlane_b32 s54, v92, 36
	s_lshl_b32 s56, s54, 9
	s_add_u32 s56, s64, s56
	s_addc_u32 s57, s65, 0
	global_load_dwordx2 v[152:153], v227, s[56:57]
	s_waitcnt lgkmcnt(1)
	v_pk_fma_f32 v[130:131], v[0:1], v[76:77], v[130:131] op_sel_hi:[1,0,1]
	v_pk_fma_f32 v[138:139], v[2:3], v[76:77], v[138:139] op_sel_hi:[1,0,1]
	v_pk_fma_f32 v[140:141], v[4:5], v[76:77], v[140:141] op_sel_hi:[1,0,1]
	v_pk_fma_f32 v[142:143], v[6:7], v[76:77], v[142:143] op_sel_hi:[1,0,1]
	v_pk_fma_f32 v[128:129], v[8:9], v[76:77], v[128:129] op_sel_hi:[1,0,1]
	v_pk_fma_f32 v[132:133], v[10:11], v[76:77], v[132:133] op_sel_hi:[1,0,1]
	v_pk_fma_f32 v[134:135], v[12:13], v[76:77], v[134:135] op_sel_hi:[1,0,1]
	v_pk_fma_f32 v[136:137], v[14:15], v[76:77], v[136:137] op_sel_hi:[1,0,1]
	ds_read_b32 v76, v193 offset:600
	s_waitcnt vmcnt(15)
	v_cvt_scalef32_pk_f32_fp4 v[0:1], v154, 1.0
	v_cvt_scalef32_pk_f32_fp4 v[2:3], v154, 1.0 op_sel:[1,0,0]
	v_cvt_scalef32_pk_f32_fp4 v[4:5], v154, 1.0 op_sel:[0,1,0]
	v_cvt_scalef32_pk_f32_fp4 v[6:7], v154, 1.0 op_sel:[1,1,0]
	v_cvt_scalef32_pk_f32_fp4 v[8:9], v155, 1.0
	v_cvt_scalef32_pk_f32_fp4 v[10:11], v155, 1.0 op_sel:[1,0,0]
	v_cvt_scalef32_pk_f32_fp4 v[12:13], v155, 1.0 op_sel:[0,1,0]
	v_cvt_scalef32_pk_f32_fp4 v[14:15], v155, 1.0 op_sel:[1,1,0]
	v_readlane_b32 s54, v92, 37
	s_lshl_b32 s56, s54, 9
	s_add_u32 s56, s64, s56
	s_addc_u32 s57, s65, 0
	global_load_dwordx2 v[154:155], v227, s[56:57]
	s_waitcnt lgkmcnt(1)
; __device__ void peer_gather_phase(const Params& P, int l, bool do_store) {
;     ...
;       const float avec = gelu_t(dvec * sux) * gsx;
; #pragma unroll
;       for (int j = 0; j < 8; ++j) {
;         const float a = __builtin_bit_cast(float, __builtin_amdgcn_readlane(__builtin_bit_cast(int, avec), kb + j));
;         const f32x2 aa = f32x2{a, a};
;         y[0] += aa * __builtin_amdgcn_cvt_scalef32_pk_f32_fp4(v8[j].x, 1.0f, 0); y[1] += aa * __builtin_amdgcn_cvt_scalef32_pk_f32_fp4(v8[j].x, 1.0f, 1);
;         y[2] += aa * __builtin_amdgcn_cvt_scalef32_pk_f32_fp4(v8[j].x, 1.0f, 2); y[3] += aa * __builtin_amdgcn_cvt_scalef32_pk_f32_fp4(v8[j].x, 1.0f, 3);
;         y[4] += aa * __builtin_amdgcn_cvt_scalef32_pk_f32_fp4(v8[j].y, 1.0f, 0); y[5] += aa * __builtin_amdgcn_cvt_scalef32_pk_f32_fp4(v8[j].y, 1.0f, 1);
;         y[6] += aa * __builtin_amdgcn_cvt_scalef32_pk_f32_fp4(v8[j].y, 1.0f, 2); y[7] += aa * __builtin_amdgcn_cvt_scalef32_pk_f32_fp4(v8[j].y, 1.0f, 3);
	v_pk_fma_f32 v[130:131], v[0:1], v[194:195], v[130:131] op_sel_hi:[1,0,1]
	v_pk_fma_f32 v[138:139], v[2:3], v[194:195], v[138:139] op_sel_hi:[1,0,1]
	v_pk_fma_f32 v[140:141], v[4:5], v[194:195], v[140:141] op_sel_hi:[1,0,1]
	v_pk_fma_f32 v[142:143], v[6:7], v[194:195], v[142:143] op_sel_hi:[1,0,1]
	v_pk_fma_f32 v[128:129], v[8:9], v[194:195], v[128:129] op_sel_hi:[1,0,1]
	v_pk_fma_f32 v[132:133], v[10:11], v[194:195], v[132:133] op_sel_hi:[1,0,1]
	v_pk_fma_f32 v[134:135], v[12:13], v[194:195], v[134:135] op_sel_hi:[1,0,1]
	v_pk_fma_f32 v[136:137], v[14:15], v[194:195], v[136:137] op_sel_hi:[1,0,1]
	ds_read_b32 v194, v193 offset:604
	s_waitcnt vmcnt(15)
	v_cvt_scalef32_pk_f32_fp4 v[0:1], v156, 1.0
	v_cvt_scalef32_pk_f32_fp4 v[2:3], v156, 1.0 op_sel:[1,0,0]
	v_cvt_scalef32_pk_f32_fp4 v[4:5], v156, 1.0 op_sel:[0,1,0]
	v_cvt_scalef32_pk_f32_fp4 v[6:7], v156, 1.0 op_sel:[1,1,0]
	v_cvt_scalef32_pk_f32_fp4 v[8:9], v157, 1.0
	v_cvt_scalef32_pk_f32_fp4 v[10:11], v157, 1.0 op_sel:[1,0,0]
	v_cvt_scalef32_pk_f32_fp4 v[12:13], v157, 1.0 op_sel:[0,1,0]
	v_cvt_scalef32_pk_f32_fp4 v[14:15], v157, 1.0 op_sel:[1,1,0]
	v_readlane_b32 s54, v92, 38
	s_lshl_b32 s56, s54, 9
	s_add_u32 s56, s64, s56
	s_addc_u32 s57, s65, 0
	global_load_dwordx2 v[156:157], v227, s[56:57]
	s_waitcnt lgkmcnt(1)
	v_pk_fma_f32 v[130:131], v[0:1], v[76:77], v[130:131] op_sel_hi:[1,0,1]
	v_pk_fma_f32 v[138:139], v[2:3], v[76:77], v[138:139] op_sel_hi:[1,0,1]
	v_pk_fma_f32 v[140:141], v[4:5], v[76:77], v[140:141] op_sel_hi:[1,0,1]
	v_pk_fma_f32 v[142:143], v[6:7], v[76:77], v[142:143] op_sel_hi:[1,0,1]
	v_pk_fma_f32 v[128:129], v[8:9], v[76:77], v[128:129] op_sel_hi:[1,0,1]
	v_pk_fma_f32 v[132:133], v[10:11], v[76:77], v[132:133] op_sel_hi:[1,0,1]
	v_pk_fma_f32 v[134:135], v[12:13], v[76:77], v[134:135] op_sel_hi:[1,0,1]
	v_pk_fma_f32 v[136:137], v[14:15], v[76:77], v[136:137] op_sel_hi:[1,0,1]
	ds_read_b32 v76, v193 offset:608
	s_waitcnt vmcnt(15)
	v_cvt_scalef32_pk_f32_fp4 v[0:1], v158, 1.0
	v_cvt_scalef32_pk_f32_fp4 v[2:3], v158, 1.0 op_sel:[1,0,0]
	v_cvt_scalef32_pk_f32_fp4 v[4:5], v158, 1.0 op_sel:[0,1,0]
	v_cvt_scalef32_pk_f32_fp4 v[6:7], v158, 1.0 op_sel:[1,1,0]
	v_cvt_scalef32_pk_f32_fp4 v[8:9], v159, 1.0
	v_cvt_scalef32_pk_f32_fp4 v[10:11], v159, 1.0 op_sel:[1,0,0]
	v_cvt_scalef32_pk_f32_fp4 v[12:13], v159, 1.0 op_sel:[0,1,0]
	v_cvt_scalef32_pk_f32_fp4 v[14:15], v159, 1.0 op_sel:[1,1,0]
	v_readlane_b32 s54, v92, 39
	s_lshl_b32 s56, s54, 9
	s_add_u32 s56, s64, s56
	s_addc_u32 s57, s65, 0
	global_load_dwordx2 v[158:159], v227, s[56:57]
	s_waitcnt lgkmcnt(1)
	v_pk_fma_f32 v[130:131], v[0:1], v[194:195], v[130:131] op_sel_hi:[1,0,1]
	v_pk_fma_f32 v[138:139], v[2:3], v[194:195], v[138:139] op_sel_hi:[1,0,1]
	v_pk_fma_f32 v[140:141], v[4:5], v[194:195], v[140:141] op_sel_hi:[1,0,1]
	v_pk_fma_f32 v[142:143], v[6:7], v[194:195], v[142:143] op_sel_hi:[1,0,1]
	v_pk_fma_f32 v[128:129], v[8:9], v[194:195], v[128:129] op_sel_hi:[1,0,1]
	v_pk_fma_f32 v[132:133], v[10:11], v[194:195], v[132:133] op_sel_hi:[1,0,1]
	v_pk_fma_f32 v[134:135], v[12:13], v[194:195], v[134:135] op_sel_hi:[1,0,1]
	v_pk_fma_f32 v[136:137], v[14:15], v[194:195], v[136:137] op_sel_hi:[1,0,1]
	ds_read_b32 v194, v193 offset:612
	s_waitcnt vmcnt(15)
	v_cvt_scalef32_pk_f32_fp4 v[0:1], v168, 1.0
	v_cvt_scalef32_pk_f32_fp4 v[2:3], v168, 1.0 op_sel:[1,0,0]
	v_cvt_scalef32_pk_f32_fp4 v[4:5], v168, 1.0 op_sel:[0,1,0]
	v_cvt_scalef32_pk_f32_fp4 v[6:7], v168, 1.0 op_sel:[1,1,0]
	v_cvt_scalef32_pk_f32_fp4 v[8:9], v169, 1.0
	v_cvt_scalef32_pk_f32_fp4 v[10:11], v169, 1.0 op_sel:[1,0,0]
	v_cvt_scalef32_pk_f32_fp4 v[12:13], v169, 1.0 op_sel:[0,1,0]
	v_cvt_scalef32_pk_f32_fp4 v[14:15], v169, 1.0 op_sel:[1,1,0]
	v_readlane_b32 s54, v92, 40
	s_lshl_b32 s56, s54, 9
	s_add_u32 s56, s64, s56
	s_addc_u32 s57, s65, 0
	global_load_dwordx2 v[168:169], v227, s[56:57]
	s_waitcnt lgkmcnt(1)
	v_pk_fma_f32 v[130:131], v[0:1], v[76:77], v[130:131] op_sel_hi:[1,0,1]
	v_pk_fma_f32 v[138:139], v[2:3], v[76:77], v[138:139] op_sel_hi:[1,0,1]
	v_pk_fma_f32 v[140:141], v[4:5], v[76:77], v[140:141] op_sel_hi:[1,0,1]
	v_pk_fma_f32 v[142:143], v[6:7], v[76:77], v[142:143] op_sel_hi:[1,0,1]
	v_pk_fma_f32 v[128:129], v[8:9], v[76:77], v[128:129] op_sel_hi:[1,0,1]
	v_pk_fma_f32 v[132:133], v[10:11], v[76:77], v[132:133] op_sel_hi:[1,0,1]
	v_pk_fma_f32 v[134:135], v[12:13], v[76:77], v[134:135] op_sel_hi:[1,0,1]
	v_pk_fma_f32 v[136:137], v[14:15], v[76:77], v[136:137] op_sel_hi:[1,0,1]
	ds_read_b32 v76, v193 offset:616
	s_waitcnt vmcnt(15)
	v_cvt_scalef32_pk_f32_fp4 v[0:1], v170, 1.0
	v_cvt_scalef32_pk_f32_fp4 v[2:3], v170, 1.0 op_sel:[1,0,0]
	v_cvt_scalef32_pk_f32_fp4 v[4:5], v170, 1.0 op_sel:[0,1,0]
	v_cvt_scalef32_pk_f32_fp4 v[6:7], v170, 1.0 op_sel:[1,1,0]
	v_cvt_scalef32_pk_f32_fp4 v[8:9], v171, 1.0
	v_cvt_scalef32_pk_f32_fp4 v[10:11], v171, 1.0 op_sel:[1,0,0]
	v_cvt_scalef32_pk_f32_fp4 v[12:13], v171, 1.0 op_sel:[0,1,0]
	v_cvt_scalef32_pk_f32_fp4 v[14:15], v171, 1.0 op_sel:[1,1,0]
	v_readlane_b32 s54, v92, 41
	s_lshl_b32 s56, s54, 9
	s_add_u32 s56, s64, s56
	s_addc_u32 s57, s65, 0
	global_load_dwordx2 v[170:171], v227, s[56:57]
	s_waitcnt lgkmcnt(1)
	v_pk_fma_f32 v[130:131], v[0:1], v[194:195], v[130:131] op_sel_hi:[1,0,1]
	v_pk_fma_f32 v[138:139], v[2:3], v[194:195], v[138:139] op_sel_hi:[1,0,1]
	v_pk_fma_f32 v[140:141], v[4:5], v[194:195], v[140:141] op_sel_hi:[1,0,1]
	v_pk_fma_f32 v[142:143], v[6:7], v[194:195], v[142:143] op_sel_hi:[1,0,1]
	v_pk_fma_f32 v[128:129], v[8:9], v[194:195], v[128:129] op_sel_hi:[1,0,1]
	v_pk_fma_f32 v[132:133], v[10:11], v[194:195], v[132:133] op_sel_hi:[1,0,1]
	v_pk_fma_f32 v[134:135], v[12:13], v[194:195], v[134:135] op_sel_hi:[1,0,1]
	v_pk_fma_f32 v[136:137], v[14:15], v[194:195], v[136:137] op_sel_hi:[1,0,1]
	ds_read_b32 v194, v193 offset:620
	s_waitcnt vmcnt(15)
; __device__ void peer_gather_phase(const Params& P, int l, bool do_store) {
;     ...
;       const float avec = gelu_t(dvec * sux) * gsx;
; #pragma unroll
;       for (int j = 0; j < 8; ++j) {
;         const float a = __builtin_bit_cast(float, __builtin_amdgcn_readlane(__builtin_bit_cast(int, avec), kb + j));
;         const f32x2 aa = f32x2{a, a};
;         y[0] += aa * __builtin_amdgcn_cvt_scalef32_pk_f32_fp4(v8[j].x, 1.0f, 0); y[1] += aa * __builtin_amdgcn_cvt_scalef32_pk_f32_fp4(v8[j].x, 1.0f, 1);
;         y[2] += aa * __builtin_amdgcn_cvt_scalef32_pk_f32_fp4(v8[j].x, 1.0f, 2); y[3] += aa * __builtin_amdgcn_cvt_scalef32_pk_f32_fp4(v8[j].x, 1.0f, 3);
;         y[4] += aa * __builtin_amdgcn_cvt_scalef32_pk_f32_fp4(v8[j].y, 1.0f, 0); y[5] += aa * __builtin_amdgcn_cvt_scalef32_pk_f32_fp4(v8[j].y, 1.0f, 1);
;         y[6] += aa * __builtin_amdgcn_cvt_scalef32_pk_f32_fp4(v8[j].y, 1.0f, 2); y[7] += aa * __builtin_amdgcn_cvt_scalef32_pk_f32_fp4(v8[j].y, 1.0f, 3);
	v_cvt_scalef32_pk_f32_fp4 v[0:1], v172, 1.0
	v_cvt_scalef32_pk_f32_fp4 v[2:3], v172, 1.0 op_sel:[1,0,0]
	v_cvt_scalef32_pk_f32_fp4 v[4:5], v172, 1.0 op_sel:[0,1,0]
	v_cvt_scalef32_pk_f32_fp4 v[6:7], v172, 1.0 op_sel:[1,1,0]
	v_cvt_scalef32_pk_f32_fp4 v[8:9], v173, 1.0
	v_cvt_scalef32_pk_f32_fp4 v[10:11], v173, 1.0 op_sel:[1,0,0]
	v_cvt_scalef32_pk_f32_fp4 v[12:13], v173, 1.0 op_sel:[0,1,0]
	v_cvt_scalef32_pk_f32_fp4 v[14:15], v173, 1.0 op_sel:[1,1,0]
	v_readlane_b32 s54, v92, 42
	s_lshl_b32 s56, s54, 9
	s_add_u32 s56, s64, s56
	s_addc_u32 s57, s65, 0
	global_load_dwordx2 v[172:173], v227, s[56:57]
	s_waitcnt lgkmcnt(1)
	v_pk_fma_f32 v[130:131], v[0:1], v[76:77], v[130:131] op_sel_hi:[1,0,1]
	v_pk_fma_f32 v[138:139], v[2:3], v[76:77], v[138:139] op_sel_hi:[1,0,1]
	v_pk_fma_f32 v[140:141], v[4:5], v[76:77], v[140:141] op_sel_hi:[1,0,1]
	v_pk_fma_f32 v[142:143], v[6:7], v[76:77], v[142:143] op_sel_hi:[1,0,1]
	v_pk_fma_f32 v[128:129], v[8:9], v[76:77], v[128:129] op_sel_hi:[1,0,1]
	v_pk_fma_f32 v[132:133], v[10:11], v[76:77], v[132:133] op_sel_hi:[1,0,1]
	v_pk_fma_f32 v[134:135], v[12:13], v[76:77], v[134:135] op_sel_hi:[1,0,1]
	v_pk_fma_f32 v[136:137], v[14:15], v[76:77], v[136:137] op_sel_hi:[1,0,1]
	ds_read_b32 v76, v193 offset:624
	s_waitcnt vmcnt(15)
	v_cvt_scalef32_pk_f32_fp4 v[0:1], v174, 1.0
	v_cvt_scalef32_pk_f32_fp4 v[2:3], v174, 1.0 op_sel:[1,0,0]
	v_cvt_scalef32_pk_f32_fp4 v[4:5], v174, 1.0 op_sel:[0,1,0]
	v_cvt_scalef32_pk_f32_fp4 v[6:7], v174, 1.0 op_sel:[1,1,0]
	v_cvt_scalef32_pk_f32_fp4 v[8:9], v175, 1.0
	v_cvt_scalef32_pk_f32_fp4 v[10:11], v175, 1.0 op_sel:[1,0,0]
	v_cvt_scalef32_pk_f32_fp4 v[12:13], v175, 1.0 op_sel:[0,1,0]
	v_cvt_scalef32_pk_f32_fp4 v[14:15], v175, 1.0 op_sel:[1,1,0]
	v_readlane_b32 s54, v92, 43
	s_lshl_b32 s56, s54, 9
	s_add_u32 s56, s64, s56
	s_addc_u32 s57, s65, 0
	global_load_dwordx2 v[174:175], v227, s[56:57]
	s_waitcnt lgkmcnt(1)
	v_pk_fma_f32 v[130:131], v[0:1], v[194:195], v[130:131] op_sel_hi:[1,0,1]
	v_pk_fma_f32 v[138:139], v[2:3], v[194:195], v[138:139] op_sel_hi:[1,0,1]
	v_pk_fma_f32 v[140:141], v[4:5], v[194:195], v[140:141] op_sel_hi:[1,0,1]
	v_pk_fma_f32 v[142:143], v[6:7], v[194:195], v[142:143] op_sel_hi:[1,0,1]
	v_pk_fma_f32 v[128:129], v[8:9], v[194:195], v[128:129] op_sel_hi:[1,0,1]
	v_pk_fma_f32 v[132:133], v[10:11], v[194:195], v[132:133] op_sel_hi:[1,0,1]
	v_pk_fma_f32 v[134:135], v[12:13], v[194:195], v[134:135] op_sel_hi:[1,0,1]
	v_pk_fma_f32 v[136:137], v[14:15], v[194:195], v[136:137] op_sel_hi:[1,0,1]
	ds_read_b32 v194, v193 offset:628
	s_waitcnt vmcnt(15)
	v_cvt_scalef32_pk_f32_fp4 v[0:1], v180, 1.0
	v_cvt_scalef32_pk_f32_fp4 v[2:3], v180, 1.0 op_sel:[1,0,0]
	v_cvt_scalef32_pk_f32_fp4 v[4:5], v180, 1.0 op_sel:[0,1,0]
	v_cvt_scalef32_pk_f32_fp4 v[6:7], v180, 1.0 op_sel:[1,1,0]
	v_cvt_scalef32_pk_f32_fp4 v[8:9], v181, 1.0
	v_cvt_scalef32_pk_f32_fp4 v[10:11], v181, 1.0 op_sel:[1,0,0]
	v_cvt_scalef32_pk_f32_fp4 v[12:13], v181, 1.0 op_sel:[0,1,0]
	v_cvt_scalef32_pk_f32_fp4 v[14:15], v181, 1.0 op_sel:[1,1,0]
	v_readlane_b32 s54, v92, 44
	s_lshl_b32 s56, s54, 9
	s_add_u32 s56, s64, s56
	s_addc_u32 s57, s65, 0
	global_load_dwordx2 v[180:181], v227, s[56:57]
	s_waitcnt lgkmcnt(1)
	v_pk_fma_f32 v[130:131], v[0:1], v[76:77], v[130:131] op_sel_hi:[1,0,1]
	v_pk_fma_f32 v[138:139], v[2:3], v[76:77], v[138:139] op_sel_hi:[1,0,1]
	v_pk_fma_f32 v[140:141], v[4:5], v[76:77], v[140:141] op_sel_hi:[1,0,1]
	v_pk_fma_f32 v[142:143], v[6:7], v[76:77], v[142:143] op_sel_hi:[1,0,1]
	v_pk_fma_f32 v[128:129], v[8:9], v[76:77], v[128:129] op_sel_hi:[1,0,1]
	v_pk_fma_f32 v[132:133], v[10:11], v[76:77], v[132:133] op_sel_hi:[1,0,1]
	v_pk_fma_f32 v[134:135], v[12:13], v[76:77], v[134:135] op_sel_hi:[1,0,1]
	v_pk_fma_f32 v[136:137], v[14:15], v[76:77], v[136:137] op_sel_hi:[1,0,1]
	ds_read_b32 v76, v193 offset:632
	s_waitcnt vmcnt(15)
	v_cvt_scalef32_pk_f32_fp4 v[0:1], v182, 1.0
	v_cvt_scalef32_pk_f32_fp4 v[2:3], v182, 1.0 op_sel:[1,0,0]
	v_cvt_scalef32_pk_f32_fp4 v[4:5], v182, 1.0 op_sel:[0,1,0]
	v_cvt_scalef32_pk_f32_fp4 v[6:7], v182, 1.0 op_sel:[1,1,0]
	v_cvt_scalef32_pk_f32_fp4 v[8:9], v183, 1.0
	v_cvt_scalef32_pk_f32_fp4 v[10:11], v183, 1.0 op_sel:[1,0,0]
	v_cvt_scalef32_pk_f32_fp4 v[12:13], v183, 1.0 op_sel:[0,1,0]
	v_cvt_scalef32_pk_f32_fp4 v[14:15], v183, 1.0 op_sel:[1,1,0]
	v_readlane_b32 s54, v92, 45
	s_lshl_b32 s56, s54, 9
	s_add_u32 s56, s64, s56
	s_addc_u32 s57, s65, 0
	global_load_dwordx2 v[182:183], v227, s[56:57]
	s_waitcnt lgkmcnt(1)
	v_pk_fma_f32 v[130:131], v[0:1], v[194:195], v[130:131] op_sel_hi:[1,0,1]
	v_pk_fma_f32 v[138:139], v[2:3], v[194:195], v[138:139] op_sel_hi:[1,0,1]
	v_pk_fma_f32 v[140:141], v[4:5], v[194:195], v[140:141] op_sel_hi:[1,0,1]
	v_pk_fma_f32 v[142:143], v[6:7], v[194:195], v[142:143] op_sel_hi:[1,0,1]
	v_pk_fma_f32 v[128:129], v[8:9], v[194:195], v[128:129] op_sel_hi:[1,0,1]
	v_pk_fma_f32 v[132:133], v[10:11], v[194:195], v[132:133] op_sel_hi:[1,0,1]
	v_pk_fma_f32 v[134:135], v[12:13], v[194:195], v[134:135] op_sel_hi:[1,0,1]
	v_pk_fma_f32 v[136:137], v[14:15], v[194:195], v[136:137] op_sel_hi:[1,0,1]
	ds_read_b32 v194, v193 offset:636
	s_waitcnt vmcnt(15)
	v_cvt_scalef32_pk_f32_fp4 v[0:1], v184, 1.0
	v_cvt_scalef32_pk_f32_fp4 v[2:3], v184, 1.0 op_sel:[1,0,0]
	v_cvt_scalef32_pk_f32_fp4 v[4:5], v184, 1.0 op_sel:[0,1,0]
	v_cvt_scalef32_pk_f32_fp4 v[6:7], v184, 1.0 op_sel:[1,1,0]
	v_cvt_scalef32_pk_f32_fp4 v[8:9], v185, 1.0
	v_cvt_scalef32_pk_f32_fp4 v[10:11], v185, 1.0 op_sel:[1,0,0]
	v_cvt_scalef32_pk_f32_fp4 v[12:13], v185, 1.0 op_sel:[0,1,0]
	v_cvt_scalef32_pk_f32_fp4 v[14:15], v185, 1.0 op_sel:[1,1,0]
	v_readlane_b32 s54, v92, 46
	s_lshl_b32 s56, s54, 9
	s_add_u32 s56, s64, s56
	s_addc_u32 s57, s65, 0
	global_load_dwordx2 v[184:185], v227, s[56:57]
	s_waitcnt lgkmcnt(1)
; __device__ void peer_gather_phase(const Params& P, int l, bool do_store) {
;     ...
;       const float avec = gelu_t(dvec * sux) * gsx;
; #pragma unroll
;       for (int j = 0; j < 8; ++j) {
;         const float a = __builtin_bit_cast(float, __builtin_amdgcn_readlane(__builtin_bit_cast(int, avec), kb + j));
;         const f32x2 aa = f32x2{a, a};
;         y[0] += aa * __builtin_amdgcn_cvt_scalef32_pk_f32_fp4(v8[j].x, 1.0f, 0); y[1] += aa * __builtin_amdgcn_cvt_scalef32_pk_f32_fp4(v8[j].x, 1.0f, 1);
;         y[2] += aa * __builtin_amdgcn_cvt_scalef32_pk_f32_fp4(v8[j].x, 1.0f, 2); y[3] += aa * __builtin_amdgcn_cvt_scalef32_pk_f32_fp4(v8[j].x, 1.0f, 3);
;         y[4] += aa * __builtin_amdgcn_cvt_scalef32_pk_f32_fp4(v8[j].y, 1.0f, 0); y[5] += aa * __builtin_amdgcn_cvt_scalef32_pk_f32_fp4(v8[j].y, 1.0f, 1);
;         y[6] += aa * __builtin_amdgcn_cvt_scalef32_pk_f32_fp4(v8[j].y, 1.0f, 2); y[7] += aa * __builtin_amdgcn_cvt_scalef32_pk_f32_fp4(v8[j].y, 1.0f, 3);
	v_pk_fma_f32 v[130:131], v[0:1], v[76:77], v[130:131] op_sel_hi:[1,0,1]
	v_pk_fma_f32 v[138:139], v[2:3], v[76:77], v[138:139] op_sel_hi:[1,0,1]
	v_pk_fma_f32 v[140:141], v[4:5], v[76:77], v[140:141] op_sel_hi:[1,0,1]
	v_pk_fma_f32 v[142:143], v[6:7], v[76:77], v[142:143] op_sel_hi:[1,0,1]
	v_pk_fma_f32 v[128:129], v[8:9], v[76:77], v[128:129] op_sel_hi:[1,0,1]
	v_pk_fma_f32 v[132:133], v[10:11], v[76:77], v[132:133] op_sel_hi:[1,0,1]
	v_pk_fma_f32 v[134:135], v[12:13], v[76:77], v[134:135] op_sel_hi:[1,0,1]
	v_pk_fma_f32 v[136:137], v[14:15], v[76:77], v[136:137] op_sel_hi:[1,0,1]
	ds_read_b32 v76, v193 offset:640
	s_waitcnt vmcnt(15)
	v_cvt_scalef32_pk_f32_fp4 v[0:1], v186, 1.0
	v_cvt_scalef32_pk_f32_fp4 v[2:3], v186, 1.0 op_sel:[1,0,0]
	v_cvt_scalef32_pk_f32_fp4 v[4:5], v186, 1.0 op_sel:[0,1,0]
	v_cvt_scalef32_pk_f32_fp4 v[6:7], v186, 1.0 op_sel:[1,1,0]
	v_cvt_scalef32_pk_f32_fp4 v[8:9], v187, 1.0
	v_cvt_scalef32_pk_f32_fp4 v[10:11], v187, 1.0 op_sel:[1,0,0]
	v_cvt_scalef32_pk_f32_fp4 v[12:13], v187, 1.0 op_sel:[0,1,0]
	v_cvt_scalef32_pk_f32_fp4 v[14:15], v187, 1.0 op_sel:[1,1,0]
	v_readlane_b32 s54, v92, 47
	s_lshl_b32 s56, s54, 9
	s_add_u32 s56, s64, s56
	s_addc_u32 s57, s65, 0
	global_load_dwordx2 v[186:187], v227, s[56:57]
	s_waitcnt lgkmcnt(1)
	v_pk_fma_f32 v[130:131], v[0:1], v[194:195], v[130:131] op_sel_hi:[1,0,1]
	v_pk_fma_f32 v[138:139], v[2:3], v[194:195], v[138:139] op_sel_hi:[1,0,1]
	v_pk_fma_f32 v[140:141], v[4:5], v[194:195], v[140:141] op_sel_hi:[1,0,1]
	v_pk_fma_f32 v[142:143], v[6:7], v[194:195], v[142:143] op_sel_hi:[1,0,1]
	v_pk_fma_f32 v[128:129], v[8:9], v[194:195], v[128:129] op_sel_hi:[1,0,1]
	v_pk_fma_f32 v[132:133], v[10:11], v[194:195], v[132:133] op_sel_hi:[1,0,1]
	v_pk_fma_f32 v[134:135], v[12:13], v[194:195], v[134:135] op_sel_hi:[1,0,1]
	v_pk_fma_f32 v[136:137], v[14:15], v[194:195], v[136:137] op_sel_hi:[1,0,1]
	ds_read_b32 v194, v193 offset:644
	s_waitcnt vmcnt(15)
	v_cvt_scalef32_pk_f32_fp4 v[0:1], v144, 1.0
	v_cvt_scalef32_pk_f32_fp4 v[2:3], v144, 1.0 op_sel:[1,0,0]
	v_cvt_scalef32_pk_f32_fp4 v[4:5], v144, 1.0 op_sel:[0,1,0]
	v_cvt_scalef32_pk_f32_fp4 v[6:7], v144, 1.0 op_sel:[1,1,0]
	v_cvt_scalef32_pk_f32_fp4 v[8:9], v145, 1.0
	v_cvt_scalef32_pk_f32_fp4 v[10:11], v145, 1.0 op_sel:[1,0,0]
	v_cvt_scalef32_pk_f32_fp4 v[12:13], v145, 1.0 op_sel:[0,1,0]
	v_cvt_scalef32_pk_f32_fp4 v[14:15], v145, 1.0 op_sel:[1,1,0]
	v_readlane_b32 s54, v92, 48
	s_lshl_b32 s56, s54, 9
	s_add_u32 s56, s64, s56
	s_addc_u32 s57, s65, 0
	global_load_dwordx2 v[144:145], v227, s[56:57]
	s_waitcnt lgkmcnt(1)
	v_pk_fma_f32 v[130:131], v[0:1], v[76:77], v[130:131] op_sel_hi:[1,0,1]
	v_pk_fma_f32 v[138:139], v[2:3], v[76:77], v[138:139] op_sel_hi:[1,0,1]
	v_pk_fma_f32 v[140:141], v[4:5], v[76:77], v[140:141] op_sel_hi:[1,0,1]
	v_pk_fma_f32 v[142:143], v[6:7], v[76:77], v[142:143] op_sel_hi:[1,0,1]
	v_pk_fma_f32 v[128:129], v[8:9], v[76:77], v[128:129] op_sel_hi:[1,0,1]
	v_pk_fma_f32 v[132:133], v[10:11], v[76:77], v[132:133] op_sel_hi:[1,0,1]
	v_pk_fma_f32 v[134:135], v[12:13], v[76:77], v[134:135] op_sel_hi:[1,0,1]
	v_pk_fma_f32 v[136:137], v[14:15], v[76:77], v[136:137] op_sel_hi:[1,0,1]
	ds_read_b32 v76, v193 offset:648
	s_waitcnt vmcnt(15)
	v_cvt_scalef32_pk_f32_fp4 v[0:1], v146, 1.0
	v_cvt_scalef32_pk_f32_fp4 v[2:3], v146, 1.0 op_sel:[1,0,0]
	v_cvt_scalef32_pk_f32_fp4 v[4:5], v146, 1.0 op_sel:[0,1,0]
	v_cvt_scalef32_pk_f32_fp4 v[6:7], v146, 1.0 op_sel:[1,1,0]
	v_cvt_scalef32_pk_f32_fp4 v[8:9], v147, 1.0
	v_cvt_scalef32_pk_f32_fp4 v[10:11], v147, 1.0 op_sel:[1,0,0]
	v_cvt_scalef32_pk_f32_fp4 v[12:13], v147, 1.0 op_sel:[0,1,0]
	v_cvt_scalef32_pk_f32_fp4 v[14:15], v147, 1.0 op_sel:[1,1,0]
	v_readlane_b32 s54, v92, 49
	s_lshl_b32 s56, s54, 9
	s_add_u32 s56, s64, s56
	s_addc_u32 s57, s65, 0
	global_load_dwordx2 v[146:147], v227, s[56:57]
	s_waitcnt lgkmcnt(1)
	v_pk_fma_f32 v[130:131], v[0:1], v[194:195], v[130:131] op_sel_hi:[1,0,1]
	v_pk_fma_f32 v[138:139], v[2:3], v[194:195], v[138:139] op_sel_hi:[1,0,1]
	v_pk_fma_f32 v[140:141], v[4:5], v[194:195], v[140:141] op_sel_hi:[1,0,1]
	v_pk_fma_f32 v[142:143], v[6:7], v[194:195], v[142:143] op_sel_hi:[1,0,1]
	v_pk_fma_f32 v[128:129], v[8:9], v[194:195], v[128:129] op_sel_hi:[1,0,1]
	v_pk_fma_f32 v[132:133], v[10:11], v[194:195], v[132:133] op_sel_hi:[1,0,1]
	v_pk_fma_f32 v[134:135], v[12:13], v[194:195], v[134:135] op_sel_hi:[1,0,1]
	v_pk_fma_f32 v[136:137], v[14:15], v[194:195], v[136:137] op_sel_hi:[1,0,1]
	ds_read_b32 v194, v193 offset:652
	s_waitcnt vmcnt(15)
	v_cvt_scalef32_pk_f32_fp4 v[0:1], v148, 1.0
	v_cvt_scalef32_pk_f32_fp4 v[2:3], v148, 1.0 op_sel:[1,0,0]
	v_cvt_scalef32_pk_f32_fp4 v[4:5], v148, 1.0 op_sel:[0,1,0]
	v_cvt_scalef32_pk_f32_fp4 v[6:7], v148, 1.0 op_sel:[1,1,0]
	v_cvt_scalef32_pk_f32_fp4 v[8:9], v149, 1.0
	v_cvt_scalef32_pk_f32_fp4 v[10:11], v149, 1.0 op_sel:[1,0,0]
	v_cvt_scalef32_pk_f32_fp4 v[12:13], v149, 1.0 op_sel:[0,1,0]
	v_cvt_scalef32_pk_f32_fp4 v[14:15], v149, 1.0 op_sel:[1,1,0]
	v_readlane_b32 s54, v92, 50
	s_lshl_b32 s56, s54, 9
	s_add_u32 s56, s64, s56
	s_addc_u32 s57, s65, 0
	global_load_dwordx2 v[148:149], v227, s[56:57]
	s_waitcnt lgkmcnt(1)
	v_pk_fma_f32 v[130:131], v[0:1], v[76:77], v[130:131] op_sel_hi:[1,0,1]
	v_pk_fma_f32 v[138:139], v[2:3], v[76:77], v[138:139] op_sel_hi:[1,0,1]
	v_pk_fma_f32 v[140:141], v[4:5], v[76:77], v[140:141] op_sel_hi:[1,0,1]
	v_pk_fma_f32 v[142:143], v[6:7], v[76:77], v[142:143] op_sel_hi:[1,0,1]
	v_pk_fma_f32 v[128:129], v[8:9], v[76:77], v[128:129] op_sel_hi:[1,0,1]
	v_pk_fma_f32 v[132:133], v[10:11], v[76:77], v[132:133] op_sel_hi:[1,0,1]
	v_pk_fma_f32 v[134:135], v[12:13], v[76:77], v[134:135] op_sel_hi:[1,0,1]
	v_pk_fma_f32 v[136:137], v[14:15], v[76:77], v[136:137] op_sel_hi:[1,0,1]
	ds_read_b32 v76, v193 offset:656
	s_waitcnt vmcnt(15)
; __device__ void peer_gather_phase(const Params& P, int l, bool do_store) {
;     ...
;         v8[2 * pr] = *(const uint2*)(V + (size_t)ea * 512);
;         v8[2 * pr + 1] = *(const uint2*)(V + (size_t)eb * 512);
;     ...
; #pragma unroll
;       for (int j = 0; j < 8; ++j) {
;         const float a = __builtin_bit_cast(float, __builtin_amdgcn_readlane(__builtin_bit_cast(int, avec), kb + j));
;         const f32x2 aa = f32x2{a, a};
;         y[0] += aa * __builtin_amdgcn_cvt_scalef32_pk_f32_fp4(v8[j].x, 1.0f, 0); y[1] += aa * __builtin_amdgcn_cvt_scalef32_pk_f32_fp4(v8[j].x, 1.0f, 1);
;         y[2] += aa * __builtin_amdgcn_cvt_scalef32_pk_f32_fp4(v8[j].x, 1.0f, 2); y[3] += aa * __builtin_amdgcn_cvt_scalef32_pk_f32_fp4(v8[j].x, 1.0f, 3);
;         y[4] += aa * __builtin_amdgcn_cvt_scalef32_pk_f32_fp4(v8[j].y, 1.0f, 0); y[5] += aa * __builtin_amdgcn_cvt_scalef32_pk_f32_fp4(v8[j].y, 1.0f, 1);
;         y[6] += aa * __builtin_amdgcn_cvt_scalef32_pk_f32_fp4(v8[j].y, 1.0f, 2); y[7] += aa * __builtin_amdgcn_cvt_scalef32_pk_f32_fp4(v8[j].y, 1.0f, 3);
	v_cvt_scalef32_pk_f32_fp4 v[0:1], v150, 1.0
	v_cvt_scalef32_pk_f32_fp4 v[2:3], v150, 1.0 op_sel:[1,0,0]
	v_cvt_scalef32_pk_f32_fp4 v[4:5], v150, 1.0 op_sel:[0,1,0]
	v_cvt_scalef32_pk_f32_fp4 v[6:7], v150, 1.0 op_sel:[1,1,0]
	v_cvt_scalef32_pk_f32_fp4 v[8:9], v151, 1.0
	v_cvt_scalef32_pk_f32_fp4 v[10:11], v151, 1.0 op_sel:[1,0,0]
	v_cvt_scalef32_pk_f32_fp4 v[12:13], v151, 1.0 op_sel:[0,1,0]
	v_cvt_scalef32_pk_f32_fp4 v[14:15], v151, 1.0 op_sel:[1,1,0]
	v_readlane_b32 s54, v92, 51
	s_lshl_b32 s56, s54, 9
	s_add_u32 s56, s64, s56
	s_addc_u32 s57, s65, 0
	global_load_dwordx2 v[150:151], v227, s[56:57]
	s_waitcnt lgkmcnt(1)
	v_pk_fma_f32 v[130:131], v[0:1], v[194:195], v[130:131] op_sel_hi:[1,0,1]
	v_pk_fma_f32 v[138:139], v[2:3], v[194:195], v[138:139] op_sel_hi:[1,0,1]
	v_pk_fma_f32 v[140:141], v[4:5], v[194:195], v[140:141] op_sel_hi:[1,0,1]
	v_pk_fma_f32 v[142:143], v[6:7], v[194:195], v[142:143] op_sel_hi:[1,0,1]
	v_pk_fma_f32 v[128:129], v[8:9], v[194:195], v[128:129] op_sel_hi:[1,0,1]
	v_pk_fma_f32 v[132:133], v[10:11], v[194:195], v[132:133] op_sel_hi:[1,0,1]
	v_pk_fma_f32 v[134:135], v[12:13], v[194:195], v[134:135] op_sel_hi:[1,0,1]
	v_pk_fma_f32 v[136:137], v[14:15], v[194:195], v[136:137] op_sel_hi:[1,0,1]
	ds_read_b32 v194, v193 offset:660
	s_waitcnt vmcnt(15)
	v_cvt_scalef32_pk_f32_fp4 v[0:1], v152, 1.0
	v_cvt_scalef32_pk_f32_fp4 v[2:3], v152, 1.0 op_sel:[1,0,0]
	v_cvt_scalef32_pk_f32_fp4 v[4:5], v152, 1.0 op_sel:[0,1,0]
	v_cvt_scalef32_pk_f32_fp4 v[6:7], v152, 1.0 op_sel:[1,1,0]
	v_cvt_scalef32_pk_f32_fp4 v[8:9], v153, 1.0
	v_cvt_scalef32_pk_f32_fp4 v[10:11], v153, 1.0 op_sel:[1,0,0]
	v_cvt_scalef32_pk_f32_fp4 v[12:13], v153, 1.0 op_sel:[0,1,0]
	v_cvt_scalef32_pk_f32_fp4 v[14:15], v153, 1.0 op_sel:[1,1,0]
	v_readlane_b32 s54, v92, 52
	s_lshl_b32 s56, s54, 9
	s_add_u32 s56, s64, s56
	s_addc_u32 s57, s65, 0
	global_load_dwordx2 v[152:153], v227, s[56:57]
	s_waitcnt lgkmcnt(1)
	v_pk_fma_f32 v[130:131], v[0:1], v[76:77], v[130:131] op_sel_hi:[1,0,1]
	v_pk_fma_f32 v[138:139], v[2:3], v[76:77], v[138:139] op_sel_hi:[1,0,1]
	v_pk_fma_f32 v[140:141], v[4:5], v[76:77], v[140:141] op_sel_hi:[1,0,1]
	v_pk_fma_f32 v[142:143], v[6:7], v[76:77], v[142:143] op_sel_hi:[1,0,1]
	v_pk_fma_f32 v[128:129], v[8:9], v[76:77], v[128:129] op_sel_hi:[1,0,1]
	v_pk_fma_f32 v[132:133], v[10:11], v[76:77], v[132:133] op_sel_hi:[1,0,1]
	v_pk_fma_f32 v[134:135], v[12:13], v[76:77], v[134:135] op_sel_hi:[1,0,1]
	v_pk_fma_f32 v[136:137], v[14:15], v[76:77], v[136:137] op_sel_hi:[1,0,1]
	ds_read_b32 v76, v193 offset:664
	s_waitcnt vmcnt(15)
	v_cvt_scalef32_pk_f32_fp4 v[0:1], v154, 1.0
	v_cvt_scalef32_pk_f32_fp4 v[2:3], v154, 1.0 op_sel:[1,0,0]
	v_cvt_scalef32_pk_f32_fp4 v[4:5], v154, 1.0 op_sel:[0,1,0]
	v_cvt_scalef32_pk_f32_fp4 v[6:7], v154, 1.0 op_sel:[1,1,0]
	v_cvt_scalef32_pk_f32_fp4 v[8:9], v155, 1.0
	v_cvt_scalef32_pk_f32_fp4 v[10:11], v155, 1.0 op_sel:[1,0,0]
	v_cvt_scalef32_pk_f32_fp4 v[12:13], v155, 1.0 op_sel:[0,1,0]
	v_cvt_scalef32_pk_f32_fp4 v[14:15], v155, 1.0 op_sel:[1,1,0]
	v_readlane_b32 s54, v92, 53
	s_lshl_b32 s56, s54, 9
	s_add_u32 s56, s64, s56
	s_addc_u32 s57, s65, 0
	global_load_dwordx2 v[154:155], v227, s[56:57]
	s_waitcnt lgkmcnt(1)
	v_pk_fma_f32 v[130:131], v[0:1], v[194:195], v[130:131] op_sel_hi:[1,0,1]
	v_pk_fma_f32 v[138:139], v[2:3], v[194:195], v[138:139] op_sel_hi:[1,0,1]
	v_pk_fma_f32 v[140:141], v[4:5], v[194:195], v[140:141] op_sel_hi:[1,0,1]
	v_pk_fma_f32 v[142:143], v[6:7], v[194:195], v[142:143] op_sel_hi:[1,0,1]
	v_pk_fma_f32 v[128:129], v[8:9], v[194:195], v[128:129] op_sel_hi:[1,0,1]
	v_pk_fma_f32 v[132:133], v[10:11], v[194:195], v[132:133] op_sel_hi:[1,0,1]
	v_pk_fma_f32 v[134:135], v[12:13], v[194:195], v[134:135] op_sel_hi:[1,0,1]
	v_pk_fma_f32 v[136:137], v[14:15], v[194:195], v[136:137] op_sel_hi:[1,0,1]
	ds_read_b32 v194, v193 offset:668
	s_waitcnt vmcnt(15)
	v_cvt_scalef32_pk_f32_fp4 v[0:1], v156, 1.0
	v_cvt_scalef32_pk_f32_fp4 v[2:3], v156, 1.0 op_sel:[1,0,0]
	v_cvt_scalef32_pk_f32_fp4 v[4:5], v156, 1.0 op_sel:[0,1,0]
	v_cvt_scalef32_pk_f32_fp4 v[6:7], v156, 1.0 op_sel:[1,1,0]
	v_cvt_scalef32_pk_f32_fp4 v[8:9], v157, 1.0
	v_cvt_scalef32_pk_f32_fp4 v[10:11], v157, 1.0 op_sel:[1,0,0]
	v_cvt_scalef32_pk_f32_fp4 v[12:13], v157, 1.0 op_sel:[0,1,0]
	v_cvt_scalef32_pk_f32_fp4 v[14:15], v157, 1.0 op_sel:[1,1,0]
	v_readlane_b32 s54, v92, 54
	s_lshl_b32 s56, s54, 9
	s_add_u32 s56, s64, s56
	s_addc_u32 s57, s65, 0
	global_load_dwordx2 v[156:157], v227, s[56:57]
	s_waitcnt lgkmcnt(1)
	v_pk_fma_f32 v[130:131], v[0:1], v[76:77], v[130:131] op_sel_hi:[1,0,1]
	v_pk_fma_f32 v[138:139], v[2:3], v[76:77], v[138:139] op_sel_hi:[1,0,1]
	v_pk_fma_f32 v[140:141], v[4:5], v[76:77], v[140:141] op_sel_hi:[1,0,1]
	v_pk_fma_f32 v[142:143], v[6:7], v[76:77], v[142:143] op_sel_hi:[1,0,1]
	v_pk_fma_f32 v[128:129], v[8:9], v[76:77], v[128:129] op_sel_hi:[1,0,1]
	v_pk_fma_f32 v[132:133], v[10:11], v[76:77], v[132:133] op_sel_hi:[1,0,1]
	v_pk_fma_f32 v[134:135], v[12:13], v[76:77], v[134:135] op_sel_hi:[1,0,1]
	v_pk_fma_f32 v[136:137], v[14:15], v[76:77], v[136:137] op_sel_hi:[1,0,1]
	ds_read_b32 v76, v193 offset:672
	s_waitcnt vmcnt(15)
	v_cvt_scalef32_pk_f32_fp4 v[0:1], v158, 1.0
	v_cvt_scalef32_pk_f32_fp4 v[2:3], v158, 1.0 op_sel:[1,0,0]
	v_cvt_scalef32_pk_f32_fp4 v[4:5], v158, 1.0 op_sel:[0,1,0]
	v_cvt_scalef32_pk_f32_fp4 v[6:7], v158, 1.0 op_sel:[1,1,0]
	v_cvt_scalef32_pk_f32_fp4 v[8:9], v159, 1.0
	v_cvt_scalef32_pk_f32_fp4 v[10:11], v159, 1.0 op_sel:[1,0,0]
	v_cvt_scalef32_pk_f32_fp4 v[12:13], v159, 1.0 op_sel:[0,1,0]
	v_cvt_scalef32_pk_f32_fp4 v[14:15], v159, 1.0 op_sel:[1,1,0]
	v_readlane_b32 s54, v92, 55
	s_lshl_b32 s56, s54, 9
	s_add_u32 s56, s64, s56
	s_addc_u32 s57, s65, 0
	global_load_dwordx2 v[158:159], v227, s[56:57]
	s_waitcnt lgkmcnt(1)
; __device__ void peer_gather_phase(const Params& P, int l, bool do_store) {
;     ...
;         v8[2 * pr] = *(const uint2*)(V + (size_t)ea * 512);
;         v8[2 * pr + 1] = *(const uint2*)(V + (size_t)eb * 512);
;     ...
; #pragma unroll
;       for (int j = 0; j < 8; ++j) {
;         const float a = __builtin_bit_cast(float, __builtin_amdgcn_readlane(__builtin_bit_cast(int, avec), kb + j));
;         const f32x2 aa = f32x2{a, a};
;         y[0] += aa * __builtin_amdgcn_cvt_scalef32_pk_f32_fp4(v8[j].x, 1.0f, 0); y[1] += aa * __builtin_amdgcn_cvt_scalef32_pk_f32_fp4(v8[j].x, 1.0f, 1);
;         y[2] += aa * __builtin_amdgcn_cvt_scalef32_pk_f32_fp4(v8[j].x, 1.0f, 2); y[3] += aa * __builtin_amdgcn_cvt_scalef32_pk_f32_fp4(v8[j].x, 1.0f, 3);
;         y[4] += aa * __builtin_amdgcn_cvt_scalef32_pk_f32_fp4(v8[j].y, 1.0f, 0); y[5] += aa * __builtin_amdgcn_cvt_scalef32_pk_f32_fp4(v8[j].y, 1.0f, 1);
;         y[6] += aa * __builtin_amdgcn_cvt_scalef32_pk_f32_fp4(v8[j].y, 1.0f, 2); y[7] += aa * __builtin_amdgcn_cvt_scalef32_pk_f32_fp4(v8[j].y, 1.0f, 3);
	v_pk_fma_f32 v[130:131], v[0:1], v[194:195], v[130:131] op_sel_hi:[1,0,1]
	v_pk_fma_f32 v[138:139], v[2:3], v[194:195], v[138:139] op_sel_hi:[1,0,1]
	v_pk_fma_f32 v[140:141], v[4:5], v[194:195], v[140:141] op_sel_hi:[1,0,1]
	v_pk_fma_f32 v[142:143], v[6:7], v[194:195], v[142:143] op_sel_hi:[1,0,1]
	v_pk_fma_f32 v[128:129], v[8:9], v[194:195], v[128:129] op_sel_hi:[1,0,1]
	v_pk_fma_f32 v[132:133], v[10:11], v[194:195], v[132:133] op_sel_hi:[1,0,1]
	v_pk_fma_f32 v[134:135], v[12:13], v[194:195], v[134:135] op_sel_hi:[1,0,1]
	v_pk_fma_f32 v[136:137], v[14:15], v[194:195], v[136:137] op_sel_hi:[1,0,1]
	ds_read_b32 v194, v193 offset:676
	s_waitcnt vmcnt(15)
	v_cvt_scalef32_pk_f32_fp4 v[0:1], v168, 1.0
	v_cvt_scalef32_pk_f32_fp4 v[2:3], v168, 1.0 op_sel:[1,0,0]
	v_cvt_scalef32_pk_f32_fp4 v[4:5], v168, 1.0 op_sel:[0,1,0]
	v_cvt_scalef32_pk_f32_fp4 v[6:7], v168, 1.0 op_sel:[1,1,0]
	v_cvt_scalef32_pk_f32_fp4 v[8:9], v169, 1.0
	v_cvt_scalef32_pk_f32_fp4 v[10:11], v169, 1.0 op_sel:[1,0,0]
	v_cvt_scalef32_pk_f32_fp4 v[12:13], v169, 1.0 op_sel:[0,1,0]
	v_cvt_scalef32_pk_f32_fp4 v[14:15], v169, 1.0 op_sel:[1,1,0]
	v_readlane_b32 s54, v92, 56
	s_lshl_b32 s56, s54, 9
	s_add_u32 s56, s64, s56
	s_addc_u32 s57, s65, 0
	global_load_dwordx2 v[168:169], v227, s[56:57]
	s_waitcnt lgkmcnt(1)
	v_pk_fma_f32 v[130:131], v[0:1], v[76:77], v[130:131] op_sel_hi:[1,0,1]
	v_pk_fma_f32 v[138:139], v[2:3], v[76:77], v[138:139] op_sel_hi:[1,0,1]
	v_pk_fma_f32 v[140:141], v[4:5], v[76:77], v[140:141] op_sel_hi:[1,0,1]
	v_pk_fma_f32 v[142:143], v[6:7], v[76:77], v[142:143] op_sel_hi:[1,0,1]
	v_pk_fma_f32 v[128:129], v[8:9], v[76:77], v[128:129] op_sel_hi:[1,0,1]
	v_pk_fma_f32 v[132:133], v[10:11], v[76:77], v[132:133] op_sel_hi:[1,0,1]
	v_pk_fma_f32 v[134:135], v[12:13], v[76:77], v[134:135] op_sel_hi:[1,0,1]
	v_pk_fma_f32 v[136:137], v[14:15], v[76:77], v[136:137] op_sel_hi:[1,0,1]
	ds_read_b32 v76, v193 offset:680
	s_waitcnt vmcnt(15)
	v_cvt_scalef32_pk_f32_fp4 v[0:1], v170, 1.0
	v_cvt_scalef32_pk_f32_fp4 v[2:3], v170, 1.0 op_sel:[1,0,0]
	v_cvt_scalef32_pk_f32_fp4 v[4:5], v170, 1.0 op_sel:[0,1,0]
	v_cvt_scalef32_pk_f32_fp4 v[6:7], v170, 1.0 op_sel:[1,1,0]
	v_cvt_scalef32_pk_f32_fp4 v[8:9], v171, 1.0
	v_cvt_scalef32_pk_f32_fp4 v[10:11], v171, 1.0 op_sel:[1,0,0]
	v_cvt_scalef32_pk_f32_fp4 v[12:13], v171, 1.0 op_sel:[0,1,0]
	v_cvt_scalef32_pk_f32_fp4 v[14:15], v171, 1.0 op_sel:[1,1,0]
	v_readlane_b32 s54, v92, 57
	s_lshl_b32 s56, s54, 9
	s_add_u32 s56, s64, s56
	s_addc_u32 s57, s65, 0
	global_load_dwordx2 v[170:171], v227, s[56:57]
	s_waitcnt lgkmcnt(1)
	v_pk_fma_f32 v[130:131], v[0:1], v[194:195], v[130:131] op_sel_hi:[1,0,1]
	v_pk_fma_f32 v[138:139], v[2:3], v[194:195], v[138:139] op_sel_hi:[1,0,1]
	v_pk_fma_f32 v[140:141], v[4:5], v[194:195], v[140:141] op_sel_hi:[1,0,1]
	v_pk_fma_f32 v[142:143], v[6:7], v[194:195], v[142:143] op_sel_hi:[1,0,1]
	v_pk_fma_f32 v[128:129], v[8:9], v[194:195], v[128:129] op_sel_hi:[1,0,1]
	v_pk_fma_f32 v[132:133], v[10:11], v[194:195], v[132:133] op_sel_hi:[1,0,1]
	v_pk_fma_f32 v[134:135], v[12:13], v[194:195], v[134:135] op_sel_hi:[1,0,1]
	v_pk_fma_f32 v[136:137], v[14:15], v[194:195], v[136:137] op_sel_hi:[1,0,1]
	ds_read_b32 v194, v193 offset:684
	s_waitcnt vmcnt(15)
	v_cvt_scalef32_pk_f32_fp4 v[0:1], v172, 1.0
	v_cvt_scalef32_pk_f32_fp4 v[2:3], v172, 1.0 op_sel:[1,0,0]
	v_cvt_scalef32_pk_f32_fp4 v[4:5], v172, 1.0 op_sel:[0,1,0]
	v_cvt_scalef32_pk_f32_fp4 v[6:7], v172, 1.0 op_sel:[1,1,0]
	v_cvt_scalef32_pk_f32_fp4 v[8:9], v173, 1.0
	v_cvt_scalef32_pk_f32_fp4 v[10:11], v173, 1.0 op_sel:[1,0,0]
	v_cvt_scalef32_pk_f32_fp4 v[12:13], v173, 1.0 op_sel:[0,1,0]
	v_cvt_scalef32_pk_f32_fp4 v[14:15], v173, 1.0 op_sel:[1,1,0]
	v_readlane_b32 s54, v92, 58
	s_lshl_b32 s56, s54, 9
	s_add_u32 s56, s64, s56
	s_addc_u32 s57, s65, 0
	global_load_dwordx2 v[172:173], v227, s[56:57]
	s_waitcnt lgkmcnt(1)
	v_pk_fma_f32 v[130:131], v[0:1], v[76:77], v[130:131] op_sel_hi:[1,0,1]
	v_pk_fma_f32 v[138:139], v[2:3], v[76:77], v[138:139] op_sel_hi:[1,0,1]
	v_pk_fma_f32 v[140:141], v[4:5], v[76:77], v[140:141] op_sel_hi:[1,0,1]
	v_pk_fma_f32 v[142:143], v[6:7], v[76:77], v[142:143] op_sel_hi:[1,0,1]
	v_pk_fma_f32 v[128:129], v[8:9], v[76:77], v[128:129] op_sel_hi:[1,0,1]
	v_pk_fma_f32 v[132:133], v[10:11], v[76:77], v[132:133] op_sel_hi:[1,0,1]
	v_pk_fma_f32 v[134:135], v[12:13], v[76:77], v[134:135] op_sel_hi:[1,0,1]
	v_pk_fma_f32 v[136:137], v[14:15], v[76:77], v[136:137] op_sel_hi:[1,0,1]
	ds_read_b32 v76, v193 offset:688
	s_waitcnt vmcnt(15)
	v_cvt_scalef32_pk_f32_fp4 v[0:1], v174, 1.0
	v_cvt_scalef32_pk_f32_fp4 v[2:3], v174, 1.0 op_sel:[1,0,0]
	v_cvt_scalef32_pk_f32_fp4 v[4:5], v174, 1.0 op_sel:[0,1,0]
	v_cvt_scalef32_pk_f32_fp4 v[6:7], v174, 1.0 op_sel:[1,1,0]
	v_cvt_scalef32_pk_f32_fp4 v[8:9], v175, 1.0
	v_cvt_scalef32_pk_f32_fp4 v[10:11], v175, 1.0 op_sel:[1,0,0]
	v_cvt_scalef32_pk_f32_fp4 v[12:13], v175, 1.0 op_sel:[0,1,0]
	v_cvt_scalef32_pk_f32_fp4 v[14:15], v175, 1.0 op_sel:[1,1,0]
	v_readlane_b32 s54, v92, 59
	s_lshl_b32 s56, s54, 9
	s_add_u32 s56, s64, s56
	s_addc_u32 s57, s65, 0
	global_load_dwordx2 v[174:175], v227, s[56:57]
	s_waitcnt lgkmcnt(1)
	v_pk_fma_f32 v[130:131], v[0:1], v[194:195], v[130:131] op_sel_hi:[1,0,1]
	v_pk_fma_f32 v[138:139], v[2:3], v[194:195], v[138:139] op_sel_hi:[1,0,1]
	v_pk_fma_f32 v[140:141], v[4:5], v[194:195], v[140:141] op_sel_hi:[1,0,1]
	v_pk_fma_f32 v[142:143], v[6:7], v[194:195], v[142:143] op_sel_hi:[1,0,1]
	v_pk_fma_f32 v[128:129], v[8:9], v[194:195], v[128:129] op_sel_hi:[1,0,1]
	v_pk_fma_f32 v[132:133], v[10:11], v[194:195], v[132:133] op_sel_hi:[1,0,1]
	v_pk_fma_f32 v[134:135], v[12:13], v[194:195], v[134:135] op_sel_hi:[1,0,1]
	v_pk_fma_f32 v[136:137], v[14:15], v[194:195], v[136:137] op_sel_hi:[1,0,1]
	ds_read_b32 v194, v193 offset:692
	s_waitcnt vmcnt(15)
; __device__ void peer_gather_phase(const Params& P, int l, bool do_store) {
;     ...
;         v8[2 * pr] = *(const uint2*)(V + (size_t)ea * 512);
;         v8[2 * pr + 1] = *(const uint2*)(V + (size_t)eb * 512);
;     ...
; #pragma unroll
;       for (int j = 0; j < 8; ++j) {
;         const float a = __builtin_bit_cast(float, __builtin_amdgcn_readlane(__builtin_bit_cast(int, avec), kb + j));
;         const f32x2 aa = f32x2{a, a};
;         y[0] += aa * __builtin_amdgcn_cvt_scalef32_pk_f32_fp4(v8[j].x, 1.0f, 0); y[1] += aa * __builtin_amdgcn_cvt_scalef32_pk_f32_fp4(v8[j].x, 1.0f, 1);
;         y[2] += aa * __builtin_amdgcn_cvt_scalef32_pk_f32_fp4(v8[j].x, 1.0f, 2); y[3] += aa * __builtin_amdgcn_cvt_scalef32_pk_f32_fp4(v8[j].x, 1.0f, 3);
;         y[4] += aa * __builtin_amdgcn_cvt_scalef32_pk_f32_fp4(v8[j].y, 1.0f, 0); y[5] += aa * __builtin_amdgcn_cvt_scalef32_pk_f32_fp4(v8[j].y, 1.0f, 1);
;         y[6] += aa * __builtin_amdgcn_cvt_scalef32_pk_f32_fp4(v8[j].y, 1.0f, 2); y[7] += aa * __builtin_amdgcn_cvt_scalef32_pk_f32_fp4(v8[j].y, 1.0f, 3);
	v_cvt_scalef32_pk_f32_fp4 v[0:1], v180, 1.0
	v_cvt_scalef32_pk_f32_fp4 v[2:3], v180, 1.0 op_sel:[1,0,0]
	v_cvt_scalef32_pk_f32_fp4 v[4:5], v180, 1.0 op_sel:[0,1,0]
	v_cvt_scalef32_pk_f32_fp4 v[6:7], v180, 1.0 op_sel:[1,1,0]
	v_cvt_scalef32_pk_f32_fp4 v[8:9], v181, 1.0
	v_cvt_scalef32_pk_f32_fp4 v[10:11], v181, 1.0 op_sel:[1,0,0]
	v_cvt_scalef32_pk_f32_fp4 v[12:13], v181, 1.0 op_sel:[0,1,0]
	v_cvt_scalef32_pk_f32_fp4 v[14:15], v181, 1.0 op_sel:[1,1,0]
	v_readlane_b32 s54, v92, 60
	s_lshl_b32 s56, s54, 9
	s_add_u32 s56, s64, s56
	s_addc_u32 s57, s65, 0
	global_load_dwordx2 v[180:181], v227, s[56:57]
	s_waitcnt lgkmcnt(1)
	v_pk_fma_f32 v[130:131], v[0:1], v[76:77], v[130:131] op_sel_hi:[1,0,1]
	v_pk_fma_f32 v[138:139], v[2:3], v[76:77], v[138:139] op_sel_hi:[1,0,1]
	v_pk_fma_f32 v[140:141], v[4:5], v[76:77], v[140:141] op_sel_hi:[1,0,1]
	v_pk_fma_f32 v[142:143], v[6:7], v[76:77], v[142:143] op_sel_hi:[1,0,1]
	v_pk_fma_f32 v[128:129], v[8:9], v[76:77], v[128:129] op_sel_hi:[1,0,1]
	v_pk_fma_f32 v[132:133], v[10:11], v[76:77], v[132:133] op_sel_hi:[1,0,1]
	v_pk_fma_f32 v[134:135], v[12:13], v[76:77], v[134:135] op_sel_hi:[1,0,1]
	v_pk_fma_f32 v[136:137], v[14:15], v[76:77], v[136:137] op_sel_hi:[1,0,1]
	ds_read_b32 v76, v193 offset:696
	s_waitcnt vmcnt(15)
	v_cvt_scalef32_pk_f32_fp4 v[0:1], v182, 1.0
	v_cvt_scalef32_pk_f32_fp4 v[2:3], v182, 1.0 op_sel:[1,0,0]
	v_cvt_scalef32_pk_f32_fp4 v[4:5], v182, 1.0 op_sel:[0,1,0]
	v_cvt_scalef32_pk_f32_fp4 v[6:7], v182, 1.0 op_sel:[1,1,0]
	v_cvt_scalef32_pk_f32_fp4 v[8:9], v183, 1.0
	v_cvt_scalef32_pk_f32_fp4 v[10:11], v183, 1.0 op_sel:[1,0,0]
	v_cvt_scalef32_pk_f32_fp4 v[12:13], v183, 1.0 op_sel:[0,1,0]
	v_cvt_scalef32_pk_f32_fp4 v[14:15], v183, 1.0 op_sel:[1,1,0]
	v_readlane_b32 s54, v92, 61
	s_lshl_b32 s56, s54, 9
	s_add_u32 s56, s64, s56
	s_addc_u32 s57, s65, 0
	global_load_dwordx2 v[182:183], v227, s[56:57]
	s_waitcnt lgkmcnt(1)
	v_pk_fma_f32 v[130:131], v[0:1], v[194:195], v[130:131] op_sel_hi:[1,0,1]
	v_pk_fma_f32 v[138:139], v[2:3], v[194:195], v[138:139] op_sel_hi:[1,0,1]
	v_pk_fma_f32 v[140:141], v[4:5], v[194:195], v[140:141] op_sel_hi:[1,0,1]
	v_pk_fma_f32 v[142:143], v[6:7], v[194:195], v[142:143] op_sel_hi:[1,0,1]
	v_pk_fma_f32 v[128:129], v[8:9], v[194:195], v[128:129] op_sel_hi:[1,0,1]
	v_pk_fma_f32 v[132:133], v[10:11], v[194:195], v[132:133] op_sel_hi:[1,0,1]
	v_pk_fma_f32 v[134:135], v[12:13], v[194:195], v[134:135] op_sel_hi:[1,0,1]
	v_pk_fma_f32 v[136:137], v[14:15], v[194:195], v[136:137] op_sel_hi:[1,0,1]
	ds_read_b32 v194, v193 offset:700
	s_waitcnt vmcnt(15)
	v_cvt_scalef32_pk_f32_fp4 v[0:1], v184, 1.0
	v_cvt_scalef32_pk_f32_fp4 v[2:3], v184, 1.0 op_sel:[1,0,0]
	v_cvt_scalef32_pk_f32_fp4 v[4:5], v184, 1.0 op_sel:[0,1,0]
	v_cvt_scalef32_pk_f32_fp4 v[6:7], v184, 1.0 op_sel:[1,1,0]
	v_cvt_scalef32_pk_f32_fp4 v[8:9], v185, 1.0
	v_cvt_scalef32_pk_f32_fp4 v[10:11], v185, 1.0 op_sel:[1,0,0]
	v_cvt_scalef32_pk_f32_fp4 v[12:13], v185, 1.0 op_sel:[0,1,0]
	v_cvt_scalef32_pk_f32_fp4 v[14:15], v185, 1.0 op_sel:[1,1,0]
	v_readlane_b32 s54, v92, 62
	s_lshl_b32 s56, s54, 9
	s_add_u32 s56, s64, s56
	s_addc_u32 s57, s65, 0
	global_load_dwordx2 v[184:185], v227, s[56:57]
	s_waitcnt lgkmcnt(1)
	v_pk_fma_f32 v[130:131], v[0:1], v[76:77], v[130:131] op_sel_hi:[1,0,1]
	v_pk_fma_f32 v[138:139], v[2:3], v[76:77], v[138:139] op_sel_hi:[1,0,1]
	v_pk_fma_f32 v[140:141], v[4:5], v[76:77], v[140:141] op_sel_hi:[1,0,1]
	v_pk_fma_f32 v[142:143], v[6:7], v[76:77], v[142:143] op_sel_hi:[1,0,1]
	v_pk_fma_f32 v[128:129], v[8:9], v[76:77], v[128:129] op_sel_hi:[1,0,1]
	v_pk_fma_f32 v[132:133], v[10:11], v[76:77], v[132:133] op_sel_hi:[1,0,1]
	v_pk_fma_f32 v[134:135], v[12:13], v[76:77], v[134:135] op_sel_hi:[1,0,1]
	v_pk_fma_f32 v[136:137], v[14:15], v[76:77], v[136:137] op_sel_hi:[1,0,1]
	ds_read_b32 v76, v193 offset:704
	s_waitcnt vmcnt(15)
	v_cvt_scalef32_pk_f32_fp4 v[0:1], v186, 1.0
	v_cvt_scalef32_pk_f32_fp4 v[2:3], v186, 1.0 op_sel:[1,0,0]
	v_cvt_scalef32_pk_f32_fp4 v[4:5], v186, 1.0 op_sel:[0,1,0]
	v_cvt_scalef32_pk_f32_fp4 v[6:7], v186, 1.0 op_sel:[1,1,0]
	v_cvt_scalef32_pk_f32_fp4 v[8:9], v187, 1.0
	v_cvt_scalef32_pk_f32_fp4 v[10:11], v187, 1.0 op_sel:[1,0,0]
	v_cvt_scalef32_pk_f32_fp4 v[12:13], v187, 1.0 op_sel:[0,1,0]
	v_cvt_scalef32_pk_f32_fp4 v[14:15], v187, 1.0 op_sel:[1,1,0]
	v_readlane_b32 s54, v92, 63
	s_lshl_b32 s56, s54, 9
	s_add_u32 s56, s64, s56
	s_addc_u32 s57, s65, 0
	global_load_dwordx2 v[186:187], v227, s[56:57]
	s_waitcnt lgkmcnt(1)
	v_pk_fma_f32 v[130:131], v[0:1], v[194:195], v[130:131] op_sel_hi:[1,0,1]
	v_pk_fma_f32 v[138:139], v[2:3], v[194:195], v[138:139] op_sel_hi:[1,0,1]
	v_pk_fma_f32 v[140:141], v[4:5], v[194:195], v[140:141] op_sel_hi:[1,0,1]
	v_pk_fma_f32 v[142:143], v[6:7], v[194:195], v[142:143] op_sel_hi:[1,0,1]
	v_pk_fma_f32 v[128:129], v[8:9], v[194:195], v[128:129] op_sel_hi:[1,0,1]
	v_pk_fma_f32 v[132:133], v[10:11], v[194:195], v[132:133] op_sel_hi:[1,0,1]
	v_pk_fma_f32 v[134:135], v[12:13], v[194:195], v[134:135] op_sel_hi:[1,0,1]
	v_pk_fma_f32 v[136:137], v[14:15], v[194:195], v[136:137] op_sel_hi:[1,0,1]
	ds_read_b32 v194, v193 offset:708
	s_waitcnt vmcnt(15)
	v_cvt_scalef32_pk_f32_fp4 v[0:1], v144, 1.0
	v_cvt_scalef32_pk_f32_fp4 v[2:3], v144, 1.0 op_sel:[1,0,0]
	v_cvt_scalef32_pk_f32_fp4 v[4:5], v144, 1.0 op_sel:[0,1,0]
	v_cvt_scalef32_pk_f32_fp4 v[6:7], v144, 1.0 op_sel:[1,1,0]
	v_cvt_scalef32_pk_f32_fp4 v[8:9], v145, 1.0
	v_cvt_scalef32_pk_f32_fp4 v[10:11], v145, 1.0 op_sel:[1,0,0]
	v_cvt_scalef32_pk_f32_fp4 v[12:13], v145, 1.0 op_sel:[0,1,0]
	v_cvt_scalef32_pk_f32_fp4 v[14:15], v145, 1.0 op_sel:[1,1,0]
	v_readlane_b32 s54, v90, 0
	s_lshl_b32 s56, s54, 9
	s_add_u32 s56, s64, s56
	s_addc_u32 s57, s65, 0
	global_load_dwordx2 v[144:145], v227, s[56:57]
	s_waitcnt lgkmcnt(1)
; __device__ void peer_gather_phase(const Params& P, int l, bool do_store) {
;     ...
;         v8[2 * pr] = *(const uint2*)(V + (size_t)ea * 512);
;         v8[2 * pr + 1] = *(const uint2*)(V + (size_t)eb * 512);
;     ...
; #pragma unroll
;       for (int j = 0; j < 8; ++j) {
;         const float a = __builtin_bit_cast(float, __builtin_amdgcn_readlane(__builtin_bit_cast(int, avec), kb + j));
;         const f32x2 aa = f32x2{a, a};
;         y[0] += aa * __builtin_amdgcn_cvt_scalef32_pk_f32_fp4(v8[j].x, 1.0f, 0); y[1] += aa * __builtin_amdgcn_cvt_scalef32_pk_f32_fp4(v8[j].x, 1.0f, 1);
;         y[2] += aa * __builtin_amdgcn_cvt_scalef32_pk_f32_fp4(v8[j].x, 1.0f, 2); y[3] += aa * __builtin_amdgcn_cvt_scalef32_pk_f32_fp4(v8[j].x, 1.0f, 3);
;         y[4] += aa * __builtin_amdgcn_cvt_scalef32_pk_f32_fp4(v8[j].y, 1.0f, 0); y[5] += aa * __builtin_amdgcn_cvt_scalef32_pk_f32_fp4(v8[j].y, 1.0f, 1);
;         y[6] += aa * __builtin_amdgcn_cvt_scalef32_pk_f32_fp4(v8[j].y, 1.0f, 2); y[7] += aa * __builtin_amdgcn_cvt_scalef32_pk_f32_fp4(v8[j].y, 1.0f, 3);
	v_pk_fma_f32 v[130:131], v[0:1], v[76:77], v[130:131] op_sel_hi:[1,0,1]
	v_pk_fma_f32 v[138:139], v[2:3], v[76:77], v[138:139] op_sel_hi:[1,0,1]
	v_pk_fma_f32 v[140:141], v[4:5], v[76:77], v[140:141] op_sel_hi:[1,0,1]
	v_pk_fma_f32 v[142:143], v[6:7], v[76:77], v[142:143] op_sel_hi:[1,0,1]
	v_pk_fma_f32 v[128:129], v[8:9], v[76:77], v[128:129] op_sel_hi:[1,0,1]
	v_pk_fma_f32 v[132:133], v[10:11], v[76:77], v[132:133] op_sel_hi:[1,0,1]
	v_pk_fma_f32 v[134:135], v[12:13], v[76:77], v[134:135] op_sel_hi:[1,0,1]
	v_pk_fma_f32 v[136:137], v[14:15], v[76:77], v[136:137] op_sel_hi:[1,0,1]
	ds_read_b32 v76, v193 offset:712
	s_waitcnt vmcnt(15)
	v_cvt_scalef32_pk_f32_fp4 v[0:1], v146, 1.0
	v_cvt_scalef32_pk_f32_fp4 v[2:3], v146, 1.0 op_sel:[1,0,0]
	v_cvt_scalef32_pk_f32_fp4 v[4:5], v146, 1.0 op_sel:[0,1,0]
	v_cvt_scalef32_pk_f32_fp4 v[6:7], v146, 1.0 op_sel:[1,1,0]
	v_cvt_scalef32_pk_f32_fp4 v[8:9], v147, 1.0
	v_cvt_scalef32_pk_f32_fp4 v[10:11], v147, 1.0 op_sel:[1,0,0]
	v_cvt_scalef32_pk_f32_fp4 v[12:13], v147, 1.0 op_sel:[0,1,0]
	v_cvt_scalef32_pk_f32_fp4 v[14:15], v147, 1.0 op_sel:[1,1,0]
	v_readlane_b32 s54, v90, 1
	s_lshl_b32 s56, s54, 9
	s_add_u32 s56, s64, s56
	s_addc_u32 s57, s65, 0
	global_load_dwordx2 v[146:147], v227, s[56:57]
	s_waitcnt lgkmcnt(1)
	v_pk_fma_f32 v[130:131], v[0:1], v[194:195], v[130:131] op_sel_hi:[1,0,1]
	v_pk_fma_f32 v[138:139], v[2:3], v[194:195], v[138:139] op_sel_hi:[1,0,1]
	v_pk_fma_f32 v[140:141], v[4:5], v[194:195], v[140:141] op_sel_hi:[1,0,1]
	v_pk_fma_f32 v[142:143], v[6:7], v[194:195], v[142:143] op_sel_hi:[1,0,1]
	v_pk_fma_f32 v[128:129], v[8:9], v[194:195], v[128:129] op_sel_hi:[1,0,1]
	v_pk_fma_f32 v[132:133], v[10:11], v[194:195], v[132:133] op_sel_hi:[1,0,1]
	v_pk_fma_f32 v[134:135], v[12:13], v[194:195], v[134:135] op_sel_hi:[1,0,1]
	v_pk_fma_f32 v[136:137], v[14:15], v[194:195], v[136:137] op_sel_hi:[1,0,1]
	ds_read_b32 v194, v193 offset:716
	s_waitcnt vmcnt(15)
	v_cvt_scalef32_pk_f32_fp4 v[0:1], v148, 1.0
	v_cvt_scalef32_pk_f32_fp4 v[2:3], v148, 1.0 op_sel:[1,0,0]
	v_cvt_scalef32_pk_f32_fp4 v[4:5], v148, 1.0 op_sel:[0,1,0]
	v_cvt_scalef32_pk_f32_fp4 v[6:7], v148, 1.0 op_sel:[1,1,0]
	v_cvt_scalef32_pk_f32_fp4 v[8:9], v149, 1.0
	v_cvt_scalef32_pk_f32_fp4 v[10:11], v149, 1.0 op_sel:[1,0,0]
	v_cvt_scalef32_pk_f32_fp4 v[12:13], v149, 1.0 op_sel:[0,1,0]
	v_cvt_scalef32_pk_f32_fp4 v[14:15], v149, 1.0 op_sel:[1,1,0]
	v_readlane_b32 s54, v90, 2
	s_lshl_b32 s56, s54, 9
	s_add_u32 s56, s64, s56
	s_addc_u32 s57, s65, 0
	global_load_dwordx2 v[148:149], v227, s[56:57]
	s_waitcnt lgkmcnt(1)
	v_pk_fma_f32 v[130:131], v[0:1], v[76:77], v[130:131] op_sel_hi:[1,0,1]
	v_pk_fma_f32 v[138:139], v[2:3], v[76:77], v[138:139] op_sel_hi:[1,0,1]
	v_pk_fma_f32 v[140:141], v[4:5], v[76:77], v[140:141] op_sel_hi:[1,0,1]
	v_pk_fma_f32 v[142:143], v[6:7], v[76:77], v[142:143] op_sel_hi:[1,0,1]
	v_pk_fma_f32 v[128:129], v[8:9], v[76:77], v[128:129] op_sel_hi:[1,0,1]
	v_pk_fma_f32 v[132:133], v[10:11], v[76:77], v[132:133] op_sel_hi:[1,0,1]
	v_pk_fma_f32 v[134:135], v[12:13], v[76:77], v[134:135] op_sel_hi:[1,0,1]
	v_pk_fma_f32 v[136:137], v[14:15], v[76:77], v[136:137] op_sel_hi:[1,0,1]
	ds_read_b32 v76, v193 offset:720
	s_waitcnt vmcnt(15)
	v_cvt_scalef32_pk_f32_fp4 v[0:1], v150, 1.0
	v_cvt_scalef32_pk_f32_fp4 v[2:3], v150, 1.0 op_sel:[1,0,0]
	v_cvt_scalef32_pk_f32_fp4 v[4:5], v150, 1.0 op_sel:[0,1,0]
	v_cvt_scalef32_pk_f32_fp4 v[6:7], v150, 1.0 op_sel:[1,1,0]
	v_cvt_scalef32_pk_f32_fp4 v[8:9], v151, 1.0
	v_cvt_scalef32_pk_f32_fp4 v[10:11], v151, 1.0 op_sel:[1,0,0]
	v_cvt_scalef32_pk_f32_fp4 v[12:13], v151, 1.0 op_sel:[0,1,0]
	v_cvt_scalef32_pk_f32_fp4 v[14:15], v151, 1.0 op_sel:[1,1,0]
	v_readlane_b32 s54, v90, 3
	s_lshl_b32 s56, s54, 9
	s_add_u32 s56, s64, s56
	s_addc_u32 s57, s65, 0
	global_load_dwordx2 v[150:151], v227, s[56:57]
	s_waitcnt lgkmcnt(1)
	v_pk_fma_f32 v[130:131], v[0:1], v[194:195], v[130:131] op_sel_hi:[1,0,1]
	v_pk_fma_f32 v[138:139], v[2:3], v[194:195], v[138:139] op_sel_hi:[1,0,1]
	v_pk_fma_f32 v[140:141], v[4:5], v[194:195], v[140:141] op_sel_hi:[1,0,1]
	v_pk_fma_f32 v[142:143], v[6:7], v[194:195], v[142:143] op_sel_hi:[1,0,1]
	v_pk_fma_f32 v[128:129], v[8:9], v[194:195], v[128:129] op_sel_hi:[1,0,1]
	v_pk_fma_f32 v[132:133], v[10:11], v[194:195], v[132:133] op_sel_hi:[1,0,1]
	v_pk_fma_f32 v[134:135], v[12:13], v[194:195], v[134:135] op_sel_hi:[1,0,1]
	v_pk_fma_f32 v[136:137], v[14:15], v[194:195], v[136:137] op_sel_hi:[1,0,1]
	ds_read_b32 v194, v193 offset:724
	s_waitcnt vmcnt(15)
	v_cvt_scalef32_pk_f32_fp4 v[0:1], v152, 1.0
	v_cvt_scalef32_pk_f32_fp4 v[2:3], v152, 1.0 op_sel:[1,0,0]
	v_cvt_scalef32_pk_f32_fp4 v[4:5], v152, 1.0 op_sel:[0,1,0]
	v_cvt_scalef32_pk_f32_fp4 v[6:7], v152, 1.0 op_sel:[1,1,0]
	v_cvt_scalef32_pk_f32_fp4 v[8:9], v153, 1.0
	v_cvt_scalef32_pk_f32_fp4 v[10:11], v153, 1.0 op_sel:[1,0,0]
	v_cvt_scalef32_pk_f32_fp4 v[12:13], v153, 1.0 op_sel:[0,1,0]
	v_cvt_scalef32_pk_f32_fp4 v[14:15], v153, 1.0 op_sel:[1,1,0]
	v_readlane_b32 s54, v90, 4
	s_lshl_b32 s56, s54, 9
	s_add_u32 s56, s64, s56
	s_addc_u32 s57, s65, 0
	global_load_dwordx2 v[152:153], v227, s[56:57]
	s_waitcnt lgkmcnt(1)
	v_pk_fma_f32 v[130:131], v[0:1], v[76:77], v[130:131] op_sel_hi:[1,0,1]
	v_pk_fma_f32 v[138:139], v[2:3], v[76:77], v[138:139] op_sel_hi:[1,0,1]
	v_pk_fma_f32 v[140:141], v[4:5], v[76:77], v[140:141] op_sel_hi:[1,0,1]
	v_pk_fma_f32 v[142:143], v[6:7], v[76:77], v[142:143] op_sel_hi:[1,0,1]
	v_pk_fma_f32 v[128:129], v[8:9], v[76:77], v[128:129] op_sel_hi:[1,0,1]
	v_pk_fma_f32 v[132:133], v[10:11], v[76:77], v[132:133] op_sel_hi:[1,0,1]
	v_pk_fma_f32 v[134:135], v[12:13], v[76:77], v[134:135] op_sel_hi:[1,0,1]
	v_pk_fma_f32 v[136:137], v[14:15], v[76:77], v[136:137] op_sel_hi:[1,0,1]
	ds_read_b32 v76, v193 offset:728
	s_waitcnt vmcnt(15)
; __device__ void peer_gather_phase(const Params& P, int l, bool do_store) {
;     ...
;         v8[2 * pr] = *(const uint2*)(V + (size_t)ea * 512);
;         v8[2 * pr + 1] = *(const uint2*)(V + (size_t)eb * 512);
;     ...
; #pragma unroll
;       for (int j = 0; j < 8; ++j) {
;         const float a = __builtin_bit_cast(float, __builtin_amdgcn_readlane(__builtin_bit_cast(int, avec), kb + j));
;         const f32x2 aa = f32x2{a, a};
;         y[0] += aa * __builtin_amdgcn_cvt_scalef32_pk_f32_fp4(v8[j].x, 1.0f, 0); y[1] += aa * __builtin_amdgcn_cvt_scalef32_pk_f32_fp4(v8[j].x, 1.0f, 1);
;         y[2] += aa * __builtin_amdgcn_cvt_scalef32_pk_f32_fp4(v8[j].x, 1.0f, 2); y[3] += aa * __builtin_amdgcn_cvt_scalef32_pk_f32_fp4(v8[j].x, 1.0f, 3);
;         y[4] += aa * __builtin_amdgcn_cvt_scalef32_pk_f32_fp4(v8[j].y, 1.0f, 0); y[5] += aa * __builtin_amdgcn_cvt_scalef32_pk_f32_fp4(v8[j].y, 1.0f, 1);
;         y[6] += aa * __builtin_amdgcn_cvt_scalef32_pk_f32_fp4(v8[j].y, 1.0f, 2); y[7] += aa * __builtin_amdgcn_cvt_scalef32_pk_f32_fp4(v8[j].y, 1.0f, 3);
	v_cvt_scalef32_pk_f32_fp4 v[0:1], v154, 1.0
	v_cvt_scalef32_pk_f32_fp4 v[2:3], v154, 1.0 op_sel:[1,0,0]
	v_cvt_scalef32_pk_f32_fp4 v[4:5], v154, 1.0 op_sel:[0,1,0]
	v_cvt_scalef32_pk_f32_fp4 v[6:7], v154, 1.0 op_sel:[1,1,0]
	v_cvt_scalef32_pk_f32_fp4 v[8:9], v155, 1.0
	v_cvt_scalef32_pk_f32_fp4 v[10:11], v155, 1.0 op_sel:[1,0,0]
	v_cvt_scalef32_pk_f32_fp4 v[12:13], v155, 1.0 op_sel:[0,1,0]
	v_cvt_scalef32_pk_f32_fp4 v[14:15], v155, 1.0 op_sel:[1,1,0]
	v_readlane_b32 s54, v90, 5
	s_lshl_b32 s56, s54, 9
	s_add_u32 s56, s64, s56
	s_addc_u32 s57, s65, 0
	global_load_dwordx2 v[154:155], v227, s[56:57]
	s_waitcnt lgkmcnt(1)
	v_pk_fma_f32 v[130:131], v[0:1], v[194:195], v[130:131] op_sel_hi:[1,0,1]
	v_pk_fma_f32 v[138:139], v[2:3], v[194:195], v[138:139] op_sel_hi:[1,0,1]
	v_pk_fma_f32 v[140:141], v[4:5], v[194:195], v[140:141] op_sel_hi:[1,0,1]
	v_pk_fma_f32 v[142:143], v[6:7], v[194:195], v[142:143] op_sel_hi:[1,0,1]
	v_pk_fma_f32 v[128:129], v[8:9], v[194:195], v[128:129] op_sel_hi:[1,0,1]
	v_pk_fma_f32 v[132:133], v[10:11], v[194:195], v[132:133] op_sel_hi:[1,0,1]
	v_pk_fma_f32 v[134:135], v[12:13], v[194:195], v[134:135] op_sel_hi:[1,0,1]
	v_pk_fma_f32 v[136:137], v[14:15], v[194:195], v[136:137] op_sel_hi:[1,0,1]
	ds_read_b32 v194, v193 offset:732
	s_waitcnt vmcnt(15)
	v_cvt_scalef32_pk_f32_fp4 v[0:1], v156, 1.0
	v_cvt_scalef32_pk_f32_fp4 v[2:3], v156, 1.0 op_sel:[1,0,0]
	v_cvt_scalef32_pk_f32_fp4 v[4:5], v156, 1.0 op_sel:[0,1,0]
	v_cvt_scalef32_pk_f32_fp4 v[6:7], v156, 1.0 op_sel:[1,1,0]
	v_cvt_scalef32_pk_f32_fp4 v[8:9], v157, 1.0
	v_cvt_scalef32_pk_f32_fp4 v[10:11], v157, 1.0 op_sel:[1,0,0]
	v_cvt_scalef32_pk_f32_fp4 v[12:13], v157, 1.0 op_sel:[0,1,0]
	v_cvt_scalef32_pk_f32_fp4 v[14:15], v157, 1.0 op_sel:[1,1,0]
	v_readlane_b32 s54, v90, 6
	s_lshl_b32 s56, s54, 9
	s_add_u32 s56, s64, s56
	s_addc_u32 s57, s65, 0
	global_load_dwordx2 v[156:157], v227, s[56:57]
	s_waitcnt lgkmcnt(1)
	v_pk_fma_f32 v[130:131], v[0:1], v[76:77], v[130:131] op_sel_hi:[1,0,1]
	v_pk_fma_f32 v[138:139], v[2:3], v[76:77], v[138:139] op_sel_hi:[1,0,1]
	v_pk_fma_f32 v[140:141], v[4:5], v[76:77], v[140:141] op_sel_hi:[1,0,1]
	v_pk_fma_f32 v[142:143], v[6:7], v[76:77], v[142:143] op_sel_hi:[1,0,1]
	v_pk_fma_f32 v[128:129], v[8:9], v[76:77], v[128:129] op_sel_hi:[1,0,1]
	v_pk_fma_f32 v[132:133], v[10:11], v[76:77], v[132:133] op_sel_hi:[1,0,1]
	v_pk_fma_f32 v[134:135], v[12:13], v[76:77], v[134:135] op_sel_hi:[1,0,1]
	v_pk_fma_f32 v[136:137], v[14:15], v[76:77], v[136:137] op_sel_hi:[1,0,1]
	ds_read_b32 v76, v193 offset:736
	s_waitcnt vmcnt(15)
	v_cvt_scalef32_pk_f32_fp4 v[0:1], v158, 1.0
	v_cvt_scalef32_pk_f32_fp4 v[2:3], v158, 1.0 op_sel:[1,0,0]
	v_cvt_scalef32_pk_f32_fp4 v[4:5], v158, 1.0 op_sel:[0,1,0]
	v_cvt_scalef32_pk_f32_fp4 v[6:7], v158, 1.0 op_sel:[1,1,0]
	v_cvt_scalef32_pk_f32_fp4 v[8:9], v159, 1.0
	v_cvt_scalef32_pk_f32_fp4 v[10:11], v159, 1.0 op_sel:[1,0,0]
	v_cvt_scalef32_pk_f32_fp4 v[12:13], v159, 1.0 op_sel:[0,1,0]
	v_cvt_scalef32_pk_f32_fp4 v[14:15], v159, 1.0 op_sel:[1,1,0]
	v_readlane_b32 s54, v90, 7
	s_lshl_b32 s56, s54, 9
	s_add_u32 s56, s64, s56
	s_addc_u32 s57, s65, 0
	global_load_dwordx2 v[158:159], v227, s[56:57]
	s_waitcnt lgkmcnt(1)
	v_pk_fma_f32 v[130:131], v[0:1], v[194:195], v[130:131] op_sel_hi:[1,0,1]
	v_pk_fma_f32 v[138:139], v[2:3], v[194:195], v[138:139] op_sel_hi:[1,0,1]
	v_pk_fma_f32 v[140:141], v[4:5], v[194:195], v[140:141] op_sel_hi:[1,0,1]
	v_pk_fma_f32 v[142:143], v[6:7], v[194:195], v[142:143] op_sel_hi:[1,0,1]
	v_pk_fma_f32 v[128:129], v[8:9], v[194:195], v[128:129] op_sel_hi:[1,0,1]
	v_pk_fma_f32 v[132:133], v[10:11], v[194:195], v[132:133] op_sel_hi:[1,0,1]
	v_pk_fma_f32 v[134:135], v[12:13], v[194:195], v[134:135] op_sel_hi:[1,0,1]
	v_pk_fma_f32 v[136:137], v[14:15], v[194:195], v[136:137] op_sel_hi:[1,0,1]
	ds_read_b32 v194, v193 offset:740
	s_waitcnt vmcnt(15)
	v_cvt_scalef32_pk_f32_fp4 v[0:1], v168, 1.0
	v_cvt_scalef32_pk_f32_fp4 v[2:3], v168, 1.0 op_sel:[1,0,0]
	v_cvt_scalef32_pk_f32_fp4 v[4:5], v168, 1.0 op_sel:[0,1,0]
	v_cvt_scalef32_pk_f32_fp4 v[6:7], v168, 1.0 op_sel:[1,1,0]
	v_cvt_scalef32_pk_f32_fp4 v[8:9], v169, 1.0
	v_cvt_scalef32_pk_f32_fp4 v[10:11], v169, 1.0 op_sel:[1,0,0]
	v_cvt_scalef32_pk_f32_fp4 v[12:13], v169, 1.0 op_sel:[0,1,0]
	v_cvt_scalef32_pk_f32_fp4 v[14:15], v169, 1.0 op_sel:[1,1,0]
	v_readlane_b32 s54, v90, 8
	s_lshl_b32 s56, s54, 9
	s_add_u32 s56, s64, s56
	s_addc_u32 s57, s65, 0
	global_load_dwordx2 v[168:169], v227, s[56:57]
	s_waitcnt lgkmcnt(1)
	v_pk_fma_f32 v[130:131], v[0:1], v[76:77], v[130:131] op_sel_hi:[1,0,1]
	v_pk_fma_f32 v[138:139], v[2:3], v[76:77], v[138:139] op_sel_hi:[1,0,1]
	v_pk_fma_f32 v[140:141], v[4:5], v[76:77], v[140:141] op_sel_hi:[1,0,1]
	v_pk_fma_f32 v[142:143], v[6:7], v[76:77], v[142:143] op_sel_hi:[1,0,1]
	v_pk_fma_f32 v[128:129], v[8:9], v[76:77], v[128:129] op_sel_hi:[1,0,1]
	v_pk_fma_f32 v[132:133], v[10:11], v[76:77], v[132:133] op_sel_hi:[1,0,1]
	v_pk_fma_f32 v[134:135], v[12:13], v[76:77], v[134:135] op_sel_hi:[1,0,1]
	v_pk_fma_f32 v[136:137], v[14:15], v[76:77], v[136:137] op_sel_hi:[1,0,1]
	ds_read_b32 v76, v193 offset:744
	s_waitcnt vmcnt(15)
	v_cvt_scalef32_pk_f32_fp4 v[0:1], v170, 1.0
	v_cvt_scalef32_pk_f32_fp4 v[2:3], v170, 1.0 op_sel:[1,0,0]
	v_cvt_scalef32_pk_f32_fp4 v[4:5], v170, 1.0 op_sel:[0,1,0]
	v_cvt_scalef32_pk_f32_fp4 v[6:7], v170, 1.0 op_sel:[1,1,0]
	v_cvt_scalef32_pk_f32_fp4 v[8:9], v171, 1.0
	v_cvt_scalef32_pk_f32_fp4 v[10:11], v171, 1.0 op_sel:[1,0,0]
	v_cvt_scalef32_pk_f32_fp4 v[12:13], v171, 1.0 op_sel:[0,1,0]
	v_cvt_scalef32_pk_f32_fp4 v[14:15], v171, 1.0 op_sel:[1,1,0]
	v_readlane_b32 s54, v90, 9
	s_lshl_b32 s56, s54, 9
	s_add_u32 s56, s64, s56
	s_addc_u32 s57, s65, 0
	global_load_dwordx2 v[170:171], v227, s[56:57]
	s_waitcnt lgkmcnt(1)
; __device__ void peer_gather_phase(const Params& P, int l, bool do_store) {
;     ...
;         v8[2 * pr] = *(const uint2*)(V + (size_t)ea * 512);
;         v8[2 * pr + 1] = *(const uint2*)(V + (size_t)eb * 512);
;     ...
; #pragma unroll
;       for (int j = 0; j < 8; ++j) {
;         const float a = __builtin_bit_cast(float, __builtin_amdgcn_readlane(__builtin_bit_cast(int, avec), kb + j));
;         const f32x2 aa = f32x2{a, a};
;         y[0] += aa * __builtin_amdgcn_cvt_scalef32_pk_f32_fp4(v8[j].x, 1.0f, 0); y[1] += aa * __builtin_amdgcn_cvt_scalef32_pk_f32_fp4(v8[j].x, 1.0f, 1);
;         y[2] += aa * __builtin_amdgcn_cvt_scalef32_pk_f32_fp4(v8[j].x, 1.0f, 2); y[3] += aa * __builtin_amdgcn_cvt_scalef32_pk_f32_fp4(v8[j].x, 1.0f, 3);
;         y[4] += aa * __builtin_amdgcn_cvt_scalef32_pk_f32_fp4(v8[j].y, 1.0f, 0); y[5] += aa * __builtin_amdgcn_cvt_scalef32_pk_f32_fp4(v8[j].y, 1.0f, 1);
;         y[6] += aa * __builtin_amdgcn_cvt_scalef32_pk_f32_fp4(v8[j].y, 1.0f, 2); y[7] += aa * __builtin_amdgcn_cvt_scalef32_pk_f32_fp4(v8[j].y, 1.0f, 3);
	v_pk_fma_f32 v[130:131], v[0:1], v[194:195], v[130:131] op_sel_hi:[1,0,1]
	v_pk_fma_f32 v[138:139], v[2:3], v[194:195], v[138:139] op_sel_hi:[1,0,1]
	v_pk_fma_f32 v[140:141], v[4:5], v[194:195], v[140:141] op_sel_hi:[1,0,1]
	v_pk_fma_f32 v[142:143], v[6:7], v[194:195], v[142:143] op_sel_hi:[1,0,1]
	v_pk_fma_f32 v[128:129], v[8:9], v[194:195], v[128:129] op_sel_hi:[1,0,1]
	v_pk_fma_f32 v[132:133], v[10:11], v[194:195], v[132:133] op_sel_hi:[1,0,1]
	v_pk_fma_f32 v[134:135], v[12:13], v[194:195], v[134:135] op_sel_hi:[1,0,1]
	v_pk_fma_f32 v[136:137], v[14:15], v[194:195], v[136:137] op_sel_hi:[1,0,1]
	ds_read_b32 v194, v193 offset:748
	s_waitcnt vmcnt(15)
	v_cvt_scalef32_pk_f32_fp4 v[0:1], v172, 1.0
	v_cvt_scalef32_pk_f32_fp4 v[2:3], v172, 1.0 op_sel:[1,0,0]
	v_cvt_scalef32_pk_f32_fp4 v[4:5], v172, 1.0 op_sel:[0,1,0]
	v_cvt_scalef32_pk_f32_fp4 v[6:7], v172, 1.0 op_sel:[1,1,0]
	v_cvt_scalef32_pk_f32_fp4 v[8:9], v173, 1.0
	v_cvt_scalef32_pk_f32_fp4 v[10:11], v173, 1.0 op_sel:[1,0,0]
	v_cvt_scalef32_pk_f32_fp4 v[12:13], v173, 1.0 op_sel:[0,1,0]
	v_cvt_scalef32_pk_f32_fp4 v[14:15], v173, 1.0 op_sel:[1,1,0]
	v_readlane_b32 s54, v90, 10
	s_lshl_b32 s56, s54, 9
	s_add_u32 s56, s64, s56
	s_addc_u32 s57, s65, 0
	global_load_dwordx2 v[172:173], v227, s[56:57]
	s_waitcnt lgkmcnt(1)
	v_pk_fma_f32 v[130:131], v[0:1], v[76:77], v[130:131] op_sel_hi:[1,0,1]
	v_pk_fma_f32 v[138:139], v[2:3], v[76:77], v[138:139] op_sel_hi:[1,0,1]
	v_pk_fma_f32 v[140:141], v[4:5], v[76:77], v[140:141] op_sel_hi:[1,0,1]
	v_pk_fma_f32 v[142:143], v[6:7], v[76:77], v[142:143] op_sel_hi:[1,0,1]
	v_pk_fma_f32 v[128:129], v[8:9], v[76:77], v[128:129] op_sel_hi:[1,0,1]
	v_pk_fma_f32 v[132:133], v[10:11], v[76:77], v[132:133] op_sel_hi:[1,0,1]
	v_pk_fma_f32 v[134:135], v[12:13], v[76:77], v[134:135] op_sel_hi:[1,0,1]
	v_pk_fma_f32 v[136:137], v[14:15], v[76:77], v[136:137] op_sel_hi:[1,0,1]
	ds_read_b32 v76, v193 offset:752
	s_waitcnt vmcnt(15)
	v_cvt_scalef32_pk_f32_fp4 v[0:1], v174, 1.0
	v_cvt_scalef32_pk_f32_fp4 v[2:3], v174, 1.0 op_sel:[1,0,0]
	v_cvt_scalef32_pk_f32_fp4 v[4:5], v174, 1.0 op_sel:[0,1,0]
	v_cvt_scalef32_pk_f32_fp4 v[6:7], v174, 1.0 op_sel:[1,1,0]
	v_cvt_scalef32_pk_f32_fp4 v[8:9], v175, 1.0
	v_cvt_scalef32_pk_f32_fp4 v[10:11], v175, 1.0 op_sel:[1,0,0]
	v_cvt_scalef32_pk_f32_fp4 v[12:13], v175, 1.0 op_sel:[0,1,0]
	v_cvt_scalef32_pk_f32_fp4 v[14:15], v175, 1.0 op_sel:[1,1,0]
	v_readlane_b32 s54, v90, 11
	s_lshl_b32 s56, s54, 9
	s_add_u32 s56, s64, s56
	s_addc_u32 s57, s65, 0
	global_load_dwordx2 v[174:175], v227, s[56:57]
	s_waitcnt lgkmcnt(1)
	v_pk_fma_f32 v[130:131], v[0:1], v[194:195], v[130:131] op_sel_hi:[1,0,1]
	v_pk_fma_f32 v[138:139], v[2:3], v[194:195], v[138:139] op_sel_hi:[1,0,1]
	v_pk_fma_f32 v[140:141], v[4:5], v[194:195], v[140:141] op_sel_hi:[1,0,1]
	v_pk_fma_f32 v[142:143], v[6:7], v[194:195], v[142:143] op_sel_hi:[1,0,1]
	v_pk_fma_f32 v[128:129], v[8:9], v[194:195], v[128:129] op_sel_hi:[1,0,1]
	v_pk_fma_f32 v[132:133], v[10:11], v[194:195], v[132:133] op_sel_hi:[1,0,1]
	v_pk_fma_f32 v[134:135], v[12:13], v[194:195], v[134:135] op_sel_hi:[1,0,1]
	v_pk_fma_f32 v[136:137], v[14:15], v[194:195], v[136:137] op_sel_hi:[1,0,1]
	ds_read_b32 v194, v193 offset:756
	s_waitcnt vmcnt(15)
	v_cvt_scalef32_pk_f32_fp4 v[0:1], v180, 1.0
	v_cvt_scalef32_pk_f32_fp4 v[2:3], v180, 1.0 op_sel:[1,0,0]
	v_cvt_scalef32_pk_f32_fp4 v[4:5], v180, 1.0 op_sel:[0,1,0]
	v_cvt_scalef32_pk_f32_fp4 v[6:7], v180, 1.0 op_sel:[1,1,0]
	v_cvt_scalef32_pk_f32_fp4 v[8:9], v181, 1.0
	v_cvt_scalef32_pk_f32_fp4 v[10:11], v181, 1.0 op_sel:[1,0,0]
	v_cvt_scalef32_pk_f32_fp4 v[12:13], v181, 1.0 op_sel:[0,1,0]
	v_cvt_scalef32_pk_f32_fp4 v[14:15], v181, 1.0 op_sel:[1,1,0]
	v_readlane_b32 s54, v90, 12
	s_lshl_b32 s56, s54, 9
	s_add_u32 s56, s64, s56
	s_addc_u32 s57, s65, 0
	global_load_dwordx2 v[180:181], v227, s[56:57]
	s_waitcnt lgkmcnt(1)
	v_pk_fma_f32 v[130:131], v[0:1], v[76:77], v[130:131] op_sel_hi:[1,0,1]
	v_pk_fma_f32 v[138:139], v[2:3], v[76:77], v[138:139] op_sel_hi:[1,0,1]
	v_pk_fma_f32 v[140:141], v[4:5], v[76:77], v[140:141] op_sel_hi:[1,0,1]
	v_pk_fma_f32 v[142:143], v[6:7], v[76:77], v[142:143] op_sel_hi:[1,0,1]
	v_pk_fma_f32 v[128:129], v[8:9], v[76:77], v[128:129] op_sel_hi:[1,0,1]
	v_pk_fma_f32 v[132:133], v[10:11], v[76:77], v[132:133] op_sel_hi:[1,0,1]
	v_pk_fma_f32 v[134:135], v[12:13], v[76:77], v[134:135] op_sel_hi:[1,0,1]
	v_pk_fma_f32 v[136:137], v[14:15], v[76:77], v[136:137] op_sel_hi:[1,0,1]
	ds_read_b32 v76, v193 offset:760
	s_waitcnt vmcnt(15)
	v_cvt_scalef32_pk_f32_fp4 v[0:1], v182, 1.0
	v_cvt_scalef32_pk_f32_fp4 v[2:3], v182, 1.0 op_sel:[1,0,0]
	v_cvt_scalef32_pk_f32_fp4 v[4:5], v182, 1.0 op_sel:[0,1,0]
	v_cvt_scalef32_pk_f32_fp4 v[6:7], v182, 1.0 op_sel:[1,1,0]
	v_cvt_scalef32_pk_f32_fp4 v[8:9], v183, 1.0
	v_cvt_scalef32_pk_f32_fp4 v[10:11], v183, 1.0 op_sel:[1,0,0]
	v_cvt_scalef32_pk_f32_fp4 v[12:13], v183, 1.0 op_sel:[0,1,0]
	v_cvt_scalef32_pk_f32_fp4 v[14:15], v183, 1.0 op_sel:[1,1,0]
	v_readlane_b32 s54, v90, 13
	s_lshl_b32 s56, s54, 9
	s_add_u32 s56, s64, s56
	s_addc_u32 s57, s65, 0
	global_load_dwordx2 v[182:183], v227, s[56:57]
	s_waitcnt lgkmcnt(1)
	v_pk_fma_f32 v[130:131], v[0:1], v[194:195], v[130:131] op_sel_hi:[1,0,1]
	v_pk_fma_f32 v[138:139], v[2:3], v[194:195], v[138:139] op_sel_hi:[1,0,1]
	v_pk_fma_f32 v[140:141], v[4:5], v[194:195], v[140:141] op_sel_hi:[1,0,1]
	v_pk_fma_f32 v[142:143], v[6:7], v[194:195], v[142:143] op_sel_hi:[1,0,1]
	v_pk_fma_f32 v[128:129], v[8:9], v[194:195], v[128:129] op_sel_hi:[1,0,1]
	v_pk_fma_f32 v[132:133], v[10:11], v[194:195], v[132:133] op_sel_hi:[1,0,1]
	v_pk_fma_f32 v[134:135], v[12:13], v[194:195], v[134:135] op_sel_hi:[1,0,1]
	v_pk_fma_f32 v[136:137], v[14:15], v[194:195], v[136:137] op_sel_hi:[1,0,1]
	ds_read_b32 v194, v193 offset:764
	s_waitcnt vmcnt(15)
; __device__ void peer_gather_phase(const Params& P, int l, bool do_store) {
;     ...
;       for (int pr = 0; pr < 4; ++pr) {
;         v6u_t qv; qv[0] = u6[3 * pr].x; qv[1] = u6[3 * pr].y; qv[2] = u6[3 * pr + 1].x; qv[3] = u6[3 * pr + 1].y; qv[4] = u6[3 * pr + 2].x; qv[5] = u6[3 * pr + 2].y;
;         const v32f_t wv = __builtin_amdgcn_cvt_scalef32_pk32_f32_fp6(qv, 1.0f);
;         f32x2 a2 = f32x2{0.f, 0.f};
; #pragma unroll
;         for (int i = 0; i < 16; ++i) a2 += f32x2{wv[2 * i], wv[2 * i + 1]} * xu[i];
;         float hs = a2.x + a2.y;
;         hs += dpp_row_shr(hs, 1); hs += dpp_row_shr(hs, 2); hs += dpp_row_shr(hs, 4); hs += dpp_row_shr(hs, 8);
;         hs += __builtin_bit_cast(float, __builtin_amdgcn_update_dpp(0, __builtin_bit_cast(int, hs), 0x142, 0xa, 0xf, false));
;         const float da = __builtin_bit_cast(float, __builtin_amdgcn_readlane(__builtin_bit_cast(int, hs), 31));
;         const float db = __builtin_bit_cast(float, __builtin_amdgcn_readlane(__builtin_bit_cast(int, hs), 63));
;     ...
; #pragma unroll
;       for (int j = 0; j < 8; ++j) {
;         const float a = __builtin_bit_cast(float, __builtin_amdgcn_readlane(__builtin_bit_cast(int, avec), kb + j));
;         const f32x2 aa = f32x2{a, a};
;         y[0] += aa * __builtin_amdgcn_cvt_scalef32_pk_f32_fp4(v8[j].x, 1.0f, 0); y[1] += aa * __builtin_amdgcn_cvt_scalef32_pk_f32_fp4(v8[j].x, 1.0f, 1);
;         y[2] += aa * __builtin_amdgcn_cvt_scalef32_pk_f32_fp4(v8[j].x, 1.0f, 2); y[3] += aa * __builtin_amdgcn_cvt_scalef32_pk_f32_fp4(v8[j].x, 1.0f, 3);
;         y[4] += aa * __builtin_amdgcn_cvt_scalef32_pk_f32_fp4(v8[j].y, 1.0f, 0); y[5] += aa * __builtin_amdgcn_cvt_scalef32_pk_f32_fp4(v8[j].y, 1.0f, 1);
;         y[6] += aa * __builtin_amdgcn_cvt_scalef32_pk_f32_fp4(v8[j].y, 1.0f, 2); y[7] += aa * __builtin_amdgcn_cvt_scalef32_pk_f32_fp4(v8[j].y, 1.0f, 3);
	v_cvt_scalef32_pk_f32_fp4 v[0:1], v184, 1.0
	v_cvt_scalef32_pk_f32_fp4 v[2:3], v184, 1.0 op_sel:[1,0,0]
	v_cvt_scalef32_pk_f32_fp4 v[4:5], v184, 1.0 op_sel:[0,1,0]
	v_cvt_scalef32_pk_f32_fp4 v[6:7], v184, 1.0 op_sel:[1,1,0]
	v_cvt_scalef32_pk_f32_fp4 v[8:9], v185, 1.0
	v_cvt_scalef32_pk_f32_fp4 v[10:11], v185, 1.0 op_sel:[1,0,0]
	v_cvt_scalef32_pk_f32_fp4 v[12:13], v185, 1.0 op_sel:[0,1,0]
	v_cvt_scalef32_pk_f32_fp4 v[14:15], v185, 1.0 op_sel:[1,1,0]
	v_readlane_b32 s54, v90, 14
	s_lshl_b32 s56, s54, 9
	s_add_u32 s56, s64, s56
	s_addc_u32 s57, s65, 0
	global_load_dwordx2 v[184:185], v227, s[56:57]
	s_waitcnt lgkmcnt(1)
	v_pk_fma_f32 v[130:131], v[0:1], v[76:77], v[130:131] op_sel_hi:[1,0,1]
	v_pk_fma_f32 v[138:139], v[2:3], v[76:77], v[138:139] op_sel_hi:[1,0,1]
	v_pk_fma_f32 v[140:141], v[4:5], v[76:77], v[140:141] op_sel_hi:[1,0,1]
	v_pk_fma_f32 v[142:143], v[6:7], v[76:77], v[142:143] op_sel_hi:[1,0,1]
	v_pk_fma_f32 v[128:129], v[8:9], v[76:77], v[128:129] op_sel_hi:[1,0,1]
	v_pk_fma_f32 v[132:133], v[10:11], v[76:77], v[132:133] op_sel_hi:[1,0,1]
	v_pk_fma_f32 v[134:135], v[12:13], v[76:77], v[134:135] op_sel_hi:[1,0,1]
	v_pk_fma_f32 v[136:137], v[14:15], v[76:77], v[136:137] op_sel_hi:[1,0,1]
	s_waitcnt vmcnt(15)
	v_cvt_scalef32_pk_f32_fp4 v[0:1], v186, 1.0
	v_cvt_scalef32_pk_f32_fp4 v[2:3], v186, 1.0 op_sel:[1,0,0]
	v_cvt_scalef32_pk_f32_fp4 v[4:5], v186, 1.0 op_sel:[0,1,0]
	v_cvt_scalef32_pk_f32_fp4 v[6:7], v186, 1.0 op_sel:[1,1,0]
	v_cvt_scalef32_pk_f32_fp4 v[8:9], v187, 1.0
	v_cvt_scalef32_pk_f32_fp4 v[10:11], v187, 1.0 op_sel:[1,0,0]
	v_cvt_scalef32_pk_f32_fp4 v[12:13], v187, 1.0 op_sel:[0,1,0]
	v_cvt_scalef32_pk_f32_fp4 v[14:15], v187, 1.0 op_sel:[1,1,0]
	v_readlane_b32 s54, v90, 15
	s_lshl_b32 s56, s54, 9
	s_add_u32 s56, s64, s56
	s_addc_u32 s57, s65, 0
	global_load_dwordx2 v[186:187], v227, s[56:57]
	s_waitcnt lgkmcnt(0)
	v_pk_fma_f32 v[130:131], v[0:1], v[194:195], v[130:131] op_sel_hi:[1,0,1]
	v_pk_fma_f32 v[138:139], v[2:3], v[194:195], v[138:139] op_sel_hi:[1,0,1]
	v_pk_fma_f32 v[140:141], v[4:5], v[194:195], v[140:141] op_sel_hi:[1,0,1]
	v_pk_fma_f32 v[142:143], v[6:7], v[194:195], v[142:143] op_sel_hi:[1,0,1]
	v_pk_fma_f32 v[128:129], v[8:9], v[194:195], v[128:129] op_sel_hi:[1,0,1]
	v_pk_fma_f32 v[132:133], v[10:11], v[194:195], v[132:133] op_sel_hi:[1,0,1]
	v_pk_fma_f32 v[134:135], v[12:13], v[194:195], v[134:135] op_sel_hi:[1,0,1]
	v_pk_fma_f32 v[136:137], v[14:15], v[194:195], v[136:137] op_sel_hi:[1,0,1]
	ds_read_b32 v76, v74 offset:320
	s_waitcnt lgkmcnt(0)
	v_mad_u32_u24 v167, v76, s33, v195
	ds_read_b32 v77, v74 offset:328
	s_waitcnt vmcnt(48)
	v_cvt_scalef32_pk32_f32_fp6 v[0:31], v[50:55], 1.0
	global_load_dwordx2 v[54:55], v167, s[62:63] offset:16
	global_load_dwordx4 v[50:53], v167, s[62:63]
	v_pk_mul_f32 v[246:247], v[0:1], v[96:97]
	v_pk_mul_f32 v[254:255], v[2:3], v[98:99]
	v_pk_mul_f32 v[160:161], v[4:5], v[100:101]
	v_pk_fma_f32 v[246:247], v[6:7], v[102:103], v[246:247]
	v_pk_fma_f32 v[254:255], v[8:9], v[104:105], v[254:255]
	v_pk_fma_f32 v[160:161], v[10:11], v[106:107], v[160:161]
	v_pk_fma_f32 v[246:247], v[12:13], v[108:109], v[246:247]
	v_pk_fma_f32 v[254:255], v[14:15], v[110:111], v[254:255]
	v_pk_fma_f32 v[160:161], v[16:17], v[112:113], v[160:161]
	v_pk_fma_f32 v[246:247], v[18:19], v[114:115], v[246:247]
	v_pk_fma_f32 v[254:255], v[20:21], v[116:117], v[254:255]
	v_pk_fma_f32 v[160:161], v[22:23], v[118:119], v[160:161]
	v_pk_fma_f32 v[246:247], v[24:25], v[120:121], v[246:247]
	v_pk_fma_f32 v[254:255], v[26:27], v[122:123], v[254:255]
	v_pk_fma_f32 v[160:161], v[28:29], v[124:125], v[160:161]
	v_pk_fma_f32 v[246:247], v[30:31], v[126:127], v[246:247]
	v_pk_add_f32 v[254:255], v[254:255], v[160:161]
	s_nop 0
	v_pk_add_f32 v[246:247], v[246:247], v[254:255]
	s_nop 0
	v_add_f32_e32 v162, v246, v247
	s_waitcnt lgkmcnt(0)
	v_mad_u32_u24 v167, v77, s33, v195
	ds_read_b32 v76, v74 offset:336
	s_waitcnt vmcnt(48)
	v_cvt_scalef32_pk32_f32_fp6 v[0:31], v[44:49], 1.0
	global_load_dwordx2 v[48:49], v167, s[62:63] offset:16
	global_load_dwordx4 v[44:47], v167, s[62:63]
	v_pk_mul_f32 v[246:247], v[0:1], v[96:97]
	v_pk_mul_f32 v[254:255], v[2:3], v[98:99]
	v_pk_mul_f32 v[160:161], v[4:5], v[100:101]
	v_pk_fma_f32 v[246:247], v[6:7], v[102:103], v[246:247]
	v_pk_fma_f32 v[254:255], v[8:9], v[104:105], v[254:255]
	v_pk_fma_f32 v[160:161], v[10:11], v[106:107], v[160:161]
	v_pk_fma_f32 v[246:247], v[12:13], v[108:109], v[246:247]
	v_pk_fma_f32 v[254:255], v[14:15], v[110:111], v[254:255]
	v_pk_fma_f32 v[160:161], v[16:17], v[112:113], v[160:161]
	v_pk_fma_f32 v[246:247], v[18:19], v[114:115], v[246:247]
	v_pk_fma_f32 v[254:255], v[20:21], v[116:117], v[254:255]
	v_pk_fma_f32 v[160:161], v[22:23], v[118:119], v[160:161]
	v_pk_fma_f32 v[246:247], v[24:25], v[120:121], v[246:247]
	v_pk_fma_f32 v[254:255], v[26:27], v[122:123], v[254:255]
	v_pk_fma_f32 v[160:161], v[28:29], v[124:125], v[160:161]
	v_pk_fma_f32 v[246:247], v[30:31], v[126:127], v[246:247]
	v_pk_add_f32 v[254:255], v[254:255], v[160:161]
	s_nop 0
	v_pk_add_f32 v[246:247], v[246:247], v[254:255]
	s_nop 0
	v_add_f32_e32 v163, v246, v247
	s_waitcnt lgkmcnt(0)
	v_mad_u32_u24 v167, v76, s33, v195
	ds_read_b32 v77, v74 offset:344
	s_waitcnt vmcnt(48)
; __device__ void peer_gather_phase(const Params& P, int l, bool do_store) {
;     ...
;         const int ea = __builtin_amdgcn_readlane(evs, kb + 2 * pr), eb = __builtin_amdgcn_readlane(evs, kb + 2 * pr + 1);
;         const uint2* up = (const uint2*)(U + (size_t)(uphi ? eb : ea) * 768);
;         u6[3 * pr] = up[0]; u6[3 * pr + 1] = up[1]; u6[3 * pr + 2] = up[2];
;         v8[2 * pr] = *(const uint2*)(V + (size_t)ea * 512);
;         v8[2 * pr + 1] = *(const uint2*)(V + (size_t)eb * 512);
;       }
;     };
;     auto compute_batch = [&](const uint2 (&u6)[12], const uint2 (&v8)[8], int bt) {
;       const int kb = (bt & 7) * 8;
;       float dvec = 0.f;
; #pragma unroll
;       for (int pr = 0; pr < 4; ++pr) {
;         v6u_t qv; qv[0] = u6[3 * pr].x; qv[1] = u6[3 * pr].y; qv[2] = u6[3 * pr + 1].x; qv[3] = u6[3 * pr + 1].y; qv[4] = u6[3 * pr + 2].x; qv[5] = u6[3 * pr + 2].y;
;         const v32f_t wv = __builtin_amdgcn_cvt_scalef32_pk32_f32_fp6(qv, 1.0f);
;         f32x2 a2 = f32x2{0.f, 0.f};
; #pragma unroll
;         for (int i = 0; i < 16; ++i) a2 += f32x2{wv[2 * i], wv[2 * i + 1]} * xu[i];
;         float hs = a2.x + a2.y;
;         hs += dpp_row_shr(hs, 1); hs += dpp_row_shr(hs, 2); hs += dpp_row_shr(hs, 4); hs += dpp_row_shr(hs, 8);
;         hs += __builtin_bit_cast(float, __builtin_amdgcn_update_dpp(0, __builtin_bit_cast(int, hs), 0x142, 0xa, 0xf, false));
;         const float da = __builtin_bit_cast(float, __builtin_amdgcn_readlane(__builtin_bit_cast(int, hs), 31));
;         const float db = __builtin_bit_cast(float, __builtin_amdgcn_readlane(__builtin_bit_cast(int, hs), 63));
	v_cvt_scalef32_pk32_f32_fp6 v[0:31], v[38:43], 1.0
	global_load_dwordx2 v[42:43], v167, s[62:63] offset:16
	global_load_dwordx4 v[38:41], v167, s[62:63]
	v_pk_mul_f32 v[246:247], v[0:1], v[96:97]
	v_pk_mul_f32 v[254:255], v[2:3], v[98:99]
	v_pk_mul_f32 v[160:161], v[4:5], v[100:101]
	v_pk_fma_f32 v[246:247], v[6:7], v[102:103], v[246:247]
	v_pk_fma_f32 v[254:255], v[8:9], v[104:105], v[254:255]
	v_pk_fma_f32 v[160:161], v[10:11], v[106:107], v[160:161]
	v_pk_fma_f32 v[246:247], v[12:13], v[108:109], v[246:247]
	v_pk_fma_f32 v[254:255], v[14:15], v[110:111], v[254:255]
	v_pk_fma_f32 v[160:161], v[16:17], v[112:113], v[160:161]
	v_pk_fma_f32 v[246:247], v[18:19], v[114:115], v[246:247]
	v_pk_fma_f32 v[254:255], v[20:21], v[116:117], v[254:255]
	v_pk_fma_f32 v[160:161], v[22:23], v[118:119], v[160:161]
	v_pk_fma_f32 v[246:247], v[24:25], v[120:121], v[246:247]
	v_pk_fma_f32 v[254:255], v[26:27], v[122:123], v[254:255]
	v_pk_fma_f32 v[160:161], v[28:29], v[124:125], v[160:161]
	v_pk_fma_f32 v[246:247], v[30:31], v[126:127], v[246:247]
	v_pk_add_f32 v[254:255], v[254:255], v[160:161]
	s_nop 0
	v_pk_add_f32 v[246:247], v[246:247], v[254:255]
	s_nop 0
	v_add_f32_e32 v164, v246, v247
	s_waitcnt lgkmcnt(0)
	v_mad_u32_u24 v167, v77, s33, v195
	ds_read_b32 v76, v74 offset:352
	s_waitcnt vmcnt(48)
	v_cvt_scalef32_pk32_f32_fp6 v[0:31], v[32:37], 1.0
	global_load_dwordx2 v[36:37], v167, s[62:63] offset:16
	global_load_dwordx4 v[32:35], v167, s[62:63]
	v_pk_mul_f32 v[246:247], v[0:1], v[96:97]
	v_pk_mul_f32 v[254:255], v[2:3], v[98:99]
	v_pk_mul_f32 v[160:161], v[4:5], v[100:101]
	v_pk_fma_f32 v[246:247], v[6:7], v[102:103], v[246:247]
	v_pk_fma_f32 v[254:255], v[8:9], v[104:105], v[254:255]
	v_pk_fma_f32 v[160:161], v[10:11], v[106:107], v[160:161]
	v_pk_fma_f32 v[246:247], v[12:13], v[108:109], v[246:247]
	v_pk_fma_f32 v[254:255], v[14:15], v[110:111], v[254:255]
	v_pk_fma_f32 v[160:161], v[16:17], v[112:113], v[160:161]
	v_pk_fma_f32 v[246:247], v[18:19], v[114:115], v[246:247]
	v_pk_fma_f32 v[254:255], v[20:21], v[116:117], v[254:255]
	v_pk_fma_f32 v[160:161], v[22:23], v[118:119], v[160:161]
	v_pk_fma_f32 v[246:247], v[24:25], v[120:121], v[246:247]
	v_pk_fma_f32 v[254:255], v[26:27], v[122:123], v[254:255]
	v_pk_fma_f32 v[160:161], v[28:29], v[124:125], v[160:161]
	v_pk_fma_f32 v[246:247], v[30:31], v[126:127], v[246:247]
	v_pk_add_f32 v[254:255], v[254:255], v[160:161]
	s_nop 0
	v_pk_add_f32 v[246:247], v[246:247], v[254:255]
	s_nop 0
	v_add_f32_e32 v165, v246, v247
	v_add_f32_dpp v162, v162, v162 row_shr:1 row_mask:0xf bank_mask:0xf bound_ctrl:1
	v_add_f32_dpp v163, v163, v163 row_shr:1 row_mask:0xf bank_mask:0xf bound_ctrl:1
	v_add_f32_dpp v164, v164, v164 row_shr:1 row_mask:0xf bank_mask:0xf bound_ctrl:1
	v_add_f32_dpp v165, v165, v165 row_shr:1 row_mask:0xf bank_mask:0xf bound_ctrl:1
	v_add_f32_dpp v162, v162, v162 row_shr:2 row_mask:0xf bank_mask:0xf bound_ctrl:1
	v_add_f32_dpp v163, v163, v163 row_shr:2 row_mask:0xf bank_mask:0xf bound_ctrl:1
	v_add_f32_dpp v164, v164, v164 row_shr:2 row_mask:0xf bank_mask:0xf bound_ctrl:1
	v_add_f32_dpp v165, v165, v165 row_shr:2 row_mask:0xf bank_mask:0xf bound_ctrl:1
	v_add_f32_dpp v162, v162, v162 row_shr:4 row_mask:0xf bank_mask:0xf bound_ctrl:1
	v_add_f32_dpp v163, v163, v163 row_shr:4 row_mask:0xf bank_mask:0xf bound_ctrl:1
	v_add_f32_dpp v164, v164, v164 row_shr:4 row_mask:0xf bank_mask:0xf bound_ctrl:1
	v_add_f32_dpp v165, v165, v165 row_shr:4 row_mask:0xf bank_mask:0xf bound_ctrl:1
	v_add_f32_dpp v162, v162, v162 row_shr:8 row_mask:0xf bank_mask:0xf bound_ctrl:1
	v_add_f32_dpp v163, v163, v163 row_shr:8 row_mask:0xf bank_mask:0xf bound_ctrl:1
	v_add_f32_dpp v164, v164, v164 row_shr:8 row_mask:0xf bank_mask:0xf bound_ctrl:1
	v_add_f32_dpp v165, v165, v165 row_shr:8 row_mask:0xf bank_mask:0xf bound_ctrl:1
	v_add_f32_dpp v162, v162, v162 row_bcast:15 row_mask:0xa bank_mask:0xf
	v_add_f32_dpp v163, v163, v163 row_bcast:15 row_mask:0xa bank_mask:0xf
	v_add_f32_dpp v164, v164, v164 row_bcast:15 row_mask:0xa bank_mask:0xf
	v_add_f32_dpp v165, v165, v165 row_bcast:15 row_mask:0xa bank_mask:0xf
	s_mov_b64 s[98:99], exec
	s_mov_b32 exec_lo, 0x80000000
	s_mov_b32 exec_hi, 0x80000000
	ds_write_b32 v74, v162
	ds_write_b32 v74, v163 offset:8
	ds_write_b32 v74, v164 offset:16
	ds_write_b32 v74, v165 offset:24
	s_mov_b64 exec, s[98:99]
	s_waitcnt lgkmcnt(0)
	v_mad_u32_u24 v167, v76, s33, v195
	ds_read_b32 v77, v74 offset:360
	s_waitcnt vmcnt(48)
	v_cvt_scalef32_pk32_f32_fp6 v[0:31], v[196:201], 1.0
	global_load_dwordx2 v[200:201], v167, s[62:63] offset:16
	global_load_dwordx4 v[196:199], v167, s[62:63]
	v_pk_mul_f32 v[246:247], v[0:1], v[96:97]
	v_pk_mul_f32 v[254:255], v[2:3], v[98:99]
	v_pk_mul_f32 v[160:161], v[4:5], v[100:101]
	v_pk_fma_f32 v[246:247], v[6:7], v[102:103], v[246:247]
	v_pk_fma_f32 v[254:255], v[8:9], v[104:105], v[254:255]
	v_pk_fma_f32 v[160:161], v[10:11], v[106:107], v[160:161]
	v_pk_fma_f32 v[246:247], v[12:13], v[108:109], v[246:247]
	v_pk_fma_f32 v[254:255], v[14:15], v[110:111], v[254:255]
	v_pk_fma_f32 v[160:161], v[16:17], v[112:113], v[160:161]
	v_pk_fma_f32 v[246:247], v[18:19], v[114:115], v[246:247]
	v_pk_fma_f32 v[254:255], v[20:21], v[116:117], v[254:255]
	v_pk_fma_f32 v[160:161], v[22:23], v[118:119], v[160:161]
	v_pk_fma_f32 v[246:247], v[24:25], v[120:121], v[246:247]
	v_pk_fma_f32 v[254:255], v[26:27], v[122:123], v[254:255]
	v_pk_fma_f32 v[160:161], v[28:29], v[124:125], v[160:161]
	v_pk_fma_f32 v[246:247], v[30:31], v[126:127], v[246:247]
	v_pk_add_f32 v[254:255], v[254:255], v[160:161]
	s_nop 0
	v_pk_add_f32 v[246:247], v[246:247], v[254:255]
	s_nop 0
	v_add_f32_e32 v162, v246, v247
	s_waitcnt lgkmcnt(0)
; __device__ void peer_gather_phase(const Params& P, int l, bool do_store) {
;     ...
;         const int ea = __builtin_amdgcn_readlane(evs, kb + 2 * pr), eb = __builtin_amdgcn_readlane(evs, kb + 2 * pr + 1);
;         const uint2* up = (const uint2*)(U + (size_t)(uphi ? eb : ea) * 768);
;         u6[3 * pr] = up[0]; u6[3 * pr + 1] = up[1]; u6[3 * pr + 2] = up[2];
;         v8[2 * pr] = *(const uint2*)(V + (size_t)ea * 512);
;         v8[2 * pr + 1] = *(const uint2*)(V + (size_t)eb * 512);
;       }
;     };
;     auto compute_batch = [&](const uint2 (&u6)[12], const uint2 (&v8)[8], int bt) {
;       const int kb = (bt & 7) * 8;
;       float dvec = 0.f;
; #pragma unroll
;       for (int pr = 0; pr < 4; ++pr) {
;         v6u_t qv; qv[0] = u6[3 * pr].x; qv[1] = u6[3 * pr].y; qv[2] = u6[3 * pr + 1].x; qv[3] = u6[3 * pr + 1].y; qv[4] = u6[3 * pr + 2].x; qv[5] = u6[3 * pr + 2].y;
;         const v32f_t wv = __builtin_amdgcn_cvt_scalef32_pk32_f32_fp6(qv, 1.0f);
;         f32x2 a2 = f32x2{0.f, 0.f};
; #pragma unroll
;         for (int i = 0; i < 16; ++i) a2 += f32x2{wv[2 * i], wv[2 * i + 1]} * xu[i];
;         float hs = a2.x + a2.y;
;         hs += dpp_row_shr(hs, 1); hs += dpp_row_shr(hs, 2); hs += dpp_row_shr(hs, 4); hs += dpp_row_shr(hs, 8);
;         hs += __builtin_bit_cast(float, __builtin_amdgcn_update_dpp(0, __builtin_bit_cast(int, hs), 0x142, 0xa, 0xf, false));
;         const float da = __builtin_bit_cast(float, __builtin_amdgcn_readlane(__builtin_bit_cast(int, hs), 31));
;         const float db = __builtin_bit_cast(float, __builtin_amdgcn_readlane(__builtin_bit_cast(int, hs), 63));
	v_mad_u32_u24 v167, v77, s33, v195
	ds_read_b32 v76, v74 offset:368
	s_waitcnt vmcnt(48)
	v_cvt_scalef32_pk32_f32_fp6 v[0:31], v[228:233], 1.0
	global_load_dwordx2 v[232:233], v167, s[62:63] offset:16
	global_load_dwordx4 v[228:231], v167, s[62:63]
	v_pk_mul_f32 v[246:247], v[0:1], v[96:97]
	v_pk_mul_f32 v[254:255], v[2:3], v[98:99]
	v_pk_mul_f32 v[160:161], v[4:5], v[100:101]
	v_pk_fma_f32 v[246:247], v[6:7], v[102:103], v[246:247]
	v_pk_fma_f32 v[254:255], v[8:9], v[104:105], v[254:255]
	v_pk_fma_f32 v[160:161], v[10:11], v[106:107], v[160:161]
	v_pk_fma_f32 v[246:247], v[12:13], v[108:109], v[246:247]
	v_pk_fma_f32 v[254:255], v[14:15], v[110:111], v[254:255]
	v_pk_fma_f32 v[160:161], v[16:17], v[112:113], v[160:161]
	v_pk_fma_f32 v[246:247], v[18:19], v[114:115], v[246:247]
	v_pk_fma_f32 v[254:255], v[20:21], v[116:117], v[254:255]
	v_pk_fma_f32 v[160:161], v[22:23], v[118:119], v[160:161]
	v_pk_fma_f32 v[246:247], v[24:25], v[120:121], v[246:247]
	v_pk_fma_f32 v[254:255], v[26:27], v[122:123], v[254:255]
	v_pk_fma_f32 v[160:161], v[28:29], v[124:125], v[160:161]
	v_pk_fma_f32 v[246:247], v[30:31], v[126:127], v[246:247]
	v_pk_add_f32 v[254:255], v[254:255], v[160:161]
	s_nop 0
	v_pk_add_f32 v[246:247], v[246:247], v[254:255]
	s_nop 0
	v_add_f32_e32 v163, v246, v247
	s_waitcnt lgkmcnt(0)
	v_mad_u32_u24 v167, v76, s33, v195
	ds_read_b32 v77, v74 offset:376
	s_waitcnt vmcnt(48)
	v_cvt_scalef32_pk32_f32_fp6 v[0:31], v[234:239], 1.0
	global_load_dwordx2 v[238:239], v167, s[62:63] offset:16
	global_load_dwordx4 v[234:237], v167, s[62:63]
	v_pk_mul_f32 v[246:247], v[0:1], v[96:97]
	v_pk_mul_f32 v[254:255], v[2:3], v[98:99]
	v_pk_mul_f32 v[160:161], v[4:5], v[100:101]
	v_pk_fma_f32 v[246:247], v[6:7], v[102:103], v[246:247]
	v_pk_fma_f32 v[254:255], v[8:9], v[104:105], v[254:255]
	v_pk_fma_f32 v[160:161], v[10:11], v[106:107], v[160:161]
	v_pk_fma_f32 v[246:247], v[12:13], v[108:109], v[246:247]
	v_pk_fma_f32 v[254:255], v[14:15], v[110:111], v[254:255]
	v_pk_fma_f32 v[160:161], v[16:17], v[112:113], v[160:161]
	v_pk_fma_f32 v[246:247], v[18:19], v[114:115], v[246:247]
	v_pk_fma_f32 v[254:255], v[20:21], v[116:117], v[254:255]
	v_pk_fma_f32 v[160:161], v[22:23], v[118:119], v[160:161]
	v_pk_fma_f32 v[246:247], v[24:25], v[120:121], v[246:247]
	v_pk_fma_f32 v[254:255], v[26:27], v[122:123], v[254:255]
	v_pk_fma_f32 v[160:161], v[28:29], v[124:125], v[160:161]
	v_pk_fma_f32 v[246:247], v[30:31], v[126:127], v[246:247]
	v_pk_add_f32 v[254:255], v[254:255], v[160:161]
	s_nop 0
	v_pk_add_f32 v[246:247], v[246:247], v[254:255]
	s_nop 0
	v_add_f32_e32 v164, v246, v247
	s_waitcnt lgkmcnt(0)
	v_mad_u32_u24 v167, v77, s33, v195
	ds_read_b32 v76, v74 offset:384
	s_waitcnt vmcnt(48)
	v_cvt_scalef32_pk32_f32_fp6 v[0:31], v[240:245], 1.0
	global_load_dwordx2 v[244:245], v167, s[62:63] offset:16
	global_load_dwordx4 v[240:243], v167, s[62:63]
	v_pk_mul_f32 v[246:247], v[0:1], v[96:97]
	v_pk_mul_f32 v[254:255], v[2:3], v[98:99]
	v_pk_mul_f32 v[160:161], v[4:5], v[100:101]
	v_pk_fma_f32 v[246:247], v[6:7], v[102:103], v[246:247]
	v_pk_fma_f32 v[254:255], v[8:9], v[104:105], v[254:255]
	v_pk_fma_f32 v[160:161], v[10:11], v[106:107], v[160:161]
	v_pk_fma_f32 v[246:247], v[12:13], v[108:109], v[246:247]
	v_pk_fma_f32 v[254:255], v[14:15], v[110:111], v[254:255]
	v_pk_fma_f32 v[160:161], v[16:17], v[112:113], v[160:161]
	v_pk_fma_f32 v[246:247], v[18:19], v[114:115], v[246:247]
	v_pk_fma_f32 v[254:255], v[20:21], v[116:117], v[254:255]
	v_pk_fma_f32 v[160:161], v[22:23], v[118:119], v[160:161]
	v_pk_fma_f32 v[246:247], v[24:25], v[120:121], v[246:247]
	v_pk_fma_f32 v[254:255], v[26:27], v[122:123], v[254:255]
	v_pk_fma_f32 v[160:161], v[28:29], v[124:125], v[160:161]
	v_pk_fma_f32 v[246:247], v[30:31], v[126:127], v[246:247]
	v_pk_add_f32 v[254:255], v[254:255], v[160:161]
	s_nop 0
	v_pk_add_f32 v[246:247], v[246:247], v[254:255]
	s_nop 0
	v_add_f32_e32 v165, v246, v247
	v_add_f32_dpp v162, v162, v162 row_shr:1 row_mask:0xf bank_mask:0xf bound_ctrl:1
	v_add_f32_dpp v163, v163, v163 row_shr:1 row_mask:0xf bank_mask:0xf bound_ctrl:1
	v_add_f32_dpp v164, v164, v164 row_shr:1 row_mask:0xf bank_mask:0xf bound_ctrl:1
	v_add_f32_dpp v165, v165, v165 row_shr:1 row_mask:0xf bank_mask:0xf bound_ctrl:1
	v_add_f32_dpp v162, v162, v162 row_shr:2 row_mask:0xf bank_mask:0xf bound_ctrl:1
	v_add_f32_dpp v163, v163, v163 row_shr:2 row_mask:0xf bank_mask:0xf bound_ctrl:1
	v_add_f32_dpp v164, v164, v164 row_shr:2 row_mask:0xf bank_mask:0xf bound_ctrl:1
	v_add_f32_dpp v165, v165, v165 row_shr:2 row_mask:0xf bank_mask:0xf bound_ctrl:1
	v_add_f32_dpp v162, v162, v162 row_shr:4 row_mask:0xf bank_mask:0xf bound_ctrl:1
	v_add_f32_dpp v163, v163, v163 row_shr:4 row_mask:0xf bank_mask:0xf bound_ctrl:1
	v_add_f32_dpp v164, v164, v164 row_shr:4 row_mask:0xf bank_mask:0xf bound_ctrl:1
	v_add_f32_dpp v165, v165, v165 row_shr:4 row_mask:0xf bank_mask:0xf bound_ctrl:1
	v_add_f32_dpp v162, v162, v162 row_shr:8 row_mask:0xf bank_mask:0xf bound_ctrl:1
	v_add_f32_dpp v163, v163, v163 row_shr:8 row_mask:0xf bank_mask:0xf bound_ctrl:1
	v_add_f32_dpp v164, v164, v164 row_shr:8 row_mask:0xf bank_mask:0xf bound_ctrl:1
	v_add_f32_dpp v165, v165, v165 row_shr:8 row_mask:0xf bank_mask:0xf bound_ctrl:1
	v_add_f32_dpp v162, v162, v162 row_bcast:15 row_mask:0xa bank_mask:0xf
	v_add_f32_dpp v163, v163, v163 row_bcast:15 row_mask:0xa bank_mask:0xf
	v_add_f32_dpp v164, v164, v164 row_bcast:15 row_mask:0xa bank_mask:0xf
	v_add_f32_dpp v165, v165, v165 row_bcast:15 row_mask:0xa bank_mask:0xf
	s_mov_b64 s[98:99], exec
	s_mov_b32 exec_lo, 0x80000000
	s_mov_b32 exec_hi, 0x80000000
	ds_write_b32 v74, v162 offset:32
	ds_write_b32 v74, v163 offset:40
	ds_write_b32 v74, v164 offset:48
	ds_write_b32 v74, v165 offset:56
	s_mov_b64 exec, s[98:99]
	s_waitcnt lgkmcnt(0)
; __device__ void peer_gather_phase(const Params& P, int l, bool do_store) {
;     ...
;         const int ea = __builtin_amdgcn_readlane(evs, kb + 2 * pr), eb = __builtin_amdgcn_readlane(evs, kb + 2 * pr + 1);
;         const uint2* up = (const uint2*)(U + (size_t)(uphi ? eb : ea) * 768);
;         u6[3 * pr] = up[0]; u6[3 * pr + 1] = up[1]; u6[3 * pr + 2] = up[2];
;         v8[2 * pr] = *(const uint2*)(V + (size_t)ea * 512);
;         v8[2 * pr + 1] = *(const uint2*)(V + (size_t)eb * 512);
;       }
;     };
;     auto compute_batch = [&](const uint2 (&u6)[12], const uint2 (&v8)[8], int bt) {
;       const int kb = (bt & 7) * 8;
;       float dvec = 0.f;
; #pragma unroll
;       for (int pr = 0; pr < 4; ++pr) {
;         v6u_t qv; qv[0] = u6[3 * pr].x; qv[1] = u6[3 * pr].y; qv[2] = u6[3 * pr + 1].x; qv[3] = u6[3 * pr + 1].y; qv[4] = u6[3 * pr + 2].x; qv[5] = u6[3 * pr + 2].y;
;         const v32f_t wv = __builtin_amdgcn_cvt_scalef32_pk32_f32_fp6(qv, 1.0f);
;         f32x2 a2 = f32x2{0.f, 0.f};
; #pragma unroll
;         for (int i = 0; i < 16; ++i) a2 += f32x2{wv[2 * i], wv[2 * i + 1]} * xu[i];
;         float hs = a2.x + a2.y;
;         hs += dpp_row_shr(hs, 1); hs += dpp_row_shr(hs, 2); hs += dpp_row_shr(hs, 4); hs += dpp_row_shr(hs, 8);
;         hs += __builtin_bit_cast(float, __builtin_amdgcn_update_dpp(0, __builtin_bit_cast(int, hs), 0x142, 0xa, 0xf, false));
;         const float da = __builtin_bit_cast(float, __builtin_amdgcn_readlane(__builtin_bit_cast(int, hs), 31));
;         const float db = __builtin_bit_cast(float, __builtin_amdgcn_readlane(__builtin_bit_cast(int, hs), 63));
	v_mad_u32_u24 v167, v76, s33, v195
	ds_read_b32 v77, v74 offset:392
	s_waitcnt vmcnt(14)
	v_cvt_scalef32_pk32_f32_fp6 v[0:31], v[50:55], 1.0
	global_load_dwordx2 v[54:55], v167, s[62:63] offset:16
	global_load_dwordx4 v[50:53], v167, s[62:63]
	v_pk_mul_f32 v[246:247], v[0:1], v[96:97]
	v_pk_mul_f32 v[254:255], v[2:3], v[98:99]
	v_pk_mul_f32 v[160:161], v[4:5], v[100:101]
	v_pk_fma_f32 v[246:247], v[6:7], v[102:103], v[246:247]
	v_pk_fma_f32 v[254:255], v[8:9], v[104:105], v[254:255]
	v_pk_fma_f32 v[160:161], v[10:11], v[106:107], v[160:161]
	v_pk_fma_f32 v[246:247], v[12:13], v[108:109], v[246:247]
	v_pk_fma_f32 v[254:255], v[14:15], v[110:111], v[254:255]
	v_pk_fma_f32 v[160:161], v[16:17], v[112:113], v[160:161]
	v_pk_fma_f32 v[246:247], v[18:19], v[114:115], v[246:247]
	v_pk_fma_f32 v[254:255], v[20:21], v[116:117], v[254:255]
	v_pk_fma_f32 v[160:161], v[22:23], v[118:119], v[160:161]
	v_pk_fma_f32 v[246:247], v[24:25], v[120:121], v[246:247]
	v_pk_fma_f32 v[254:255], v[26:27], v[122:123], v[254:255]
	v_pk_fma_f32 v[160:161], v[28:29], v[124:125], v[160:161]
	v_pk_fma_f32 v[246:247], v[30:31], v[126:127], v[246:247]
	v_pk_add_f32 v[254:255], v[254:255], v[160:161]
	s_nop 0
	v_pk_add_f32 v[246:247], v[246:247], v[254:255]
	s_nop 0
	v_add_f32_e32 v162, v246, v247
	s_waitcnt lgkmcnt(0)
	v_mad_u32_u24 v167, v77, s33, v195
	ds_read_b32 v76, v74 offset:400
	s_waitcnt vmcnt(14)
	v_cvt_scalef32_pk32_f32_fp6 v[0:31], v[44:49], 1.0
	global_load_dwordx2 v[48:49], v167, s[62:63] offset:16
	global_load_dwordx4 v[44:47], v167, s[62:63]
	v_pk_mul_f32 v[246:247], v[0:1], v[96:97]
	v_pk_mul_f32 v[254:255], v[2:3], v[98:99]
	v_pk_mul_f32 v[160:161], v[4:5], v[100:101]
	v_pk_fma_f32 v[246:247], v[6:7], v[102:103], v[246:247]
	v_pk_fma_f32 v[254:255], v[8:9], v[104:105], v[254:255]
	v_pk_fma_f32 v[160:161], v[10:11], v[106:107], v[160:161]
	v_pk_fma_f32 v[246:247], v[12:13], v[108:109], v[246:247]
	v_pk_fma_f32 v[254:255], v[14:15], v[110:111], v[254:255]
	v_pk_fma_f32 v[160:161], v[16:17], v[112:113], v[160:161]
	v_pk_fma_f32 v[246:247], v[18:19], v[114:115], v[246:247]
	v_pk_fma_f32 v[254:255], v[20:21], v[116:117], v[254:255]
	v_pk_fma_f32 v[160:161], v[22:23], v[118:119], v[160:161]
	v_pk_fma_f32 v[246:247], v[24:25], v[120:121], v[246:247]
	v_pk_fma_f32 v[254:255], v[26:27], v[122:123], v[254:255]
	v_pk_fma_f32 v[160:161], v[28:29], v[124:125], v[160:161]
	v_pk_fma_f32 v[246:247], v[30:31], v[126:127], v[246:247]
	v_pk_add_f32 v[254:255], v[254:255], v[160:161]
	s_nop 0
	v_pk_add_f32 v[246:247], v[246:247], v[254:255]
	s_nop 0
	v_add_f32_e32 v163, v246, v247
	s_waitcnt lgkmcnt(0)
	v_mad_u32_u24 v167, v76, s33, v195
	ds_read_b32 v77, v74 offset:408
	s_waitcnt vmcnt(14)
	v_cvt_scalef32_pk32_f32_fp6 v[0:31], v[38:43], 1.0
	global_load_dwordx2 v[42:43], v167, s[62:63] offset:16
	global_load_dwordx4 v[38:41], v167, s[62:63]
	v_pk_mul_f32 v[246:247], v[0:1], v[96:97]
	v_pk_mul_f32 v[254:255], v[2:3], v[98:99]
	v_pk_mul_f32 v[160:161], v[4:5], v[100:101]
	v_pk_fma_f32 v[246:247], v[6:7], v[102:103], v[246:247]
	v_pk_fma_f32 v[254:255], v[8:9], v[104:105], v[254:255]
	v_pk_fma_f32 v[160:161], v[10:11], v[106:107], v[160:161]
	v_pk_fma_f32 v[246:247], v[12:13], v[108:109], v[246:247]
	v_pk_fma_f32 v[254:255], v[14:15], v[110:111], v[254:255]
	v_pk_fma_f32 v[160:161], v[16:17], v[112:113], v[160:161]
	v_pk_fma_f32 v[246:247], v[18:19], v[114:115], v[246:247]
	v_pk_fma_f32 v[254:255], v[20:21], v[116:117], v[254:255]
	v_pk_fma_f32 v[160:161], v[22:23], v[118:119], v[160:161]
	v_pk_fma_f32 v[246:247], v[24:25], v[120:121], v[246:247]
	v_pk_fma_f32 v[254:255], v[26:27], v[122:123], v[254:255]
	v_pk_fma_f32 v[160:161], v[28:29], v[124:125], v[160:161]
	v_pk_fma_f32 v[246:247], v[30:31], v[126:127], v[246:247]
	v_pk_add_f32 v[254:255], v[254:255], v[160:161]
	s_nop 0
	v_pk_add_f32 v[246:247], v[246:247], v[254:255]
	s_nop 0
	v_add_f32_e32 v164, v246, v247
	s_waitcnt lgkmcnt(0)
	v_mad_u32_u24 v167, v77, s33, v195
	ds_read_b32 v76, v74 offset:416
	s_waitcnt vmcnt(14)
	v_cvt_scalef32_pk32_f32_fp6 v[0:31], v[32:37], 1.0
	global_load_dwordx2 v[36:37], v167, s[62:63] offset:16
	global_load_dwordx4 v[32:35], v167, s[62:63]
	v_pk_mul_f32 v[246:247], v[0:1], v[96:97]
	v_pk_mul_f32 v[254:255], v[2:3], v[98:99]
	v_pk_mul_f32 v[160:161], v[4:5], v[100:101]
	v_pk_fma_f32 v[246:247], v[6:7], v[102:103], v[246:247]
	v_pk_fma_f32 v[254:255], v[8:9], v[104:105], v[254:255]
	v_pk_fma_f32 v[160:161], v[10:11], v[106:107], v[160:161]
	v_pk_fma_f32 v[246:247], v[12:13], v[108:109], v[246:247]
	v_pk_fma_f32 v[254:255], v[14:15], v[110:111], v[254:255]
	v_pk_fma_f32 v[160:161], v[16:17], v[112:113], v[160:161]
	v_pk_fma_f32 v[246:247], v[18:19], v[114:115], v[246:247]
	v_pk_fma_f32 v[254:255], v[20:21], v[116:117], v[254:255]
	v_pk_fma_f32 v[160:161], v[22:23], v[118:119], v[160:161]
	v_pk_fma_f32 v[246:247], v[24:25], v[120:121], v[246:247]
	v_pk_fma_f32 v[254:255], v[26:27], v[122:123], v[254:255]
	v_pk_fma_f32 v[160:161], v[28:29], v[124:125], v[160:161]
	v_pk_fma_f32 v[246:247], v[30:31], v[126:127], v[246:247]
	v_pk_add_f32 v[254:255], v[254:255], v[160:161]
	s_nop 0
	v_pk_add_f32 v[246:247], v[246:247], v[254:255]
	s_nop 0
	v_add_f32_e32 v165, v246, v247
	v_add_f32_dpp v162, v162, v162 row_shr:1 row_mask:0xf bank_mask:0xf bound_ctrl:1
	v_add_f32_dpp v163, v163, v163 row_shr:1 row_mask:0xf bank_mask:0xf bound_ctrl:1
	v_add_f32_dpp v164, v164, v164 row_shr:1 row_mask:0xf bank_mask:0xf bound_ctrl:1
	v_add_f32_dpp v165, v165, v165 row_shr:1 row_mask:0xf bank_mask:0xf bound_ctrl:1
	v_add_f32_dpp v162, v162, v162 row_shr:2 row_mask:0xf bank_mask:0xf bound_ctrl:1
; __device__ void peer_gather_phase(const Params& P, int l, bool do_store) {
;     ...
;         const int ea = __builtin_amdgcn_readlane(evs, kb + 2 * pr), eb = __builtin_amdgcn_readlane(evs, kb + 2 * pr + 1);
;         const uint2* up = (const uint2*)(U + (size_t)(uphi ? eb : ea) * 768);
;         u6[3 * pr] = up[0]; u6[3 * pr + 1] = up[1]; u6[3 * pr + 2] = up[2];
;         v8[2 * pr] = *(const uint2*)(V + (size_t)ea * 512);
;         v8[2 * pr + 1] = *(const uint2*)(V + (size_t)eb * 512);
;       }
;     };
;     auto compute_batch = [&](const uint2 (&u6)[12], const uint2 (&v8)[8], int bt) {
;       const int kb = (bt & 7) * 8;
;       float dvec = 0.f;
; #pragma unroll
;       for (int pr = 0; pr < 4; ++pr) {
;         v6u_t qv; qv[0] = u6[3 * pr].x; qv[1] = u6[3 * pr].y; qv[2] = u6[3 * pr + 1].x; qv[3] = u6[3 * pr + 1].y; qv[4] = u6[3 * pr + 2].x; qv[5] = u6[3 * pr + 2].y;
;         const v32f_t wv = __builtin_amdgcn_cvt_scalef32_pk32_f32_fp6(qv, 1.0f);
;         f32x2 a2 = f32x2{0.f, 0.f};
; #pragma unroll
;         for (int i = 0; i < 16; ++i) a2 += f32x2{wv[2 * i], wv[2 * i + 1]} * xu[i];
;         float hs = a2.x + a2.y;
;         hs += dpp_row_shr(hs, 1); hs += dpp_row_shr(hs, 2); hs += dpp_row_shr(hs, 4); hs += dpp_row_shr(hs, 8);
;         hs += __builtin_bit_cast(float, __builtin_amdgcn_update_dpp(0, __builtin_bit_cast(int, hs), 0x142, 0xa, 0xf, false));
;         const float da = __builtin_bit_cast(float, __builtin_amdgcn_readlane(__builtin_bit_cast(int, hs), 31));
;         const float db = __builtin_bit_cast(float, __builtin_amdgcn_readlane(__builtin_bit_cast(int, hs), 63));
	v_add_f32_dpp v163, v163, v163 row_shr:2 row_mask:0xf bank_mask:0xf bound_ctrl:1
	v_add_f32_dpp v164, v164, v164 row_shr:2 row_mask:0xf bank_mask:0xf bound_ctrl:1
	v_add_f32_dpp v165, v165, v165 row_shr:2 row_mask:0xf bank_mask:0xf bound_ctrl:1
	v_add_f32_dpp v162, v162, v162 row_shr:4 row_mask:0xf bank_mask:0xf bound_ctrl:1
	v_add_f32_dpp v163, v163, v163 row_shr:4 row_mask:0xf bank_mask:0xf bound_ctrl:1
	v_add_f32_dpp v164, v164, v164 row_shr:4 row_mask:0xf bank_mask:0xf bound_ctrl:1
	v_add_f32_dpp v165, v165, v165 row_shr:4 row_mask:0xf bank_mask:0xf bound_ctrl:1
	v_add_f32_dpp v162, v162, v162 row_shr:8 row_mask:0xf bank_mask:0xf bound_ctrl:1
	v_add_f32_dpp v163, v163, v163 row_shr:8 row_mask:0xf bank_mask:0xf bound_ctrl:1
	v_add_f32_dpp v164, v164, v164 row_shr:8 row_mask:0xf bank_mask:0xf bound_ctrl:1
	v_add_f32_dpp v165, v165, v165 row_shr:8 row_mask:0xf bank_mask:0xf bound_ctrl:1
	v_add_f32_dpp v162, v162, v162 row_bcast:15 row_mask:0xa bank_mask:0xf
	v_add_f32_dpp v163, v163, v163 row_bcast:15 row_mask:0xa bank_mask:0xf
	v_add_f32_dpp v164, v164, v164 row_bcast:15 row_mask:0xa bank_mask:0xf
	v_add_f32_dpp v165, v165, v165 row_bcast:15 row_mask:0xa bank_mask:0xf
	s_mov_b64 s[98:99], exec
	s_mov_b32 exec_lo, 0x80000000
	s_mov_b32 exec_hi, 0x80000000
	ds_write_b32 v74, v162 offset:64
	ds_write_b32 v74, v163 offset:72
	ds_write_b32 v74, v164 offset:80
	ds_write_b32 v74, v165 offset:88
	s_mov_b64 exec, s[98:99]
	s_waitcnt lgkmcnt(0)
	v_mad_u32_u24 v167, v76, s33, v195
	ds_read_b32 v77, v74 offset:424
	s_waitcnt vmcnt(14)
	v_cvt_scalef32_pk32_f32_fp6 v[0:31], v[196:201], 1.0
	global_load_dwordx2 v[200:201], v167, s[62:63] offset:16
	global_load_dwordx4 v[196:199], v167, s[62:63]
	v_pk_mul_f32 v[246:247], v[0:1], v[96:97]
	v_pk_mul_f32 v[254:255], v[2:3], v[98:99]
	v_pk_mul_f32 v[160:161], v[4:5], v[100:101]
	v_pk_fma_f32 v[246:247], v[6:7], v[102:103], v[246:247]
	v_pk_fma_f32 v[254:255], v[8:9], v[104:105], v[254:255]
	v_pk_fma_f32 v[160:161], v[10:11], v[106:107], v[160:161]
	v_pk_fma_f32 v[246:247], v[12:13], v[108:109], v[246:247]
	v_pk_fma_f32 v[254:255], v[14:15], v[110:111], v[254:255]
	v_pk_fma_f32 v[160:161], v[16:17], v[112:113], v[160:161]
	v_pk_fma_f32 v[246:247], v[18:19], v[114:115], v[246:247]
	v_pk_fma_f32 v[254:255], v[20:21], v[116:117], v[254:255]
	v_pk_fma_f32 v[160:161], v[22:23], v[118:119], v[160:161]
	v_pk_fma_f32 v[246:247], v[24:25], v[120:121], v[246:247]
	v_pk_fma_f32 v[254:255], v[26:27], v[122:123], v[254:255]
	v_pk_fma_f32 v[160:161], v[28:29], v[124:125], v[160:161]
	v_pk_fma_f32 v[246:247], v[30:31], v[126:127], v[246:247]
	v_pk_add_f32 v[254:255], v[254:255], v[160:161]
	s_nop 0
	v_pk_add_f32 v[246:247], v[246:247], v[254:255]
	s_nop 0
	v_add_f32_e32 v162, v246, v247
	s_waitcnt lgkmcnt(0)
	v_mad_u32_u24 v167, v77, s33, v195
	ds_read_b32 v76, v74 offset:432
	s_waitcnt vmcnt(14)
	v_cvt_scalef32_pk32_f32_fp6 v[0:31], v[228:233], 1.0
	global_load_dwordx2 v[232:233], v167, s[62:63] offset:16
	global_load_dwordx4 v[228:231], v167, s[62:63]
	v_pk_mul_f32 v[246:247], v[0:1], v[96:97]
	v_pk_mul_f32 v[254:255], v[2:3], v[98:99]
	v_pk_mul_f32 v[160:161], v[4:5], v[100:101]
	v_pk_fma_f32 v[246:247], v[6:7], v[102:103], v[246:247]
	v_pk_fma_f32 v[254:255], v[8:9], v[104:105], v[254:255]
	v_pk_fma_f32 v[160:161], v[10:11], v[106:107], v[160:161]
	v_pk_fma_f32 v[246:247], v[12:13], v[108:109], v[246:247]
	v_pk_fma_f32 v[254:255], v[14:15], v[110:111], v[254:255]
	v_pk_fma_f32 v[160:161], v[16:17], v[112:113], v[160:161]
	v_pk_fma_f32 v[246:247], v[18:19], v[114:115], v[246:247]
	v_pk_fma_f32 v[254:255], v[20:21], v[116:117], v[254:255]
	v_pk_fma_f32 v[160:161], v[22:23], v[118:119], v[160:161]
	v_pk_fma_f32 v[246:247], v[24:25], v[120:121], v[246:247]
	v_pk_fma_f32 v[254:255], v[26:27], v[122:123], v[254:255]
	v_pk_fma_f32 v[160:161], v[28:29], v[124:125], v[160:161]
	v_pk_fma_f32 v[246:247], v[30:31], v[126:127], v[246:247]
	v_pk_add_f32 v[254:255], v[254:255], v[160:161]
	s_nop 0
	v_pk_add_f32 v[246:247], v[246:247], v[254:255]
	s_nop 0
	v_add_f32_e32 v163, v246, v247
	s_waitcnt lgkmcnt(0)
	v_mad_u32_u24 v167, v76, s33, v195
	ds_read_b32 v77, v74 offset:440
	s_waitcnt vmcnt(14)
	v_cvt_scalef32_pk32_f32_fp6 v[0:31], v[234:239], 1.0
	global_load_dwordx2 v[238:239], v167, s[62:63] offset:16
	global_load_dwordx4 v[234:237], v167, s[62:63]
	v_pk_mul_f32 v[246:247], v[0:1], v[96:97]
	v_pk_mul_f32 v[254:255], v[2:3], v[98:99]
	v_pk_mul_f32 v[160:161], v[4:5], v[100:101]
	v_pk_fma_f32 v[246:247], v[6:7], v[102:103], v[246:247]
	v_pk_fma_f32 v[254:255], v[8:9], v[104:105], v[254:255]
	v_pk_fma_f32 v[160:161], v[10:11], v[106:107], v[160:161]
	v_pk_fma_f32 v[246:247], v[12:13], v[108:109], v[246:247]
	v_pk_fma_f32 v[254:255], v[14:15], v[110:111], v[254:255]
	v_pk_fma_f32 v[160:161], v[16:17], v[112:113], v[160:161]
	v_pk_fma_f32 v[246:247], v[18:19], v[114:115], v[246:247]
	v_pk_fma_f32 v[254:255], v[20:21], v[116:117], v[254:255]
	v_pk_fma_f32 v[160:161], v[22:23], v[118:119], v[160:161]
	v_pk_fma_f32 v[246:247], v[24:25], v[120:121], v[246:247]
	v_pk_fma_f32 v[254:255], v[26:27], v[122:123], v[254:255]
	v_pk_fma_f32 v[160:161], v[28:29], v[124:125], v[160:161]
	v_pk_fma_f32 v[246:247], v[30:31], v[126:127], v[246:247]
	v_pk_add_f32 v[254:255], v[254:255], v[160:161]
	s_nop 0
	v_pk_add_f32 v[246:247], v[246:247], v[254:255]
	s_nop 0
	v_add_f32_e32 v164, v246, v247
	s_waitcnt lgkmcnt(0)
	v_mad_u32_u24 v167, v77, s33, v195
	ds_read_b32 v76, v74 offset:448
	s_waitcnt vmcnt(14)
; __device__ void peer_gather_phase(const Params& P, int l, bool do_store) {
;     ...
;         const int ea = __builtin_amdgcn_readlane(evs, kb + 2 * pr), eb = __builtin_amdgcn_readlane(evs, kb + 2 * pr + 1);
;         const uint2* up = (const uint2*)(U + (size_t)(uphi ? eb : ea) * 768);
;         u6[3 * pr] = up[0]; u6[3 * pr + 1] = up[1]; u6[3 * pr + 2] = up[2];
;         v8[2 * pr] = *(const uint2*)(V + (size_t)ea * 512);
;         v8[2 * pr + 1] = *(const uint2*)(V + (size_t)eb * 512);
;       }
;     };
;     auto compute_batch = [&](const uint2 (&u6)[12], const uint2 (&v8)[8], int bt) {
;       const int kb = (bt & 7) * 8;
;       float dvec = 0.f;
; #pragma unroll
;       for (int pr = 0; pr < 4; ++pr) {
;         v6u_t qv; qv[0] = u6[3 * pr].x; qv[1] = u6[3 * pr].y; qv[2] = u6[3 * pr + 1].x; qv[3] = u6[3 * pr + 1].y; qv[4] = u6[3 * pr + 2].x; qv[5] = u6[3 * pr + 2].y;
;         const v32f_t wv = __builtin_amdgcn_cvt_scalef32_pk32_f32_fp6(qv, 1.0f);
;         f32x2 a2 = f32x2{0.f, 0.f};
; #pragma unroll
;         for (int i = 0; i < 16; ++i) a2 += f32x2{wv[2 * i], wv[2 * i + 1]} * xu[i];
;         float hs = a2.x + a2.y;
;         hs += dpp_row_shr(hs, 1); hs += dpp_row_shr(hs, 2); hs += dpp_row_shr(hs, 4); hs += dpp_row_shr(hs, 8);
;         hs += __builtin_bit_cast(float, __builtin_amdgcn_update_dpp(0, __builtin_bit_cast(int, hs), 0x142, 0xa, 0xf, false));
;         const float da = __builtin_bit_cast(float, __builtin_amdgcn_readlane(__builtin_bit_cast(int, hs), 31));
;         const float db = __builtin_bit_cast(float, __builtin_amdgcn_readlane(__builtin_bit_cast(int, hs), 63));
	v_cvt_scalef32_pk32_f32_fp6 v[0:31], v[240:245], 1.0
	global_load_dwordx2 v[244:245], v167, s[62:63] offset:16
	global_load_dwordx4 v[240:243], v167, s[62:63]
	v_pk_mul_f32 v[246:247], v[0:1], v[96:97]
	v_pk_mul_f32 v[254:255], v[2:3], v[98:99]
	v_pk_mul_f32 v[160:161], v[4:5], v[100:101]
	v_pk_fma_f32 v[246:247], v[6:7], v[102:103], v[246:247]
	v_pk_fma_f32 v[254:255], v[8:9], v[104:105], v[254:255]
	v_pk_fma_f32 v[160:161], v[10:11], v[106:107], v[160:161]
	v_pk_fma_f32 v[246:247], v[12:13], v[108:109], v[246:247]
	v_pk_fma_f32 v[254:255], v[14:15], v[110:111], v[254:255]
	v_pk_fma_f32 v[160:161], v[16:17], v[112:113], v[160:161]
	v_pk_fma_f32 v[246:247], v[18:19], v[114:115], v[246:247]
	v_pk_fma_f32 v[254:255], v[20:21], v[116:117], v[254:255]
	v_pk_fma_f32 v[160:161], v[22:23], v[118:119], v[160:161]
	v_pk_fma_f32 v[246:247], v[24:25], v[120:121], v[246:247]
	v_pk_fma_f32 v[254:255], v[26:27], v[122:123], v[254:255]
	v_pk_fma_f32 v[160:161], v[28:29], v[124:125], v[160:161]
	v_pk_fma_f32 v[246:247], v[30:31], v[126:127], v[246:247]
	v_pk_add_f32 v[254:255], v[254:255], v[160:161]
	s_nop 0
	v_pk_add_f32 v[246:247], v[246:247], v[254:255]
	s_nop 0
	v_add_f32_e32 v165, v246, v247
	v_add_f32_dpp v162, v162, v162 row_shr:1 row_mask:0xf bank_mask:0xf bound_ctrl:1
	v_add_f32_dpp v163, v163, v163 row_shr:1 row_mask:0xf bank_mask:0xf bound_ctrl:1
	v_add_f32_dpp v164, v164, v164 row_shr:1 row_mask:0xf bank_mask:0xf bound_ctrl:1
	v_add_f32_dpp v165, v165, v165 row_shr:1 row_mask:0xf bank_mask:0xf bound_ctrl:1
	v_add_f32_dpp v162, v162, v162 row_shr:2 row_mask:0xf bank_mask:0xf bound_ctrl:1
	v_add_f32_dpp v163, v163, v163 row_shr:2 row_mask:0xf bank_mask:0xf bound_ctrl:1
	v_add_f32_dpp v164, v164, v164 row_shr:2 row_mask:0xf bank_mask:0xf bound_ctrl:1
	v_add_f32_dpp v165, v165, v165 row_shr:2 row_mask:0xf bank_mask:0xf bound_ctrl:1
	v_add_f32_dpp v162, v162, v162 row_shr:4 row_mask:0xf bank_mask:0xf bound_ctrl:1
	v_add_f32_dpp v163, v163, v163 row_shr:4 row_mask:0xf bank_mask:0xf bound_ctrl:1
	v_add_f32_dpp v164, v164, v164 row_shr:4 row_mask:0xf bank_mask:0xf bound_ctrl:1
	v_add_f32_dpp v165, v165, v165 row_shr:4 row_mask:0xf bank_mask:0xf bound_ctrl:1
	v_add_f32_dpp v162, v162, v162 row_shr:8 row_mask:0xf bank_mask:0xf bound_ctrl:1
	v_add_f32_dpp v163, v163, v163 row_shr:8 row_mask:0xf bank_mask:0xf bound_ctrl:1
	v_add_f32_dpp v164, v164, v164 row_shr:8 row_mask:0xf bank_mask:0xf bound_ctrl:1
	v_add_f32_dpp v165, v165, v165 row_shr:8 row_mask:0xf bank_mask:0xf bound_ctrl:1
	v_add_f32_dpp v162, v162, v162 row_bcast:15 row_mask:0xa bank_mask:0xf
	v_add_f32_dpp v163, v163, v163 row_bcast:15 row_mask:0xa bank_mask:0xf
	v_add_f32_dpp v164, v164, v164 row_bcast:15 row_mask:0xa bank_mask:0xf
	v_add_f32_dpp v165, v165, v165 row_bcast:15 row_mask:0xa bank_mask:0xf
	s_mov_b64 s[98:99], exec
	s_mov_b32 exec_lo, 0x80000000
	s_mov_b32 exec_hi, 0x80000000
	ds_write_b32 v74, v162 offset:96
	ds_write_b32 v74, v163 offset:104
	ds_write_b32 v74, v164 offset:112
	ds_write_b32 v74, v165 offset:120
	s_mov_b64 exec, s[98:99]
	s_waitcnt lgkmcnt(0)
	v_mad_u32_u24 v167, v76, s33, v195
	ds_read_b32 v77, v74 offset:456
	s_waitcnt vmcnt(14)
	v_cvt_scalef32_pk32_f32_fp6 v[0:31], v[50:55], 1.0
	global_load_dwordx2 v[54:55], v167, s[62:63] offset:16
	global_load_dwordx4 v[50:53], v167, s[62:63]
	v_pk_mul_f32 v[246:247], v[0:1], v[96:97]
	v_pk_mul_f32 v[254:255], v[2:3], v[98:99]
	v_pk_mul_f32 v[160:161], v[4:5], v[100:101]
	v_pk_fma_f32 v[246:247], v[6:7], v[102:103], v[246:247]
	v_pk_fma_f32 v[254:255], v[8:9], v[104:105], v[254:255]
	v_pk_fma_f32 v[160:161], v[10:11], v[106:107], v[160:161]
	v_pk_fma_f32 v[246:247], v[12:13], v[108:109], v[246:247]
	v_pk_fma_f32 v[254:255], v[14:15], v[110:111], v[254:255]
	v_pk_fma_f32 v[160:161], v[16:17], v[112:113], v[160:161]
	v_pk_fma_f32 v[246:247], v[18:19], v[114:115], v[246:247]
	v_pk_fma_f32 v[254:255], v[20:21], v[116:117], v[254:255]
	v_pk_fma_f32 v[160:161], v[22:23], v[118:119], v[160:161]
	v_pk_fma_f32 v[246:247], v[24:25], v[120:121], v[246:247]
	v_pk_fma_f32 v[254:255], v[26:27], v[122:123], v[254:255]
	v_pk_fma_f32 v[160:161], v[28:29], v[124:125], v[160:161]
	v_pk_fma_f32 v[246:247], v[30:31], v[126:127], v[246:247]
	v_pk_add_f32 v[254:255], v[254:255], v[160:161]
	s_nop 0
	v_pk_add_f32 v[246:247], v[246:247], v[254:255]
	s_nop 0
	v_add_f32_e32 v162, v246, v247
	s_waitcnt lgkmcnt(0)
	v_mad_u32_u24 v167, v77, s33, v195
	ds_read_b32 v76, v74 offset:464
	s_waitcnt vmcnt(14)
	v_cvt_scalef32_pk32_f32_fp6 v[0:31], v[44:49], 1.0
	global_load_dwordx2 v[48:49], v167, s[62:63] offset:16
	global_load_dwordx4 v[44:47], v167, s[62:63]
	v_pk_mul_f32 v[246:247], v[0:1], v[96:97]
	v_pk_mul_f32 v[254:255], v[2:3], v[98:99]
	v_pk_mul_f32 v[160:161], v[4:5], v[100:101]
	v_pk_fma_f32 v[246:247], v[6:7], v[102:103], v[246:247]
	v_pk_fma_f32 v[254:255], v[8:9], v[104:105], v[254:255]
	v_pk_fma_f32 v[160:161], v[10:11], v[106:107], v[160:161]
	v_pk_fma_f32 v[246:247], v[12:13], v[108:109], v[246:247]
	v_pk_fma_f32 v[254:255], v[14:15], v[110:111], v[254:255]
	v_pk_fma_f32 v[160:161], v[16:17], v[112:113], v[160:161]
	v_pk_fma_f32 v[246:247], v[18:19], v[114:115], v[246:247]
	v_pk_fma_f32 v[254:255], v[20:21], v[116:117], v[254:255]
	v_pk_fma_f32 v[160:161], v[22:23], v[118:119], v[160:161]
	v_pk_fma_f32 v[246:247], v[24:25], v[120:121], v[246:247]
	v_pk_fma_f32 v[254:255], v[26:27], v[122:123], v[254:255]
	v_pk_fma_f32 v[160:161], v[28:29], v[124:125], v[160:161]
	v_pk_fma_f32 v[246:247], v[30:31], v[126:127], v[246:247]
	v_pk_add_f32 v[254:255], v[254:255], v[160:161]
	s_nop 0
	v_pk_add_f32 v[246:247], v[246:247], v[254:255]
	s_nop 0
	v_add_f32_e32 v163, v246, v247
	s_waitcnt lgkmcnt(0)
; __device__ void peer_gather_phase(const Params& P, int l, bool do_store) {
;     ...
;         const int ea = __builtin_amdgcn_readlane(evs, kb + 2 * pr), eb = __builtin_amdgcn_readlane(evs, kb + 2 * pr + 1);
;         const uint2* up = (const uint2*)(U + (size_t)(uphi ? eb : ea) * 768);
;         u6[3 * pr] = up[0]; u6[3 * pr + 1] = up[1]; u6[3 * pr + 2] = up[2];
;         v8[2 * pr] = *(const uint2*)(V + (size_t)ea * 512);
;         v8[2 * pr + 1] = *(const uint2*)(V + (size_t)eb * 512);
;       }
;     };
;     auto compute_batch = [&](const uint2 (&u6)[12], const uint2 (&v8)[8], int bt) {
;       const int kb = (bt & 7) * 8;
;       float dvec = 0.f;
; #pragma unroll
;       for (int pr = 0; pr < 4; ++pr) {
;         v6u_t qv; qv[0] = u6[3 * pr].x; qv[1] = u6[3 * pr].y; qv[2] = u6[3 * pr + 1].x; qv[3] = u6[3 * pr + 1].y; qv[4] = u6[3 * pr + 2].x; qv[5] = u6[3 * pr + 2].y;
;         const v32f_t wv = __builtin_amdgcn_cvt_scalef32_pk32_f32_fp6(qv, 1.0f);
;         f32x2 a2 = f32x2{0.f, 0.f};
; #pragma unroll
;         for (int i = 0; i < 16; ++i) a2 += f32x2{wv[2 * i], wv[2 * i + 1]} * xu[i];
;         float hs = a2.x + a2.y;
;         hs += dpp_row_shr(hs, 1); hs += dpp_row_shr(hs, 2); hs += dpp_row_shr(hs, 4); hs += dpp_row_shr(hs, 8);
;         hs += __builtin_bit_cast(float, __builtin_amdgcn_update_dpp(0, __builtin_bit_cast(int, hs), 0x142, 0xa, 0xf, false));
;         const float da = __builtin_bit_cast(float, __builtin_amdgcn_readlane(__builtin_bit_cast(int, hs), 31));
;         const float db = __builtin_bit_cast(float, __builtin_amdgcn_readlane(__builtin_bit_cast(int, hs), 63));
	v_mad_u32_u24 v167, v76, s33, v195
	ds_read_b32 v77, v74 offset:472
	s_waitcnt vmcnt(14)
	v_cvt_scalef32_pk32_f32_fp6 v[0:31], v[38:43], 1.0
	global_load_dwordx2 v[42:43], v167, s[62:63] offset:16
	global_load_dwordx4 v[38:41], v167, s[62:63]
	v_pk_mul_f32 v[246:247], v[0:1], v[96:97]
	v_pk_mul_f32 v[254:255], v[2:3], v[98:99]
	v_pk_mul_f32 v[160:161], v[4:5], v[100:101]
	v_pk_fma_f32 v[246:247], v[6:7], v[102:103], v[246:247]
	v_pk_fma_f32 v[254:255], v[8:9], v[104:105], v[254:255]
	v_pk_fma_f32 v[160:161], v[10:11], v[106:107], v[160:161]
	v_pk_fma_f32 v[246:247], v[12:13], v[108:109], v[246:247]
	v_pk_fma_f32 v[254:255], v[14:15], v[110:111], v[254:255]
	v_pk_fma_f32 v[160:161], v[16:17], v[112:113], v[160:161]
	v_pk_fma_f32 v[246:247], v[18:19], v[114:115], v[246:247]
	v_pk_fma_f32 v[254:255], v[20:21], v[116:117], v[254:255]
	v_pk_fma_f32 v[160:161], v[22:23], v[118:119], v[160:161]
	v_pk_fma_f32 v[246:247], v[24:25], v[120:121], v[246:247]
	v_pk_fma_f32 v[254:255], v[26:27], v[122:123], v[254:255]
	v_pk_fma_f32 v[160:161], v[28:29], v[124:125], v[160:161]
	v_pk_fma_f32 v[246:247], v[30:31], v[126:127], v[246:247]
	v_pk_add_f32 v[254:255], v[254:255], v[160:161]
	s_nop 0
	v_pk_add_f32 v[246:247], v[246:247], v[254:255]
	s_nop 0
	v_add_f32_e32 v164, v246, v247
	s_waitcnt lgkmcnt(0)
	v_mad_u32_u24 v167, v77, s33, v195
	ds_read_b32 v76, v74 offset:480
	s_waitcnt vmcnt(14)
	v_cvt_scalef32_pk32_f32_fp6 v[0:31], v[32:37], 1.0
	global_load_dwordx2 v[36:37], v167, s[62:63] offset:16
	global_load_dwordx4 v[32:35], v167, s[62:63]
	v_pk_mul_f32 v[246:247], v[0:1], v[96:97]
	v_pk_mul_f32 v[254:255], v[2:3], v[98:99]
	v_pk_mul_f32 v[160:161], v[4:5], v[100:101]
	v_pk_fma_f32 v[246:247], v[6:7], v[102:103], v[246:247]
	v_pk_fma_f32 v[254:255], v[8:9], v[104:105], v[254:255]
	v_pk_fma_f32 v[160:161], v[10:11], v[106:107], v[160:161]
	v_pk_fma_f32 v[246:247], v[12:13], v[108:109], v[246:247]
	v_pk_fma_f32 v[254:255], v[14:15], v[110:111], v[254:255]
	v_pk_fma_f32 v[160:161], v[16:17], v[112:113], v[160:161]
	v_pk_fma_f32 v[246:247], v[18:19], v[114:115], v[246:247]
	v_pk_fma_f32 v[254:255], v[20:21], v[116:117], v[254:255]
	v_pk_fma_f32 v[160:161], v[22:23], v[118:119], v[160:161]
	v_pk_fma_f32 v[246:247], v[24:25], v[120:121], v[246:247]
	v_pk_fma_f32 v[254:255], v[26:27], v[122:123], v[254:255]
	v_pk_fma_f32 v[160:161], v[28:29], v[124:125], v[160:161]
	v_pk_fma_f32 v[246:247], v[30:31], v[126:127], v[246:247]
	v_pk_add_f32 v[254:255], v[254:255], v[160:161]
	s_nop 0
	v_pk_add_f32 v[246:247], v[246:247], v[254:255]
	s_nop 0
	v_add_f32_e32 v165, v246, v247
	v_add_f32_dpp v162, v162, v162 row_shr:1 row_mask:0xf bank_mask:0xf bound_ctrl:1
	v_add_f32_dpp v163, v163, v163 row_shr:1 row_mask:0xf bank_mask:0xf bound_ctrl:1
	v_add_f32_dpp v164, v164, v164 row_shr:1 row_mask:0xf bank_mask:0xf bound_ctrl:1
	v_add_f32_dpp v165, v165, v165 row_shr:1 row_mask:0xf bank_mask:0xf bound_ctrl:1
	v_add_f32_dpp v162, v162, v162 row_shr:2 row_mask:0xf bank_mask:0xf bound_ctrl:1
	v_add_f32_dpp v163, v163, v163 row_shr:2 row_mask:0xf bank_mask:0xf bound_ctrl:1
	v_add_f32_dpp v164, v164, v164 row_shr:2 row_mask:0xf bank_mask:0xf bound_ctrl:1
	v_add_f32_dpp v165, v165, v165 row_shr:2 row_mask:0xf bank_mask:0xf bound_ctrl:1
	v_add_f32_dpp v162, v162, v162 row_shr:4 row_mask:0xf bank_mask:0xf bound_ctrl:1
	v_add_f32_dpp v163, v163, v163 row_shr:4 row_mask:0xf bank_mask:0xf bound_ctrl:1
	v_add_f32_dpp v164, v164, v164 row_shr:4 row_mask:0xf bank_mask:0xf bound_ctrl:1
	v_add_f32_dpp v165, v165, v165 row_shr:4 row_mask:0xf bank_mask:0xf bound_ctrl:1
	v_add_f32_dpp v162, v162, v162 row_shr:8 row_mask:0xf bank_mask:0xf bound_ctrl:1
	v_add_f32_dpp v163, v163, v163 row_shr:8 row_mask:0xf bank_mask:0xf bound_ctrl:1
	v_add_f32_dpp v164, v164, v164 row_shr:8 row_mask:0xf bank_mask:0xf bound_ctrl:1
	v_add_f32_dpp v165, v165, v165 row_shr:8 row_mask:0xf bank_mask:0xf bound_ctrl:1
	v_add_f32_dpp v162, v162, v162 row_bcast:15 row_mask:0xa bank_mask:0xf
	v_add_f32_dpp v163, v163, v163 row_bcast:15 row_mask:0xa bank_mask:0xf
	v_add_f32_dpp v164, v164, v164 row_bcast:15 row_mask:0xa bank_mask:0xf
	v_add_f32_dpp v165, v165, v165 row_bcast:15 row_mask:0xa bank_mask:0xf
	s_mov_b64 s[98:99], exec
	s_mov_b32 exec_lo, 0x80000000
	s_mov_b32 exec_hi, 0x80000000
	ds_write_b32 v74, v162 offset:128
	ds_write_b32 v74, v163 offset:136
	ds_write_b32 v74, v164 offset:144
	ds_write_b32 v74, v165 offset:152
	s_mov_b64 exec, s[98:99]
	s_waitcnt lgkmcnt(0)
	v_mad_u32_u24 v167, v76, s33, v195
	ds_read_b32 v77, v74 offset:488
	s_waitcnt vmcnt(14)
	v_cvt_scalef32_pk32_f32_fp6 v[0:31], v[196:201], 1.0
	global_load_dwordx2 v[200:201], v167, s[62:63] offset:16
	global_load_dwordx4 v[196:199], v167, s[62:63]
	v_pk_mul_f32 v[246:247], v[0:1], v[96:97]
	v_pk_mul_f32 v[254:255], v[2:3], v[98:99]
	v_pk_mul_f32 v[160:161], v[4:5], v[100:101]
	v_pk_fma_f32 v[246:247], v[6:7], v[102:103], v[246:247]
	v_pk_fma_f32 v[254:255], v[8:9], v[104:105], v[254:255]
	v_pk_fma_f32 v[160:161], v[10:11], v[106:107], v[160:161]
	v_pk_fma_f32 v[246:247], v[12:13], v[108:109], v[246:247]
	v_pk_fma_f32 v[254:255], v[14:15], v[110:111], v[254:255]
	v_pk_fma_f32 v[160:161], v[16:17], v[112:113], v[160:161]
	v_pk_fma_f32 v[246:247], v[18:19], v[114:115], v[246:247]
	v_pk_fma_f32 v[254:255], v[20:21], v[116:117], v[254:255]
	v_pk_fma_f32 v[160:161], v[22:23], v[118:119], v[160:161]
	v_pk_fma_f32 v[246:247], v[24:25], v[120:121], v[246:247]
	v_pk_fma_f32 v[254:255], v[26:27], v[122:123], v[254:255]
	v_pk_fma_f32 v[160:161], v[28:29], v[124:125], v[160:161]
	v_pk_fma_f32 v[246:247], v[30:31], v[126:127], v[246:247]
	v_pk_add_f32 v[254:255], v[254:255], v[160:161]
	s_nop 0
	v_pk_add_f32 v[246:247], v[246:247], v[254:255]
	s_nop 0
	v_add_f32_e32 v162, v246, v247
	s_waitcnt lgkmcnt(0)
; __device__ void peer_gather_phase(const Params& P, int l, bool do_store) {
;     ...
;         const int ea = __builtin_amdgcn_readlane(evs, kb + 2 * pr), eb = __builtin_amdgcn_readlane(evs, kb + 2 * pr + 1);
;         const uint2* up = (const uint2*)(U + (size_t)(uphi ? eb : ea) * 768);
;         u6[3 * pr] = up[0]; u6[3 * pr + 1] = up[1]; u6[3 * pr + 2] = up[2];
;         v8[2 * pr] = *(const uint2*)(V + (size_t)ea * 512);
;         v8[2 * pr + 1] = *(const uint2*)(V + (size_t)eb * 512);
;       }
;     };
;     auto compute_batch = [&](const uint2 (&u6)[12], const uint2 (&v8)[8], int bt) {
;       const int kb = (bt & 7) * 8;
;       float dvec = 0.f;
; #pragma unroll
;       for (int pr = 0; pr < 4; ++pr) {
;         v6u_t qv; qv[0] = u6[3 * pr].x; qv[1] = u6[3 * pr].y; qv[2] = u6[3 * pr + 1].x; qv[3] = u6[3 * pr + 1].y; qv[4] = u6[3 * pr + 2].x; qv[5] = u6[3 * pr + 2].y;
;         const v32f_t wv = __builtin_amdgcn_cvt_scalef32_pk32_f32_fp6(qv, 1.0f);
;         f32x2 a2 = f32x2{0.f, 0.f};
; #pragma unroll
;         for (int i = 0; i < 16; ++i) a2 += f32x2{wv[2 * i], wv[2 * i + 1]} * xu[i];
;         float hs = a2.x + a2.y;
;         hs += dpp_row_shr(hs, 1); hs += dpp_row_shr(hs, 2); hs += dpp_row_shr(hs, 4); hs += dpp_row_shr(hs, 8);
;         hs += __builtin_bit_cast(float, __builtin_amdgcn_update_dpp(0, __builtin_bit_cast(int, hs), 0x142, 0xa, 0xf, false));
;         const float da = __builtin_bit_cast(float, __builtin_amdgcn_readlane(__builtin_bit_cast(int, hs), 31));
;         const float db = __builtin_bit_cast(float, __builtin_amdgcn_readlane(__builtin_bit_cast(int, hs), 63));
	v_mad_u32_u24 v167, v77, s33, v195
	ds_read_b32 v76, v74 offset:496
	s_waitcnt vmcnt(14)
	v_cvt_scalef32_pk32_f32_fp6 v[0:31], v[228:233], 1.0
	global_load_dwordx2 v[232:233], v167, s[62:63] offset:16
	global_load_dwordx4 v[228:231], v167, s[62:63]
	v_pk_mul_f32 v[246:247], v[0:1], v[96:97]
	v_pk_mul_f32 v[254:255], v[2:3], v[98:99]
	v_pk_mul_f32 v[160:161], v[4:5], v[100:101]
	v_pk_fma_f32 v[246:247], v[6:7], v[102:103], v[246:247]
	v_pk_fma_f32 v[254:255], v[8:9], v[104:105], v[254:255]
	v_pk_fma_f32 v[160:161], v[10:11], v[106:107], v[160:161]
	v_pk_fma_f32 v[246:247], v[12:13], v[108:109], v[246:247]
	v_pk_fma_f32 v[254:255], v[14:15], v[110:111], v[254:255]
	v_pk_fma_f32 v[160:161], v[16:17], v[112:113], v[160:161]
	v_pk_fma_f32 v[246:247], v[18:19], v[114:115], v[246:247]
	v_pk_fma_f32 v[254:255], v[20:21], v[116:117], v[254:255]
	v_pk_fma_f32 v[160:161], v[22:23], v[118:119], v[160:161]
	v_pk_fma_f32 v[246:247], v[24:25], v[120:121], v[246:247]
	v_pk_fma_f32 v[254:255], v[26:27], v[122:123], v[254:255]
	v_pk_fma_f32 v[160:161], v[28:29], v[124:125], v[160:161]
	v_pk_fma_f32 v[246:247], v[30:31], v[126:127], v[246:247]
	v_pk_add_f32 v[254:255], v[254:255], v[160:161]
	s_nop 0
	v_pk_add_f32 v[246:247], v[246:247], v[254:255]
	s_nop 0
	v_add_f32_e32 v163, v246, v247
	s_waitcnt lgkmcnt(0)
	v_mad_u32_u24 v167, v76, s33, v195
	ds_read_b32 v77, v74 offset:504
	s_waitcnt vmcnt(14)
	v_cvt_scalef32_pk32_f32_fp6 v[0:31], v[234:239], 1.0
	global_load_dwordx2 v[238:239], v167, s[62:63] offset:16
	global_load_dwordx4 v[234:237], v167, s[62:63]
	v_pk_mul_f32 v[246:247], v[0:1], v[96:97]
	v_pk_mul_f32 v[254:255], v[2:3], v[98:99]
	v_pk_mul_f32 v[160:161], v[4:5], v[100:101]
	v_pk_fma_f32 v[246:247], v[6:7], v[102:103], v[246:247]
	v_pk_fma_f32 v[254:255], v[8:9], v[104:105], v[254:255]
	v_pk_fma_f32 v[160:161], v[10:11], v[106:107], v[160:161]
	v_pk_fma_f32 v[246:247], v[12:13], v[108:109], v[246:247]
	v_pk_fma_f32 v[254:255], v[14:15], v[110:111], v[254:255]
	v_pk_fma_f32 v[160:161], v[16:17], v[112:113], v[160:161]
	v_pk_fma_f32 v[246:247], v[18:19], v[114:115], v[246:247]
	v_pk_fma_f32 v[254:255], v[20:21], v[116:117], v[254:255]
	v_pk_fma_f32 v[160:161], v[22:23], v[118:119], v[160:161]
	v_pk_fma_f32 v[246:247], v[24:25], v[120:121], v[246:247]
	v_pk_fma_f32 v[254:255], v[26:27], v[122:123], v[254:255]
	v_pk_fma_f32 v[160:161], v[28:29], v[124:125], v[160:161]
	v_pk_fma_f32 v[246:247], v[30:31], v[126:127], v[246:247]
	v_pk_add_f32 v[254:255], v[254:255], v[160:161]
	s_nop 0
	v_pk_add_f32 v[246:247], v[246:247], v[254:255]
	s_nop 0
	v_add_f32_e32 v164, v246, v247
	s_waitcnt lgkmcnt(0)
	v_mad_u32_u24 v167, v77, s33, v195
	s_waitcnt vmcnt(14)
	v_cvt_scalef32_pk32_f32_fp6 v[0:31], v[240:245], 1.0
	global_load_dwordx2 v[244:245], v167, s[62:63] offset:16
	global_load_dwordx4 v[240:243], v167, s[62:63]
	v_pk_mul_f32 v[246:247], v[0:1], v[96:97]
	v_pk_mul_f32 v[254:255], v[2:3], v[98:99]
	v_pk_mul_f32 v[160:161], v[4:5], v[100:101]
	v_pk_fma_f32 v[246:247], v[6:7], v[102:103], v[246:247]
	v_pk_fma_f32 v[254:255], v[8:9], v[104:105], v[254:255]
	v_pk_fma_f32 v[160:161], v[10:11], v[106:107], v[160:161]
	v_pk_fma_f32 v[246:247], v[12:13], v[108:109], v[246:247]
	v_pk_fma_f32 v[254:255], v[14:15], v[110:111], v[254:255]
	v_pk_fma_f32 v[160:161], v[16:17], v[112:113], v[160:161]
	v_pk_fma_f32 v[246:247], v[18:19], v[114:115], v[246:247]
	v_pk_fma_f32 v[254:255], v[20:21], v[116:117], v[254:255]
	v_pk_fma_f32 v[160:161], v[22:23], v[118:119], v[160:161]
	v_pk_fma_f32 v[246:247], v[24:25], v[120:121], v[246:247]
	v_pk_fma_f32 v[254:255], v[26:27], v[122:123], v[254:255]
	v_pk_fma_f32 v[160:161], v[28:29], v[124:125], v[160:161]
	v_pk_fma_f32 v[246:247], v[30:31], v[126:127], v[246:247]
	v_pk_add_f32 v[254:255], v[254:255], v[160:161]
	s_nop 0
	v_pk_add_f32 v[246:247], v[246:247], v[254:255]
	s_nop 0
	v_add_f32_e32 v165, v246, v247
	v_add_f32_dpp v162, v162, v162 row_shr:1 row_mask:0xf bank_mask:0xf bound_ctrl:1
	v_add_f32_dpp v163, v163, v163 row_shr:1 row_mask:0xf bank_mask:0xf bound_ctrl:1
	v_add_f32_dpp v164, v164, v164 row_shr:1 row_mask:0xf bank_mask:0xf bound_ctrl:1
	v_add_f32_dpp v165, v165, v165 row_shr:1 row_mask:0xf bank_mask:0xf bound_ctrl:1
	v_add_f32_dpp v162, v162, v162 row_shr:2 row_mask:0xf bank_mask:0xf bound_ctrl:1
	v_add_f32_dpp v163, v163, v163 row_shr:2 row_mask:0xf bank_mask:0xf bound_ctrl:1
	v_add_f32_dpp v164, v164, v164 row_shr:2 row_mask:0xf bank_mask:0xf bound_ctrl:1
	v_add_f32_dpp v165, v165, v165 row_shr:2 row_mask:0xf bank_mask:0xf bound_ctrl:1
	v_add_f32_dpp v162, v162, v162 row_shr:4 row_mask:0xf bank_mask:0xf bound_ctrl:1
	v_add_f32_dpp v163, v163, v163 row_shr:4 row_mask:0xf bank_mask:0xf bound_ctrl:1
	v_add_f32_dpp v164, v164, v164 row_shr:4 row_mask:0xf bank_mask:0xf bound_ctrl:1
	v_add_f32_dpp v165, v165, v165 row_shr:4 row_mask:0xf bank_mask:0xf bound_ctrl:1
	v_add_f32_dpp v162, v162, v162 row_shr:8 row_mask:0xf bank_mask:0xf bound_ctrl:1
	v_add_f32_dpp v163, v163, v163 row_shr:8 row_mask:0xf bank_mask:0xf bound_ctrl:1
	v_add_f32_dpp v164, v164, v164 row_shr:8 row_mask:0xf bank_mask:0xf bound_ctrl:1
	v_add_f32_dpp v165, v165, v165 row_shr:8 row_mask:0xf bank_mask:0xf bound_ctrl:1
	v_add_f32_dpp v162, v162, v162 row_bcast:15 row_mask:0xa bank_mask:0xf
	v_add_f32_dpp v163, v163, v163 row_bcast:15 row_mask:0xa bank_mask:0xf
	v_add_f32_dpp v164, v164, v164 row_bcast:15 row_mask:0xa bank_mask:0xf
	v_add_f32_dpp v165, v165, v165 row_bcast:15 row_mask:0xa bank_mask:0xf
	s_mov_b64 s[98:99], exec
	s_mov_b32 exec_lo, 0x80000000
	s_mov_b32 exec_hi, 0x80000000
	ds_write_b32 v74, v162 offset:160
	ds_write_b32 v74, v163 offset:168
	ds_write_b32 v74, v164 offset:176
	ds_write_b32 v74, v165 offset:184
	s_mov_b64 exec, s[98:99]
	s_waitcnt vmcnt(14)
; __device__ void peer_gather_phase(const Params& P, int l, bool do_store) {
;     ...
;       for (int pr = 0; pr < 4; ++pr) {
;         v6u_t qv; qv[0] = u6[3 * pr].x; qv[1] = u6[3 * pr].y; qv[2] = u6[3 * pr + 1].x; qv[3] = u6[3 * pr + 1].y; qv[4] = u6[3 * pr + 2].x; qv[5] = u6[3 * pr + 2].y;
;         const v32f_t wv = __builtin_amdgcn_cvt_scalef32_pk32_f32_fp6(qv, 1.0f);
;         f32x2 a2 = f32x2{0.f, 0.f};
; #pragma unroll
;         for (int i = 0; i < 16; ++i) a2 += f32x2{wv[2 * i], wv[2 * i + 1]} * xu[i];
;         float hs = a2.x + a2.y;
;         hs += dpp_row_shr(hs, 1); hs += dpp_row_shr(hs, 2); hs += dpp_row_shr(hs, 4); hs += dpp_row_shr(hs, 8);
;         hs += __builtin_bit_cast(float, __builtin_amdgcn_update_dpp(0, __builtin_bit_cast(int, hs), 0x142, 0xa, 0xf, false));
;         const float da = __builtin_bit_cast(float, __builtin_amdgcn_readlane(__builtin_bit_cast(int, hs), 31));
;         const float db = __builtin_bit_cast(float, __builtin_amdgcn_readlane(__builtin_bit_cast(int, hs), 63));
	v_cvt_scalef32_pk32_f32_fp6 v[0:31], v[50:55], 1.0
	v_pk_mul_f32 v[246:247], v[0:1], v[96:97]
	v_pk_mul_f32 v[254:255], v[2:3], v[98:99]
	v_pk_mul_f32 v[160:161], v[4:5], v[100:101]
	v_pk_fma_f32 v[246:247], v[6:7], v[102:103], v[246:247]
	v_pk_fma_f32 v[254:255], v[8:9], v[104:105], v[254:255]
	v_pk_fma_f32 v[160:161], v[10:11], v[106:107], v[160:161]
	v_pk_fma_f32 v[246:247], v[12:13], v[108:109], v[246:247]
	v_pk_fma_f32 v[254:255], v[14:15], v[110:111], v[254:255]
	v_pk_fma_f32 v[160:161], v[16:17], v[112:113], v[160:161]
	v_pk_fma_f32 v[246:247], v[18:19], v[114:115], v[246:247]
	v_pk_fma_f32 v[254:255], v[20:21], v[116:117], v[254:255]
	v_pk_fma_f32 v[160:161], v[22:23], v[118:119], v[160:161]
	v_pk_fma_f32 v[246:247], v[24:25], v[120:121], v[246:247]
	v_pk_fma_f32 v[254:255], v[26:27], v[122:123], v[254:255]
	v_pk_fma_f32 v[160:161], v[28:29], v[124:125], v[160:161]
	v_pk_fma_f32 v[246:247], v[30:31], v[126:127], v[246:247]
	v_pk_add_f32 v[254:255], v[254:255], v[160:161]
	s_nop 0
	v_pk_add_f32 v[246:247], v[246:247], v[254:255]
	s_nop 0
	v_add_f32_e32 v162, v246, v247
	s_waitcnt vmcnt(12)
	v_cvt_scalef32_pk32_f32_fp6 v[0:31], v[44:49], 1.0
	v_pk_mul_f32 v[246:247], v[0:1], v[96:97]
	v_pk_mul_f32 v[254:255], v[2:3], v[98:99]
	v_pk_mul_f32 v[160:161], v[4:5], v[100:101]
	v_pk_fma_f32 v[246:247], v[6:7], v[102:103], v[246:247]
	v_pk_fma_f32 v[254:255], v[8:9], v[104:105], v[254:255]
	v_pk_fma_f32 v[160:161], v[10:11], v[106:107], v[160:161]
	v_pk_fma_f32 v[246:247], v[12:13], v[108:109], v[246:247]
	v_pk_fma_f32 v[254:255], v[14:15], v[110:111], v[254:255]
	v_pk_fma_f32 v[160:161], v[16:17], v[112:113], v[160:161]
	v_pk_fma_f32 v[246:247], v[18:19], v[114:115], v[246:247]
	v_pk_fma_f32 v[254:255], v[20:21], v[116:117], v[254:255]
	v_pk_fma_f32 v[160:161], v[22:23], v[118:119], v[160:161]
	v_pk_fma_f32 v[246:247], v[24:25], v[120:121], v[246:247]
	v_pk_fma_f32 v[254:255], v[26:27], v[122:123], v[254:255]
	v_pk_fma_f32 v[160:161], v[28:29], v[124:125], v[160:161]
	v_pk_fma_f32 v[246:247], v[30:31], v[126:127], v[246:247]
	v_pk_add_f32 v[254:255], v[254:255], v[160:161]
	s_nop 0
	v_pk_add_f32 v[246:247], v[246:247], v[254:255]
	s_nop 0
	v_add_f32_e32 v163, v246, v247
	s_waitcnt vmcnt(10)
	v_cvt_scalef32_pk32_f32_fp6 v[0:31], v[38:43], 1.0
	v_pk_mul_f32 v[246:247], v[0:1], v[96:97]
	v_pk_mul_f32 v[254:255], v[2:3], v[98:99]
	v_pk_mul_f32 v[160:161], v[4:5], v[100:101]
	v_pk_fma_f32 v[246:247], v[6:7], v[102:103], v[246:247]
	v_pk_fma_f32 v[254:255], v[8:9], v[104:105], v[254:255]
	v_pk_fma_f32 v[160:161], v[10:11], v[106:107], v[160:161]
	v_pk_fma_f32 v[246:247], v[12:13], v[108:109], v[246:247]
	v_pk_fma_f32 v[254:255], v[14:15], v[110:111], v[254:255]
	v_pk_fma_f32 v[160:161], v[16:17], v[112:113], v[160:161]
	v_pk_fma_f32 v[246:247], v[18:19], v[114:115], v[246:247]
	v_pk_fma_f32 v[254:255], v[20:21], v[116:117], v[254:255]
	v_pk_fma_f32 v[160:161], v[22:23], v[118:119], v[160:161]
	v_pk_fma_f32 v[246:247], v[24:25], v[120:121], v[246:247]
	v_pk_fma_f32 v[254:255], v[26:27], v[122:123], v[254:255]
	v_pk_fma_f32 v[160:161], v[28:29], v[124:125], v[160:161]
	v_pk_fma_f32 v[246:247], v[30:31], v[126:127], v[246:247]
	v_pk_add_f32 v[254:255], v[254:255], v[160:161]
	s_nop 0
	v_pk_add_f32 v[246:247], v[246:247], v[254:255]
	s_nop 0
	v_add_f32_e32 v164, v246, v247
	s_waitcnt vmcnt(8)
	v_cvt_scalef32_pk32_f32_fp6 v[0:31], v[32:37], 1.0
	v_pk_mul_f32 v[246:247], v[0:1], v[96:97]
	v_pk_mul_f32 v[254:255], v[2:3], v[98:99]
	v_pk_mul_f32 v[160:161], v[4:5], v[100:101]
	v_pk_fma_f32 v[246:247], v[6:7], v[102:103], v[246:247]
	v_pk_fma_f32 v[254:255], v[8:9], v[104:105], v[254:255]
	v_pk_fma_f32 v[160:161], v[10:11], v[106:107], v[160:161]
	v_pk_fma_f32 v[246:247], v[12:13], v[108:109], v[246:247]
	v_pk_fma_f32 v[254:255], v[14:15], v[110:111], v[254:255]
	v_pk_fma_f32 v[160:161], v[16:17], v[112:113], v[160:161]
	v_pk_fma_f32 v[246:247], v[18:19], v[114:115], v[246:247]
	v_pk_fma_f32 v[254:255], v[20:21], v[116:117], v[254:255]
	v_pk_fma_f32 v[160:161], v[22:23], v[118:119], v[160:161]
	v_pk_fma_f32 v[246:247], v[24:25], v[120:121], v[246:247]
	v_pk_fma_f32 v[254:255], v[26:27], v[122:123], v[254:255]
	v_pk_fma_f32 v[160:161], v[28:29], v[124:125], v[160:161]
	v_pk_fma_f32 v[246:247], v[30:31], v[126:127], v[246:247]
	v_pk_add_f32 v[254:255], v[254:255], v[160:161]
	s_nop 0
	v_pk_add_f32 v[246:247], v[246:247], v[254:255]
	s_nop 0
	v_add_f32_e32 v165, v246, v247
	v_add_f32_dpp v162, v162, v162 row_shr:1 row_mask:0xf bank_mask:0xf bound_ctrl:1
	v_add_f32_dpp v163, v163, v163 row_shr:1 row_mask:0xf bank_mask:0xf bound_ctrl:1
	v_add_f32_dpp v164, v164, v164 row_shr:1 row_mask:0xf bank_mask:0xf bound_ctrl:1
	v_add_f32_dpp v165, v165, v165 row_shr:1 row_mask:0xf bank_mask:0xf bound_ctrl:1
	v_add_f32_dpp v162, v162, v162 row_shr:2 row_mask:0xf bank_mask:0xf bound_ctrl:1
	v_add_f32_dpp v163, v163, v163 row_shr:2 row_mask:0xf bank_mask:0xf bound_ctrl:1
	v_add_f32_dpp v164, v164, v164 row_shr:2 row_mask:0xf bank_mask:0xf bound_ctrl:1
	v_add_f32_dpp v165, v165, v165 row_shr:2 row_mask:0xf bank_mask:0xf bound_ctrl:1
	v_add_f32_dpp v162, v162, v162 row_shr:4 row_mask:0xf bank_mask:0xf bound_ctrl:1
	v_add_f32_dpp v163, v163, v163 row_shr:4 row_mask:0xf bank_mask:0xf bound_ctrl:1
	v_add_f32_dpp v164, v164, v164 row_shr:4 row_mask:0xf bank_mask:0xf bound_ctrl:1
	v_add_f32_dpp v165, v165, v165 row_shr:4 row_mask:0xf bank_mask:0xf bound_ctrl:1
	v_add_f32_dpp v162, v162, v162 row_shr:8 row_mask:0xf bank_mask:0xf bound_ctrl:1
	v_add_f32_dpp v163, v163, v163 row_shr:8 row_mask:0xf bank_mask:0xf bound_ctrl:1
	v_add_f32_dpp v164, v164, v164 row_shr:8 row_mask:0xf bank_mask:0xf bound_ctrl:1
	v_add_f32_dpp v165, v165, v165 row_shr:8 row_mask:0xf bank_mask:0xf bound_ctrl:1
	v_add_f32_dpp v162, v162, v162 row_bcast:15 row_mask:0xa bank_mask:0xf
	v_add_f32_dpp v163, v163, v163 row_bcast:15 row_mask:0xa bank_mask:0xf
	v_add_f32_dpp v164, v164, v164 row_bcast:15 row_mask:0xa bank_mask:0xf
	v_add_f32_dpp v165, v165, v165 row_bcast:15 row_mask:0xa bank_mask:0xf
	s_mov_b64 s[98:99], exec
	s_mov_b32 exec_lo, 0x80000000
	s_mov_b32 exec_hi, 0x80000000
	ds_write_b32 v74, v162 offset:192
	ds_write_b32 v74, v163 offset:200
	ds_write_b32 v74, v164 offset:208
	ds_write_b32 v74, v165 offset:216
	s_mov_b64 exec, s[98:99]
	s_waitcnt vmcnt(6)
; __device__ void peer_gather_phase(const Params& P, int l, bool do_store) {
;     ...
;       for (int pr = 0; pr < 4; ++pr) {
;         v6u_t qv; qv[0] = u6[3 * pr].x; qv[1] = u6[3 * pr].y; qv[2] = u6[3 * pr + 1].x; qv[3] = u6[3 * pr + 1].y; qv[4] = u6[3 * pr + 2].x; qv[5] = u6[3 * pr + 2].y;
;         const v32f_t wv = __builtin_amdgcn_cvt_scalef32_pk32_f32_fp6(qv, 1.0f);
;         f32x2 a2 = f32x2{0.f, 0.f};
; #pragma unroll
;         for (int i = 0; i < 16; ++i) a2 += f32x2{wv[2 * i], wv[2 * i + 1]} * xu[i];
;         float hs = a2.x + a2.y;
;         hs += dpp_row_shr(hs, 1); hs += dpp_row_shr(hs, 2); hs += dpp_row_shr(hs, 4); hs += dpp_row_shr(hs, 8);
;         hs += __builtin_bit_cast(float, __builtin_amdgcn_update_dpp(0, __builtin_bit_cast(int, hs), 0x142, 0xa, 0xf, false));
;         const float da = __builtin_bit_cast(float, __builtin_amdgcn_readlane(__builtin_bit_cast(int, hs), 31));
;         const float db = __builtin_bit_cast(float, __builtin_amdgcn_readlane(__builtin_bit_cast(int, hs), 63));
;         dvec = (lane == kb + 2 * pr) ? da : dvec;
;         dvec = (lane == kb + 2 * pr + 1) ? db : dvec;
	v_cvt_scalef32_pk32_f32_fp6 v[0:31], v[196:201], 1.0
	v_pk_mul_f32 v[246:247], v[0:1], v[96:97]
	v_pk_mul_f32 v[254:255], v[2:3], v[98:99]
	v_pk_mul_f32 v[160:161], v[4:5], v[100:101]
	v_pk_fma_f32 v[246:247], v[6:7], v[102:103], v[246:247]
	v_pk_fma_f32 v[254:255], v[8:9], v[104:105], v[254:255]
	v_pk_fma_f32 v[160:161], v[10:11], v[106:107], v[160:161]
	v_pk_fma_f32 v[246:247], v[12:13], v[108:109], v[246:247]
	v_pk_fma_f32 v[254:255], v[14:15], v[110:111], v[254:255]
	v_pk_fma_f32 v[160:161], v[16:17], v[112:113], v[160:161]
	v_pk_fma_f32 v[246:247], v[18:19], v[114:115], v[246:247]
	v_pk_fma_f32 v[254:255], v[20:21], v[116:117], v[254:255]
	v_pk_fma_f32 v[160:161], v[22:23], v[118:119], v[160:161]
	v_pk_fma_f32 v[246:247], v[24:25], v[120:121], v[246:247]
	v_pk_fma_f32 v[254:255], v[26:27], v[122:123], v[254:255]
	v_pk_fma_f32 v[160:161], v[28:29], v[124:125], v[160:161]
	v_pk_fma_f32 v[246:247], v[30:31], v[126:127], v[246:247]
	v_pk_add_f32 v[254:255], v[254:255], v[160:161]
	s_nop 0
	v_pk_add_f32 v[246:247], v[246:247], v[254:255]
	s_nop 0
	v_add_f32_e32 v162, v246, v247
	s_waitcnt vmcnt(4)
	v_cvt_scalef32_pk32_f32_fp6 v[0:31], v[228:233], 1.0
	v_pk_mul_f32 v[246:247], v[0:1], v[96:97]
	v_pk_mul_f32 v[254:255], v[2:3], v[98:99]
	v_pk_mul_f32 v[160:161], v[4:5], v[100:101]
	v_pk_fma_f32 v[246:247], v[6:7], v[102:103], v[246:247]
	v_pk_fma_f32 v[254:255], v[8:9], v[104:105], v[254:255]
	v_pk_fma_f32 v[160:161], v[10:11], v[106:107], v[160:161]
	v_pk_fma_f32 v[246:247], v[12:13], v[108:109], v[246:247]
	v_pk_fma_f32 v[254:255], v[14:15], v[110:111], v[254:255]
	v_pk_fma_f32 v[160:161], v[16:17], v[112:113], v[160:161]
	v_pk_fma_f32 v[246:247], v[18:19], v[114:115], v[246:247]
	v_pk_fma_f32 v[254:255], v[20:21], v[116:117], v[254:255]
	v_pk_fma_f32 v[160:161], v[22:23], v[118:119], v[160:161]
	v_pk_fma_f32 v[246:247], v[24:25], v[120:121], v[246:247]
	v_pk_fma_f32 v[254:255], v[26:27], v[122:123], v[254:255]
	v_pk_fma_f32 v[160:161], v[28:29], v[124:125], v[160:161]
	v_pk_fma_f32 v[246:247], v[30:31], v[126:127], v[246:247]
	v_pk_add_f32 v[254:255], v[254:255], v[160:161]
	s_nop 0
	v_pk_add_f32 v[246:247], v[246:247], v[254:255]
	s_nop 0
	v_add_f32_e32 v163, v246, v247
	s_waitcnt vmcnt(2)
	v_cvt_scalef32_pk32_f32_fp6 v[0:31], v[234:239], 1.0
	v_pk_mul_f32 v[246:247], v[0:1], v[96:97]
	v_pk_mul_f32 v[254:255], v[2:3], v[98:99]
	v_pk_mul_f32 v[160:161], v[4:5], v[100:101]
	v_pk_fma_f32 v[246:247], v[6:7], v[102:103], v[246:247]
	v_pk_fma_f32 v[254:255], v[8:9], v[104:105], v[254:255]
	v_pk_fma_f32 v[160:161], v[10:11], v[106:107], v[160:161]
	v_pk_fma_f32 v[246:247], v[12:13], v[108:109], v[246:247]
	v_pk_fma_f32 v[254:255], v[14:15], v[110:111], v[254:255]
	v_pk_fma_f32 v[160:161], v[16:17], v[112:113], v[160:161]
	v_pk_fma_f32 v[246:247], v[18:19], v[114:115], v[246:247]
	v_pk_fma_f32 v[254:255], v[20:21], v[116:117], v[254:255]
	v_pk_fma_f32 v[160:161], v[22:23], v[118:119], v[160:161]
	v_pk_fma_f32 v[246:247], v[24:25], v[120:121], v[246:247]
	v_pk_fma_f32 v[254:255], v[26:27], v[122:123], v[254:255]
	v_pk_fma_f32 v[160:161], v[28:29], v[124:125], v[160:161]
	v_pk_fma_f32 v[246:247], v[30:31], v[126:127], v[246:247]
	v_pk_add_f32 v[254:255], v[254:255], v[160:161]
	s_nop 0
	v_pk_add_f32 v[246:247], v[246:247], v[254:255]
	s_nop 0
	v_add_f32_e32 v164, v246, v247
	s_waitcnt vmcnt(0)
	v_cvt_scalef32_pk32_f32_fp6 v[0:31], v[240:245], 1.0
	v_pk_mul_f32 v[246:247], v[0:1], v[96:97]
	v_pk_mul_f32 v[254:255], v[2:3], v[98:99]
	v_pk_mul_f32 v[160:161], v[4:5], v[100:101]
	v_pk_fma_f32 v[246:247], v[6:7], v[102:103], v[246:247]
	v_pk_fma_f32 v[254:255], v[8:9], v[104:105], v[254:255]
	v_pk_fma_f32 v[160:161], v[10:11], v[106:107], v[160:161]
	v_pk_fma_f32 v[246:247], v[12:13], v[108:109], v[246:247]
	v_pk_fma_f32 v[254:255], v[14:15], v[110:111], v[254:255]
	v_pk_fma_f32 v[160:161], v[16:17], v[112:113], v[160:161]
	v_pk_fma_f32 v[246:247], v[18:19], v[114:115], v[246:247]
	v_pk_fma_f32 v[254:255], v[20:21], v[116:117], v[254:255]
	v_pk_fma_f32 v[160:161], v[22:23], v[118:119], v[160:161]
	v_pk_fma_f32 v[246:247], v[24:25], v[120:121], v[246:247]
	v_pk_fma_f32 v[254:255], v[26:27], v[122:123], v[254:255]
	v_pk_fma_f32 v[160:161], v[28:29], v[124:125], v[160:161]
	v_pk_fma_f32 v[246:247], v[30:31], v[126:127], v[246:247]
	v_pk_add_f32 v[254:255], v[254:255], v[160:161]
	s_nop 0
	v_pk_add_f32 v[246:247], v[246:247], v[254:255]
	s_nop 0
	v_add_f32_e32 v165, v246, v247
	v_add_f32_dpp v162, v162, v162 row_shr:1 row_mask:0xf bank_mask:0xf bound_ctrl:1
	v_add_f32_dpp v163, v163, v163 row_shr:1 row_mask:0xf bank_mask:0xf bound_ctrl:1
	v_add_f32_dpp v164, v164, v164 row_shr:1 row_mask:0xf bank_mask:0xf bound_ctrl:1
	v_add_f32_dpp v165, v165, v165 row_shr:1 row_mask:0xf bank_mask:0xf bound_ctrl:1
	v_add_f32_dpp v162, v162, v162 row_shr:2 row_mask:0xf bank_mask:0xf bound_ctrl:1
	v_add_f32_dpp v163, v163, v163 row_shr:2 row_mask:0xf bank_mask:0xf bound_ctrl:1
	v_add_f32_dpp v164, v164, v164 row_shr:2 row_mask:0xf bank_mask:0xf bound_ctrl:1
	v_add_f32_dpp v165, v165, v165 row_shr:2 row_mask:0xf bank_mask:0xf bound_ctrl:1
	v_add_f32_dpp v162, v162, v162 row_shr:4 row_mask:0xf bank_mask:0xf bound_ctrl:1
	v_add_f32_dpp v163, v163, v163 row_shr:4 row_mask:0xf bank_mask:0xf bound_ctrl:1
	v_add_f32_dpp v164, v164, v164 row_shr:4 row_mask:0xf bank_mask:0xf bound_ctrl:1
	v_add_f32_dpp v165, v165, v165 row_shr:4 row_mask:0xf bank_mask:0xf bound_ctrl:1
	v_add_f32_dpp v162, v162, v162 row_shr:8 row_mask:0xf bank_mask:0xf bound_ctrl:1
	v_add_f32_dpp v163, v163, v163 row_shr:8 row_mask:0xf bank_mask:0xf bound_ctrl:1
	v_add_f32_dpp v164, v164, v164 row_shr:8 row_mask:0xf bank_mask:0xf bound_ctrl:1
	v_add_f32_dpp v165, v165, v165 row_shr:8 row_mask:0xf bank_mask:0xf bound_ctrl:1
	v_add_f32_dpp v162, v162, v162 row_bcast:15 row_mask:0xa bank_mask:0xf
	v_add_f32_dpp v163, v163, v163 row_bcast:15 row_mask:0xa bank_mask:0xf
	v_add_f32_dpp v164, v164, v164 row_bcast:15 row_mask:0xa bank_mask:0xf
	v_add_f32_dpp v165, v165, v165 row_bcast:15 row_mask:0xa bank_mask:0xf
	s_mov_b64 s[98:99], exec
	s_mov_b32 exec_lo, 0x80000000
	s_mov_b32 exec_hi, 0x80000000
	ds_write_b32 v74, v162 offset:224
	ds_write_b32 v74, v163 offset:232
	ds_write_b32 v74, v164 offset:240
	ds_write_b32 v74, v165 offset:248
	s_mov_b64 exec, s[98:99]
	ds_read_b32 v166, v75
	s_waitcnt lgkmcnt(0)
; DEV float gelu_t(float x) {
;   float z = 0.7978845608028654f * (x + 0.044715f * x * x * x);
;   float e = __expf(2.f * z);
;   float th = 1.f - 2.f / (e + 1.f);
;   return 0.5f * x * (1.f + th);
; }
; __device__ void peer_gather_phase(const Params& P, int l, bool do_store) {
;     ...
;       const float sux = (bt < 8) ? sux0 : sux1;
;       const float gsx = (bt < 8) ? gsx0 : gsx1;
;       const float avec = gelu_t(dvec * sux) * gsx;
; #pragma unroll
;       for (int j = 0; j < 8; ++j) {
;         const float a = __builtin_bit_cast(float, __builtin_amdgcn_readlane(__builtin_bit_cast(int, avec), kb + j));
;         const f32x2 aa = f32x2{a, a};
;         y[0] += aa * __builtin_amdgcn_cvt_scalef32_pk_f32_fp4(v8[j].x, 1.0f, 0); y[1] += aa * __builtin_amdgcn_cvt_scalef32_pk_f32_fp4(v8[j].x, 1.0f, 1);
;         y[2] += aa * __builtin_amdgcn_cvt_scalef32_pk_f32_fp4(v8[j].x, 1.0f, 2); y[3] += aa * __builtin_amdgcn_cvt_scalef32_pk_f32_fp4(v8[j].x, 1.0f, 3);
;         y[4] += aa * __builtin_amdgcn_cvt_scalef32_pk_f32_fp4(v8[j].y, 1.0f, 0); y[5] += aa * __builtin_amdgcn_cvt_scalef32_pk_f32_fp4(v8[j].y, 1.0f, 1);
;         y[6] += aa * __builtin_amdgcn_cvt_scalef32_pk_f32_fp4(v8[j].y, 1.0f, 2); y[7] += aa * __builtin_amdgcn_cvt_scalef32_pk_f32_fp4(v8[j].y, 1.0f, 3);
	v_mul_f32_e32 v0, v190, v166
	v_mul_f32_e32 v1, 0x3d372713, v0
	v_mul_f32_e32 v1, v0, v1
	v_fma_f32 v1, v0, v1, v0
	v_mul_f32_e32 v1, 0x3f4c422a, v1
	v_add_f32_e32 v1, v1, v1
	v_mul_f32_e32 v1, 0x3fb8aa3b, v1
	v_exp_f32_e32 v1, v1
	v_mul_f32_e32 v0, 0.5, v0
	v_add_f32_e32 v1, 1.0, v1
	v_div_scale_f32 v2, s[0:1], v1, v1, 2.0
	v_rcp_f32_e32 v3, v2
	s_nop 0
	v_fma_f32 v4, -v2, v3, 1.0
	v_fmac_f32_e32 v3, v4, v3
	v_div_scale_f32 v4, vcc, 2.0, v1, 2.0
	v_mul_f32_e32 v5, v4, v3
	v_fma_f32 v6, -v2, v5, v4
	v_fmac_f32_e32 v5, v6, v3
	v_fma_f32 v2, -v2, v5, v4
	v_div_fmas_f32 v2, v2, v3, v5
	v_div_fixup_f32 v1, v2, v1, 2.0
	v_sub_f32_e32 v1, 1.0, v1
	v_add_f32_e32 v1, 1.0, v1
	v_mul_f32_e32 v0, v0, v1
	v_mul_f32_e32 v167, v192, v0
	ds_write_b32 v75, v167 offset:512
	ds_read_b32 v76, v193 offset:512
	ds_read_b32 v194, v193 offset:516
	s_waitcnt vmcnt(48)
	v_cvt_scalef32_pk_f32_fp4 v[0:1], v144, 1.0
	v_cvt_scalef32_pk_f32_fp4 v[2:3], v144, 1.0 op_sel:[1,0,0]
	v_cvt_scalef32_pk_f32_fp4 v[4:5], v144, 1.0 op_sel:[0,1,0]
	v_cvt_scalef32_pk_f32_fp4 v[6:7], v144, 1.0 op_sel:[1,1,0]
	v_cvt_scalef32_pk_f32_fp4 v[8:9], v145, 1.0
	v_cvt_scalef32_pk_f32_fp4 v[10:11], v145, 1.0 op_sel:[1,0,0]
	v_cvt_scalef32_pk_f32_fp4 v[12:13], v145, 1.0 op_sel:[0,1,0]
	v_cvt_scalef32_pk_f32_fp4 v[14:15], v145, 1.0 op_sel:[1,1,0]
	v_readlane_b32 s54, v90, 16
	s_lshl_b32 s56, s54, 9
	s_add_u32 s56, s64, s56
	s_addc_u32 s57, s65, 0
	global_load_dwordx2 v[144:145], v227, s[56:57]
	s_waitcnt lgkmcnt(1)
	v_pk_fma_f32 v[130:131], v[0:1], v[76:77], v[130:131] op_sel_hi:[1,0,1]
	v_pk_fma_f32 v[138:139], v[2:3], v[76:77], v[138:139] op_sel_hi:[1,0,1]
	v_pk_fma_f32 v[140:141], v[4:5], v[76:77], v[140:141] op_sel_hi:[1,0,1]
	v_pk_fma_f32 v[142:143], v[6:7], v[76:77], v[142:143] op_sel_hi:[1,0,1]
	v_pk_fma_f32 v[128:129], v[8:9], v[76:77], v[128:129] op_sel_hi:[1,0,1]
	v_pk_fma_f32 v[132:133], v[10:11], v[76:77], v[132:133] op_sel_hi:[1,0,1]
	v_pk_fma_f32 v[134:135], v[12:13], v[76:77], v[134:135] op_sel_hi:[1,0,1]
	v_pk_fma_f32 v[136:137], v[14:15], v[76:77], v[136:137] op_sel_hi:[1,0,1]
	ds_read_b32 v76, v193 offset:520
	s_waitcnt vmcnt(48)
	v_cvt_scalef32_pk_f32_fp4 v[0:1], v146, 1.0
	v_cvt_scalef32_pk_f32_fp4 v[2:3], v146, 1.0 op_sel:[1,0,0]
	v_cvt_scalef32_pk_f32_fp4 v[4:5], v146, 1.0 op_sel:[0,1,0]
	v_cvt_scalef32_pk_f32_fp4 v[6:7], v146, 1.0 op_sel:[1,1,0]
	v_cvt_scalef32_pk_f32_fp4 v[8:9], v147, 1.0
	v_cvt_scalef32_pk_f32_fp4 v[10:11], v147, 1.0 op_sel:[1,0,0]
	v_cvt_scalef32_pk_f32_fp4 v[12:13], v147, 1.0 op_sel:[0,1,0]
	v_cvt_scalef32_pk_f32_fp4 v[14:15], v147, 1.0 op_sel:[1,1,0]
	v_readlane_b32 s54, v90, 17
	s_lshl_b32 s56, s54, 9
	s_add_u32 s56, s64, s56
	s_addc_u32 s57, s65, 0
	global_load_dwordx2 v[146:147], v227, s[56:57]
	s_waitcnt lgkmcnt(1)
	v_pk_fma_f32 v[130:131], v[0:1], v[194:195], v[130:131] op_sel_hi:[1,0,1]
	v_pk_fma_f32 v[138:139], v[2:3], v[194:195], v[138:139] op_sel_hi:[1,0,1]
	v_pk_fma_f32 v[140:141], v[4:5], v[194:195], v[140:141] op_sel_hi:[1,0,1]
	v_pk_fma_f32 v[142:143], v[6:7], v[194:195], v[142:143] op_sel_hi:[1,0,1]
	v_pk_fma_f32 v[128:129], v[8:9], v[194:195], v[128:129] op_sel_hi:[1,0,1]
	v_pk_fma_f32 v[132:133], v[10:11], v[194:195], v[132:133] op_sel_hi:[1,0,1]
	v_pk_fma_f32 v[134:135], v[12:13], v[194:195], v[134:135] op_sel_hi:[1,0,1]
	v_pk_fma_f32 v[136:137], v[14:15], v[194:195], v[136:137] op_sel_hi:[1,0,1]
	ds_read_b32 v194, v193 offset:524
	s_waitcnt vmcnt(48)
	v_cvt_scalef32_pk_f32_fp4 v[0:1], v148, 1.0
	v_cvt_scalef32_pk_f32_fp4 v[2:3], v148, 1.0 op_sel:[1,0,0]
	v_cvt_scalef32_pk_f32_fp4 v[4:5], v148, 1.0 op_sel:[0,1,0]
	v_cvt_scalef32_pk_f32_fp4 v[6:7], v148, 1.0 op_sel:[1,1,0]
	v_cvt_scalef32_pk_f32_fp4 v[8:9], v149, 1.0
	v_cvt_scalef32_pk_f32_fp4 v[10:11], v149, 1.0 op_sel:[1,0,0]
	v_cvt_scalef32_pk_f32_fp4 v[12:13], v149, 1.0 op_sel:[0,1,0]
	v_cvt_scalef32_pk_f32_fp4 v[14:15], v149, 1.0 op_sel:[1,1,0]
	v_readlane_b32 s54, v90, 18
	s_lshl_b32 s56, s54, 9
	s_add_u32 s56, s64, s56
	s_addc_u32 s57, s65, 0
	global_load_dwordx2 v[148:149], v227, s[56:57]
	s_waitcnt lgkmcnt(1)
	v_pk_fma_f32 v[130:131], v[0:1], v[76:77], v[130:131] op_sel_hi:[1,0,1]
	v_pk_fma_f32 v[138:139], v[2:3], v[76:77], v[138:139] op_sel_hi:[1,0,1]
	v_pk_fma_f32 v[140:141], v[4:5], v[76:77], v[140:141] op_sel_hi:[1,0,1]
	v_pk_fma_f32 v[142:143], v[6:7], v[76:77], v[142:143] op_sel_hi:[1,0,1]
	v_pk_fma_f32 v[128:129], v[8:9], v[76:77], v[128:129] op_sel_hi:[1,0,1]
	v_pk_fma_f32 v[132:133], v[10:11], v[76:77], v[132:133] op_sel_hi:[1,0,1]
	v_pk_fma_f32 v[134:135], v[12:13], v[76:77], v[134:135] op_sel_hi:[1,0,1]
	v_pk_fma_f32 v[136:137], v[14:15], v[76:77], v[136:137] op_sel_hi:[1,0,1]
	ds_read_b32 v76, v193 offset:528
	s_waitcnt vmcnt(48)
	v_cvt_scalef32_pk_f32_fp4 v[0:1], v150, 1.0
	v_cvt_scalef32_pk_f32_fp4 v[2:3], v150, 1.0 op_sel:[1,0,0]
	v_cvt_scalef32_pk_f32_fp4 v[4:5], v150, 1.0 op_sel:[0,1,0]
	v_cvt_scalef32_pk_f32_fp4 v[6:7], v150, 1.0 op_sel:[1,1,0]
	v_cvt_scalef32_pk_f32_fp4 v[8:9], v151, 1.0
	v_cvt_scalef32_pk_f32_fp4 v[10:11], v151, 1.0 op_sel:[1,0,0]
	v_cvt_scalef32_pk_f32_fp4 v[12:13], v151, 1.0 op_sel:[0,1,0]
	v_cvt_scalef32_pk_f32_fp4 v[14:15], v151, 1.0 op_sel:[1,1,0]
	v_readlane_b32 s54, v90, 19
	s_lshl_b32 s56, s54, 9
	s_add_u32 s56, s64, s56
	s_addc_u32 s57, s65, 0
	global_load_dwordx2 v[150:151], v227, s[56:57]
	s_waitcnt lgkmcnt(1)
; __device__ void peer_gather_phase(const Params& P, int l, bool do_store) {
;     ...
; #pragma unroll
;       for (int j = 0; j < 8; ++j) {
;         const float a = __builtin_bit_cast(float, __builtin_amdgcn_readlane(__builtin_bit_cast(int, avec), kb + j));
;         const f32x2 aa = f32x2{a, a};
;         y[0] += aa * __builtin_amdgcn_cvt_scalef32_pk_f32_fp4(v8[j].x, 1.0f, 0); y[1] += aa * __builtin_amdgcn_cvt_scalef32_pk_f32_fp4(v8[j].x, 1.0f, 1);
;         y[2] += aa * __builtin_amdgcn_cvt_scalef32_pk_f32_fp4(v8[j].x, 1.0f, 2); y[3] += aa * __builtin_amdgcn_cvt_scalef32_pk_f32_fp4(v8[j].x, 1.0f, 3);
;         y[4] += aa * __builtin_amdgcn_cvt_scalef32_pk_f32_fp4(v8[j].y, 1.0f, 0); y[5] += aa * __builtin_amdgcn_cvt_scalef32_pk_f32_fp4(v8[j].y, 1.0f, 1);
;         y[6] += aa * __builtin_amdgcn_cvt_scalef32_pk_f32_fp4(v8[j].y, 1.0f, 2); y[7] += aa * __builtin_amdgcn_cvt_scalef32_pk_f32_fp4(v8[j].y, 1.0f, 3);
;       }
	v_pk_fma_f32 v[130:131], v[0:1], v[194:195], v[130:131] op_sel_hi:[1,0,1]
	v_pk_fma_f32 v[138:139], v[2:3], v[194:195], v[138:139] op_sel_hi:[1,0,1]
	v_pk_fma_f32 v[140:141], v[4:5], v[194:195], v[140:141] op_sel_hi:[1,0,1]
	v_pk_fma_f32 v[142:143], v[6:7], v[194:195], v[142:143] op_sel_hi:[1,0,1]
	v_pk_fma_f32 v[128:129], v[8:9], v[194:195], v[128:129] op_sel_hi:[1,0,1]
	v_pk_fma_f32 v[132:133], v[10:11], v[194:195], v[132:133] op_sel_hi:[1,0,1]
	v_pk_fma_f32 v[134:135], v[12:13], v[194:195], v[134:135] op_sel_hi:[1,0,1]
	v_pk_fma_f32 v[136:137], v[14:15], v[194:195], v[136:137] op_sel_hi:[1,0,1]
	ds_read_b32 v194, v193 offset:532
	s_waitcnt vmcnt(48)
	v_cvt_scalef32_pk_f32_fp4 v[0:1], v152, 1.0
	v_cvt_scalef32_pk_f32_fp4 v[2:3], v152, 1.0 op_sel:[1,0,0]
	v_cvt_scalef32_pk_f32_fp4 v[4:5], v152, 1.0 op_sel:[0,1,0]
	v_cvt_scalef32_pk_f32_fp4 v[6:7], v152, 1.0 op_sel:[1,1,0]
	v_cvt_scalef32_pk_f32_fp4 v[8:9], v153, 1.0
	v_cvt_scalef32_pk_f32_fp4 v[10:11], v153, 1.0 op_sel:[1,0,0]
	v_cvt_scalef32_pk_f32_fp4 v[12:13], v153, 1.0 op_sel:[0,1,0]
	v_cvt_scalef32_pk_f32_fp4 v[14:15], v153, 1.0 op_sel:[1,1,0]
	v_readlane_b32 s54, v90, 20
	s_lshl_b32 s56, s54, 9
	s_add_u32 s56, s64, s56
	s_addc_u32 s57, s65, 0
	global_load_dwordx2 v[152:153], v227, s[56:57]
	s_waitcnt lgkmcnt(1)
	v_pk_fma_f32 v[130:131], v[0:1], v[76:77], v[130:131] op_sel_hi:[1,0,1]
	v_pk_fma_f32 v[138:139], v[2:3], v[76:77], v[138:139] op_sel_hi:[1,0,1]
	v_pk_fma_f32 v[140:141], v[4:5], v[76:77], v[140:141] op_sel_hi:[1,0,1]
	v_pk_fma_f32 v[142:143], v[6:7], v[76:77], v[142:143] op_sel_hi:[1,0,1]
	v_pk_fma_f32 v[128:129], v[8:9], v[76:77], v[128:129] op_sel_hi:[1,0,1]
	v_pk_fma_f32 v[132:133], v[10:11], v[76:77], v[132:133] op_sel_hi:[1,0,1]
	v_pk_fma_f32 v[134:135], v[12:13], v[76:77], v[134:135] op_sel_hi:[1,0,1]
	v_pk_fma_f32 v[136:137], v[14:15], v[76:77], v[136:137] op_sel_hi:[1,0,1]
	ds_read_b32 v76, v193 offset:536
	s_waitcnt vmcnt(48)
	v_cvt_scalef32_pk_f32_fp4 v[0:1], v154, 1.0
	v_cvt_scalef32_pk_f32_fp4 v[2:3], v154, 1.0 op_sel:[1,0,0]
	v_cvt_scalef32_pk_f32_fp4 v[4:5], v154, 1.0 op_sel:[0,1,0]
	v_cvt_scalef32_pk_f32_fp4 v[6:7], v154, 1.0 op_sel:[1,1,0]
	v_cvt_scalef32_pk_f32_fp4 v[8:9], v155, 1.0
	v_cvt_scalef32_pk_f32_fp4 v[10:11], v155, 1.0 op_sel:[1,0,0]
	v_cvt_scalef32_pk_f32_fp4 v[12:13], v155, 1.0 op_sel:[0,1,0]
	v_cvt_scalef32_pk_f32_fp4 v[14:15], v155, 1.0 op_sel:[1,1,0]
	v_readlane_b32 s54, v90, 21
	s_lshl_b32 s56, s54, 9
	s_add_u32 s56, s64, s56
	s_addc_u32 s57, s65, 0
	global_load_dwordx2 v[154:155], v227, s[56:57]
	s_waitcnt lgkmcnt(1)
	v_pk_fma_f32 v[130:131], v[0:1], v[194:195], v[130:131] op_sel_hi:[1,0,1]
	v_pk_fma_f32 v[138:139], v[2:3], v[194:195], v[138:139] op_sel_hi:[1,0,1]
	v_pk_fma_f32 v[140:141], v[4:5], v[194:195], v[140:141] op_sel_hi:[1,0,1]
	v_pk_fma_f32 v[142:143], v[6:7], v[194:195], v[142:143] op_sel_hi:[1,0,1]
	v_pk_fma_f32 v[128:129], v[8:9], v[194:195], v[128:129] op_sel_hi:[1,0,1]
	v_pk_fma_f32 v[132:133], v[10:11], v[194:195], v[132:133] op_sel_hi:[1,0,1]
	v_pk_fma_f32 v[134:135], v[12:13], v[194:195], v[134:135] op_sel_hi:[1,0,1]
	v_pk_fma_f32 v[136:137], v[14:15], v[194:195], v[136:137] op_sel_hi:[1,0,1]
	ds_read_b32 v194, v193 offset:540
	s_waitcnt vmcnt(48)
	v_cvt_scalef32_pk_f32_fp4 v[0:1], v156, 1.0
	v_cvt_scalef32_pk_f32_fp4 v[2:3], v156, 1.0 op_sel:[1,0,0]
	v_cvt_scalef32_pk_f32_fp4 v[4:5], v156, 1.0 op_sel:[0,1,0]
	v_cvt_scalef32_pk_f32_fp4 v[6:7], v156, 1.0 op_sel:[1,1,0]
	v_cvt_scalef32_pk_f32_fp4 v[8:9], v157, 1.0
	v_cvt_scalef32_pk_f32_fp4 v[10:11], v157, 1.0 op_sel:[1,0,0]
	v_cvt_scalef32_pk_f32_fp4 v[12:13], v157, 1.0 op_sel:[0,1,0]
	v_cvt_scalef32_pk_f32_fp4 v[14:15], v157, 1.0 op_sel:[1,1,0]
	v_readlane_b32 s54, v90, 22
	s_lshl_b32 s56, s54, 9
	s_add_u32 s56, s64, s56
	s_addc_u32 s57, s65, 0
	global_load_dwordx2 v[156:157], v227, s[56:57]
	s_waitcnt lgkmcnt(1)
	v_pk_fma_f32 v[130:131], v[0:1], v[76:77], v[130:131] op_sel_hi:[1,0,1]
	v_pk_fma_f32 v[138:139], v[2:3], v[76:77], v[138:139] op_sel_hi:[1,0,1]
	v_pk_fma_f32 v[140:141], v[4:5], v[76:77], v[140:141] op_sel_hi:[1,0,1]
	v_pk_fma_f32 v[142:143], v[6:7], v[76:77], v[142:143] op_sel_hi:[1,0,1]
	v_pk_fma_f32 v[128:129], v[8:9], v[76:77], v[128:129] op_sel_hi:[1,0,1]
	v_pk_fma_f32 v[132:133], v[10:11], v[76:77], v[132:133] op_sel_hi:[1,0,1]
	v_pk_fma_f32 v[134:135], v[12:13], v[76:77], v[134:135] op_sel_hi:[1,0,1]
	v_pk_fma_f32 v[136:137], v[14:15], v[76:77], v[136:137] op_sel_hi:[1,0,1]
	ds_read_b32 v76, v193 offset:544
	s_waitcnt vmcnt(48)
	v_cvt_scalef32_pk_f32_fp4 v[0:1], v158, 1.0
	v_cvt_scalef32_pk_f32_fp4 v[2:3], v158, 1.0 op_sel:[1,0,0]
	v_cvt_scalef32_pk_f32_fp4 v[4:5], v158, 1.0 op_sel:[0,1,0]
	v_cvt_scalef32_pk_f32_fp4 v[6:7], v158, 1.0 op_sel:[1,1,0]
	v_cvt_scalef32_pk_f32_fp4 v[8:9], v159, 1.0
	v_cvt_scalef32_pk_f32_fp4 v[10:11], v159, 1.0 op_sel:[1,0,0]
	v_cvt_scalef32_pk_f32_fp4 v[12:13], v159, 1.0 op_sel:[0,1,0]
	v_cvt_scalef32_pk_f32_fp4 v[14:15], v159, 1.0 op_sel:[1,1,0]
	v_readlane_b32 s54, v90, 23
	s_lshl_b32 s56, s54, 9
	s_add_u32 s56, s64, s56
	s_addc_u32 s57, s65, 0
	global_load_dwordx2 v[158:159], v227, s[56:57]
	s_waitcnt lgkmcnt(1)
	v_pk_fma_f32 v[130:131], v[0:1], v[194:195], v[130:131] op_sel_hi:[1,0,1]
	v_pk_fma_f32 v[138:139], v[2:3], v[194:195], v[138:139] op_sel_hi:[1,0,1]
	v_pk_fma_f32 v[140:141], v[4:5], v[194:195], v[140:141] op_sel_hi:[1,0,1]
	v_pk_fma_f32 v[142:143], v[6:7], v[194:195], v[142:143] op_sel_hi:[1,0,1]
	v_pk_fma_f32 v[128:129], v[8:9], v[194:195], v[128:129] op_sel_hi:[1,0,1]
	v_pk_fma_f32 v[132:133], v[10:11], v[194:195], v[132:133] op_sel_hi:[1,0,1]
	v_pk_fma_f32 v[134:135], v[12:13], v[194:195], v[134:135] op_sel_hi:[1,0,1]
	v_pk_fma_f32 v[136:137], v[14:15], v[194:195], v[136:137] op_sel_hi:[1,0,1]
	ds_read_b32 v194, v193 offset:548
	s_waitcnt vmcnt(48)
; __device__ void peer_gather_phase(const Params& P, int l, bool do_store) {
;     ...
; #pragma unroll
;       for (int j = 0; j < 8; ++j) {
;         const float a = __builtin_bit_cast(float, __builtin_amdgcn_readlane(__builtin_bit_cast(int, avec), kb + j));
;         const f32x2 aa = f32x2{a, a};
;         y[0] += aa * __builtin_amdgcn_cvt_scalef32_pk_f32_fp4(v8[j].x, 1.0f, 0); y[1] += aa * __builtin_amdgcn_cvt_scalef32_pk_f32_fp4(v8[j].x, 1.0f, 1);
;         y[2] += aa * __builtin_amdgcn_cvt_scalef32_pk_f32_fp4(v8[j].x, 1.0f, 2); y[3] += aa * __builtin_amdgcn_cvt_scalef32_pk_f32_fp4(v8[j].x, 1.0f, 3);
;         y[4] += aa * __builtin_amdgcn_cvt_scalef32_pk_f32_fp4(v8[j].y, 1.0f, 0); y[5] += aa * __builtin_amdgcn_cvt_scalef32_pk_f32_fp4(v8[j].y, 1.0f, 1);
;         y[6] += aa * __builtin_amdgcn_cvt_scalef32_pk_f32_fp4(v8[j].y, 1.0f, 2); y[7] += aa * __builtin_amdgcn_cvt_scalef32_pk_f32_fp4(v8[j].y, 1.0f, 3);
;       }
	v_cvt_scalef32_pk_f32_fp4 v[0:1], v168, 1.0
	v_cvt_scalef32_pk_f32_fp4 v[2:3], v168, 1.0 op_sel:[1,0,0]
	v_cvt_scalef32_pk_f32_fp4 v[4:5], v168, 1.0 op_sel:[0,1,0]
	v_cvt_scalef32_pk_f32_fp4 v[6:7], v168, 1.0 op_sel:[1,1,0]
	v_cvt_scalef32_pk_f32_fp4 v[8:9], v169, 1.0
	v_cvt_scalef32_pk_f32_fp4 v[10:11], v169, 1.0 op_sel:[1,0,0]
	v_cvt_scalef32_pk_f32_fp4 v[12:13], v169, 1.0 op_sel:[0,1,0]
	v_cvt_scalef32_pk_f32_fp4 v[14:15], v169, 1.0 op_sel:[1,1,0]
	v_readlane_b32 s54, v90, 24
	s_lshl_b32 s56, s54, 9
	s_add_u32 s56, s64, s56
	s_addc_u32 s57, s65, 0
	global_load_dwordx2 v[168:169], v227, s[56:57]
	s_waitcnt lgkmcnt(1)
	v_pk_fma_f32 v[130:131], v[0:1], v[76:77], v[130:131] op_sel_hi:[1,0,1]
	v_pk_fma_f32 v[138:139], v[2:3], v[76:77], v[138:139] op_sel_hi:[1,0,1]
	v_pk_fma_f32 v[140:141], v[4:5], v[76:77], v[140:141] op_sel_hi:[1,0,1]
	v_pk_fma_f32 v[142:143], v[6:7], v[76:77], v[142:143] op_sel_hi:[1,0,1]
	v_pk_fma_f32 v[128:129], v[8:9], v[76:77], v[128:129] op_sel_hi:[1,0,1]
	v_pk_fma_f32 v[132:133], v[10:11], v[76:77], v[132:133] op_sel_hi:[1,0,1]
	v_pk_fma_f32 v[134:135], v[12:13], v[76:77], v[134:135] op_sel_hi:[1,0,1]
	v_pk_fma_f32 v[136:137], v[14:15], v[76:77], v[136:137] op_sel_hi:[1,0,1]
	ds_read_b32 v76, v193 offset:552
	s_waitcnt vmcnt(48)
	v_cvt_scalef32_pk_f32_fp4 v[0:1], v170, 1.0
	v_cvt_scalef32_pk_f32_fp4 v[2:3], v170, 1.0 op_sel:[1,0,0]
	v_cvt_scalef32_pk_f32_fp4 v[4:5], v170, 1.0 op_sel:[0,1,0]
	v_cvt_scalef32_pk_f32_fp4 v[6:7], v170, 1.0 op_sel:[1,1,0]
	v_cvt_scalef32_pk_f32_fp4 v[8:9], v171, 1.0
	v_cvt_scalef32_pk_f32_fp4 v[10:11], v171, 1.0 op_sel:[1,0,0]
	v_cvt_scalef32_pk_f32_fp4 v[12:13], v171, 1.0 op_sel:[0,1,0]
	v_cvt_scalef32_pk_f32_fp4 v[14:15], v171, 1.0 op_sel:[1,1,0]
	v_readlane_b32 s54, v90, 25
	s_lshl_b32 s56, s54, 9
	s_add_u32 s56, s64, s56
	s_addc_u32 s57, s65, 0
	global_load_dwordx2 v[170:171], v227, s[56:57]
	s_waitcnt lgkmcnt(1)
	v_pk_fma_f32 v[130:131], v[0:1], v[194:195], v[130:131] op_sel_hi:[1,0,1]
	v_pk_fma_f32 v[138:139], v[2:3], v[194:195], v[138:139] op_sel_hi:[1,0,1]
	v_pk_fma_f32 v[140:141], v[4:5], v[194:195], v[140:141] op_sel_hi:[1,0,1]
	v_pk_fma_f32 v[142:143], v[6:7], v[194:195], v[142:143] op_sel_hi:[1,0,1]
	v_pk_fma_f32 v[128:129], v[8:9], v[194:195], v[128:129] op_sel_hi:[1,0,1]
	v_pk_fma_f32 v[132:133], v[10:11], v[194:195], v[132:133] op_sel_hi:[1,0,1]
	v_pk_fma_f32 v[134:135], v[12:13], v[194:195], v[134:135] op_sel_hi:[1,0,1]
	v_pk_fma_f32 v[136:137], v[14:15], v[194:195], v[136:137] op_sel_hi:[1,0,1]
	ds_read_b32 v194, v193 offset:556
	s_waitcnt vmcnt(48)
	v_cvt_scalef32_pk_f32_fp4 v[0:1], v172, 1.0
	v_cvt_scalef32_pk_f32_fp4 v[2:3], v172, 1.0 op_sel:[1,0,0]
	v_cvt_scalef32_pk_f32_fp4 v[4:5], v172, 1.0 op_sel:[0,1,0]
	v_cvt_scalef32_pk_f32_fp4 v[6:7], v172, 1.0 op_sel:[1,1,0]
	v_cvt_scalef32_pk_f32_fp4 v[8:9], v173, 1.0
	v_cvt_scalef32_pk_f32_fp4 v[10:11], v173, 1.0 op_sel:[1,0,0]
	v_cvt_scalef32_pk_f32_fp4 v[12:13], v173, 1.0 op_sel:[0,1,0]
	v_cvt_scalef32_pk_f32_fp4 v[14:15], v173, 1.0 op_sel:[1,1,0]
	v_readlane_b32 s54, v90, 26
	s_lshl_b32 s56, s54, 9
	s_add_u32 s56, s64, s56
	s_addc_u32 s57, s65, 0
	global_load_dwordx2 v[172:173], v227, s[56:57]
	s_waitcnt lgkmcnt(1)
	v_pk_fma_f32 v[130:131], v[0:1], v[76:77], v[130:131] op_sel_hi:[1,0,1]
	v_pk_fma_f32 v[138:139], v[2:3], v[76:77], v[138:139] op_sel_hi:[1,0,1]
	v_pk_fma_f32 v[140:141], v[4:5], v[76:77], v[140:141] op_sel_hi:[1,0,1]
	v_pk_fma_f32 v[142:143], v[6:7], v[76:77], v[142:143] op_sel_hi:[1,0,1]
	v_pk_fma_f32 v[128:129], v[8:9], v[76:77], v[128:129] op_sel_hi:[1,0,1]
	v_pk_fma_f32 v[132:133], v[10:11], v[76:77], v[132:133] op_sel_hi:[1,0,1]
	v_pk_fma_f32 v[134:135], v[12:13], v[76:77], v[134:135] op_sel_hi:[1,0,1]
	v_pk_fma_f32 v[136:137], v[14:15], v[76:77], v[136:137] op_sel_hi:[1,0,1]
	ds_read_b32 v76, v193 offset:560
	s_waitcnt vmcnt(48)
	v_cvt_scalef32_pk_f32_fp4 v[0:1], v174, 1.0
	v_cvt_scalef32_pk_f32_fp4 v[2:3], v174, 1.0 op_sel:[1,0,0]
	v_cvt_scalef32_pk_f32_fp4 v[4:5], v174, 1.0 op_sel:[0,1,0]
	v_cvt_scalef32_pk_f32_fp4 v[6:7], v174, 1.0 op_sel:[1,1,0]
	v_cvt_scalef32_pk_f32_fp4 v[8:9], v175, 1.0
	v_cvt_scalef32_pk_f32_fp4 v[10:11], v175, 1.0 op_sel:[1,0,0]
	v_cvt_scalef32_pk_f32_fp4 v[12:13], v175, 1.0 op_sel:[0,1,0]
	v_cvt_scalef32_pk_f32_fp4 v[14:15], v175, 1.0 op_sel:[1,1,0]
	v_readlane_b32 s54, v90, 27
	s_lshl_b32 s56, s54, 9
	s_add_u32 s56, s64, s56
	s_addc_u32 s57, s65, 0
	global_load_dwordx2 v[174:175], v227, s[56:57]
	s_waitcnt lgkmcnt(1)
	v_pk_fma_f32 v[130:131], v[0:1], v[194:195], v[130:131] op_sel_hi:[1,0,1]
	v_pk_fma_f32 v[138:139], v[2:3], v[194:195], v[138:139] op_sel_hi:[1,0,1]
	v_pk_fma_f32 v[140:141], v[4:5], v[194:195], v[140:141] op_sel_hi:[1,0,1]
	v_pk_fma_f32 v[142:143], v[6:7], v[194:195], v[142:143] op_sel_hi:[1,0,1]
	v_pk_fma_f32 v[128:129], v[8:9], v[194:195], v[128:129] op_sel_hi:[1,0,1]
	v_pk_fma_f32 v[132:133], v[10:11], v[194:195], v[132:133] op_sel_hi:[1,0,1]
	v_pk_fma_f32 v[134:135], v[12:13], v[194:195], v[134:135] op_sel_hi:[1,0,1]
	v_pk_fma_f32 v[136:137], v[14:15], v[194:195], v[136:137] op_sel_hi:[1,0,1]
	ds_read_b32 v194, v193 offset:564
	s_waitcnt vmcnt(48)
	v_cvt_scalef32_pk_f32_fp4 v[0:1], v180, 1.0
	v_cvt_scalef32_pk_f32_fp4 v[2:3], v180, 1.0 op_sel:[1,0,0]
	v_cvt_scalef32_pk_f32_fp4 v[4:5], v180, 1.0 op_sel:[0,1,0]
	v_cvt_scalef32_pk_f32_fp4 v[6:7], v180, 1.0 op_sel:[1,1,0]
	v_cvt_scalef32_pk_f32_fp4 v[8:9], v181, 1.0
	v_cvt_scalef32_pk_f32_fp4 v[10:11], v181, 1.0 op_sel:[1,0,0]
	v_cvt_scalef32_pk_f32_fp4 v[12:13], v181, 1.0 op_sel:[0,1,0]
	v_cvt_scalef32_pk_f32_fp4 v[14:15], v181, 1.0 op_sel:[1,1,0]
	v_readlane_b32 s54, v90, 28
	s_lshl_b32 s56, s54, 9
	s_add_u32 s56, s64, s56
	s_addc_u32 s57, s65, 0
	global_load_dwordx2 v[180:181], v227, s[56:57]
	s_waitcnt lgkmcnt(1)
; __device__ void peer_gather_phase(const Params& P, int l, bool do_store) {
;     ...
; #pragma unroll
;       for (int j = 0; j < 8; ++j) {
;         const float a = __builtin_bit_cast(float, __builtin_amdgcn_readlane(__builtin_bit_cast(int, avec), kb + j));
;         const f32x2 aa = f32x2{a, a};
;         y[0] += aa * __builtin_amdgcn_cvt_scalef32_pk_f32_fp4(v8[j].x, 1.0f, 0); y[1] += aa * __builtin_amdgcn_cvt_scalef32_pk_f32_fp4(v8[j].x, 1.0f, 1);
;         y[2] += aa * __builtin_amdgcn_cvt_scalef32_pk_f32_fp4(v8[j].x, 1.0f, 2); y[3] += aa * __builtin_amdgcn_cvt_scalef32_pk_f32_fp4(v8[j].x, 1.0f, 3);
;         y[4] += aa * __builtin_amdgcn_cvt_scalef32_pk_f32_fp4(v8[j].y, 1.0f, 0); y[5] += aa * __builtin_amdgcn_cvt_scalef32_pk_f32_fp4(v8[j].y, 1.0f, 1);
;         y[6] += aa * __builtin_amdgcn_cvt_scalef32_pk_f32_fp4(v8[j].y, 1.0f, 2); y[7] += aa * __builtin_amdgcn_cvt_scalef32_pk_f32_fp4(v8[j].y, 1.0f, 3);
;       }
	v_pk_fma_f32 v[130:131], v[0:1], v[76:77], v[130:131] op_sel_hi:[1,0,1]
	v_pk_fma_f32 v[138:139], v[2:3], v[76:77], v[138:139] op_sel_hi:[1,0,1]
	v_pk_fma_f32 v[140:141], v[4:5], v[76:77], v[140:141] op_sel_hi:[1,0,1]
	v_pk_fma_f32 v[142:143], v[6:7], v[76:77], v[142:143] op_sel_hi:[1,0,1]
	v_pk_fma_f32 v[128:129], v[8:9], v[76:77], v[128:129] op_sel_hi:[1,0,1]
	v_pk_fma_f32 v[132:133], v[10:11], v[76:77], v[132:133] op_sel_hi:[1,0,1]
	v_pk_fma_f32 v[134:135], v[12:13], v[76:77], v[134:135] op_sel_hi:[1,0,1]
	v_pk_fma_f32 v[136:137], v[14:15], v[76:77], v[136:137] op_sel_hi:[1,0,1]
	ds_read_b32 v76, v193 offset:568
	s_waitcnt vmcnt(48)
	v_cvt_scalef32_pk_f32_fp4 v[0:1], v182, 1.0
	v_cvt_scalef32_pk_f32_fp4 v[2:3], v182, 1.0 op_sel:[1,0,0]
	v_cvt_scalef32_pk_f32_fp4 v[4:5], v182, 1.0 op_sel:[0,1,0]
	v_cvt_scalef32_pk_f32_fp4 v[6:7], v182, 1.0 op_sel:[1,1,0]
	v_cvt_scalef32_pk_f32_fp4 v[8:9], v183, 1.0
	v_cvt_scalef32_pk_f32_fp4 v[10:11], v183, 1.0 op_sel:[1,0,0]
	v_cvt_scalef32_pk_f32_fp4 v[12:13], v183, 1.0 op_sel:[0,1,0]
	v_cvt_scalef32_pk_f32_fp4 v[14:15], v183, 1.0 op_sel:[1,1,0]
	v_readlane_b32 s54, v90, 29
	s_lshl_b32 s56, s54, 9
	s_add_u32 s56, s64, s56
	s_addc_u32 s57, s65, 0
	global_load_dwordx2 v[182:183], v227, s[56:57]
	s_waitcnt lgkmcnt(1)
	v_pk_fma_f32 v[130:131], v[0:1], v[194:195], v[130:131] op_sel_hi:[1,0,1]
	v_pk_fma_f32 v[138:139], v[2:3], v[194:195], v[138:139] op_sel_hi:[1,0,1]
	v_pk_fma_f32 v[140:141], v[4:5], v[194:195], v[140:141] op_sel_hi:[1,0,1]
	v_pk_fma_f32 v[142:143], v[6:7], v[194:195], v[142:143] op_sel_hi:[1,0,1]
	v_pk_fma_f32 v[128:129], v[8:9], v[194:195], v[128:129] op_sel_hi:[1,0,1]
	v_pk_fma_f32 v[132:133], v[10:11], v[194:195], v[132:133] op_sel_hi:[1,0,1]
	v_pk_fma_f32 v[134:135], v[12:13], v[194:195], v[134:135] op_sel_hi:[1,0,1]
	v_pk_fma_f32 v[136:137], v[14:15], v[194:195], v[136:137] op_sel_hi:[1,0,1]
	ds_read_b32 v194, v193 offset:572
	s_waitcnt vmcnt(48)
	v_cvt_scalef32_pk_f32_fp4 v[0:1], v184, 1.0
	v_cvt_scalef32_pk_f32_fp4 v[2:3], v184, 1.0 op_sel:[1,0,0]
	v_cvt_scalef32_pk_f32_fp4 v[4:5], v184, 1.0 op_sel:[0,1,0]
	v_cvt_scalef32_pk_f32_fp4 v[6:7], v184, 1.0 op_sel:[1,1,0]
	v_cvt_scalef32_pk_f32_fp4 v[8:9], v185, 1.0
	v_cvt_scalef32_pk_f32_fp4 v[10:11], v185, 1.0 op_sel:[1,0,0]
	v_cvt_scalef32_pk_f32_fp4 v[12:13], v185, 1.0 op_sel:[0,1,0]
	v_cvt_scalef32_pk_f32_fp4 v[14:15], v185, 1.0 op_sel:[1,1,0]
	v_readlane_b32 s54, v90, 30
	s_lshl_b32 s56, s54, 9
	s_add_u32 s56, s64, s56
	s_addc_u32 s57, s65, 0
	global_load_dwordx2 v[184:185], v227, s[56:57]
	s_waitcnt lgkmcnt(1)
	v_pk_fma_f32 v[130:131], v[0:1], v[76:77], v[130:131] op_sel_hi:[1,0,1]
	v_pk_fma_f32 v[138:139], v[2:3], v[76:77], v[138:139] op_sel_hi:[1,0,1]
	v_pk_fma_f32 v[140:141], v[4:5], v[76:77], v[140:141] op_sel_hi:[1,0,1]
	v_pk_fma_f32 v[142:143], v[6:7], v[76:77], v[142:143] op_sel_hi:[1,0,1]
	v_pk_fma_f32 v[128:129], v[8:9], v[76:77], v[128:129] op_sel_hi:[1,0,1]
	v_pk_fma_f32 v[132:133], v[10:11], v[76:77], v[132:133] op_sel_hi:[1,0,1]
	v_pk_fma_f32 v[134:135], v[12:13], v[76:77], v[134:135] op_sel_hi:[1,0,1]
	v_pk_fma_f32 v[136:137], v[14:15], v[76:77], v[136:137] op_sel_hi:[1,0,1]
	ds_read_b32 v76, v193 offset:576
	s_waitcnt vmcnt(48)
	v_cvt_scalef32_pk_f32_fp4 v[0:1], v186, 1.0
	v_cvt_scalef32_pk_f32_fp4 v[2:3], v186, 1.0 op_sel:[1,0,0]
	v_cvt_scalef32_pk_f32_fp4 v[4:5], v186, 1.0 op_sel:[0,1,0]
	v_cvt_scalef32_pk_f32_fp4 v[6:7], v186, 1.0 op_sel:[1,1,0]
	v_cvt_scalef32_pk_f32_fp4 v[8:9], v187, 1.0
	v_cvt_scalef32_pk_f32_fp4 v[10:11], v187, 1.0 op_sel:[1,0,0]
	v_cvt_scalef32_pk_f32_fp4 v[12:13], v187, 1.0 op_sel:[0,1,0]
	v_cvt_scalef32_pk_f32_fp4 v[14:15], v187, 1.0 op_sel:[1,1,0]
	v_readlane_b32 s54, v90, 31
	s_lshl_b32 s56, s54, 9
	s_add_u32 s56, s64, s56
	s_addc_u32 s57, s65, 0
	global_load_dwordx2 v[186:187], v227, s[56:57]
	s_waitcnt lgkmcnt(1)
	v_pk_fma_f32 v[130:131], v[0:1], v[194:195], v[130:131] op_sel_hi:[1,0,1]
	v_pk_fma_f32 v[138:139], v[2:3], v[194:195], v[138:139] op_sel_hi:[1,0,1]
	v_pk_fma_f32 v[140:141], v[4:5], v[194:195], v[140:141] op_sel_hi:[1,0,1]
	v_pk_fma_f32 v[142:143], v[6:7], v[194:195], v[142:143] op_sel_hi:[1,0,1]
	v_pk_fma_f32 v[128:129], v[8:9], v[194:195], v[128:129] op_sel_hi:[1,0,1]
	v_pk_fma_f32 v[132:133], v[10:11], v[194:195], v[132:133] op_sel_hi:[1,0,1]
	v_pk_fma_f32 v[134:135], v[12:13], v[194:195], v[134:135] op_sel_hi:[1,0,1]
	v_pk_fma_f32 v[136:137], v[14:15], v[194:195], v[136:137] op_sel_hi:[1,0,1]
	ds_read_b32 v194, v193 offset:580
	s_waitcnt vmcnt(15)
	v_cvt_scalef32_pk_f32_fp4 v[0:1], v144, 1.0
	v_cvt_scalef32_pk_f32_fp4 v[2:3], v144, 1.0 op_sel:[1,0,0]
	v_cvt_scalef32_pk_f32_fp4 v[4:5], v144, 1.0 op_sel:[0,1,0]
	v_cvt_scalef32_pk_f32_fp4 v[6:7], v144, 1.0 op_sel:[1,1,0]
	v_cvt_scalef32_pk_f32_fp4 v[8:9], v145, 1.0
	v_cvt_scalef32_pk_f32_fp4 v[10:11], v145, 1.0 op_sel:[1,0,0]
	v_cvt_scalef32_pk_f32_fp4 v[12:13], v145, 1.0 op_sel:[0,1,0]
	v_cvt_scalef32_pk_f32_fp4 v[14:15], v145, 1.0 op_sel:[1,1,0]
	v_readlane_b32 s54, v90, 32
	s_lshl_b32 s56, s54, 9
	s_add_u32 s56, s64, s56
	s_addc_u32 s57, s65, 0
	global_load_dwordx2 v[144:145], v227, s[56:57]
	s_waitcnt lgkmcnt(1)
	v_pk_fma_f32 v[130:131], v[0:1], v[76:77], v[130:131] op_sel_hi:[1,0,1]
	v_pk_fma_f32 v[138:139], v[2:3], v[76:77], v[138:139] op_sel_hi:[1,0,1]
	v_pk_fma_f32 v[140:141], v[4:5], v[76:77], v[140:141] op_sel_hi:[1,0,1]
	v_pk_fma_f32 v[142:143], v[6:7], v[76:77], v[142:143] op_sel_hi:[1,0,1]
	v_pk_fma_f32 v[128:129], v[8:9], v[76:77], v[128:129] op_sel_hi:[1,0,1]
	v_pk_fma_f32 v[132:133], v[10:11], v[76:77], v[132:133] op_sel_hi:[1,0,1]
	v_pk_fma_f32 v[134:135], v[12:13], v[76:77], v[134:135] op_sel_hi:[1,0,1]
	v_pk_fma_f32 v[136:137], v[14:15], v[76:77], v[136:137] op_sel_hi:[1,0,1]
	ds_read_b32 v76, v193 offset:584
	s_waitcnt vmcnt(15)
; __device__ void peer_gather_phase(const Params& P, int l, bool do_store) {
;     ...
; #pragma unroll
;       for (int j = 0; j < 8; ++j) {
;         const float a = __builtin_bit_cast(float, __builtin_amdgcn_readlane(__builtin_bit_cast(int, avec), kb + j));
;         const f32x2 aa = f32x2{a, a};
;         y[0] += aa * __builtin_amdgcn_cvt_scalef32_pk_f32_fp4(v8[j].x, 1.0f, 0); y[1] += aa * __builtin_amdgcn_cvt_scalef32_pk_f32_fp4(v8[j].x, 1.0f, 1);
;         y[2] += aa * __builtin_amdgcn_cvt_scalef32_pk_f32_fp4(v8[j].x, 1.0f, 2); y[3] += aa * __builtin_amdgcn_cvt_scalef32_pk_f32_fp4(v8[j].x, 1.0f, 3);
;         y[4] += aa * __builtin_amdgcn_cvt_scalef32_pk_f32_fp4(v8[j].y, 1.0f, 0); y[5] += aa * __builtin_amdgcn_cvt_scalef32_pk_f32_fp4(v8[j].y, 1.0f, 1);
;         y[6] += aa * __builtin_amdgcn_cvt_scalef32_pk_f32_fp4(v8[j].y, 1.0f, 2); y[7] += aa * __builtin_amdgcn_cvt_scalef32_pk_f32_fp4(v8[j].y, 1.0f, 3);
;       }
	v_cvt_scalef32_pk_f32_fp4 v[0:1], v146, 1.0
	v_cvt_scalef32_pk_f32_fp4 v[2:3], v146, 1.0 op_sel:[1,0,0]
	v_cvt_scalef32_pk_f32_fp4 v[4:5], v146, 1.0 op_sel:[0,1,0]
	v_cvt_scalef32_pk_f32_fp4 v[6:7], v146, 1.0 op_sel:[1,1,0]
	v_cvt_scalef32_pk_f32_fp4 v[8:9], v147, 1.0
	v_cvt_scalef32_pk_f32_fp4 v[10:11], v147, 1.0 op_sel:[1,0,0]
	v_cvt_scalef32_pk_f32_fp4 v[12:13], v147, 1.0 op_sel:[0,1,0]
	v_cvt_scalef32_pk_f32_fp4 v[14:15], v147, 1.0 op_sel:[1,1,0]
	v_readlane_b32 s54, v90, 33
	s_lshl_b32 s56, s54, 9
	s_add_u32 s56, s64, s56
	s_addc_u32 s57, s65, 0
	global_load_dwordx2 v[146:147], v227, s[56:57]
	s_waitcnt lgkmcnt(1)
	v_pk_fma_f32 v[130:131], v[0:1], v[194:195], v[130:131] op_sel_hi:[1,0,1]
	v_pk_fma_f32 v[138:139], v[2:3], v[194:195], v[138:139] op_sel_hi:[1,0,1]
	v_pk_fma_f32 v[140:141], v[4:5], v[194:195], v[140:141] op_sel_hi:[1,0,1]
	v_pk_fma_f32 v[142:143], v[6:7], v[194:195], v[142:143] op_sel_hi:[1,0,1]
	v_pk_fma_f32 v[128:129], v[8:9], v[194:195], v[128:129] op_sel_hi:[1,0,1]
	v_pk_fma_f32 v[132:133], v[10:11], v[194:195], v[132:133] op_sel_hi:[1,0,1]
	v_pk_fma_f32 v[134:135], v[12:13], v[194:195], v[134:135] op_sel_hi:[1,0,1]
	v_pk_fma_f32 v[136:137], v[14:15], v[194:195], v[136:137] op_sel_hi:[1,0,1]
	ds_read_b32 v194, v193 offset:588
	s_waitcnt vmcnt(15)
	v_cvt_scalef32_pk_f32_fp4 v[0:1], v148, 1.0
	v_cvt_scalef32_pk_f32_fp4 v[2:3], v148, 1.0 op_sel:[1,0,0]
	v_cvt_scalef32_pk_f32_fp4 v[4:5], v148, 1.0 op_sel:[0,1,0]
	v_cvt_scalef32_pk_f32_fp4 v[6:7], v148, 1.0 op_sel:[1,1,0]
	v_cvt_scalef32_pk_f32_fp4 v[8:9], v149, 1.0
	v_cvt_scalef32_pk_f32_fp4 v[10:11], v149, 1.0 op_sel:[1,0,0]
	v_cvt_scalef32_pk_f32_fp4 v[12:13], v149, 1.0 op_sel:[0,1,0]
	v_cvt_scalef32_pk_f32_fp4 v[14:15], v149, 1.0 op_sel:[1,1,0]
	v_readlane_b32 s54, v90, 34
	s_lshl_b32 s56, s54, 9
	s_add_u32 s56, s64, s56
	s_addc_u32 s57, s65, 0
	global_load_dwordx2 v[148:149], v227, s[56:57]
	s_waitcnt lgkmcnt(1)
	v_pk_fma_f32 v[130:131], v[0:1], v[76:77], v[130:131] op_sel_hi:[1,0,1]
	v_pk_fma_f32 v[138:139], v[2:3], v[76:77], v[138:139] op_sel_hi:[1,0,1]
	v_pk_fma_f32 v[140:141], v[4:5], v[76:77], v[140:141] op_sel_hi:[1,0,1]
	v_pk_fma_f32 v[142:143], v[6:7], v[76:77], v[142:143] op_sel_hi:[1,0,1]
	v_pk_fma_f32 v[128:129], v[8:9], v[76:77], v[128:129] op_sel_hi:[1,0,1]
	v_pk_fma_f32 v[132:133], v[10:11], v[76:77], v[132:133] op_sel_hi:[1,0,1]
	v_pk_fma_f32 v[134:135], v[12:13], v[76:77], v[134:135] op_sel_hi:[1,0,1]
	v_pk_fma_f32 v[136:137], v[14:15], v[76:77], v[136:137] op_sel_hi:[1,0,1]
	ds_read_b32 v76, v193 offset:592
	s_waitcnt vmcnt(15)
	v_cvt_scalef32_pk_f32_fp4 v[0:1], v150, 1.0
	v_cvt_scalef32_pk_f32_fp4 v[2:3], v150, 1.0 op_sel:[1,0,0]
	v_cvt_scalef32_pk_f32_fp4 v[4:5], v150, 1.0 op_sel:[0,1,0]
	v_cvt_scalef32_pk_f32_fp4 v[6:7], v150, 1.0 op_sel:[1,1,0]
	v_cvt_scalef32_pk_f32_fp4 v[8:9], v151, 1.0
	v_cvt_scalef32_pk_f32_fp4 v[10:11], v151, 1.0 op_sel:[1,0,0]
	v_cvt_scalef32_pk_f32_fp4 v[12:13], v151, 1.0 op_sel:[0,1,0]
	v_cvt_scalef32_pk_f32_fp4 v[14:15], v151, 1.0 op_sel:[1,1,0]
	v_readlane_b32 s54, v90, 35
	s_lshl_b32 s56, s54, 9
	s_add_u32 s56, s64, s56
	s_addc_u32 s57, s65, 0
	global_load_dwordx2 v[150:151], v227, s[56:57]
	s_waitcnt lgkmcnt(1)
	v_pk_fma_f32 v[130:131], v[0:1], v[194:195], v[130:131] op_sel_hi:[1,0,1]
	v_pk_fma_f32 v[138:139], v[2:3], v[194:195], v[138:139] op_sel_hi:[1,0,1]
	v_pk_fma_f32 v[140:141], v[4:5], v[194:195], v[140:141] op_sel_hi:[1,0,1]
	v_pk_fma_f32 v[142:143], v[6:7], v[194:195], v[142:143] op_sel_hi:[1,0,1]
	v_pk_fma_f32 v[128:129], v[8:9], v[194:195], v[128:129] op_sel_hi:[1,0,1]
	v_pk_fma_f32 v[132:133], v[10:11], v[194:195], v[132:133] op_sel_hi:[1,0,1]
	v_pk_fma_f32 v[134:135], v[12:13], v[194:195], v[134:135] op_sel_hi:[1,0,1]
	v_pk_fma_f32 v[136:137], v[14:15], v[194:195], v[136:137] op_sel_hi:[1,0,1]
	ds_read_b32 v194, v193 offset:596
	s_waitcnt vmcnt(15)
	v_cvt_scalef32_pk_f32_fp4 v[0:1], v152, 1.0
	v_cvt_scalef32_pk_f32_fp4 v[2:3], v152, 1.0 op_sel:[1,0,0]
	v_cvt_scalef32_pk_f32_fp4 v[4:5], v152, 1.0 op_sel:[0,1,0]
	v_cvt_scalef32_pk_f32_fp4 v[6:7], v152, 1.0 op_sel:[1,1,0]
	v_cvt_scalef32_pk_f32_fp4 v[8:9], v153, 1.0
	v_cvt_scalef32_pk_f32_fp4 v[10:11], v153, 1.0 op_sel:[1,0,0]
	v_cvt_scalef32_pk_f32_fp4 v[12:13], v153, 1.0 op_sel:[0,1,0]
	v_cvt_scalef32_pk_f32_fp4 v[14:15], v153, 1.0 op_sel:[1,1,0]
	v_readlane_b32 s54, v90, 36
	s_lshl_b32 s56, s54, 9
	s_add_u32 s56, s64, s56
	s_addc_u32 s57, s65, 0
	global_load_dwordx2 v[152:153], v227, s[56:57]
	s_waitcnt lgkmcnt(1)
	v_pk_fma_f32 v[130:131], v[0:1], v[76:77], v[130:131] op_sel_hi:[1,0,1]
	v_pk_fma_f32 v[138:139], v[2:3], v[76:77], v[138:139] op_sel_hi:[1,0,1]
	v_pk_fma_f32 v[140:141], v[4:5], v[76:77], v[140:141] op_sel_hi:[1,0,1]
	v_pk_fma_f32 v[142:143], v[6:7], v[76:77], v[142:143] op_sel_hi:[1,0,1]
	v_pk_fma_f32 v[128:129], v[8:9], v[76:77], v[128:129] op_sel_hi:[1,0,1]
	v_pk_fma_f32 v[132:133], v[10:11], v[76:77], v[132:133] op_sel_hi:[1,0,1]
	v_pk_fma_f32 v[134:135], v[12:13], v[76:77], v[134:135] op_sel_hi:[1,0,1]
	v_pk_fma_f32 v[136:137], v[14:15], v[76:77], v[136:137] op_sel_hi:[1,0,1]
	ds_read_b32 v76, v193 offset:600
	s_waitcnt vmcnt(15)
	v_cvt_scalef32_pk_f32_fp4 v[0:1], v154, 1.0
	v_cvt_scalef32_pk_f32_fp4 v[2:3], v154, 1.0 op_sel:[1,0,0]
	v_cvt_scalef32_pk_f32_fp4 v[4:5], v154, 1.0 op_sel:[0,1,0]
	v_cvt_scalef32_pk_f32_fp4 v[6:7], v154, 1.0 op_sel:[1,1,0]
	v_cvt_scalef32_pk_f32_fp4 v[8:9], v155, 1.0
	v_cvt_scalef32_pk_f32_fp4 v[10:11], v155, 1.0 op_sel:[1,0,0]
	v_cvt_scalef32_pk_f32_fp4 v[12:13], v155, 1.0 op_sel:[0,1,0]
	v_cvt_scalef32_pk_f32_fp4 v[14:15], v155, 1.0 op_sel:[1,1,0]
	v_readlane_b32 s54, v90, 37
	s_lshl_b32 s56, s54, 9
	s_add_u32 s56, s64, s56
	s_addc_u32 s57, s65, 0
	global_load_dwordx2 v[154:155], v227, s[56:57]
	s_waitcnt lgkmcnt(1)
; __device__ void peer_gather_phase(const Params& P, int l, bool do_store) {
;     ...
; #pragma unroll
;       for (int j = 0; j < 8; ++j) {
;         const float a = __builtin_bit_cast(float, __builtin_amdgcn_readlane(__builtin_bit_cast(int, avec), kb + j));
;         const f32x2 aa = f32x2{a, a};
;         y[0] += aa * __builtin_amdgcn_cvt_scalef32_pk_f32_fp4(v8[j].x, 1.0f, 0); y[1] += aa * __builtin_amdgcn_cvt_scalef32_pk_f32_fp4(v8[j].x, 1.0f, 1);
;         y[2] += aa * __builtin_amdgcn_cvt_scalef32_pk_f32_fp4(v8[j].x, 1.0f, 2); y[3] += aa * __builtin_amdgcn_cvt_scalef32_pk_f32_fp4(v8[j].x, 1.0f, 3);
;         y[4] += aa * __builtin_amdgcn_cvt_scalef32_pk_f32_fp4(v8[j].y, 1.0f, 0); y[5] += aa * __builtin_amdgcn_cvt_scalef32_pk_f32_fp4(v8[j].y, 1.0f, 1);
;         y[6] += aa * __builtin_amdgcn_cvt_scalef32_pk_f32_fp4(v8[j].y, 1.0f, 2); y[7] += aa * __builtin_amdgcn_cvt_scalef32_pk_f32_fp4(v8[j].y, 1.0f, 3);
;       }
	v_pk_fma_f32 v[130:131], v[0:1], v[194:195], v[130:131] op_sel_hi:[1,0,1]
	v_pk_fma_f32 v[138:139], v[2:3], v[194:195], v[138:139] op_sel_hi:[1,0,1]
	v_pk_fma_f32 v[140:141], v[4:5], v[194:195], v[140:141] op_sel_hi:[1,0,1]
	v_pk_fma_f32 v[142:143], v[6:7], v[194:195], v[142:143] op_sel_hi:[1,0,1]
	v_pk_fma_f32 v[128:129], v[8:9], v[194:195], v[128:129] op_sel_hi:[1,0,1]
	v_pk_fma_f32 v[132:133], v[10:11], v[194:195], v[132:133] op_sel_hi:[1,0,1]
	v_pk_fma_f32 v[134:135], v[12:13], v[194:195], v[134:135] op_sel_hi:[1,0,1]
	v_pk_fma_f32 v[136:137], v[14:15], v[194:195], v[136:137] op_sel_hi:[1,0,1]
	ds_read_b32 v194, v193 offset:604
	s_waitcnt vmcnt(15)
	v_cvt_scalef32_pk_f32_fp4 v[0:1], v156, 1.0
	v_cvt_scalef32_pk_f32_fp4 v[2:3], v156, 1.0 op_sel:[1,0,0]
	v_cvt_scalef32_pk_f32_fp4 v[4:5], v156, 1.0 op_sel:[0,1,0]
	v_cvt_scalef32_pk_f32_fp4 v[6:7], v156, 1.0 op_sel:[1,1,0]
	v_cvt_scalef32_pk_f32_fp4 v[8:9], v157, 1.0
	v_cvt_scalef32_pk_f32_fp4 v[10:11], v157, 1.0 op_sel:[1,0,0]
	v_cvt_scalef32_pk_f32_fp4 v[12:13], v157, 1.0 op_sel:[0,1,0]
	v_cvt_scalef32_pk_f32_fp4 v[14:15], v157, 1.0 op_sel:[1,1,0]
	v_readlane_b32 s54, v90, 38
	s_lshl_b32 s56, s54, 9
	s_add_u32 s56, s64, s56
	s_addc_u32 s57, s65, 0
	global_load_dwordx2 v[156:157], v227, s[56:57]
	s_waitcnt lgkmcnt(1)
	v_pk_fma_f32 v[130:131], v[0:1], v[76:77], v[130:131] op_sel_hi:[1,0,1]
	v_pk_fma_f32 v[138:139], v[2:3], v[76:77], v[138:139] op_sel_hi:[1,0,1]
	v_pk_fma_f32 v[140:141], v[4:5], v[76:77], v[140:141] op_sel_hi:[1,0,1]
	v_pk_fma_f32 v[142:143], v[6:7], v[76:77], v[142:143] op_sel_hi:[1,0,1]
	v_pk_fma_f32 v[128:129], v[8:9], v[76:77], v[128:129] op_sel_hi:[1,0,1]
	v_pk_fma_f32 v[132:133], v[10:11], v[76:77], v[132:133] op_sel_hi:[1,0,1]
	v_pk_fma_f32 v[134:135], v[12:13], v[76:77], v[134:135] op_sel_hi:[1,0,1]
	v_pk_fma_f32 v[136:137], v[14:15], v[76:77], v[136:137] op_sel_hi:[1,0,1]
	ds_read_b32 v76, v193 offset:608
	s_waitcnt vmcnt(15)
	v_cvt_scalef32_pk_f32_fp4 v[0:1], v158, 1.0
	v_cvt_scalef32_pk_f32_fp4 v[2:3], v158, 1.0 op_sel:[1,0,0]
	v_cvt_scalef32_pk_f32_fp4 v[4:5], v158, 1.0 op_sel:[0,1,0]
	v_cvt_scalef32_pk_f32_fp4 v[6:7], v158, 1.0 op_sel:[1,1,0]
	v_cvt_scalef32_pk_f32_fp4 v[8:9], v159, 1.0
	v_cvt_scalef32_pk_f32_fp4 v[10:11], v159, 1.0 op_sel:[1,0,0]
	v_cvt_scalef32_pk_f32_fp4 v[12:13], v159, 1.0 op_sel:[0,1,0]
	v_cvt_scalef32_pk_f32_fp4 v[14:15], v159, 1.0 op_sel:[1,1,0]
	v_readlane_b32 s54, v90, 39
	s_lshl_b32 s56, s54, 9
	s_add_u32 s56, s64, s56
	s_addc_u32 s57, s65, 0
	global_load_dwordx2 v[158:159], v227, s[56:57]
	s_waitcnt lgkmcnt(1)
	v_pk_fma_f32 v[130:131], v[0:1], v[194:195], v[130:131] op_sel_hi:[1,0,1]
	v_pk_fma_f32 v[138:139], v[2:3], v[194:195], v[138:139] op_sel_hi:[1,0,1]
	v_pk_fma_f32 v[140:141], v[4:5], v[194:195], v[140:141] op_sel_hi:[1,0,1]
	v_pk_fma_f32 v[142:143], v[6:7], v[194:195], v[142:143] op_sel_hi:[1,0,1]
	v_pk_fma_f32 v[128:129], v[8:9], v[194:195], v[128:129] op_sel_hi:[1,0,1]
	v_pk_fma_f32 v[132:133], v[10:11], v[194:195], v[132:133] op_sel_hi:[1,0,1]
	v_pk_fma_f32 v[134:135], v[12:13], v[194:195], v[134:135] op_sel_hi:[1,0,1]
	v_pk_fma_f32 v[136:137], v[14:15], v[194:195], v[136:137] op_sel_hi:[1,0,1]
	ds_read_b32 v194, v193 offset:612
	s_waitcnt vmcnt(15)
	v_cvt_scalef32_pk_f32_fp4 v[0:1], v168, 1.0
	v_cvt_scalef32_pk_f32_fp4 v[2:3], v168, 1.0 op_sel:[1,0,0]
	v_cvt_scalef32_pk_f32_fp4 v[4:5], v168, 1.0 op_sel:[0,1,0]
	v_cvt_scalef32_pk_f32_fp4 v[6:7], v168, 1.0 op_sel:[1,1,0]
	v_cvt_scalef32_pk_f32_fp4 v[8:9], v169, 1.0
	v_cvt_scalef32_pk_f32_fp4 v[10:11], v169, 1.0 op_sel:[1,0,0]
	v_cvt_scalef32_pk_f32_fp4 v[12:13], v169, 1.0 op_sel:[0,1,0]
	v_cvt_scalef32_pk_f32_fp4 v[14:15], v169, 1.0 op_sel:[1,1,0]
	v_readlane_b32 s54, v90, 40
	s_lshl_b32 s56, s54, 9
	s_add_u32 s56, s64, s56
	s_addc_u32 s57, s65, 0
	global_load_dwordx2 v[168:169], v227, s[56:57]
	s_waitcnt lgkmcnt(1)
	v_pk_fma_f32 v[130:131], v[0:1], v[76:77], v[130:131] op_sel_hi:[1,0,1]
	v_pk_fma_f32 v[138:139], v[2:3], v[76:77], v[138:139] op_sel_hi:[1,0,1]
	v_pk_fma_f32 v[140:141], v[4:5], v[76:77], v[140:141] op_sel_hi:[1,0,1]
	v_pk_fma_f32 v[142:143], v[6:7], v[76:77], v[142:143] op_sel_hi:[1,0,1]
	v_pk_fma_f32 v[128:129], v[8:9], v[76:77], v[128:129] op_sel_hi:[1,0,1]
	v_pk_fma_f32 v[132:133], v[10:11], v[76:77], v[132:133] op_sel_hi:[1,0,1]
	v_pk_fma_f32 v[134:135], v[12:13], v[76:77], v[134:135] op_sel_hi:[1,0,1]
	v_pk_fma_f32 v[136:137], v[14:15], v[76:77], v[136:137] op_sel_hi:[1,0,1]
	ds_read_b32 v76, v193 offset:616
	s_waitcnt vmcnt(15)
	v_cvt_scalef32_pk_f32_fp4 v[0:1], v170, 1.0
	v_cvt_scalef32_pk_f32_fp4 v[2:3], v170, 1.0 op_sel:[1,0,0]
	v_cvt_scalef32_pk_f32_fp4 v[4:5], v170, 1.0 op_sel:[0,1,0]
	v_cvt_scalef32_pk_f32_fp4 v[6:7], v170, 1.0 op_sel:[1,1,0]
	v_cvt_scalef32_pk_f32_fp4 v[8:9], v171, 1.0
	v_cvt_scalef32_pk_f32_fp4 v[10:11], v171, 1.0 op_sel:[1,0,0]
	v_cvt_scalef32_pk_f32_fp4 v[12:13], v171, 1.0 op_sel:[0,1,0]
	v_cvt_scalef32_pk_f32_fp4 v[14:15], v171, 1.0 op_sel:[1,1,0]
	v_readlane_b32 s54, v90, 41
	s_lshl_b32 s56, s54, 9
	s_add_u32 s56, s64, s56
	s_addc_u32 s57, s65, 0
	global_load_dwordx2 v[170:171], v227, s[56:57]
	s_waitcnt lgkmcnt(1)
	v_pk_fma_f32 v[130:131], v[0:1], v[194:195], v[130:131] op_sel_hi:[1,0,1]
	v_pk_fma_f32 v[138:139], v[2:3], v[194:195], v[138:139] op_sel_hi:[1,0,1]
	v_pk_fma_f32 v[140:141], v[4:5], v[194:195], v[140:141] op_sel_hi:[1,0,1]
	v_pk_fma_f32 v[142:143], v[6:7], v[194:195], v[142:143] op_sel_hi:[1,0,1]
	v_pk_fma_f32 v[128:129], v[8:9], v[194:195], v[128:129] op_sel_hi:[1,0,1]
	v_pk_fma_f32 v[132:133], v[10:11], v[194:195], v[132:133] op_sel_hi:[1,0,1]
	v_pk_fma_f32 v[134:135], v[12:13], v[194:195], v[134:135] op_sel_hi:[1,0,1]
	v_pk_fma_f32 v[136:137], v[14:15], v[194:195], v[136:137] op_sel_hi:[1,0,1]
	ds_read_b32 v194, v193 offset:620
	s_waitcnt vmcnt(15)
; __device__ void peer_gather_phase(const Params& P, int l, bool do_store) {
;     ...
; #pragma unroll
;       for (int j = 0; j < 8; ++j) {
;         const float a = __builtin_bit_cast(float, __builtin_amdgcn_readlane(__builtin_bit_cast(int, avec), kb + j));
;         const f32x2 aa = f32x2{a, a};
;         y[0] += aa * __builtin_amdgcn_cvt_scalef32_pk_f32_fp4(v8[j].x, 1.0f, 0); y[1] += aa * __builtin_amdgcn_cvt_scalef32_pk_f32_fp4(v8[j].x, 1.0f, 1);
;         y[2] += aa * __builtin_amdgcn_cvt_scalef32_pk_f32_fp4(v8[j].x, 1.0f, 2); y[3] += aa * __builtin_amdgcn_cvt_scalef32_pk_f32_fp4(v8[j].x, 1.0f, 3);
;         y[4] += aa * __builtin_amdgcn_cvt_scalef32_pk_f32_fp4(v8[j].y, 1.0f, 0); y[5] += aa * __builtin_amdgcn_cvt_scalef32_pk_f32_fp4(v8[j].y, 1.0f, 1);
;         y[6] += aa * __builtin_amdgcn_cvt_scalef32_pk_f32_fp4(v8[j].y, 1.0f, 2); y[7] += aa * __builtin_amdgcn_cvt_scalef32_pk_f32_fp4(v8[j].y, 1.0f, 3);
;       }
	v_cvt_scalef32_pk_f32_fp4 v[0:1], v172, 1.0
	v_cvt_scalef32_pk_f32_fp4 v[2:3], v172, 1.0 op_sel:[1,0,0]
	v_cvt_scalef32_pk_f32_fp4 v[4:5], v172, 1.0 op_sel:[0,1,0]
	v_cvt_scalef32_pk_f32_fp4 v[6:7], v172, 1.0 op_sel:[1,1,0]
	v_cvt_scalef32_pk_f32_fp4 v[8:9], v173, 1.0
	v_cvt_scalef32_pk_f32_fp4 v[10:11], v173, 1.0 op_sel:[1,0,0]
	v_cvt_scalef32_pk_f32_fp4 v[12:13], v173, 1.0 op_sel:[0,1,0]
	v_cvt_scalef32_pk_f32_fp4 v[14:15], v173, 1.0 op_sel:[1,1,0]
	v_readlane_b32 s54, v90, 42
	s_lshl_b32 s56, s54, 9
	s_add_u32 s56, s64, s56
	s_addc_u32 s57, s65, 0
	global_load_dwordx2 v[172:173], v227, s[56:57]
	s_waitcnt lgkmcnt(1)
	v_pk_fma_f32 v[130:131], v[0:1], v[76:77], v[130:131] op_sel_hi:[1,0,1]
	v_pk_fma_f32 v[138:139], v[2:3], v[76:77], v[138:139] op_sel_hi:[1,0,1]
	v_pk_fma_f32 v[140:141], v[4:5], v[76:77], v[140:141] op_sel_hi:[1,0,1]
	v_pk_fma_f32 v[142:143], v[6:7], v[76:77], v[142:143] op_sel_hi:[1,0,1]
	v_pk_fma_f32 v[128:129], v[8:9], v[76:77], v[128:129] op_sel_hi:[1,0,1]
	v_pk_fma_f32 v[132:133], v[10:11], v[76:77], v[132:133] op_sel_hi:[1,0,1]
	v_pk_fma_f32 v[134:135], v[12:13], v[76:77], v[134:135] op_sel_hi:[1,0,1]
	v_pk_fma_f32 v[136:137], v[14:15], v[76:77], v[136:137] op_sel_hi:[1,0,1]
	ds_read_b32 v76, v193 offset:624
	s_waitcnt vmcnt(15)
	v_cvt_scalef32_pk_f32_fp4 v[0:1], v174, 1.0
	v_cvt_scalef32_pk_f32_fp4 v[2:3], v174, 1.0 op_sel:[1,0,0]
	v_cvt_scalef32_pk_f32_fp4 v[4:5], v174, 1.0 op_sel:[0,1,0]
	v_cvt_scalef32_pk_f32_fp4 v[6:7], v174, 1.0 op_sel:[1,1,0]
	v_cvt_scalef32_pk_f32_fp4 v[8:9], v175, 1.0
	v_cvt_scalef32_pk_f32_fp4 v[10:11], v175, 1.0 op_sel:[1,0,0]
	v_cvt_scalef32_pk_f32_fp4 v[12:13], v175, 1.0 op_sel:[0,1,0]
	v_cvt_scalef32_pk_f32_fp4 v[14:15], v175, 1.0 op_sel:[1,1,0]
	v_readlane_b32 s54, v90, 43
	s_lshl_b32 s56, s54, 9
	s_add_u32 s56, s64, s56
	s_addc_u32 s57, s65, 0
	global_load_dwordx2 v[174:175], v227, s[56:57]
	s_waitcnt lgkmcnt(1)
	v_pk_fma_f32 v[130:131], v[0:1], v[194:195], v[130:131] op_sel_hi:[1,0,1]
	v_pk_fma_f32 v[138:139], v[2:3], v[194:195], v[138:139] op_sel_hi:[1,0,1]
	v_pk_fma_f32 v[140:141], v[4:5], v[194:195], v[140:141] op_sel_hi:[1,0,1]
	v_pk_fma_f32 v[142:143], v[6:7], v[194:195], v[142:143] op_sel_hi:[1,0,1]
	v_pk_fma_f32 v[128:129], v[8:9], v[194:195], v[128:129] op_sel_hi:[1,0,1]
	v_pk_fma_f32 v[132:133], v[10:11], v[194:195], v[132:133] op_sel_hi:[1,0,1]
	v_pk_fma_f32 v[134:135], v[12:13], v[194:195], v[134:135] op_sel_hi:[1,0,1]
	v_pk_fma_f32 v[136:137], v[14:15], v[194:195], v[136:137] op_sel_hi:[1,0,1]
	ds_read_b32 v194, v193 offset:628
	s_waitcnt vmcnt(15)
	v_cvt_scalef32_pk_f32_fp4 v[0:1], v180, 1.0
	v_cvt_scalef32_pk_f32_fp4 v[2:3], v180, 1.0 op_sel:[1,0,0]
	v_cvt_scalef32_pk_f32_fp4 v[4:5], v180, 1.0 op_sel:[0,1,0]
	v_cvt_scalef32_pk_f32_fp4 v[6:7], v180, 1.0 op_sel:[1,1,0]
	v_cvt_scalef32_pk_f32_fp4 v[8:9], v181, 1.0
	v_cvt_scalef32_pk_f32_fp4 v[10:11], v181, 1.0 op_sel:[1,0,0]
	v_cvt_scalef32_pk_f32_fp4 v[12:13], v181, 1.0 op_sel:[0,1,0]
	v_cvt_scalef32_pk_f32_fp4 v[14:15], v181, 1.0 op_sel:[1,1,0]
	v_readlane_b32 s54, v90, 44
	s_lshl_b32 s56, s54, 9
	s_add_u32 s56, s64, s56
	s_addc_u32 s57, s65, 0
	global_load_dwordx2 v[180:181], v227, s[56:57]
	s_waitcnt lgkmcnt(1)
	v_pk_fma_f32 v[130:131], v[0:1], v[76:77], v[130:131] op_sel_hi:[1,0,1]
	v_pk_fma_f32 v[138:139], v[2:3], v[76:77], v[138:139] op_sel_hi:[1,0,1]
	v_pk_fma_f32 v[140:141], v[4:5], v[76:77], v[140:141] op_sel_hi:[1,0,1]
	v_pk_fma_f32 v[142:143], v[6:7], v[76:77], v[142:143] op_sel_hi:[1,0,1]
	v_pk_fma_f32 v[128:129], v[8:9], v[76:77], v[128:129] op_sel_hi:[1,0,1]
	v_pk_fma_f32 v[132:133], v[10:11], v[76:77], v[132:133] op_sel_hi:[1,0,1]
	v_pk_fma_f32 v[134:135], v[12:13], v[76:77], v[134:135] op_sel_hi:[1,0,1]
	v_pk_fma_f32 v[136:137], v[14:15], v[76:77], v[136:137] op_sel_hi:[1,0,1]
	ds_read_b32 v76, v193 offset:632
	s_waitcnt vmcnt(15)
	v_cvt_scalef32_pk_f32_fp4 v[0:1], v182, 1.0
	v_cvt_scalef32_pk_f32_fp4 v[2:3], v182, 1.0 op_sel:[1,0,0]
	v_cvt_scalef32_pk_f32_fp4 v[4:5], v182, 1.0 op_sel:[0,1,0]
	v_cvt_scalef32_pk_f32_fp4 v[6:7], v182, 1.0 op_sel:[1,1,0]
	v_cvt_scalef32_pk_f32_fp4 v[8:9], v183, 1.0
	v_cvt_scalef32_pk_f32_fp4 v[10:11], v183, 1.0 op_sel:[1,0,0]
	v_cvt_scalef32_pk_f32_fp4 v[12:13], v183, 1.0 op_sel:[0,1,0]
	v_cvt_scalef32_pk_f32_fp4 v[14:15], v183, 1.0 op_sel:[1,1,0]
	v_readlane_b32 s54, v90, 45
	s_lshl_b32 s56, s54, 9
	s_add_u32 s56, s64, s56
	s_addc_u32 s57, s65, 0
	global_load_dwordx2 v[182:183], v227, s[56:57]
	s_waitcnt lgkmcnt(1)
	v_pk_fma_f32 v[130:131], v[0:1], v[194:195], v[130:131] op_sel_hi:[1,0,1]
	v_pk_fma_f32 v[138:139], v[2:3], v[194:195], v[138:139] op_sel_hi:[1,0,1]
	v_pk_fma_f32 v[140:141], v[4:5], v[194:195], v[140:141] op_sel_hi:[1,0,1]
	v_pk_fma_f32 v[142:143], v[6:7], v[194:195], v[142:143] op_sel_hi:[1,0,1]
	v_pk_fma_f32 v[128:129], v[8:9], v[194:195], v[128:129] op_sel_hi:[1,0,1]
	v_pk_fma_f32 v[132:133], v[10:11], v[194:195], v[132:133] op_sel_hi:[1,0,1]
	v_pk_fma_f32 v[134:135], v[12:13], v[194:195], v[134:135] op_sel_hi:[1,0,1]
	v_pk_fma_f32 v[136:137], v[14:15], v[194:195], v[136:137] op_sel_hi:[1,0,1]
	ds_read_b32 v194, v193 offset:636
	s_waitcnt vmcnt(15)
	v_cvt_scalef32_pk_f32_fp4 v[0:1], v184, 1.0
	v_cvt_scalef32_pk_f32_fp4 v[2:3], v184, 1.0 op_sel:[1,0,0]
	v_cvt_scalef32_pk_f32_fp4 v[4:5], v184, 1.0 op_sel:[0,1,0]
	v_cvt_scalef32_pk_f32_fp4 v[6:7], v184, 1.0 op_sel:[1,1,0]
	v_cvt_scalef32_pk_f32_fp4 v[8:9], v185, 1.0
	v_cvt_scalef32_pk_f32_fp4 v[10:11], v185, 1.0 op_sel:[1,0,0]
	v_cvt_scalef32_pk_f32_fp4 v[12:13], v185, 1.0 op_sel:[0,1,0]
	v_cvt_scalef32_pk_f32_fp4 v[14:15], v185, 1.0 op_sel:[1,1,0]
	v_readlane_b32 s54, v90, 46
	s_lshl_b32 s56, s54, 9
	s_add_u32 s56, s64, s56
	s_addc_u32 s57, s65, 0
	global_load_dwordx2 v[184:185], v227, s[56:57]
	s_waitcnt lgkmcnt(1)
; __device__ void peer_gather_phase(const Params& P, int l, bool do_store) {
;     ...
; #pragma unroll
;       for (int j = 0; j < 8; ++j) {
;         const float a = __builtin_bit_cast(float, __builtin_amdgcn_readlane(__builtin_bit_cast(int, avec), kb + j));
;         const f32x2 aa = f32x2{a, a};
;         y[0] += aa * __builtin_amdgcn_cvt_scalef32_pk_f32_fp4(v8[j].x, 1.0f, 0); y[1] += aa * __builtin_amdgcn_cvt_scalef32_pk_f32_fp4(v8[j].x, 1.0f, 1);
;         y[2] += aa * __builtin_amdgcn_cvt_scalef32_pk_f32_fp4(v8[j].x, 1.0f, 2); y[3] += aa * __builtin_amdgcn_cvt_scalef32_pk_f32_fp4(v8[j].x, 1.0f, 3);
;         y[4] += aa * __builtin_amdgcn_cvt_scalef32_pk_f32_fp4(v8[j].y, 1.0f, 0); y[5] += aa * __builtin_amdgcn_cvt_scalef32_pk_f32_fp4(v8[j].y, 1.0f, 1);
;         y[6] += aa * __builtin_amdgcn_cvt_scalef32_pk_f32_fp4(v8[j].y, 1.0f, 2); y[7] += aa * __builtin_amdgcn_cvt_scalef32_pk_f32_fp4(v8[j].y, 1.0f, 3);
;       }
	v_pk_fma_f32 v[130:131], v[0:1], v[76:77], v[130:131] op_sel_hi:[1,0,1]
	v_pk_fma_f32 v[138:139], v[2:3], v[76:77], v[138:139] op_sel_hi:[1,0,1]
	v_pk_fma_f32 v[140:141], v[4:5], v[76:77], v[140:141] op_sel_hi:[1,0,1]
	v_pk_fma_f32 v[142:143], v[6:7], v[76:77], v[142:143] op_sel_hi:[1,0,1]
	v_pk_fma_f32 v[128:129], v[8:9], v[76:77], v[128:129] op_sel_hi:[1,0,1]
	v_pk_fma_f32 v[132:133], v[10:11], v[76:77], v[132:133] op_sel_hi:[1,0,1]
	v_pk_fma_f32 v[134:135], v[12:13], v[76:77], v[134:135] op_sel_hi:[1,0,1]
	v_pk_fma_f32 v[136:137], v[14:15], v[76:77], v[136:137] op_sel_hi:[1,0,1]
	ds_read_b32 v76, v193 offset:640
	s_waitcnt vmcnt(15)
	v_cvt_scalef32_pk_f32_fp4 v[0:1], v186, 1.0
	v_cvt_scalef32_pk_f32_fp4 v[2:3], v186, 1.0 op_sel:[1,0,0]
	v_cvt_scalef32_pk_f32_fp4 v[4:5], v186, 1.0 op_sel:[0,1,0]
	v_cvt_scalef32_pk_f32_fp4 v[6:7], v186, 1.0 op_sel:[1,1,0]
	v_cvt_scalef32_pk_f32_fp4 v[8:9], v187, 1.0
	v_cvt_scalef32_pk_f32_fp4 v[10:11], v187, 1.0 op_sel:[1,0,0]
	v_cvt_scalef32_pk_f32_fp4 v[12:13], v187, 1.0 op_sel:[0,1,0]
	v_cvt_scalef32_pk_f32_fp4 v[14:15], v187, 1.0 op_sel:[1,1,0]
	v_readlane_b32 s54, v90, 47
	s_lshl_b32 s56, s54, 9
	s_add_u32 s56, s64, s56
	s_addc_u32 s57, s65, 0
	global_load_dwordx2 v[186:187], v227, s[56:57]
	s_waitcnt lgkmcnt(1)
	v_pk_fma_f32 v[130:131], v[0:1], v[194:195], v[130:131] op_sel_hi:[1,0,1]
	v_pk_fma_f32 v[138:139], v[2:3], v[194:195], v[138:139] op_sel_hi:[1,0,1]
	v_pk_fma_f32 v[140:141], v[4:5], v[194:195], v[140:141] op_sel_hi:[1,0,1]
	v_pk_fma_f32 v[142:143], v[6:7], v[194:195], v[142:143] op_sel_hi:[1,0,1]
	v_pk_fma_f32 v[128:129], v[8:9], v[194:195], v[128:129] op_sel_hi:[1,0,1]
	v_pk_fma_f32 v[132:133], v[10:11], v[194:195], v[132:133] op_sel_hi:[1,0,1]
	v_pk_fma_f32 v[134:135], v[12:13], v[194:195], v[134:135] op_sel_hi:[1,0,1]
	v_pk_fma_f32 v[136:137], v[14:15], v[194:195], v[136:137] op_sel_hi:[1,0,1]
	ds_read_b32 v194, v193 offset:644
	s_waitcnt vmcnt(15)
	v_cvt_scalef32_pk_f32_fp4 v[0:1], v144, 1.0
	v_cvt_scalef32_pk_f32_fp4 v[2:3], v144, 1.0 op_sel:[1,0,0]
	v_cvt_scalef32_pk_f32_fp4 v[4:5], v144, 1.0 op_sel:[0,1,0]
	v_cvt_scalef32_pk_f32_fp4 v[6:7], v144, 1.0 op_sel:[1,1,0]
	v_cvt_scalef32_pk_f32_fp4 v[8:9], v145, 1.0
	v_cvt_scalef32_pk_f32_fp4 v[10:11], v145, 1.0 op_sel:[1,0,0]
	v_cvt_scalef32_pk_f32_fp4 v[12:13], v145, 1.0 op_sel:[0,1,0]
	v_cvt_scalef32_pk_f32_fp4 v[14:15], v145, 1.0 op_sel:[1,1,0]
	v_readlane_b32 s54, v90, 48
	s_lshl_b32 s56, s54, 9
	s_add_u32 s56, s64, s56
	s_addc_u32 s57, s65, 0
	global_load_dwordx2 v[144:145], v227, s[56:57]
	s_waitcnt lgkmcnt(1)
	v_pk_fma_f32 v[130:131], v[0:1], v[76:77], v[130:131] op_sel_hi:[1,0,1]
	v_pk_fma_f32 v[138:139], v[2:3], v[76:77], v[138:139] op_sel_hi:[1,0,1]
	v_pk_fma_f32 v[140:141], v[4:5], v[76:77], v[140:141] op_sel_hi:[1,0,1]
	v_pk_fma_f32 v[142:143], v[6:7], v[76:77], v[142:143] op_sel_hi:[1,0,1]
	v_pk_fma_f32 v[128:129], v[8:9], v[76:77], v[128:129] op_sel_hi:[1,0,1]
	v_pk_fma_f32 v[132:133], v[10:11], v[76:77], v[132:133] op_sel_hi:[1,0,1]
	v_pk_fma_f32 v[134:135], v[12:13], v[76:77], v[134:135] op_sel_hi:[1,0,1]
	v_pk_fma_f32 v[136:137], v[14:15], v[76:77], v[136:137] op_sel_hi:[1,0,1]
	ds_read_b32 v76, v193 offset:648
	s_waitcnt vmcnt(15)
	v_cvt_scalef32_pk_f32_fp4 v[0:1], v146, 1.0
	v_cvt_scalef32_pk_f32_fp4 v[2:3], v146, 1.0 op_sel:[1,0,0]
	v_cvt_scalef32_pk_f32_fp4 v[4:5], v146, 1.0 op_sel:[0,1,0]
	v_cvt_scalef32_pk_f32_fp4 v[6:7], v146, 1.0 op_sel:[1,1,0]
	v_cvt_scalef32_pk_f32_fp4 v[8:9], v147, 1.0
	v_cvt_scalef32_pk_f32_fp4 v[10:11], v147, 1.0 op_sel:[1,0,0]
	v_cvt_scalef32_pk_f32_fp4 v[12:13], v147, 1.0 op_sel:[0,1,0]
	v_cvt_scalef32_pk_f32_fp4 v[14:15], v147, 1.0 op_sel:[1,1,0]
	v_readlane_b32 s54, v90, 49
	s_lshl_b32 s56, s54, 9
	s_add_u32 s56, s64, s56
	s_addc_u32 s57, s65, 0
	global_load_dwordx2 v[146:147], v227, s[56:57]
	s_waitcnt lgkmcnt(1)
	v_pk_fma_f32 v[130:131], v[0:1], v[194:195], v[130:131] op_sel_hi:[1,0,1]
	v_pk_fma_f32 v[138:139], v[2:3], v[194:195], v[138:139] op_sel_hi:[1,0,1]
	v_pk_fma_f32 v[140:141], v[4:5], v[194:195], v[140:141] op_sel_hi:[1,0,1]
	v_pk_fma_f32 v[142:143], v[6:7], v[194:195], v[142:143] op_sel_hi:[1,0,1]
	v_pk_fma_f32 v[128:129], v[8:9], v[194:195], v[128:129] op_sel_hi:[1,0,1]
	v_pk_fma_f32 v[132:133], v[10:11], v[194:195], v[132:133] op_sel_hi:[1,0,1]
	v_pk_fma_f32 v[134:135], v[12:13], v[194:195], v[134:135] op_sel_hi:[1,0,1]
	v_pk_fma_f32 v[136:137], v[14:15], v[194:195], v[136:137] op_sel_hi:[1,0,1]
	ds_read_b32 v194, v193 offset:652
	s_waitcnt vmcnt(15)
	v_cvt_scalef32_pk_f32_fp4 v[0:1], v148, 1.0
	v_cvt_scalef32_pk_f32_fp4 v[2:3], v148, 1.0 op_sel:[1,0,0]
	v_cvt_scalef32_pk_f32_fp4 v[4:5], v148, 1.0 op_sel:[0,1,0]
	v_cvt_scalef32_pk_f32_fp4 v[6:7], v148, 1.0 op_sel:[1,1,0]
	v_cvt_scalef32_pk_f32_fp4 v[8:9], v149, 1.0
	v_cvt_scalef32_pk_f32_fp4 v[10:11], v149, 1.0 op_sel:[1,0,0]
	v_cvt_scalef32_pk_f32_fp4 v[12:13], v149, 1.0 op_sel:[0,1,0]
	v_cvt_scalef32_pk_f32_fp4 v[14:15], v149, 1.0 op_sel:[1,1,0]
	v_readlane_b32 s54, v90, 50
	s_lshl_b32 s56, s54, 9
	s_add_u32 s56, s64, s56
	s_addc_u32 s57, s65, 0
	global_load_dwordx2 v[148:149], v227, s[56:57]
	s_waitcnt lgkmcnt(1)
	v_pk_fma_f32 v[130:131], v[0:1], v[76:77], v[130:131] op_sel_hi:[1,0,1]
	v_pk_fma_f32 v[138:139], v[2:3], v[76:77], v[138:139] op_sel_hi:[1,0,1]
	v_pk_fma_f32 v[140:141], v[4:5], v[76:77], v[140:141] op_sel_hi:[1,0,1]
	v_pk_fma_f32 v[142:143], v[6:7], v[76:77], v[142:143] op_sel_hi:[1,0,1]
	v_pk_fma_f32 v[128:129], v[8:9], v[76:77], v[128:129] op_sel_hi:[1,0,1]
	v_pk_fma_f32 v[132:133], v[10:11], v[76:77], v[132:133] op_sel_hi:[1,0,1]
	v_pk_fma_f32 v[134:135], v[12:13], v[76:77], v[134:135] op_sel_hi:[1,0,1]
	v_pk_fma_f32 v[136:137], v[14:15], v[76:77], v[136:137] op_sel_hi:[1,0,1]
	ds_read_b32 v76, v193 offset:656
	s_waitcnt vmcnt(15)
; __device__ void peer_gather_phase(const Params& P, int l, bool do_store) {
;     ...
; #pragma unroll
;       for (int j = 0; j < 8; ++j) {
;         const float a = __builtin_bit_cast(float, __builtin_amdgcn_readlane(__builtin_bit_cast(int, avec), kb + j));
;         const f32x2 aa = f32x2{a, a};
;         y[0] += aa * __builtin_amdgcn_cvt_scalef32_pk_f32_fp4(v8[j].x, 1.0f, 0); y[1] += aa * __builtin_amdgcn_cvt_scalef32_pk_f32_fp4(v8[j].x, 1.0f, 1);
;         y[2] += aa * __builtin_amdgcn_cvt_scalef32_pk_f32_fp4(v8[j].x, 1.0f, 2); y[3] += aa * __builtin_amdgcn_cvt_scalef32_pk_f32_fp4(v8[j].x, 1.0f, 3);
;         y[4] += aa * __builtin_amdgcn_cvt_scalef32_pk_f32_fp4(v8[j].y, 1.0f, 0); y[5] += aa * __builtin_amdgcn_cvt_scalef32_pk_f32_fp4(v8[j].y, 1.0f, 1);
;         y[6] += aa * __builtin_amdgcn_cvt_scalef32_pk_f32_fp4(v8[j].y, 1.0f, 2); y[7] += aa * __builtin_amdgcn_cvt_scalef32_pk_f32_fp4(v8[j].y, 1.0f, 3);
;       }
	v_cvt_scalef32_pk_f32_fp4 v[0:1], v150, 1.0
	v_cvt_scalef32_pk_f32_fp4 v[2:3], v150, 1.0 op_sel:[1,0,0]
	v_cvt_scalef32_pk_f32_fp4 v[4:5], v150, 1.0 op_sel:[0,1,0]
	v_cvt_scalef32_pk_f32_fp4 v[6:7], v150, 1.0 op_sel:[1,1,0]
	v_cvt_scalef32_pk_f32_fp4 v[8:9], v151, 1.0
	v_cvt_scalef32_pk_f32_fp4 v[10:11], v151, 1.0 op_sel:[1,0,0]
	v_cvt_scalef32_pk_f32_fp4 v[12:13], v151, 1.0 op_sel:[0,1,0]
	v_cvt_scalef32_pk_f32_fp4 v[14:15], v151, 1.0 op_sel:[1,1,0]
	v_readlane_b32 s54, v90, 51
	s_lshl_b32 s56, s54, 9
	s_add_u32 s56, s64, s56
	s_addc_u32 s57, s65, 0
	global_load_dwordx2 v[150:151], v227, s[56:57]
	s_waitcnt lgkmcnt(1)
	v_pk_fma_f32 v[130:131], v[0:1], v[194:195], v[130:131] op_sel_hi:[1,0,1]
	v_pk_fma_f32 v[138:139], v[2:3], v[194:195], v[138:139] op_sel_hi:[1,0,1]
	v_pk_fma_f32 v[140:141], v[4:5], v[194:195], v[140:141] op_sel_hi:[1,0,1]
	v_pk_fma_f32 v[142:143], v[6:7], v[194:195], v[142:143] op_sel_hi:[1,0,1]
	v_pk_fma_f32 v[128:129], v[8:9], v[194:195], v[128:129] op_sel_hi:[1,0,1]
	v_pk_fma_f32 v[132:133], v[10:11], v[194:195], v[132:133] op_sel_hi:[1,0,1]
	v_pk_fma_f32 v[134:135], v[12:13], v[194:195], v[134:135] op_sel_hi:[1,0,1]
	v_pk_fma_f32 v[136:137], v[14:15], v[194:195], v[136:137] op_sel_hi:[1,0,1]
	ds_read_b32 v194, v193 offset:660
	s_waitcnt vmcnt(15)
	v_cvt_scalef32_pk_f32_fp4 v[0:1], v152, 1.0
	v_cvt_scalef32_pk_f32_fp4 v[2:3], v152, 1.0 op_sel:[1,0,0]
	v_cvt_scalef32_pk_f32_fp4 v[4:5], v152, 1.0 op_sel:[0,1,0]
	v_cvt_scalef32_pk_f32_fp4 v[6:7], v152, 1.0 op_sel:[1,1,0]
	v_cvt_scalef32_pk_f32_fp4 v[8:9], v153, 1.0
	v_cvt_scalef32_pk_f32_fp4 v[10:11], v153, 1.0 op_sel:[1,0,0]
	v_cvt_scalef32_pk_f32_fp4 v[12:13], v153, 1.0 op_sel:[0,1,0]
	v_cvt_scalef32_pk_f32_fp4 v[14:15], v153, 1.0 op_sel:[1,1,0]
	v_readlane_b32 s54, v90, 52
	s_lshl_b32 s56, s54, 9
	s_add_u32 s56, s64, s56
	s_addc_u32 s57, s65, 0
	global_load_dwordx2 v[152:153], v227, s[56:57]
	s_waitcnt lgkmcnt(1)
	v_pk_fma_f32 v[130:131], v[0:1], v[76:77], v[130:131] op_sel_hi:[1,0,1]
	v_pk_fma_f32 v[138:139], v[2:3], v[76:77], v[138:139] op_sel_hi:[1,0,1]
	v_pk_fma_f32 v[140:141], v[4:5], v[76:77], v[140:141] op_sel_hi:[1,0,1]
	v_pk_fma_f32 v[142:143], v[6:7], v[76:77], v[142:143] op_sel_hi:[1,0,1]
	v_pk_fma_f32 v[128:129], v[8:9], v[76:77], v[128:129] op_sel_hi:[1,0,1]
	v_pk_fma_f32 v[132:133], v[10:11], v[76:77], v[132:133] op_sel_hi:[1,0,1]
	v_pk_fma_f32 v[134:135], v[12:13], v[76:77], v[134:135] op_sel_hi:[1,0,1]
	v_pk_fma_f32 v[136:137], v[14:15], v[76:77], v[136:137] op_sel_hi:[1,0,1]
	ds_read_b32 v76, v193 offset:664
	s_waitcnt vmcnt(15)
	v_cvt_scalef32_pk_f32_fp4 v[0:1], v154, 1.0
	v_cvt_scalef32_pk_f32_fp4 v[2:3], v154, 1.0 op_sel:[1,0,0]
	v_cvt_scalef32_pk_f32_fp4 v[4:5], v154, 1.0 op_sel:[0,1,0]
	v_cvt_scalef32_pk_f32_fp4 v[6:7], v154, 1.0 op_sel:[1,1,0]
	v_cvt_scalef32_pk_f32_fp4 v[8:9], v155, 1.0
	v_cvt_scalef32_pk_f32_fp4 v[10:11], v155, 1.0 op_sel:[1,0,0]
	v_cvt_scalef32_pk_f32_fp4 v[12:13], v155, 1.0 op_sel:[0,1,0]
	v_cvt_scalef32_pk_f32_fp4 v[14:15], v155, 1.0 op_sel:[1,1,0]
	v_readlane_b32 s54, v90, 53
	s_lshl_b32 s56, s54, 9
	s_add_u32 s56, s64, s56
	s_addc_u32 s57, s65, 0
	global_load_dwordx2 v[154:155], v227, s[56:57]
	s_waitcnt lgkmcnt(1)
	v_pk_fma_f32 v[130:131], v[0:1], v[194:195], v[130:131] op_sel_hi:[1,0,1]
	v_pk_fma_f32 v[138:139], v[2:3], v[194:195], v[138:139] op_sel_hi:[1,0,1]
	v_pk_fma_f32 v[140:141], v[4:5], v[194:195], v[140:141] op_sel_hi:[1,0,1]
	v_pk_fma_f32 v[142:143], v[6:7], v[194:195], v[142:143] op_sel_hi:[1,0,1]
	v_pk_fma_f32 v[128:129], v[8:9], v[194:195], v[128:129] op_sel_hi:[1,0,1]
	v_pk_fma_f32 v[132:133], v[10:11], v[194:195], v[132:133] op_sel_hi:[1,0,1]
	v_pk_fma_f32 v[134:135], v[12:13], v[194:195], v[134:135] op_sel_hi:[1,0,1]
	v_pk_fma_f32 v[136:137], v[14:15], v[194:195], v[136:137] op_sel_hi:[1,0,1]
	ds_read_b32 v194, v193 offset:668
	s_waitcnt vmcnt(15)
	v_cvt_scalef32_pk_f32_fp4 v[0:1], v156, 1.0
	v_cvt_scalef32_pk_f32_fp4 v[2:3], v156, 1.0 op_sel:[1,0,0]
	v_cvt_scalef32_pk_f32_fp4 v[4:5], v156, 1.0 op_sel:[0,1,0]
	v_cvt_scalef32_pk_f32_fp4 v[6:7], v156, 1.0 op_sel:[1,1,0]
	v_cvt_scalef32_pk_f32_fp4 v[8:9], v157, 1.0
	v_cvt_scalef32_pk_f32_fp4 v[10:11], v157, 1.0 op_sel:[1,0,0]
	v_cvt_scalef32_pk_f32_fp4 v[12:13], v157, 1.0 op_sel:[0,1,0]
	v_cvt_scalef32_pk_f32_fp4 v[14:15], v157, 1.0 op_sel:[1,1,0]
	v_readlane_b32 s54, v90, 54
	s_lshl_b32 s56, s54, 9
	s_add_u32 s56, s64, s56
	s_addc_u32 s57, s65, 0
	global_load_dwordx2 v[156:157], v227, s[56:57]
	s_waitcnt lgkmcnt(1)
	v_pk_fma_f32 v[130:131], v[0:1], v[76:77], v[130:131] op_sel_hi:[1,0,1]
	v_pk_fma_f32 v[138:139], v[2:3], v[76:77], v[138:139] op_sel_hi:[1,0,1]
	v_pk_fma_f32 v[140:141], v[4:5], v[76:77], v[140:141] op_sel_hi:[1,0,1]
	v_pk_fma_f32 v[142:143], v[6:7], v[76:77], v[142:143] op_sel_hi:[1,0,1]
	v_pk_fma_f32 v[128:129], v[8:9], v[76:77], v[128:129] op_sel_hi:[1,0,1]
	v_pk_fma_f32 v[132:133], v[10:11], v[76:77], v[132:133] op_sel_hi:[1,0,1]
	v_pk_fma_f32 v[134:135], v[12:13], v[76:77], v[134:135] op_sel_hi:[1,0,1]
	v_pk_fma_f32 v[136:137], v[14:15], v[76:77], v[136:137] op_sel_hi:[1,0,1]
	ds_read_b32 v76, v193 offset:672
	s_waitcnt vmcnt(15)
	v_cvt_scalef32_pk_f32_fp4 v[0:1], v158, 1.0
	v_cvt_scalef32_pk_f32_fp4 v[2:3], v158, 1.0 op_sel:[1,0,0]
	v_cvt_scalef32_pk_f32_fp4 v[4:5], v158, 1.0 op_sel:[0,1,0]
	v_cvt_scalef32_pk_f32_fp4 v[6:7], v158, 1.0 op_sel:[1,1,0]
	v_cvt_scalef32_pk_f32_fp4 v[8:9], v159, 1.0
	v_cvt_scalef32_pk_f32_fp4 v[10:11], v159, 1.0 op_sel:[1,0,0]
	v_cvt_scalef32_pk_f32_fp4 v[12:13], v159, 1.0 op_sel:[0,1,0]
	v_cvt_scalef32_pk_f32_fp4 v[14:15], v159, 1.0 op_sel:[1,1,0]
	v_readlane_b32 s54, v90, 55
	s_lshl_b32 s56, s54, 9
	s_add_u32 s56, s64, s56
	s_addc_u32 s57, s65, 0
	global_load_dwordx2 v[158:159], v227, s[56:57]
	s_waitcnt lgkmcnt(1)
; __device__ void peer_gather_phase(const Params& P, int l, bool do_store) {
;     ...
; #pragma unroll
;       for (int j = 0; j < 8; ++j) {
;         const float a = __builtin_bit_cast(float, __builtin_amdgcn_readlane(__builtin_bit_cast(int, avec), kb + j));
;         const f32x2 aa = f32x2{a, a};
;         y[0] += aa * __builtin_amdgcn_cvt_scalef32_pk_f32_fp4(v8[j].x, 1.0f, 0); y[1] += aa * __builtin_amdgcn_cvt_scalef32_pk_f32_fp4(v8[j].x, 1.0f, 1);
;         y[2] += aa * __builtin_amdgcn_cvt_scalef32_pk_f32_fp4(v8[j].x, 1.0f, 2); y[3] += aa * __builtin_amdgcn_cvt_scalef32_pk_f32_fp4(v8[j].x, 1.0f, 3);
;         y[4] += aa * __builtin_amdgcn_cvt_scalef32_pk_f32_fp4(v8[j].y, 1.0f, 0); y[5] += aa * __builtin_amdgcn_cvt_scalef32_pk_f32_fp4(v8[j].y, 1.0f, 1);
;         y[6] += aa * __builtin_amdgcn_cvt_scalef32_pk_f32_fp4(v8[j].y, 1.0f, 2); y[7] += aa * __builtin_amdgcn_cvt_scalef32_pk_f32_fp4(v8[j].y, 1.0f, 3);
;       }
	v_pk_fma_f32 v[130:131], v[0:1], v[194:195], v[130:131] op_sel_hi:[1,0,1]
	v_pk_fma_f32 v[138:139], v[2:3], v[194:195], v[138:139] op_sel_hi:[1,0,1]
	v_pk_fma_f32 v[140:141], v[4:5], v[194:195], v[140:141] op_sel_hi:[1,0,1]
	v_pk_fma_f32 v[142:143], v[6:7], v[194:195], v[142:143] op_sel_hi:[1,0,1]
	v_pk_fma_f32 v[128:129], v[8:9], v[194:195], v[128:129] op_sel_hi:[1,0,1]
	v_pk_fma_f32 v[132:133], v[10:11], v[194:195], v[132:133] op_sel_hi:[1,0,1]
	v_pk_fma_f32 v[134:135], v[12:13], v[194:195], v[134:135] op_sel_hi:[1,0,1]
	v_pk_fma_f32 v[136:137], v[14:15], v[194:195], v[136:137] op_sel_hi:[1,0,1]
	ds_read_b32 v194, v193 offset:676
	s_waitcnt vmcnt(15)
	v_cvt_scalef32_pk_f32_fp4 v[0:1], v168, 1.0
	v_cvt_scalef32_pk_f32_fp4 v[2:3], v168, 1.0 op_sel:[1,0,0]
	v_cvt_scalef32_pk_f32_fp4 v[4:5], v168, 1.0 op_sel:[0,1,0]
	v_cvt_scalef32_pk_f32_fp4 v[6:7], v168, 1.0 op_sel:[1,1,0]
	v_cvt_scalef32_pk_f32_fp4 v[8:9], v169, 1.0
	v_cvt_scalef32_pk_f32_fp4 v[10:11], v169, 1.0 op_sel:[1,0,0]
	v_cvt_scalef32_pk_f32_fp4 v[12:13], v169, 1.0 op_sel:[0,1,0]
	v_cvt_scalef32_pk_f32_fp4 v[14:15], v169, 1.0 op_sel:[1,1,0]
	v_readlane_b32 s54, v90, 56
	s_lshl_b32 s56, s54, 9
	s_add_u32 s56, s64, s56
	s_addc_u32 s57, s65, 0
	global_load_dwordx2 v[168:169], v227, s[56:57]
	s_waitcnt lgkmcnt(1)
	v_pk_fma_f32 v[130:131], v[0:1], v[76:77], v[130:131] op_sel_hi:[1,0,1]
	v_pk_fma_f32 v[138:139], v[2:3], v[76:77], v[138:139] op_sel_hi:[1,0,1]
	v_pk_fma_f32 v[140:141], v[4:5], v[76:77], v[140:141] op_sel_hi:[1,0,1]
	v_pk_fma_f32 v[142:143], v[6:7], v[76:77], v[142:143] op_sel_hi:[1,0,1]
	v_pk_fma_f32 v[128:129], v[8:9], v[76:77], v[128:129] op_sel_hi:[1,0,1]
	v_pk_fma_f32 v[132:133], v[10:11], v[76:77], v[132:133] op_sel_hi:[1,0,1]
	v_pk_fma_f32 v[134:135], v[12:13], v[76:77], v[134:135] op_sel_hi:[1,0,1]
	v_pk_fma_f32 v[136:137], v[14:15], v[76:77], v[136:137] op_sel_hi:[1,0,1]
	ds_read_b32 v76, v193 offset:680
	s_waitcnt vmcnt(15)
	v_cvt_scalef32_pk_f32_fp4 v[0:1], v170, 1.0
	v_cvt_scalef32_pk_f32_fp4 v[2:3], v170, 1.0 op_sel:[1,0,0]
	v_cvt_scalef32_pk_f32_fp4 v[4:5], v170, 1.0 op_sel:[0,1,0]
	v_cvt_scalef32_pk_f32_fp4 v[6:7], v170, 1.0 op_sel:[1,1,0]
	v_cvt_scalef32_pk_f32_fp4 v[8:9], v171, 1.0
	v_cvt_scalef32_pk_f32_fp4 v[10:11], v171, 1.0 op_sel:[1,0,0]
	v_cvt_scalef32_pk_f32_fp4 v[12:13], v171, 1.0 op_sel:[0,1,0]
	v_cvt_scalef32_pk_f32_fp4 v[14:15], v171, 1.0 op_sel:[1,1,0]
	v_readlane_b32 s54, v90, 57
	s_lshl_b32 s56, s54, 9
	s_add_u32 s56, s64, s56
	s_addc_u32 s57, s65, 0
	global_load_dwordx2 v[170:171], v227, s[56:57]
	s_waitcnt lgkmcnt(1)
	v_pk_fma_f32 v[130:131], v[0:1], v[194:195], v[130:131] op_sel_hi:[1,0,1]
	v_pk_fma_f32 v[138:139], v[2:3], v[194:195], v[138:139] op_sel_hi:[1,0,1]
	v_pk_fma_f32 v[140:141], v[4:5], v[194:195], v[140:141] op_sel_hi:[1,0,1]
	v_pk_fma_f32 v[142:143], v[6:7], v[194:195], v[142:143] op_sel_hi:[1,0,1]
	v_pk_fma_f32 v[128:129], v[8:9], v[194:195], v[128:129] op_sel_hi:[1,0,1]
	v_pk_fma_f32 v[132:133], v[10:11], v[194:195], v[132:133] op_sel_hi:[1,0,1]
	v_pk_fma_f32 v[134:135], v[12:13], v[194:195], v[134:135] op_sel_hi:[1,0,1]
	v_pk_fma_f32 v[136:137], v[14:15], v[194:195], v[136:137] op_sel_hi:[1,0,1]
	ds_read_b32 v194, v193 offset:684
	s_waitcnt vmcnt(15)
	v_cvt_scalef32_pk_f32_fp4 v[0:1], v172, 1.0
	v_cvt_scalef32_pk_f32_fp4 v[2:3], v172, 1.0 op_sel:[1,0,0]
	v_cvt_scalef32_pk_f32_fp4 v[4:5], v172, 1.0 op_sel:[0,1,0]
	v_cvt_scalef32_pk_f32_fp4 v[6:7], v172, 1.0 op_sel:[1,1,0]
	v_cvt_scalef32_pk_f32_fp4 v[8:9], v173, 1.0
	v_cvt_scalef32_pk_f32_fp4 v[10:11], v173, 1.0 op_sel:[1,0,0]
	v_cvt_scalef32_pk_f32_fp4 v[12:13], v173, 1.0 op_sel:[0,1,0]
	v_cvt_scalef32_pk_f32_fp4 v[14:15], v173, 1.0 op_sel:[1,1,0]
	v_readlane_b32 s54, v90, 58
	s_lshl_b32 s56, s54, 9
	s_add_u32 s56, s64, s56
	s_addc_u32 s57, s65, 0
	global_load_dwordx2 v[172:173], v227, s[56:57]
	s_waitcnt lgkmcnt(1)
	v_pk_fma_f32 v[130:131], v[0:1], v[76:77], v[130:131] op_sel_hi:[1,0,1]
	v_pk_fma_f32 v[138:139], v[2:3], v[76:77], v[138:139] op_sel_hi:[1,0,1]
	v_pk_fma_f32 v[140:141], v[4:5], v[76:77], v[140:141] op_sel_hi:[1,0,1]
	v_pk_fma_f32 v[142:143], v[6:7], v[76:77], v[142:143] op_sel_hi:[1,0,1]
	v_pk_fma_f32 v[128:129], v[8:9], v[76:77], v[128:129] op_sel_hi:[1,0,1]
	v_pk_fma_f32 v[132:133], v[10:11], v[76:77], v[132:133] op_sel_hi:[1,0,1]
	v_pk_fma_f32 v[134:135], v[12:13], v[76:77], v[134:135] op_sel_hi:[1,0,1]
	v_pk_fma_f32 v[136:137], v[14:15], v[76:77], v[136:137] op_sel_hi:[1,0,1]
	ds_read_b32 v76, v193 offset:688
	s_waitcnt vmcnt(15)
	v_cvt_scalef32_pk_f32_fp4 v[0:1], v174, 1.0
	v_cvt_scalef32_pk_f32_fp4 v[2:3], v174, 1.0 op_sel:[1,0,0]
	v_cvt_scalef32_pk_f32_fp4 v[4:5], v174, 1.0 op_sel:[0,1,0]
	v_cvt_scalef32_pk_f32_fp4 v[6:7], v174, 1.0 op_sel:[1,1,0]
	v_cvt_scalef32_pk_f32_fp4 v[8:9], v175, 1.0
	v_cvt_scalef32_pk_f32_fp4 v[10:11], v175, 1.0 op_sel:[1,0,0]
	v_cvt_scalef32_pk_f32_fp4 v[12:13], v175, 1.0 op_sel:[0,1,0]
	v_cvt_scalef32_pk_f32_fp4 v[14:15], v175, 1.0 op_sel:[1,1,0]
	v_readlane_b32 s54, v90, 59
	s_lshl_b32 s56, s54, 9
	s_add_u32 s56, s64, s56
	s_addc_u32 s57, s65, 0
	global_load_dwordx2 v[174:175], v227, s[56:57]
	s_waitcnt lgkmcnt(1)
	v_pk_fma_f32 v[130:131], v[0:1], v[194:195], v[130:131] op_sel_hi:[1,0,1]
	v_pk_fma_f32 v[138:139], v[2:3], v[194:195], v[138:139] op_sel_hi:[1,0,1]
	v_pk_fma_f32 v[140:141], v[4:5], v[194:195], v[140:141] op_sel_hi:[1,0,1]
	v_pk_fma_f32 v[142:143], v[6:7], v[194:195], v[142:143] op_sel_hi:[1,0,1]
	v_pk_fma_f32 v[128:129], v[8:9], v[194:195], v[128:129] op_sel_hi:[1,0,1]
	v_pk_fma_f32 v[132:133], v[10:11], v[194:195], v[132:133] op_sel_hi:[1,0,1]
	v_pk_fma_f32 v[134:135], v[12:13], v[194:195], v[134:135] op_sel_hi:[1,0,1]
	v_pk_fma_f32 v[136:137], v[14:15], v[194:195], v[136:137] op_sel_hi:[1,0,1]
	ds_read_b32 v194, v193 offset:692
	s_waitcnt vmcnt(15)
; __device__ void peer_gather_phase(const Params& P, int l, bool do_store) {
;     ...
; #pragma unroll
;       for (int j = 0; j < 8; ++j) {
;         const float a = __builtin_bit_cast(float, __builtin_amdgcn_readlane(__builtin_bit_cast(int, avec), kb + j));
;         const f32x2 aa = f32x2{a, a};
;         y[0] += aa * __builtin_amdgcn_cvt_scalef32_pk_f32_fp4(v8[j].x, 1.0f, 0); y[1] += aa * __builtin_amdgcn_cvt_scalef32_pk_f32_fp4(v8[j].x, 1.0f, 1);
;         y[2] += aa * __builtin_amdgcn_cvt_scalef32_pk_f32_fp4(v8[j].x, 1.0f, 2); y[3] += aa * __builtin_amdgcn_cvt_scalef32_pk_f32_fp4(v8[j].x, 1.0f, 3);
;         y[4] += aa * __builtin_amdgcn_cvt_scalef32_pk_f32_fp4(v8[j].y, 1.0f, 0); y[5] += aa * __builtin_amdgcn_cvt_scalef32_pk_f32_fp4(v8[j].y, 1.0f, 1);
;         y[6] += aa * __builtin_amdgcn_cvt_scalef32_pk_f32_fp4(v8[j].y, 1.0f, 2); y[7] += aa * __builtin_amdgcn_cvt_scalef32_pk_f32_fp4(v8[j].y, 1.0f, 3);
;       }
	v_cvt_scalef32_pk_f32_fp4 v[0:1], v180, 1.0
	v_cvt_scalef32_pk_f32_fp4 v[2:3], v180, 1.0 op_sel:[1,0,0]
	v_cvt_scalef32_pk_f32_fp4 v[4:5], v180, 1.0 op_sel:[0,1,0]
	v_cvt_scalef32_pk_f32_fp4 v[6:7], v180, 1.0 op_sel:[1,1,0]
	v_cvt_scalef32_pk_f32_fp4 v[8:9], v181, 1.0
	v_cvt_scalef32_pk_f32_fp4 v[10:11], v181, 1.0 op_sel:[1,0,0]
	v_cvt_scalef32_pk_f32_fp4 v[12:13], v181, 1.0 op_sel:[0,1,0]
	v_cvt_scalef32_pk_f32_fp4 v[14:15], v181, 1.0 op_sel:[1,1,0]
	v_readlane_b32 s54, v90, 60
	s_lshl_b32 s56, s54, 9
	s_add_u32 s56, s64, s56
	s_addc_u32 s57, s65, 0
	global_load_dwordx2 v[180:181], v227, s[56:57]
	s_waitcnt lgkmcnt(1)
	v_pk_fma_f32 v[130:131], v[0:1], v[76:77], v[130:131] op_sel_hi:[1,0,1]
	v_pk_fma_f32 v[138:139], v[2:3], v[76:77], v[138:139] op_sel_hi:[1,0,1]
	v_pk_fma_f32 v[140:141], v[4:5], v[76:77], v[140:141] op_sel_hi:[1,0,1]
	v_pk_fma_f32 v[142:143], v[6:7], v[76:77], v[142:143] op_sel_hi:[1,0,1]
	v_pk_fma_f32 v[128:129], v[8:9], v[76:77], v[128:129] op_sel_hi:[1,0,1]
	v_pk_fma_f32 v[132:133], v[10:11], v[76:77], v[132:133] op_sel_hi:[1,0,1]
	v_pk_fma_f32 v[134:135], v[12:13], v[76:77], v[134:135] op_sel_hi:[1,0,1]
	v_pk_fma_f32 v[136:137], v[14:15], v[76:77], v[136:137] op_sel_hi:[1,0,1]
	ds_read_b32 v76, v193 offset:696
	s_waitcnt vmcnt(15)
	v_cvt_scalef32_pk_f32_fp4 v[0:1], v182, 1.0
	v_cvt_scalef32_pk_f32_fp4 v[2:3], v182, 1.0 op_sel:[1,0,0]
	v_cvt_scalef32_pk_f32_fp4 v[4:5], v182, 1.0 op_sel:[0,1,0]
	v_cvt_scalef32_pk_f32_fp4 v[6:7], v182, 1.0 op_sel:[1,1,0]
	v_cvt_scalef32_pk_f32_fp4 v[8:9], v183, 1.0
	v_cvt_scalef32_pk_f32_fp4 v[10:11], v183, 1.0 op_sel:[1,0,0]
	v_cvt_scalef32_pk_f32_fp4 v[12:13], v183, 1.0 op_sel:[0,1,0]
	v_cvt_scalef32_pk_f32_fp4 v[14:15], v183, 1.0 op_sel:[1,1,0]
	v_readlane_b32 s54, v90, 61
	s_lshl_b32 s56, s54, 9
	s_add_u32 s56, s64, s56
	s_addc_u32 s57, s65, 0
	global_load_dwordx2 v[182:183], v227, s[56:57]
	s_waitcnt lgkmcnt(1)
	v_pk_fma_f32 v[130:131], v[0:1], v[194:195], v[130:131] op_sel_hi:[1,0,1]
	v_pk_fma_f32 v[138:139], v[2:3], v[194:195], v[138:139] op_sel_hi:[1,0,1]
	v_pk_fma_f32 v[140:141], v[4:5], v[194:195], v[140:141] op_sel_hi:[1,0,1]
	v_pk_fma_f32 v[142:143], v[6:7], v[194:195], v[142:143] op_sel_hi:[1,0,1]
	v_pk_fma_f32 v[128:129], v[8:9], v[194:195], v[128:129] op_sel_hi:[1,0,1]
	v_pk_fma_f32 v[132:133], v[10:11], v[194:195], v[132:133] op_sel_hi:[1,0,1]
	v_pk_fma_f32 v[134:135], v[12:13], v[194:195], v[134:135] op_sel_hi:[1,0,1]
	v_pk_fma_f32 v[136:137], v[14:15], v[194:195], v[136:137] op_sel_hi:[1,0,1]
	ds_read_b32 v194, v193 offset:700
	s_waitcnt vmcnt(15)
	v_cvt_scalef32_pk_f32_fp4 v[0:1], v184, 1.0
	v_cvt_scalef32_pk_f32_fp4 v[2:3], v184, 1.0 op_sel:[1,0,0]
	v_cvt_scalef32_pk_f32_fp4 v[4:5], v184, 1.0 op_sel:[0,1,0]
	v_cvt_scalef32_pk_f32_fp4 v[6:7], v184, 1.0 op_sel:[1,1,0]
	v_cvt_scalef32_pk_f32_fp4 v[8:9], v185, 1.0
	v_cvt_scalef32_pk_f32_fp4 v[10:11], v185, 1.0 op_sel:[1,0,0]
	v_cvt_scalef32_pk_f32_fp4 v[12:13], v185, 1.0 op_sel:[0,1,0]
	v_cvt_scalef32_pk_f32_fp4 v[14:15], v185, 1.0 op_sel:[1,1,0]
	v_readlane_b32 s54, v90, 62
	s_lshl_b32 s56, s54, 9
	s_add_u32 s56, s64, s56
	s_addc_u32 s57, s65, 0
	global_load_dwordx2 v[184:185], v227, s[56:57]
	s_waitcnt lgkmcnt(1)
	v_pk_fma_f32 v[130:131], v[0:1], v[76:77], v[130:131] op_sel_hi:[1,0,1]
	v_pk_fma_f32 v[138:139], v[2:3], v[76:77], v[138:139] op_sel_hi:[1,0,1]
	v_pk_fma_f32 v[140:141], v[4:5], v[76:77], v[140:141] op_sel_hi:[1,0,1]
	v_pk_fma_f32 v[142:143], v[6:7], v[76:77], v[142:143] op_sel_hi:[1,0,1]
	v_pk_fma_f32 v[128:129], v[8:9], v[76:77], v[128:129] op_sel_hi:[1,0,1]
	v_pk_fma_f32 v[132:133], v[10:11], v[76:77], v[132:133] op_sel_hi:[1,0,1]
	v_pk_fma_f32 v[134:135], v[12:13], v[76:77], v[134:135] op_sel_hi:[1,0,1]
	v_pk_fma_f32 v[136:137], v[14:15], v[76:77], v[136:137] op_sel_hi:[1,0,1]
	ds_read_b32 v76, v193 offset:704
	s_waitcnt vmcnt(15)
	v_cvt_scalef32_pk_f32_fp4 v[0:1], v186, 1.0
	v_cvt_scalef32_pk_f32_fp4 v[2:3], v186, 1.0 op_sel:[1,0,0]
	v_cvt_scalef32_pk_f32_fp4 v[4:5], v186, 1.0 op_sel:[0,1,0]
	v_cvt_scalef32_pk_f32_fp4 v[6:7], v186, 1.0 op_sel:[1,1,0]
	v_cvt_scalef32_pk_f32_fp4 v[8:9], v187, 1.0
	v_cvt_scalef32_pk_f32_fp4 v[10:11], v187, 1.0 op_sel:[1,0,0]
	v_cvt_scalef32_pk_f32_fp4 v[12:13], v187, 1.0 op_sel:[0,1,0]
	v_cvt_scalef32_pk_f32_fp4 v[14:15], v187, 1.0 op_sel:[1,1,0]
	v_readlane_b32 s54, v90, 63
	s_lshl_b32 s56, s54, 9
	s_add_u32 s56, s64, s56
	s_addc_u32 s57, s65, 0
	global_load_dwordx2 v[186:187], v227, s[56:57]
	s_waitcnt lgkmcnt(1)
	v_pk_fma_f32 v[130:131], v[0:1], v[194:195], v[130:131] op_sel_hi:[1,0,1]
	v_pk_fma_f32 v[138:139], v[2:3], v[194:195], v[138:139] op_sel_hi:[1,0,1]
	v_pk_fma_f32 v[140:141], v[4:5], v[194:195], v[140:141] op_sel_hi:[1,0,1]
	v_pk_fma_f32 v[142:143], v[6:7], v[194:195], v[142:143] op_sel_hi:[1,0,1]
	v_pk_fma_f32 v[128:129], v[8:9], v[194:195], v[128:129] op_sel_hi:[1,0,1]
	v_pk_fma_f32 v[132:133], v[10:11], v[194:195], v[132:133] op_sel_hi:[1,0,1]
	v_pk_fma_f32 v[134:135], v[12:13], v[194:195], v[134:135] op_sel_hi:[1,0,1]
	v_pk_fma_f32 v[136:137], v[14:15], v[194:195], v[136:137] op_sel_hi:[1,0,1]
	ds_read_b32 v194, v193 offset:708
	s_waitcnt vmcnt(15)
	v_cvt_scalef32_pk_f32_fp4 v[0:1], v144, 1.0
	v_cvt_scalef32_pk_f32_fp4 v[2:3], v144, 1.0 op_sel:[1,0,0]
	v_cvt_scalef32_pk_f32_fp4 v[4:5], v144, 1.0 op_sel:[0,1,0]
	v_cvt_scalef32_pk_f32_fp4 v[6:7], v144, 1.0 op_sel:[1,1,0]
	v_cvt_scalef32_pk_f32_fp4 v[8:9], v145, 1.0
	v_cvt_scalef32_pk_f32_fp4 v[10:11], v145, 1.0 op_sel:[1,0,0]
	v_cvt_scalef32_pk_f32_fp4 v[12:13], v145, 1.0 op_sel:[0,1,0]
	v_cvt_scalef32_pk_f32_fp4 v[14:15], v145, 1.0 op_sel:[1,1,0]
	s_waitcnt lgkmcnt(1)
; __device__ void peer_gather_phase(const Params& P, int l, bool do_store) {
;     ...
; #pragma unroll
;       for (int j = 0; j < 8; ++j) {
;         const float a = __builtin_bit_cast(float, __builtin_amdgcn_readlane(__builtin_bit_cast(int, avec), kb + j));
;         const f32x2 aa = f32x2{a, a};
;         y[0] += aa * __builtin_amdgcn_cvt_scalef32_pk_f32_fp4(v8[j].x, 1.0f, 0); y[1] += aa * __builtin_amdgcn_cvt_scalef32_pk_f32_fp4(v8[j].x, 1.0f, 1);
;         y[2] += aa * __builtin_amdgcn_cvt_scalef32_pk_f32_fp4(v8[j].x, 1.0f, 2); y[3] += aa * __builtin_amdgcn_cvt_scalef32_pk_f32_fp4(v8[j].x, 1.0f, 3);
;         y[4] += aa * __builtin_amdgcn_cvt_scalef32_pk_f32_fp4(v8[j].y, 1.0f, 0); y[5] += aa * __builtin_amdgcn_cvt_scalef32_pk_f32_fp4(v8[j].y, 1.0f, 1);
;         y[6] += aa * __builtin_amdgcn_cvt_scalef32_pk_f32_fp4(v8[j].y, 1.0f, 2); y[7] += aa * __builtin_amdgcn_cvt_scalef32_pk_f32_fp4(v8[j].y, 1.0f, 3);
;       }
	v_pk_fma_f32 v[130:131], v[0:1], v[76:77], v[130:131] op_sel_hi:[1,0,1]
	v_pk_fma_f32 v[138:139], v[2:3], v[76:77], v[138:139] op_sel_hi:[1,0,1]
	v_pk_fma_f32 v[140:141], v[4:5], v[76:77], v[140:141] op_sel_hi:[1,0,1]
	v_pk_fma_f32 v[142:143], v[6:7], v[76:77], v[142:143] op_sel_hi:[1,0,1]
	v_pk_fma_f32 v[128:129], v[8:9], v[76:77], v[128:129] op_sel_hi:[1,0,1]
	v_pk_fma_f32 v[132:133], v[10:11], v[76:77], v[132:133] op_sel_hi:[1,0,1]
	v_pk_fma_f32 v[134:135], v[12:13], v[76:77], v[134:135] op_sel_hi:[1,0,1]
	v_pk_fma_f32 v[136:137], v[14:15], v[76:77], v[136:137] op_sel_hi:[1,0,1]
	ds_read_b32 v76, v193 offset:712
	s_waitcnt vmcnt(14)
	v_cvt_scalef32_pk_f32_fp4 v[0:1], v146, 1.0
	v_cvt_scalef32_pk_f32_fp4 v[2:3], v146, 1.0 op_sel:[1,0,0]
	v_cvt_scalef32_pk_f32_fp4 v[4:5], v146, 1.0 op_sel:[0,1,0]
	v_cvt_scalef32_pk_f32_fp4 v[6:7], v146, 1.0 op_sel:[1,1,0]
	v_cvt_scalef32_pk_f32_fp4 v[8:9], v147, 1.0
	v_cvt_scalef32_pk_f32_fp4 v[10:11], v147, 1.0 op_sel:[1,0,0]
	v_cvt_scalef32_pk_f32_fp4 v[12:13], v147, 1.0 op_sel:[0,1,0]
	v_cvt_scalef32_pk_f32_fp4 v[14:15], v147, 1.0 op_sel:[1,1,0]
	s_waitcnt lgkmcnt(1)
	v_pk_fma_f32 v[130:131], v[0:1], v[194:195], v[130:131] op_sel_hi:[1,0,1]
	v_pk_fma_f32 v[138:139], v[2:3], v[194:195], v[138:139] op_sel_hi:[1,0,1]
	v_pk_fma_f32 v[140:141], v[4:5], v[194:195], v[140:141] op_sel_hi:[1,0,1]
	v_pk_fma_f32 v[142:143], v[6:7], v[194:195], v[142:143] op_sel_hi:[1,0,1]
	v_pk_fma_f32 v[128:129], v[8:9], v[194:195], v[128:129] op_sel_hi:[1,0,1]
	v_pk_fma_f32 v[132:133], v[10:11], v[194:195], v[132:133] op_sel_hi:[1,0,1]
	v_pk_fma_f32 v[134:135], v[12:13], v[194:195], v[134:135] op_sel_hi:[1,0,1]
	v_pk_fma_f32 v[136:137], v[14:15], v[194:195], v[136:137] op_sel_hi:[1,0,1]
	ds_read_b32 v194, v193 offset:716
	s_waitcnt vmcnt(13)
	v_cvt_scalef32_pk_f32_fp4 v[0:1], v148, 1.0
	v_cvt_scalef32_pk_f32_fp4 v[2:3], v148, 1.0 op_sel:[1,0,0]
	v_cvt_scalef32_pk_f32_fp4 v[4:5], v148, 1.0 op_sel:[0,1,0]
	v_cvt_scalef32_pk_f32_fp4 v[6:7], v148, 1.0 op_sel:[1,1,0]
	v_cvt_scalef32_pk_f32_fp4 v[8:9], v149, 1.0
	v_cvt_scalef32_pk_f32_fp4 v[10:11], v149, 1.0 op_sel:[1,0,0]
	v_cvt_scalef32_pk_f32_fp4 v[12:13], v149, 1.0 op_sel:[0,1,0]
	v_cvt_scalef32_pk_f32_fp4 v[14:15], v149, 1.0 op_sel:[1,1,0]
	s_waitcnt lgkmcnt(1)
	v_pk_fma_f32 v[130:131], v[0:1], v[76:77], v[130:131] op_sel_hi:[1,0,1]
	v_pk_fma_f32 v[138:139], v[2:3], v[76:77], v[138:139] op_sel_hi:[1,0,1]
	v_pk_fma_f32 v[140:141], v[4:5], v[76:77], v[140:141] op_sel_hi:[1,0,1]
	v_pk_fma_f32 v[142:143], v[6:7], v[76:77], v[142:143] op_sel_hi:[1,0,1]
	v_pk_fma_f32 v[128:129], v[8:9], v[76:77], v[128:129] op_sel_hi:[1,0,1]
	v_pk_fma_f32 v[132:133], v[10:11], v[76:77], v[132:133] op_sel_hi:[1,0,1]
	v_pk_fma_f32 v[134:135], v[12:13], v[76:77], v[134:135] op_sel_hi:[1,0,1]
	v_pk_fma_f32 v[136:137], v[14:15], v[76:77], v[136:137] op_sel_hi:[1,0,1]
	ds_read_b32 v76, v193 offset:720
	s_waitcnt vmcnt(12)
	v_cvt_scalef32_pk_f32_fp4 v[0:1], v150, 1.0
	v_cvt_scalef32_pk_f32_fp4 v[2:3], v150, 1.0 op_sel:[1,0,0]
	v_cvt_scalef32_pk_f32_fp4 v[4:5], v150, 1.0 op_sel:[0,1,0]
	v_cvt_scalef32_pk_f32_fp4 v[6:7], v150, 1.0 op_sel:[1,1,0]
	v_cvt_scalef32_pk_f32_fp4 v[8:9], v151, 1.0
	v_cvt_scalef32_pk_f32_fp4 v[10:11], v151, 1.0 op_sel:[1,0,0]
	v_cvt_scalef32_pk_f32_fp4 v[12:13], v151, 1.0 op_sel:[0,1,0]
	v_cvt_scalef32_pk_f32_fp4 v[14:15], v151, 1.0 op_sel:[1,1,0]
	s_waitcnt lgkmcnt(1)
	v_pk_fma_f32 v[130:131], v[0:1], v[194:195], v[130:131] op_sel_hi:[1,0,1]
	v_pk_fma_f32 v[138:139], v[2:3], v[194:195], v[138:139] op_sel_hi:[1,0,1]
	v_pk_fma_f32 v[140:141], v[4:5], v[194:195], v[140:141] op_sel_hi:[1,0,1]
	v_pk_fma_f32 v[142:143], v[6:7], v[194:195], v[142:143] op_sel_hi:[1,0,1]
	v_pk_fma_f32 v[128:129], v[8:9], v[194:195], v[128:129] op_sel_hi:[1,0,1]
	v_pk_fma_f32 v[132:133], v[10:11], v[194:195], v[132:133] op_sel_hi:[1,0,1]
	v_pk_fma_f32 v[134:135], v[12:13], v[194:195], v[134:135] op_sel_hi:[1,0,1]
	v_pk_fma_f32 v[136:137], v[14:15], v[194:195], v[136:137] op_sel_hi:[1,0,1]
	ds_read_b32 v194, v193 offset:724
	s_waitcnt vmcnt(11)
	v_cvt_scalef32_pk_f32_fp4 v[0:1], v152, 1.0
	v_cvt_scalef32_pk_f32_fp4 v[2:3], v152, 1.0 op_sel:[1,0,0]
	v_cvt_scalef32_pk_f32_fp4 v[4:5], v152, 1.0 op_sel:[0,1,0]
	v_cvt_scalef32_pk_f32_fp4 v[6:7], v152, 1.0 op_sel:[1,1,0]
	v_cvt_scalef32_pk_f32_fp4 v[8:9], v153, 1.0
	v_cvt_scalef32_pk_f32_fp4 v[10:11], v153, 1.0 op_sel:[1,0,0]
	v_cvt_scalef32_pk_f32_fp4 v[12:13], v153, 1.0 op_sel:[0,1,0]
	v_cvt_scalef32_pk_f32_fp4 v[14:15], v153, 1.0 op_sel:[1,1,0]
	s_waitcnt lgkmcnt(1)
	v_pk_fma_f32 v[130:131], v[0:1], v[76:77], v[130:131] op_sel_hi:[1,0,1]
	v_pk_fma_f32 v[138:139], v[2:3], v[76:77], v[138:139] op_sel_hi:[1,0,1]
	v_pk_fma_f32 v[140:141], v[4:5], v[76:77], v[140:141] op_sel_hi:[1,0,1]
	v_pk_fma_f32 v[142:143], v[6:7], v[76:77], v[142:143] op_sel_hi:[1,0,1]
	v_pk_fma_f32 v[128:129], v[8:9], v[76:77], v[128:129] op_sel_hi:[1,0,1]
	v_pk_fma_f32 v[132:133], v[10:11], v[76:77], v[132:133] op_sel_hi:[1,0,1]
	v_pk_fma_f32 v[134:135], v[12:13], v[76:77], v[134:135] op_sel_hi:[1,0,1]
	v_pk_fma_f32 v[136:137], v[14:15], v[76:77], v[136:137] op_sel_hi:[1,0,1]
	ds_read_b32 v76, v193 offset:728
	s_waitcnt vmcnt(10)
	v_cvt_scalef32_pk_f32_fp4 v[0:1], v154, 1.0
	v_cvt_scalef32_pk_f32_fp4 v[2:3], v154, 1.0 op_sel:[1,0,0]
	v_cvt_scalef32_pk_f32_fp4 v[4:5], v154, 1.0 op_sel:[0,1,0]
	v_cvt_scalef32_pk_f32_fp4 v[6:7], v154, 1.0 op_sel:[1,1,0]
	v_cvt_scalef32_pk_f32_fp4 v[8:9], v155, 1.0
	v_cvt_scalef32_pk_f32_fp4 v[10:11], v155, 1.0 op_sel:[1,0,0]
	v_cvt_scalef32_pk_f32_fp4 v[12:13], v155, 1.0 op_sel:[0,1,0]
	v_cvt_scalef32_pk_f32_fp4 v[14:15], v155, 1.0 op_sel:[1,1,0]
	s_waitcnt lgkmcnt(1)
; __device__ void peer_gather_phase(const Params& P, int l, bool do_store) {
;     ...
; #pragma unroll
;       for (int j = 0; j < 8; ++j) {
;         const float a = __builtin_bit_cast(float, __builtin_amdgcn_readlane(__builtin_bit_cast(int, avec), kb + j));
;         const f32x2 aa = f32x2{a, a};
;         y[0] += aa * __builtin_amdgcn_cvt_scalef32_pk_f32_fp4(v8[j].x, 1.0f, 0); y[1] += aa * __builtin_amdgcn_cvt_scalef32_pk_f32_fp4(v8[j].x, 1.0f, 1);
;         y[2] += aa * __builtin_amdgcn_cvt_scalef32_pk_f32_fp4(v8[j].x, 1.0f, 2); y[3] += aa * __builtin_amdgcn_cvt_scalef32_pk_f32_fp4(v8[j].x, 1.0f, 3);
;         y[4] += aa * __builtin_amdgcn_cvt_scalef32_pk_f32_fp4(v8[j].y, 1.0f, 0); y[5] += aa * __builtin_amdgcn_cvt_scalef32_pk_f32_fp4(v8[j].y, 1.0f, 1);
;         y[6] += aa * __builtin_amdgcn_cvt_scalef32_pk_f32_fp4(v8[j].y, 1.0f, 2); y[7] += aa * __builtin_amdgcn_cvt_scalef32_pk_f32_fp4(v8[j].y, 1.0f, 3);
;       }
	v_pk_fma_f32 v[130:131], v[0:1], v[194:195], v[130:131] op_sel_hi:[1,0,1]
	v_pk_fma_f32 v[138:139], v[2:3], v[194:195], v[138:139] op_sel_hi:[1,0,1]
	v_pk_fma_f32 v[140:141], v[4:5], v[194:195], v[140:141] op_sel_hi:[1,0,1]
	v_pk_fma_f32 v[142:143], v[6:7], v[194:195], v[142:143] op_sel_hi:[1,0,1]
	v_pk_fma_f32 v[128:129], v[8:9], v[194:195], v[128:129] op_sel_hi:[1,0,1]
	v_pk_fma_f32 v[132:133], v[10:11], v[194:195], v[132:133] op_sel_hi:[1,0,1]
	v_pk_fma_f32 v[134:135], v[12:13], v[194:195], v[134:135] op_sel_hi:[1,0,1]
	v_pk_fma_f32 v[136:137], v[14:15], v[194:195], v[136:137] op_sel_hi:[1,0,1]
	ds_read_b32 v194, v193 offset:732
	s_waitcnt vmcnt(9)
	v_cvt_scalef32_pk_f32_fp4 v[0:1], v156, 1.0
	v_cvt_scalef32_pk_f32_fp4 v[2:3], v156, 1.0 op_sel:[1,0,0]
	v_cvt_scalef32_pk_f32_fp4 v[4:5], v156, 1.0 op_sel:[0,1,0]
	v_cvt_scalef32_pk_f32_fp4 v[6:7], v156, 1.0 op_sel:[1,1,0]
	v_cvt_scalef32_pk_f32_fp4 v[8:9], v157, 1.0
	v_cvt_scalef32_pk_f32_fp4 v[10:11], v157, 1.0 op_sel:[1,0,0]
	v_cvt_scalef32_pk_f32_fp4 v[12:13], v157, 1.0 op_sel:[0,1,0]
	v_cvt_scalef32_pk_f32_fp4 v[14:15], v157, 1.0 op_sel:[1,1,0]
	s_waitcnt lgkmcnt(1)
	v_pk_fma_f32 v[130:131], v[0:1], v[76:77], v[130:131] op_sel_hi:[1,0,1]
	v_pk_fma_f32 v[138:139], v[2:3], v[76:77], v[138:139] op_sel_hi:[1,0,1]
	v_pk_fma_f32 v[140:141], v[4:5], v[76:77], v[140:141] op_sel_hi:[1,0,1]
	v_pk_fma_f32 v[142:143], v[6:7], v[76:77], v[142:143] op_sel_hi:[1,0,1]
	v_pk_fma_f32 v[128:129], v[8:9], v[76:77], v[128:129] op_sel_hi:[1,0,1]
	v_pk_fma_f32 v[132:133], v[10:11], v[76:77], v[132:133] op_sel_hi:[1,0,1]
	v_pk_fma_f32 v[134:135], v[12:13], v[76:77], v[134:135] op_sel_hi:[1,0,1]
	v_pk_fma_f32 v[136:137], v[14:15], v[76:77], v[136:137] op_sel_hi:[1,0,1]
	ds_read_b32 v76, v193 offset:736
	s_waitcnt vmcnt(8)
	v_cvt_scalef32_pk_f32_fp4 v[0:1], v158, 1.0
	v_cvt_scalef32_pk_f32_fp4 v[2:3], v158, 1.0 op_sel:[1,0,0]
	v_cvt_scalef32_pk_f32_fp4 v[4:5], v158, 1.0 op_sel:[0,1,0]
	v_cvt_scalef32_pk_f32_fp4 v[6:7], v158, 1.0 op_sel:[1,1,0]
	v_cvt_scalef32_pk_f32_fp4 v[8:9], v159, 1.0
	v_cvt_scalef32_pk_f32_fp4 v[10:11], v159, 1.0 op_sel:[1,0,0]
	v_cvt_scalef32_pk_f32_fp4 v[12:13], v159, 1.0 op_sel:[0,1,0]
	v_cvt_scalef32_pk_f32_fp4 v[14:15], v159, 1.0 op_sel:[1,1,0]
	s_waitcnt lgkmcnt(1)
	v_pk_fma_f32 v[130:131], v[0:1], v[194:195], v[130:131] op_sel_hi:[1,0,1]
	v_pk_fma_f32 v[138:139], v[2:3], v[194:195], v[138:139] op_sel_hi:[1,0,1]
	v_pk_fma_f32 v[140:141], v[4:5], v[194:195], v[140:141] op_sel_hi:[1,0,1]
	v_pk_fma_f32 v[142:143], v[6:7], v[194:195], v[142:143] op_sel_hi:[1,0,1]
	v_pk_fma_f32 v[128:129], v[8:9], v[194:195], v[128:129] op_sel_hi:[1,0,1]
	v_pk_fma_f32 v[132:133], v[10:11], v[194:195], v[132:133] op_sel_hi:[1,0,1]
	v_pk_fma_f32 v[134:135], v[12:13], v[194:195], v[134:135] op_sel_hi:[1,0,1]
	v_pk_fma_f32 v[136:137], v[14:15], v[194:195], v[136:137] op_sel_hi:[1,0,1]
	ds_read_b32 v194, v193 offset:740
	s_waitcnt vmcnt(7)
	v_cvt_scalef32_pk_f32_fp4 v[0:1], v168, 1.0
	v_cvt_scalef32_pk_f32_fp4 v[2:3], v168, 1.0 op_sel:[1,0,0]
	v_cvt_scalef32_pk_f32_fp4 v[4:5], v168, 1.0 op_sel:[0,1,0]
	v_cvt_scalef32_pk_f32_fp4 v[6:7], v168, 1.0 op_sel:[1,1,0]
	v_cvt_scalef32_pk_f32_fp4 v[8:9], v169, 1.0
	v_cvt_scalef32_pk_f32_fp4 v[10:11], v169, 1.0 op_sel:[1,0,0]
	v_cvt_scalef32_pk_f32_fp4 v[12:13], v169, 1.0 op_sel:[0,1,0]
	v_cvt_scalef32_pk_f32_fp4 v[14:15], v169, 1.0 op_sel:[1,1,0]
	s_waitcnt lgkmcnt(1)
	v_pk_fma_f32 v[130:131], v[0:1], v[76:77], v[130:131] op_sel_hi:[1,0,1]
	v_pk_fma_f32 v[138:139], v[2:3], v[76:77], v[138:139] op_sel_hi:[1,0,1]
	v_pk_fma_f32 v[140:141], v[4:5], v[76:77], v[140:141] op_sel_hi:[1,0,1]
	v_pk_fma_f32 v[142:143], v[6:7], v[76:77], v[142:143] op_sel_hi:[1,0,1]
	v_pk_fma_f32 v[128:129], v[8:9], v[76:77], v[128:129] op_sel_hi:[1,0,1]
	v_pk_fma_f32 v[132:133], v[10:11], v[76:77], v[132:133] op_sel_hi:[1,0,1]
	v_pk_fma_f32 v[134:135], v[12:13], v[76:77], v[134:135] op_sel_hi:[1,0,1]
	v_pk_fma_f32 v[136:137], v[14:15], v[76:77], v[136:137] op_sel_hi:[1,0,1]
	ds_read_b32 v76, v193 offset:744
	s_waitcnt vmcnt(6)
	v_cvt_scalef32_pk_f32_fp4 v[0:1], v170, 1.0
	v_cvt_scalef32_pk_f32_fp4 v[2:3], v170, 1.0 op_sel:[1,0,0]
	v_cvt_scalef32_pk_f32_fp4 v[4:5], v170, 1.0 op_sel:[0,1,0]
	v_cvt_scalef32_pk_f32_fp4 v[6:7], v170, 1.0 op_sel:[1,1,0]
	v_cvt_scalef32_pk_f32_fp4 v[8:9], v171, 1.0
	v_cvt_scalef32_pk_f32_fp4 v[10:11], v171, 1.0 op_sel:[1,0,0]
	v_cvt_scalef32_pk_f32_fp4 v[12:13], v171, 1.0 op_sel:[0,1,0]
	v_cvt_scalef32_pk_f32_fp4 v[14:15], v171, 1.0 op_sel:[1,1,0]
	s_waitcnt lgkmcnt(1)
	v_pk_fma_f32 v[130:131], v[0:1], v[194:195], v[130:131] op_sel_hi:[1,0,1]
	v_pk_fma_f32 v[138:139], v[2:3], v[194:195], v[138:139] op_sel_hi:[1,0,1]
	v_pk_fma_f32 v[140:141], v[4:5], v[194:195], v[140:141] op_sel_hi:[1,0,1]
	v_pk_fma_f32 v[142:143], v[6:7], v[194:195], v[142:143] op_sel_hi:[1,0,1]
	v_pk_fma_f32 v[128:129], v[8:9], v[194:195], v[128:129] op_sel_hi:[1,0,1]
	v_pk_fma_f32 v[132:133], v[10:11], v[194:195], v[132:133] op_sel_hi:[1,0,1]
	v_pk_fma_f32 v[134:135], v[12:13], v[194:195], v[134:135] op_sel_hi:[1,0,1]
	v_pk_fma_f32 v[136:137], v[14:15], v[194:195], v[136:137] op_sel_hi:[1,0,1]
	ds_read_b32 v194, v193 offset:748
	s_waitcnt vmcnt(5)
	v_cvt_scalef32_pk_f32_fp4 v[0:1], v172, 1.0
	v_cvt_scalef32_pk_f32_fp4 v[2:3], v172, 1.0 op_sel:[1,0,0]
	v_cvt_scalef32_pk_f32_fp4 v[4:5], v172, 1.0 op_sel:[0,1,0]
	v_cvt_scalef32_pk_f32_fp4 v[6:7], v172, 1.0 op_sel:[1,1,0]
	v_cvt_scalef32_pk_f32_fp4 v[8:9], v173, 1.0
	v_cvt_scalef32_pk_f32_fp4 v[10:11], v173, 1.0 op_sel:[1,0,0]
	v_cvt_scalef32_pk_f32_fp4 v[12:13], v173, 1.0 op_sel:[0,1,0]
	v_cvt_scalef32_pk_f32_fp4 v[14:15], v173, 1.0 op_sel:[1,1,0]
	s_waitcnt lgkmcnt(1)
; __device__ void peer_gather_phase(const Params& P, int l, bool do_store) {
;     ...
; #pragma unroll
;       for (int j = 0; j < 8; ++j) {
;         const float a = __builtin_bit_cast(float, __builtin_amdgcn_readlane(__builtin_bit_cast(int, avec), kb + j));
;         const f32x2 aa = f32x2{a, a};
;         y[0] += aa * __builtin_amdgcn_cvt_scalef32_pk_f32_fp4(v8[j].x, 1.0f, 0); y[1] += aa * __builtin_amdgcn_cvt_scalef32_pk_f32_fp4(v8[j].x, 1.0f, 1);
;         y[2] += aa * __builtin_amdgcn_cvt_scalef32_pk_f32_fp4(v8[j].x, 1.0f, 2); y[3] += aa * __builtin_amdgcn_cvt_scalef32_pk_f32_fp4(v8[j].x, 1.0f, 3);
;         y[4] += aa * __builtin_amdgcn_cvt_scalef32_pk_f32_fp4(v8[j].y, 1.0f, 0); y[5] += aa * __builtin_amdgcn_cvt_scalef32_pk_f32_fp4(v8[j].y, 1.0f, 1);
;         y[6] += aa * __builtin_amdgcn_cvt_scalef32_pk_f32_fp4(v8[j].y, 1.0f, 2); y[7] += aa * __builtin_amdgcn_cvt_scalef32_pk_f32_fp4(v8[j].y, 1.0f, 3);
;       }
	v_pk_fma_f32 v[130:131], v[0:1], v[76:77], v[130:131] op_sel_hi:[1,0,1]
	v_pk_fma_f32 v[138:139], v[2:3], v[76:77], v[138:139] op_sel_hi:[1,0,1]
	v_pk_fma_f32 v[140:141], v[4:5], v[76:77], v[140:141] op_sel_hi:[1,0,1]
	v_pk_fma_f32 v[142:143], v[6:7], v[76:77], v[142:143] op_sel_hi:[1,0,1]
	v_pk_fma_f32 v[128:129], v[8:9], v[76:77], v[128:129] op_sel_hi:[1,0,1]
	v_pk_fma_f32 v[132:133], v[10:11], v[76:77], v[132:133] op_sel_hi:[1,0,1]
	v_pk_fma_f32 v[134:135], v[12:13], v[76:77], v[134:135] op_sel_hi:[1,0,1]
	v_pk_fma_f32 v[136:137], v[14:15], v[76:77], v[136:137] op_sel_hi:[1,0,1]
	ds_read_b32 v76, v193 offset:752
	s_waitcnt vmcnt(4)
	v_cvt_scalef32_pk_f32_fp4 v[0:1], v174, 1.0
	v_cvt_scalef32_pk_f32_fp4 v[2:3], v174, 1.0 op_sel:[1,0,0]
	v_cvt_scalef32_pk_f32_fp4 v[4:5], v174, 1.0 op_sel:[0,1,0]
	v_cvt_scalef32_pk_f32_fp4 v[6:7], v174, 1.0 op_sel:[1,1,0]
	v_cvt_scalef32_pk_f32_fp4 v[8:9], v175, 1.0
	v_cvt_scalef32_pk_f32_fp4 v[10:11], v175, 1.0 op_sel:[1,0,0]
	v_cvt_scalef32_pk_f32_fp4 v[12:13], v175, 1.0 op_sel:[0,1,0]
	v_cvt_scalef32_pk_f32_fp4 v[14:15], v175, 1.0 op_sel:[1,1,0]
	s_waitcnt lgkmcnt(1)
	v_pk_fma_f32 v[130:131], v[0:1], v[194:195], v[130:131] op_sel_hi:[1,0,1]
	v_pk_fma_f32 v[138:139], v[2:3], v[194:195], v[138:139] op_sel_hi:[1,0,1]
	v_pk_fma_f32 v[140:141], v[4:5], v[194:195], v[140:141] op_sel_hi:[1,0,1]
	v_pk_fma_f32 v[142:143], v[6:7], v[194:195], v[142:143] op_sel_hi:[1,0,1]
	v_pk_fma_f32 v[128:129], v[8:9], v[194:195], v[128:129] op_sel_hi:[1,0,1]
	v_pk_fma_f32 v[132:133], v[10:11], v[194:195], v[132:133] op_sel_hi:[1,0,1]
	v_pk_fma_f32 v[134:135], v[12:13], v[194:195], v[134:135] op_sel_hi:[1,0,1]
	v_pk_fma_f32 v[136:137], v[14:15], v[194:195], v[136:137] op_sel_hi:[1,0,1]
	ds_read_b32 v194, v193 offset:756
	s_waitcnt vmcnt(3)
	v_cvt_scalef32_pk_f32_fp4 v[0:1], v180, 1.0
	v_cvt_scalef32_pk_f32_fp4 v[2:3], v180, 1.0 op_sel:[1,0,0]
	v_cvt_scalef32_pk_f32_fp4 v[4:5], v180, 1.0 op_sel:[0,1,0]
	v_cvt_scalef32_pk_f32_fp4 v[6:7], v180, 1.0 op_sel:[1,1,0]
	v_cvt_scalef32_pk_f32_fp4 v[8:9], v181, 1.0
	v_cvt_scalef32_pk_f32_fp4 v[10:11], v181, 1.0 op_sel:[1,0,0]
	v_cvt_scalef32_pk_f32_fp4 v[12:13], v181, 1.0 op_sel:[0,1,0]
	v_cvt_scalef32_pk_f32_fp4 v[14:15], v181, 1.0 op_sel:[1,1,0]
	s_waitcnt lgkmcnt(1)
	v_pk_fma_f32 v[130:131], v[0:1], v[76:77], v[130:131] op_sel_hi:[1,0,1]
	v_pk_fma_f32 v[138:139], v[2:3], v[76:77], v[138:139] op_sel_hi:[1,0,1]
	v_pk_fma_f32 v[140:141], v[4:5], v[76:77], v[140:141] op_sel_hi:[1,0,1]
	v_pk_fma_f32 v[142:143], v[6:7], v[76:77], v[142:143] op_sel_hi:[1,0,1]
	v_pk_fma_f32 v[128:129], v[8:9], v[76:77], v[128:129] op_sel_hi:[1,0,1]
	v_pk_fma_f32 v[132:133], v[10:11], v[76:77], v[132:133] op_sel_hi:[1,0,1]
	v_pk_fma_f32 v[134:135], v[12:13], v[76:77], v[134:135] op_sel_hi:[1,0,1]
	v_pk_fma_f32 v[136:137], v[14:15], v[76:77], v[136:137] op_sel_hi:[1,0,1]
	ds_read_b32 v76, v193 offset:760
	s_waitcnt vmcnt(2)
	v_cvt_scalef32_pk_f32_fp4 v[0:1], v182, 1.0
	v_cvt_scalef32_pk_f32_fp4 v[2:3], v182, 1.0 op_sel:[1,0,0]
	v_cvt_scalef32_pk_f32_fp4 v[4:5], v182, 1.0 op_sel:[0,1,0]
	v_cvt_scalef32_pk_f32_fp4 v[6:7], v182, 1.0 op_sel:[1,1,0]
	v_cvt_scalef32_pk_f32_fp4 v[8:9], v183, 1.0
	v_cvt_scalef32_pk_f32_fp4 v[10:11], v183, 1.0 op_sel:[1,0,0]
	v_cvt_scalef32_pk_f32_fp4 v[12:13], v183, 1.0 op_sel:[0,1,0]
	v_cvt_scalef32_pk_f32_fp4 v[14:15], v183, 1.0 op_sel:[1,1,0]
	s_waitcnt lgkmcnt(1)
	v_pk_fma_f32 v[130:131], v[0:1], v[194:195], v[130:131] op_sel_hi:[1,0,1]
	v_pk_fma_f32 v[138:139], v[2:3], v[194:195], v[138:139] op_sel_hi:[1,0,1]
	v_pk_fma_f32 v[140:141], v[4:5], v[194:195], v[140:141] op_sel_hi:[1,0,1]
	v_pk_fma_f32 v[142:143], v[6:7], v[194:195], v[142:143] op_sel_hi:[1,0,1]
	v_pk_fma_f32 v[128:129], v[8:9], v[194:195], v[128:129] op_sel_hi:[1,0,1]
	v_pk_fma_f32 v[132:133], v[10:11], v[194:195], v[132:133] op_sel_hi:[1,0,1]
	v_pk_fma_f32 v[134:135], v[12:13], v[194:195], v[134:135] op_sel_hi:[1,0,1]
	v_pk_fma_f32 v[136:137], v[14:15], v[194:195], v[136:137] op_sel_hi:[1,0,1]
	ds_read_b32 v194, v193 offset:764
	s_waitcnt vmcnt(1)
	v_cvt_scalef32_pk_f32_fp4 v[0:1], v184, 1.0
	v_cvt_scalef32_pk_f32_fp4 v[2:3], v184, 1.0 op_sel:[1,0,0]
	v_cvt_scalef32_pk_f32_fp4 v[4:5], v184, 1.0 op_sel:[0,1,0]
	v_cvt_scalef32_pk_f32_fp4 v[6:7], v184, 1.0 op_sel:[1,1,0]
	v_cvt_scalef32_pk_f32_fp4 v[8:9], v185, 1.0
	v_cvt_scalef32_pk_f32_fp4 v[10:11], v185, 1.0 op_sel:[1,0,0]
	v_cvt_scalef32_pk_f32_fp4 v[12:13], v185, 1.0 op_sel:[0,1,0]
	v_cvt_scalef32_pk_f32_fp4 v[14:15], v185, 1.0 op_sel:[1,1,0]
	s_waitcnt lgkmcnt(1)
	v_pk_fma_f32 v[130:131], v[0:1], v[76:77], v[130:131] op_sel_hi:[1,0,1]
	v_pk_fma_f32 v[138:139], v[2:3], v[76:77], v[138:139] op_sel_hi:[1,0,1]
	v_pk_fma_f32 v[140:141], v[4:5], v[76:77], v[140:141] op_sel_hi:[1,0,1]
	v_pk_fma_f32 v[142:143], v[6:7], v[76:77], v[142:143] op_sel_hi:[1,0,1]
	v_pk_fma_f32 v[128:129], v[8:9], v[76:77], v[128:129] op_sel_hi:[1,0,1]
	v_pk_fma_f32 v[132:133], v[10:11], v[76:77], v[132:133] op_sel_hi:[1,0,1]
	v_pk_fma_f32 v[134:135], v[12:13], v[76:77], v[134:135] op_sel_hi:[1,0,1]
	v_pk_fma_f32 v[136:137], v[14:15], v[76:77], v[136:137] op_sel_hi:[1,0,1]
	s_waitcnt vmcnt(0)
	v_cvt_scalef32_pk_f32_fp4 v[0:1], v186, 1.0
	v_cvt_scalef32_pk_f32_fp4 v[2:3], v186, 1.0 op_sel:[1,0,0]
	v_cvt_scalef32_pk_f32_fp4 v[4:5], v186, 1.0 op_sel:[0,1,0]
	v_cvt_scalef32_pk_f32_fp4 v[6:7], v186, 1.0 op_sel:[1,1,0]
	v_cvt_scalef32_pk_f32_fp4 v[8:9], v187, 1.0
	v_cvt_scalef32_pk_f32_fp4 v[10:11], v187, 1.0 op_sel:[1,0,0]
	v_cvt_scalef32_pk_f32_fp4 v[12:13], v187, 1.0 op_sel:[0,1,0]
	v_cvt_scalef32_pk_f32_fp4 v[14:15], v187, 1.0 op_sel:[1,1,0]
	s_waitcnt lgkmcnt(0)
; __device__ void peer_gather_phase(const Params& P, int l, bool do_store) {
;     ...
;         y[0] += aa * __builtin_amdgcn_cvt_scalef32_pk_f32_fp4(v8[j].x, 1.0f, 0); y[1] += aa * __builtin_amdgcn_cvt_scalef32_pk_f32_fp4(v8[j].x, 1.0f, 1);
;         y[2] += aa * __builtin_amdgcn_cvt_scalef32_pk_f32_fp4(v8[j].x, 1.0f, 2); y[3] += aa * __builtin_amdgcn_cvt_scalef32_pk_f32_fp4(v8[j].x, 1.0f, 3);
;         y[4] += aa * __builtin_amdgcn_cvt_scalef32_pk_f32_fp4(v8[j].y, 1.0f, 0); y[5] += aa * __builtin_amdgcn_cvt_scalef32_pk_f32_fp4(v8[j].y, 1.0f, 1);
;         y[6] += aa * __builtin_amdgcn_cvt_scalef32_pk_f32_fp4(v8[j].y, 1.0f, 2); y[7] += aa * __builtin_amdgcn_cvt_scalef32_pk_f32_fp4(v8[j].y, 1.0f, 3);
;     ...
;     float* xfp = P.out + (size_t)t * 1024 + lane * 16;
;     float pre[16];
; #pragma unroll
;     for (int k2 = 0; k2 < 8; ++k2) {
;       pre[2 * k2 + 0] = ALPHA_C * xf[k2].x + y[k2].x;
;       pre[2 * k2 + 1] = ALPHA_C * xf[k2].y + y[k2].y;
;     }
;     float sm = 0.f;
; #pragma unroll
;     for (int k = 0; k < 16; ++k) sm += pre[k];
;     const float mean = wave_sum(sm) * (1.f / 1024.f);
;     float vs = 0.f;
; #pragma unroll
;     for (int k = 0; k < 16; ++k) { const float dd = pre[k] - mean; vs += dd * dd; }
;     const float rstd = rsqrtf(wave_sum(vs) * (1.f / 1024.f) + EPS_C);
;     const float* g2 = P.ln2_g + l * 1024 + lane * 16;
;     const float* b2 = P.ln2_b + l * 1024 + lane * 16;
;     float o[16];
; #pragma unroll
;     for (int k4 = 0; k4 < 4; ++k4) {
;       const float4 gg = *(const float4*)(g2 + 4 * k4), bb = *(const float4*)(b2 + 4 * k4);
;       o[4 * k4 + 0] = (pre[4 * k4 + 0] - mean) * rstd * gg.x + bb.x; o[4 * k4 + 1] = (pre[4 * k4 + 1] - mean) * rstd * gg.y + bb.y;
;       o[4 * k4 + 2] = (pre[4 * k4 + 2] - mean) * rstd * gg.z + bb.z; o[4 * k4 + 3] = (pre[4 * k4 + 3] - mean) * rstd * gg.w + bb.w;
;       float4 ov; ov.x = o[4 * k4]; ov.y = o[4 * k4 + 1]; ov.z = o[4 * k4 + 2]; ov.w = o[4 * k4 + 3];
;       if (do_store && l == 1) *(float4*)(xfp + 4 * k4) = ov;
	v_pk_fma_f32 v[130:131], v[0:1], v[194:195], v[130:131] op_sel_hi:[1,0,1]
	v_pk_fma_f32 v[138:139], v[2:3], v[194:195], v[138:139] op_sel_hi:[1,0,1]
	v_pk_fma_f32 v[140:141], v[4:5], v[194:195], v[140:141] op_sel_hi:[1,0,1]
	v_pk_fma_f32 v[142:143], v[6:7], v[194:195], v[142:143] op_sel_hi:[1,0,1]
	v_pk_fma_f32 v[128:129], v[8:9], v[194:195], v[128:129] op_sel_hi:[1,0,1]
	v_pk_fma_f32 v[132:133], v[10:11], v[194:195], v[132:133] op_sel_hi:[1,0,1]
	v_pk_fma_f32 v[134:135], v[12:13], v[194:195], v[134:135] op_sel_hi:[1,0,1]
	v_pk_fma_f32 v[136:137], v[14:15], v[194:195], v[136:137] op_sel_hi:[1,0,1]
	v_lshlrev_b32_e32 v0, 16, v70
	v_lshlrev_b32_e32 v2, 16, v69
	v_and_b32_e32 v3, 0xffff0000, v69
	v_and_b32_e32 v1, 0xffff0000, v70
	s_mov_b32 s0, 0x3fb504f3
	v_pk_fma_f32 v[16:17], v[0:1], s[0:1], v[140:141] op_sel_hi:[1,0,1]
	v_pk_fma_f32 v[18:19], v[2:3], s[0:1], v[138:139] op_sel_hi:[1,0,1]
	global_load_dwordx4 v[0:3], v[82:83], off
	global_load_dwordx4 v[20:23], v[84:85], off
	global_load_dwordx4 v[44:47], v[82:83], off offset:16
	global_load_dwordx4 v[48:51], v[84:85], off offset:16
	global_load_dwordx4 v[52:55], v[82:83], off offset:32
	global_load_dwordx4 v[228:231], v[84:85], off offset:32
	global_load_dwordx4 v[232:235], v[82:83], off offset:48
	global_load_dwordx4 v[236:239], v[84:85], off offset:48
	v_lshlrev_b32_e32 v4, 16, v68
	v_and_b32_e32 v5, 0xffff0000, v68
	v_pk_fma_f32 v[4:5], v[4:5], s[0:1], v[130:131] op_sel_hi:[1,0,1]
	v_lshlrev_b32_e32 v10, 16, v71
	v_add_f32_e32 v24, 0, v4
	v_add_f32_e32 v24, v5, v24
	v_add_f32_e32 v24, v18, v24
	v_add_f32_e32 v24, v19, v24
	v_and_b32_e32 v11, 0xffff0000, v71
	v_add_f32_e32 v24, v16, v24
	v_pk_fma_f32 v[10:11], v[10:11], s[0:1], v[142:143] op_sel_hi:[1,0,1]
	v_add_f32_e32 v24, v17, v24
	v_lshlrev_b32_e32 v6, 16, v64
	v_lshlrev_b32_e32 v8, 16, v66
	v_lshlrev_b32_e32 v12, 16, v65
	v_lshlrev_b32_e32 v14, 16, v67
	v_and_b32_e32 v7, 0xffff0000, v64
	v_and_b32_e32 v13, 0xffff0000, v65
	v_and_b32_e32 v9, 0xffff0000, v66
	v_and_b32_e32 v15, 0xffff0000, v67
	v_add_f32_e32 v24, v10, v24
	v_add_f32_e32 v26, v11, v24
	v_pk_fma_f32 v[24:25], v[14:15], s[0:1], v[136:137] op_sel_hi:[1,0,1]
	v_pk_fma_f32 v[14:15], v[8:9], s[0:1], v[134:135] op_sel_hi:[1,0,1]
	v_pk_fma_f32 v[8:9], v[12:13], s[0:1], v[132:133] op_sel_hi:[1,0,1]
	v_pk_fma_f32 v[12:13], v[6:7], s[0:1], v[128:129] op_sel_hi:[1,0,1]
	v_mov_b32_e32 v7, v177
	v_add_f32_e32 v6, v12, v26
	v_add_f32_e32 v6, v13, v6
	v_add_f32_e32 v6, v8, v6
	v_add_f32_e32 v6, v9, v6
	v_add_f32_e32 v6, v14, v6
	v_add_f32_e32 v6, v15, v6
	v_add_f32_e32 v6, v24, v6
	v_add_f32_e32 v6, v25, v6
	s_nop 1
	v_add_f32_dpp v6, v6, v6 row_shr:1 row_mask:0xf bank_mask:0xf bound_ctrl:1
	s_nop 1
	v_add_f32_dpp v6, v6, v6 row_shr:2 row_mask:0xf bank_mask:0xf bound_ctrl:1
	s_nop 1
	v_add_f32_dpp v6, v6, v6 row_shr:4 row_mask:0xf bank_mask:0xf bound_ctrl:1
	s_nop 1
	v_add_f32_dpp v6, v6, v6 row_shr:8 row_mask:0xf bank_mask:0xf bound_ctrl:1
	s_nop 1
	v_mov_b32_dpp v7, v6 row_bcast:15 row_mask:0xa bank_mask:0xf
	v_add_f32_e32 v6, v6, v7
	v_mov_b32_e32 v7, v177
	s_nop 1
	v_mov_b32_dpp v7, v6 row_bcast:31 row_mask:0xc bank_mask:0xf
	v_add_f32_e32 v6, v6, v7
	s_nop 0
	v_readlane_b32 s0, v6, 63
	s_nop 1
	v_mul_f32_e32 v26, s0, v210
	v_pk_add_f32 v[28:29], v[4:5], v[26:27] op_sel_hi:[1,0] neg_lo:[0,1] neg_hi:[0,1]
	v_pk_add_f32 v[32:33], v[18:19], v[26:27] op_sel_hi:[1,0] neg_lo:[0,1] neg_hi:[0,1]
	v_pk_mul_f32 v[30:31], v[28:29], v[28:29]
	v_pk_mul_f32 v[18:19], v[32:33], v[32:33]
	v_pk_add_f32 v[4:5], v[16:17], v[26:27] op_sel_hi:[1,0] neg_lo:[0,1] neg_hi:[0,1]
	v_pk_add_f32 v[6:7], v[10:11], v[26:27] op_sel_hi:[1,0] neg_lo:[0,1] neg_hi:[0,1]
	v_pk_add_f32 v[10:11], v[12:13], v[26:27] op_sel_hi:[1,0] neg_lo:[0,1] neg_hi:[0,1]
	v_pk_add_f32 v[8:9], v[8:9], v[26:27] op_sel_hi:[1,0] neg_lo:[0,1] neg_hi:[0,1]
	v_pk_add_f32 v[14:15], v[14:15], v[26:27] op_sel_hi:[1,0] neg_lo:[0,1] neg_hi:[0,1]
	v_pk_add_f32 v[12:13], v[24:25], v[26:27] op_sel_hi:[1,0] neg_lo:[0,1] neg_hi:[0,1]
	v_add_f32_e32 v26, v30, v31
	v_add_f32_e32 v18, v18, v26
	v_pk_mul_f32 v[16:17], v[4:5], v[4:5]
	v_add_f32_e32 v18, v19, v18
	v_add_f32_e32 v16, v16, v18
	v_pk_mul_f32 v[34:35], v[6:7], v[6:7]
	v_add_f32_e32 v16, v17, v16
	v_add_f32_e32 v16, v34, v16
	v_pk_mul_f32 v[36:37], v[10:11], v[10:11]
	v_add_f32_e32 v16, v35, v16
	v_add_f32_e32 v16, v36, v16
	v_pk_mul_f32 v[38:39], v[8:9], v[8:9]
	v_add_f32_e32 v16, v37, v16
	v_add_f32_e32 v16, v38, v16
	v_pk_mul_f32 v[40:41], v[14:15], v[14:15]
	v_add_f32_e32 v16, v39, v16
	v_add_f32_e32 v16, v40, v16
	v_pk_mul_f32 v[24:25], v[12:13], v[12:13]
	v_add_f32_e32 v16, v41, v16
	v_add_f32_e32 v16, v24, v16
	v_add_f32_e32 v16, v25, v16
	v_mov_b32_e32 v17, v177
	s_nop 0
	v_add_f32_dpp v16, v16, v16 row_shr:1 row_mask:0xf bank_mask:0xf bound_ctrl:1
	s_nop 1
	v_add_f32_dpp v16, v16, v16 row_shr:2 row_mask:0xf bank_mask:0xf bound_ctrl:1
	s_nop 1
	v_add_f32_dpp v16, v16, v16 row_shr:4 row_mask:0xf bank_mask:0xf bound_ctrl:1
	s_nop 1
	v_add_f32_dpp v16, v16, v16 row_shr:8 row_mask:0xf bank_mask:0xf bound_ctrl:1
	s_nop 1
	v_mov_b32_dpp v17, v16 row_bcast:15 row_mask:0xa bank_mask:0xf
	v_add_f32_e32 v16, v16, v17
	v_mov_b32_e32 v17, v177
	s_nop 1
	v_mov_b32_dpp v17, v16 row_bcast:31 row_mask:0xc bank_mask:0xf
	v_add_f32_e32 v16, v16, v17
	s_nop 0
	v_readlane_b32 s0, v16, 63
	s_nop 1
	v_fma_f32 v16, s0, v210, v203
	s_mov_b32 s0, 0x800000
	v_mul_f32_e32 v17, 0x4b800000, v16
	v_cmp_gt_f32_e32 vcc, s0, v16
	s_nop 1
	v_cndmask_b32_e32 v16, v16, v17, vcc
	v_rsq_f32_e32 v18, v16
	v_lshl_add_u64 v[16:17], v[94:95], 2, v[80:81]
	v_mul_f32_e32 v19, 0x45800000, v18
	v_cndmask_b32_e32 v18, v18, v19, vcc
	v_pk_mul_f32 v[24:25], v[28:29], v[18:19] op_sel_hi:[1,0]
	s_and_b64 vcc, exec, s[38:39]
	s_waitcnt vmcnt(0)
	v_pk_fma_f32 v[0:1], v[0:1], v[24:25], v[20:21]
	v_pk_mul_f32 v[20:21], v[32:33], v[18:19] op_sel_hi:[1,0]
	s_nop 0
	v_pk_fma_f32 v[2:3], v[2:3], v[20:21], v[22:23]
	s_cbranch_vccz .LBB0_25
	global_store_dwordx4 v[16:17], v[0:3], off
